# GEMM phases: per-segment s_setprio toggles removed; one static s_setprio 1 for the trailing half-workgroup (waves 4-7) per phase, reset at the phase join
# speedup vs baseline: 1.0019x; 1.0019x over previous
; #define PG8_WAIT_V(n) asm volatile("s_waitcnt vmcnt(" #n ")" ::: "memory")
; template <class Epi, class Sched, bool ALIGN_EPI = false, bool SP2 = false>
; __device__ __forceinline__ void gemm_phase(PG8_LAS unsigned char* lds, const Gemm g, const Sched& S, const Epi& E) {
;     const int tid = threadIdx.x, wid = __builtin_amdgcn_readfirstlane(tid >> 6), lane = tid & 63, wr = wid >> 2, wc = wid & 3, fr = lane & 15, fq = lane >> 4;
;     const int K = g.K, nt = K / BK, LD = g.ld ? g.ld : g.K;
;     unsigned voffA[2], voffB[2];
; #pragma unroll
;     for (int i = 0; i < 2; ++i) { int R, C; stage_rc(tid * 16 + i * 8192, R, C); const int Rb = Epi::PERM ? ((R & ~31) + perm32(R & 31)) : R;
;         voffA[i] = (unsigned)(R * LD + C) * 2u; voffB[i] = (unsigned)(Rb * LD + C) * 2u; }
;     const size_t kstep = (size_t)(BK * 2);
;     const size_t hstep = (size_t)HALF * LD * 2;
;     const size_t tstep = 2 * hstep;
;     const unsigned ldsw = (unsigned)wid * 1024u;
;     const int aoff = lds_byte(wr * 64 + fr, fq * 8), boff = lds_byte(wc * 32 + fr, fq * 8);
;     ...
;     Unit cur, nxt; int ui = 0;
;     if (!S.next(0, cur)) return;
;     f32x4 acc[2][2][4][2];
; #pragma unroll
;     for (int a = 0; a < 2; ++a)
; #pragma unroll
;         for (int b = 0; b < 2; ++b)
; #pragma unroll
;             for (int m = 0; m < 4; ++m)
; #pragma unroll
;                 for (int n = 0; n < 2; ++n) acc[a][b][m][n] = (f32x4){0.f, 0.f, 0.f, 0.f};
;     bf16x8 At[4][2], B0[2][2], B1[2][2];
;     const char* cA = (const char*)g.A + (size_t)cur.pm * tstep + (size_t)cur.ks * K * 2; const char* cB = (const char*)g.Bt + (size_t)cur.pn * tstep + (size_t)cur.ks * K * 2;
;     S.a_ready(cur);
;     if constexpr (SP2) {
;         PG8_STAGE(PG8_SB(0, 0), cB, voffB); PG8_STAGE(PG8_SB(0, 1), cB + hstep, voffB); PG8_STAGE(PG8_SA(0, 0), cA, voffA); PG8_STAGE(PG8_SA(0, 1), cA + hstep, voffA);
;         if (wr == 1) PG8_BAR;
;         PG8_WAIT_V(2); PG8_BAR;
;         PG8_STAGE(PG8_SB(1, 0), cB + kstep, voffB); PG8_STAGE(PG8_SA(1, 0), cA + kstep, voffA); PG8_STAGE(PG8_SB(1, 1), cB + hstep + kstep, voffB);
;         PG8_WAIT_V(6); PG8_BAR;
;     ...
;             pg8::Gemm g{AC, (bf16*)(ws + WS_WIN), ML, INCP, D}; pg8::StaticOrder S; S.init(ML, INCP, (int)gridDim.x, (int)blockIdx.x);
;             EpiStoreBf16<0> E{Z, INCP};
;             pg8::gemm_phase<EpiStoreBf16<0>, pg8::StaticOrder, true, true>(lds, g, S, E); }
.LBB0_113:
	s_waitcnt lgkmcnt(0)
	s_load_dwordx16 s[4:19], s[0:1], 0x80
	s_cmp_lt_i32 s72, 3
	s_cselect_b64 s[0:1], -1, 0
	s_cmp_gt_i32 s73, 2
	s_waitcnt lgkmcnt(0)
	v_writelane_b32 v246, s4, 39
	s_nop 1
	v_writelane_b32 v246, s5, 40
	v_writelane_b32 v246, s6, 41
	v_writelane_b32 v246, s7, 42
	v_writelane_b32 v246, s8, 43
	v_writelane_b32 v246, s9, 44
	v_writelane_b32 v246, s10, 45
	v_writelane_b32 v246, s11, 46
	v_writelane_b32 v246, s12, 47
	v_writelane_b32 v246, s13, 48
	v_writelane_b32 v246, s14, 49
	v_writelane_b32 v246, s15, 50
	v_writelane_b32 v246, s16, 51
	v_writelane_b32 v246, s17, 52
	v_writelane_b32 v246, s18, 53
	v_writelane_b32 v246, s19, 54
	s_cselect_b64 s[4:5], -1, 0
	s_and_b64 s[0:1], s[0:1], s[4:5]
	s_andn2_b64 vcc, exec, s[0:1]
	s_cbranch_vccnz .LBB0_255
	v_readfirstlane_b32 vcc_lo, v174
	s_bitcmp1_b32 vcc_lo, 8
	s_cbranch_scc0 .Lsp_1
	s_setprio 1
.Lsp_1:
	s_add_u32 s3, s70, 0x100000
	v_lshlrev_b32_e32 v0, 6, v174
	s_addc_u32 s6, s71, 0
	v_and_b32_e32 v148, 0x3c0, v0
	v_lshlrev_b32_e32 v0, 2, v174
	v_readlane_b32 s2, v246, 0
	v_readfirstlane_b32 s1, v174
	v_and_b32_e32 v149, 15, v174
	s_cmpk_gt_i32 s2, 0x5ff
	v_and_b32_e32 v150, 32, v0
	s_cbranch_scc1 .LBB0_130
	v_lshrrev_b32_e32 v0, 5, v174
	v_lshrrev_b32_e32 v2, 1, v174
	v_and_b32_e32 v0, 4, v0
	v_bfe_u32 v1, v174, 2, 2
	v_and_b32_e32 v11, 24, v2
	v_or3_b32 v0, v0, v1, v11
	v_lshlrev_b32_e32 v1, 4, v174
	v_add_u32_e32 v8, 0x2000, v1
	v_lshrrev_b32_e32 v2, 7, v8
	s_movk_i32 s0, 0xe0
	v_and_b32_e32 v4, 32, v174
	v_and_or_b32 v3, v2, s0, v0
	v_bitop3_b32 v9, v1, v4, 48 bitop3:0x6c
	v_and_b32_e32 v10, 64, v174
	v_bfe_u32 v12, v174, 2, 4
	s_movk_i32 s0, 0xf0
	v_or_b32_e32 v1, v9, v10
	v_and_or_b32 v2, v2, s0, v12
	s_add_u32 s7, s70, 0x6700000
	v_lshl_or_b32 v130, v2, 12, v1
	v_lshrrev_b32_e32 v2, 3, v174
	s_movk_i32 s0, 0x60
	s_addc_u32 s28, s71, 0
	v_and_or_b32 v0, v2, s0, v0
	s_movk_i32 s0, 0x70
	s_ashr_i32 s33, s2, 31
	v_lshl_or_b32 v132, v0, 12, v1
	v_and_or_b32 v0, v2, s0, v12
	s_lshr_b32 s0, s33, 29
	s_add_i32 s0, s2, s0
	s_lshr_b32 s10, s1, 6
	s_ashr_i32 s4, s0, 3
	s_and_b32 s0, s0, -8
	s_lshr_b32 s30, s1, 8
	s_lshl_b32 s29, s10, 10
	s_sub_i32 s0, s2, s0
	s_cmp_lt_i32 s0, 0
	s_movk_i32 s52, 0xc1
	s_cselect_b32 s5, s52, 0xc0
	s_mul_i32 s0, s5, s0
	s_add_i32 s0, s0, s4
	s_mul_hi_i32 s4, s0, 0x2aaaaaab
	s_lshr_b32 s5, s4, 31
	s_ashr_i32 s4, s4, 5
	s_add_i32 s4, s4, s5
	s_lshl_b32 s5, s4, 3
	s_mulk_i32 s4, 0xc0
	s_sub_i32 s4, s0, s4
	s_sext_i32_i16 s0, s4
	s_bfe_u32 s0, s0, 0x3001c
	s_add_i32 s8, s4, s0
	s_sext_i32_i16 s0, s8
	s_and_b32 s8, s8, 0xfff8
	s_sub_i32 s4, s4, s8
	s_sext_i32_i16 s4, s4
	s_lshr_b32 s0, s0, 3
	s_add_i32 s62, s5, s4
	s_ashr_i32 s63, s62, 31
	s_bfe_i64 s[8:9], s[0:1], 0x100000
	s_lshl_b64 s[4:5], s[62:63], 20
	s_lshl_b64 s[8:9], s[8:9], 20
	s_add_u32 s86, s3, s8
	s_addc_u32 s87, s6, s9
	s_add_i32 s53, s29, 0
	s_add_i32 m0, s53, 0x10000
	v_lshl_or_b32 v128, v3, 12, v1
	global_load_lds_dwordx4 v132, s[86:87]
	s_add_i32 m0, s53, 0x12000
	s_add_u32 s8, s86, 0x80000
	global_load_lds_dwordx4 v128, s[86:87]
	s_addc_u32 s9, s87, 0
	s_add_i32 m0, s53, 0x14000
	v_lshl_or_b32 v134, v0, 12, v1
	global_load_lds_dwordx4 v132, s[8:9]
	s_add_i32 m0, s53, 0x16000
	s_add_u32 s76, s7, s4
	s_addc_u32 s77, s28, s5
	s_add_i32 s56, s53, 0x2000
	global_load_lds_dwordx4 v128, s[8:9]
	s_mov_b32 m0, s53
	s_add_u32 s4, s76, 0x80000
	global_load_lds_dwordx4 v134, s[76:77]
	s_mov_b32 m0, s56
	s_addc_u32 s5, s77, 0
	s_add_i32 s57, s53, 0x4000
	global_load_lds_dwordx4 v130, s[76:77]
	s_mov_b32 m0, s57
	s_add_i32 s63, s53, 0x6000
	global_load_lds_dwordx4 v134, s[4:5]
	s_mov_b32 m0, s63
	v_mov_b32_e32 v133, 0
	global_load_lds_dwordx4 v130, s[4:5]
	v_mov_b32_e32 v129, v133
	v_mov_b32_e32 v135, v133
	v_mov_b32_e32 v131, v133
	s_cmp_eq_u32 s30, 1
	s_mov_b32 s64, 0
	v_lshl_add_u64 v[6:7], s[86:87], 0, v[132:133]
	v_lshl_add_u64 v[4:5], s[86:87], 0, v[128:129]
	v_lshl_add_u64 v[0:1], s[76:77], 0, v[134:135]
	s_cselect_b64 s[4:5], -1, 0
	s_cmp_lg_u32 s30, 1
	v_lshl_add_u64 v[2:3], s[76:77], 0, v[130:131]
	s_cbranch_scc1 .LBB0_117
	s_barrier

; #define PG8_STAGE(bufoff, gbase, voff) do { _Pragma("unroll") for (int _i = 0; _i < 2; ++_i) \
;         __builtin_amdgcn_global_load_lds((const unsigned*)((const char*)(gbase) + (voff)[_i]), (PG8_LAS unsigned*)(lds + (bufoff) + ldsw + _i * 8192), 16, 0, 0); } while (0)
; #define PG8_LDA(dst, b, h) do { _Pragma("unroll") for (int m = 0; m < 4; ++m) _Pragma("unroll") for (int k = 0; k < 2; ++k) dst[m][k] = *(const PG8_LAS bf16x8*)(lds + PG8_SA(b, h) + aoff + m * 2048 + k * 1024); } while (0)
; #define PG8_LDB(dst, b, h) do { _Pragma("unroll") for (int n = 0; n < 2; ++n) _Pragma("unroll") for (int k = 0; k < 2; ++k) dst[n][k] = *(const PG8_LAS bf16x8*)(lds + PG8_SB(b, h) + boff + n * 2048 + k * 1024); } while (0)
; #define PG8_MMA(ai, bj, At, Bt) do { __builtin_amdgcn_s_setprio(1); _Pragma("unroll") for (int m = 0; m < 4; ++m) _Pragma("unroll") for (int n = 0; n < 2; ++n) _Pragma("unroll") for (int k = 0; k < 2; ++k) \
;         acc[ai][bj][m][n] = __builtin_amdgcn_mfma_f32_16x16x32_bf16(Bt[n][k], At[m][k], acc[ai][bj][m][n], 0, 0, 0); __builtin_amdgcn_s_setprio(0); } while (0)
; #define PG8_WAIT_V(n) asm volatile("s_waitcnt vmcnt(" #n ")" ::: "memory")
; template <class Epi, class Sched, bool ALIGN_EPI = false, bool SP2 = false>
; __device__ __forceinline__ void gemm_phase(PG8_LAS unsigned char* lds, const Gemm g, const Sched& S, const Epi& E) {
;     ...
;             PG8_LDB(B0, 0, 0); PG8_LDB(B1, 0, 1); PG8_SCHED; PG8_LDA(At, 0, 0); PG8_STAGE(PG8_SA(1, 1), a1 + hstep, voffA);
;             PG8_WAIT_V(8); PG8_WAIT_L(0); PG8_BAR; PG8_MMA(0, 0, At, B0); PG8_MMA(0, 1, At, B1); PG8_BAR; PG8_SCHED;
;             PG8_LDA(At, 0, 1); PG8_STAGE(PG8_SB(0, 0), b2, voffB); PG8_STAGE(PG8_SB(0, 1), b2 + hstep, voffB); PG8_STAGE(PG8_SA(0, 0), a2, voffA);
;             PG8_WAIT_V(8); PG8_WAIT_L(0); PG8_BAR; PG8_MMA(1, 0, At, B0); PG8_MMA(1, 1, At, B1); PG8_BAR; PG8_SCHED;
;             PG8_LDB(B0, 1, 0); PG8_LDB(B1, 1, 1); PG8_SCHED; PG8_LDA(At, 1, 0); PG8_STAGE(PG8_SA(0, 1), a2 + hstep, voffA);
;             PG8_WAIT_V(8); PG8_WAIT_L(0); PG8_BAR; PG8_MMA(0, 0, At, B0); PG8_MMA(0, 1, At, B1); PG8_BAR; PG8_SCHED;
;             PG8_LDA(At, 1, 1); PG8_STAGE(PG8_SB(1, 0), b3, voffB); PG8_STAGE(PG8_SB(1, 1), b3 + hstep, voffB); PG8_STAGE(PG8_SA(1, 0), a3, voffA);
;             PG8_WAIT_V(8); PG8_WAIT_L(0); PG8_BAR; PG8_MMA(1, 0, At, B0); PG8_MMA(1, 1, At, B1); PG8_BAR; PG8_SCHED;
.LBB0_123:
	ds_read_b128 v[144:147], v154
	ds_read_b128 v[158:161], v154 offset:1024
	ds_read_b128 v[162:165], v154 offset:2048
	ds_read_b128 v[166:169], v154 offset:3072
	ds_read_b128 v[170:173], v155
	ds_read_b128 v[176:179], v155 offset:1024
	ds_read_b128 v[180:183], v155 offset:2048
	ds_read_b128 v[184:187], v155 offset:3072
	s_add_u32 s68, s84, 0xfff80080
	s_addc_u32 s69, s85, -1
	s_cmp_eq_u32 s91, 28
	s_cselect_b32 s79, s55, s69
	s_cselect_b32 s78, s89, s68
	s_cselect_b32 s77, s35, s87
	s_cselect_b32 s76, s90, s86
	v_lshl_add_u64 v[220:221], s[84:85], 0, v[136:137]
	s_add_i32 m0, s53, 0xc000
	ds_read_b128 v[188:191], v156
	ds_read_b128 v[192:195], v156 offset:1024
	ds_read_b128 v[196:199], v156 offset:2048
	ds_read_b128 v[200:203], v156 offset:3072
	ds_read_b128 v[204:207], v156 offset:4096
	ds_read_b128 v[208:211], v156 offset:5120
	ds_read_b128 v[212:215], v156 offset:6144
	ds_read_b128 v[216:219], v156 offset:7168
	global_load_lds_dwordx4 v[220:221], off
	v_lshl_add_u64 v[220:221], s[84:85], 0, v[138:139]
	s_add_i32 m0, s53, 0xe000
	s_nop 0
	global_load_lds_dwordx4 v[220:221], off
	s_waitcnt vmcnt(8)
	s_waitcnt lgkmcnt(0)
	s_barrier
	s_waitcnt lgkmcnt(0)
	v_mfma_f32_16x16x32_bf16 v[124:127], v[144:147], v[188:191], v[124:127]
	v_mfma_f32_16x16x32_bf16 v[120:123], v[162:165], v[188:191], v[120:123]
	v_mfma_f32_16x16x32_bf16 v[116:119], v[144:147], v[196:199], v[116:119]
	v_mfma_f32_16x16x32_bf16 v[108:111], v[162:165], v[196:199], v[108:111]
	v_mfma_f32_16x16x32_bf16 v[100:103], v[144:147], v[204:207], v[100:103]
	v_mfma_f32_16x16x32_bf16 v[92:95], v[162:165], v[204:207], v[92:95]
	v_mfma_f32_16x16x32_bf16 v[84:87], v[144:147], v[212:215], v[84:87]
	v_mfma_f32_16x16x32_bf16 v[76:79], v[162:165], v[212:215], v[76:79]
	v_mfma_f32_16x16x32_bf16 v[124:127], v[158:161], v[192:195], v[124:127]
	v_mfma_f32_16x16x32_bf16 v[120:123], v[166:169], v[192:195], v[120:123]
	v_mfma_f32_16x16x32_bf16 v[116:119], v[158:161], v[200:203], v[116:119]
	v_mfma_f32_16x16x32_bf16 v[108:111], v[166:169], v[200:203], v[108:111]
	v_mfma_f32_16x16x32_bf16 v[100:103], v[158:161], v[208:211], v[100:103]
	v_mfma_f32_16x16x32_bf16 v[92:95], v[166:169], v[208:211], v[92:95]
	v_mfma_f32_16x16x32_bf16 v[84:87], v[158:161], v[216:219], v[84:87]
	v_mfma_f32_16x16x32_bf16 v[76:79], v[166:169], v[216:219], v[76:79]
	v_mfma_f32_16x16x32_bf16 v[112:115], v[170:173], v[188:191], v[112:115]
	v_mfma_f32_16x16x32_bf16 v[104:107], v[180:183], v[188:191], v[104:107]
	v_mfma_f32_16x16x32_bf16 v[96:99], v[170:173], v[196:199], v[96:99]
	v_mfma_f32_16x16x32_bf16 v[88:91], v[180:183], v[196:199], v[88:91]
	v_mfma_f32_16x16x32_bf16 v[80:83], v[170:173], v[204:207], v[80:83]
	v_mfma_f32_16x16x32_bf16 v[72:75], v[180:183], v[204:207], v[72:75]
	v_mfma_f32_16x16x32_bf16 v[68:71], v[170:173], v[212:215], v[68:71]
	v_mfma_f32_16x16x32_bf16 v[64:67], v[180:183], v[212:215], v[64:67]
	v_mfma_f32_16x16x32_bf16 v[112:115], v[176:179], v[192:195], v[112:115]
	v_mfma_f32_16x16x32_bf16 v[104:107], v[184:187], v[192:195], v[104:107]
	v_mfma_f32_16x16x32_bf16 v[96:99], v[176:179], v[200:203], v[96:99]
	v_mfma_f32_16x16x32_bf16 v[88:91], v[184:187], v[200:203], v[88:91]
	v_mfma_f32_16x16x32_bf16 v[80:83], v[176:179], v[208:211], v[80:83]
	v_mfma_f32_16x16x32_bf16 v[72:75], v[184:187], v[208:211], v[72:75]
	v_mfma_f32_16x16x32_bf16 v[68:71], v[176:179], v[216:219], v[68:71]
	v_mfma_f32_16x16x32_bf16 v[64:67], v[184:187], v[216:219], v[64:67]
	s_barrier
	s_add_i32 s68, s81, s29
	v_lshl_add_u64 v[220:221], s[76:77], 0, v[132:133]
	s_mov_b32 m0, s68
	ds_read_b128 v[188:191], v156 offset:16384
	ds_read_b128 v[192:195], v156 offset:17408
	ds_read_b128 v[196:199], v156 offset:18432
	ds_read_b128 v[200:203], v156 offset:19456
	ds_read_b128 v[204:207], v156 offset:20480
	ds_read_b128 v[208:211], v156 offset:21504
	ds_read_b128 v[212:215], v156 offset:22528
	ds_read_b128 v[216:219], v156 offset:23552
	global_load_lds_dwordx4 v[220:221], off
	s_add_i32 m0, s68, 0x2000
	s_add_u32 s68, s76, 0x80000
	v_lshl_add_u64 v[222:223], s[76:77], 0, v[128:129]
	s_addc_u32 s69, s77, 0
	s_add_i32 s70, s82, s29
	global_load_lds_dwordx4 v[222:223], off
	v_lshl_add_u64 v[224:225], s[68:69], 0, v[132:133]
	s_mov_b32 m0, s70
	v_lshl_add_u64 v[226:227], s[78:79], 0, v[130:131]
	global_load_lds_dwordx4 v[224:225], off
	v_lshl_add_u64 v[224:225], s[68:69], 0, v[128:129]
	s_add_i32 m0, s70, 0x2000
	s_nop 0
	global_load_lds_dwordx4 v[224:225], off
	v_lshl_add_u64 v[224:225], s[78:79], 0, v[134:135]
	s_mov_b32 m0, s53
	s_nop 0
	global_load_lds_dwordx4 v[224:225], off
	s_mov_b32 m0, s56
	s_nop 0
	global_load_lds_dwordx4 v[226:227], off
	s_waitcnt vmcnt(8)
	s_waitcnt lgkmcnt(0)
	s_barrier
; #define PG8_STAGE(bufoff, gbase, voff) do { _Pragma("unroll") for (int _i = 0; _i < 2; ++_i) \
;         __builtin_amdgcn_global_load_lds((const unsigned*)((const char*)(gbase) + (voff)[_i]), (PG8_LAS unsigned*)(lds + (bufoff) + ldsw + _i * 8192), 16, 0, 0); } while (0)
; #define PG8_LDA(dst, b, h) do { _Pragma("unroll") for (int m = 0; m < 4; ++m) _Pragma("unroll") for (int k = 0; k < 2; ++k) dst[m][k] = *(const PG8_LAS bf16x8*)(lds + PG8_SA(b, h) + aoff + m * 2048 + k * 1024); } while (0)
; #define PG8_LDB(dst, b, h) do { _Pragma("unroll") for (int n = 0; n < 2; ++n) _Pragma("unroll") for (int k = 0; k < 2; ++k) dst[n][k] = *(const PG8_LAS bf16x8*)(lds + PG8_SB(b, h) + boff + n * 2048 + k * 1024); } while (0)
; #define PG8_MMA(ai, bj, At, Bt) do { __builtin_amdgcn_s_setprio(1); _Pragma("unroll") for (int m = 0; m < 4; ++m) _Pragma("unroll") for (int n = 0; n < 2; ++n) _Pragma("unroll") for (int k = 0; k < 2; ++k) \
;         acc[ai][bj][m][n] = __builtin_amdgcn_mfma_f32_16x16x32_bf16(Bt[n][k], At[m][k], acc[ai][bj][m][n], 0, 0, 0); __builtin_amdgcn_s_setprio(0); } while (0)
; #define PG8_WAIT_V(n) asm volatile("s_waitcnt vmcnt(" #n ")" ::: "memory")
; template <class Epi, class Sched, bool ALIGN_EPI = false, bool SP2 = false>
; __device__ __forceinline__ void gemm_phase(PG8_LAS unsigned char* lds, const Gemm g, const Sched& S, const Epi& E) {
;     ...
;             PG8_LDB(B0, 0, 0); PG8_LDB(B1, 0, 1); PG8_SCHED; PG8_LDA(At, 0, 0); PG8_STAGE(PG8_SA(1, 1), a1 + hstep, voffA);
;             PG8_WAIT_V(8); PG8_WAIT_L(0); PG8_BAR; PG8_MMA(0, 0, At, B0); PG8_MMA(0, 1, At, B1); PG8_BAR; PG8_SCHED;
;             PG8_LDA(At, 0, 1); PG8_STAGE(PG8_SB(0, 0), b2, voffB); PG8_STAGE(PG8_SB(0, 1), b2 + hstep, voffB); PG8_STAGE(PG8_SA(0, 0), a2, voffA);
;             PG8_WAIT_V(8); PG8_WAIT_L(0); PG8_BAR; PG8_MMA(1, 0, At, B0); PG8_MMA(1, 1, At, B1); PG8_BAR; PG8_SCHED;
;             PG8_LDB(B0, 1, 0); PG8_LDB(B1, 1, 1); PG8_SCHED; PG8_LDA(At, 1, 0); PG8_STAGE(PG8_SA(0, 1), a2 + hstep, voffA);
;             PG8_WAIT_V(8); PG8_WAIT_L(0); PG8_BAR; PG8_MMA(0, 0, At, B0); PG8_MMA(0, 1, At, B1); PG8_BAR; PG8_SCHED;
;             PG8_LDA(At, 1, 1); PG8_STAGE(PG8_SB(1, 0), b3, voffB); PG8_STAGE(PG8_SB(1, 1), b3 + hstep, voffB); PG8_STAGE(PG8_SA(1, 0), a3, voffA);
;             PG8_WAIT_V(8); PG8_WAIT_L(0); PG8_BAR; PG8_MMA(1, 0, At, B0); PG8_MMA(1, 1, At, B1); PG8_BAR; PG8_SCHED;
	s_waitcnt lgkmcnt(0)
	v_mfma_f32_16x16x32_bf16 v[60:63], v[144:147], v[188:191], v[60:63]
	v_mfma_f32_16x16x32_bf16 v[56:59], v[162:165], v[188:191], v[56:59]
	v_mfma_f32_16x16x32_bf16 v[52:55], v[144:147], v[196:199], v[52:55]
	v_mfma_f32_16x16x32_bf16 v[44:47], v[162:165], v[196:199], v[44:47]
	v_mfma_f32_16x16x32_bf16 v[36:39], v[144:147], v[204:207], v[36:39]
	v_mfma_f32_16x16x32_bf16 v[28:31], v[162:165], v[204:207], v[28:31]
	v_mfma_f32_16x16x32_bf16 v[20:23], v[144:147], v[212:215], v[20:23]
	v_mfma_f32_16x16x32_bf16 v[12:15], v[162:165], v[212:215], v[12:15]
	v_mfma_f32_16x16x32_bf16 v[60:63], v[158:161], v[192:195], v[60:63]
	v_mfma_f32_16x16x32_bf16 v[56:59], v[166:169], v[192:195], v[56:59]
	v_mfma_f32_16x16x32_bf16 v[52:55], v[158:161], v[200:203], v[52:55]
	v_mfma_f32_16x16x32_bf16 v[44:47], v[166:169], v[200:203], v[44:47]
	v_mfma_f32_16x16x32_bf16 v[36:39], v[158:161], v[208:211], v[36:39]
	v_mfma_f32_16x16x32_bf16 v[28:31], v[166:169], v[208:211], v[28:31]
	v_mfma_f32_16x16x32_bf16 v[20:23], v[158:161], v[216:219], v[20:23]
	v_mfma_f32_16x16x32_bf16 v[12:15], v[166:169], v[216:219], v[12:15]
	v_mfma_f32_16x16x32_bf16 v[48:51], v[170:173], v[188:191], v[48:51]
	v_mfma_f32_16x16x32_bf16 v[40:43], v[180:183], v[188:191], v[40:43]
	v_mfma_f32_16x16x32_bf16 v[32:35], v[170:173], v[196:199], v[32:35]
	v_mfma_f32_16x16x32_bf16 v[24:27], v[180:183], v[196:199], v[24:27]
	v_mfma_f32_16x16x32_bf16 v[16:19], v[170:173], v[204:207], v[16:19]
	v_mfma_f32_16x16x32_bf16 v[8:11], v[180:183], v[204:207], v[8:11]
	v_mfma_f32_16x16x32_bf16 v[4:7], v[170:173], v[212:215], v[4:7]
	v_mfma_f32_16x16x32_bf16 v[0:3], v[180:183], v[212:215], v[0:3]
	v_mfma_f32_16x16x32_bf16 v[48:51], v[176:179], v[192:195], v[48:51]
	v_mfma_f32_16x16x32_bf16 v[40:43], v[184:187], v[192:195], v[40:43]
	v_mfma_f32_16x16x32_bf16 v[32:35], v[176:179], v[200:203], v[32:35]
	v_mfma_f32_16x16x32_bf16 v[24:27], v[184:187], v[200:203], v[24:27]
	v_mfma_f32_16x16x32_bf16 v[16:19], v[176:179], v[208:211], v[16:19]
	v_mfma_f32_16x16x32_bf16 v[8:11], v[184:187], v[208:211], v[8:11]
	v_mfma_f32_16x16x32_bf16 v[4:7], v[176:179], v[216:219], v[4:7]
	v_mfma_f32_16x16x32_bf16 v[0:3], v[184:187], v[216:219], v[0:3]
	s_barrier
	s_add_i32 s70, 0, 0x18000
	v_add_u32_e32 v157, s70, v152
	s_add_i32 s71, 0, 0x1c000
	ds_read_b128 v[144:147], v157
	ds_read_b128 v[158:161], v157 offset:1024
	ds_read_b128 v[162:165], v157 offset:2048
	ds_read_b128 v[166:169], v157 offset:3072
	v_add_u32_e32 v157, s71, v152
	ds_read_b128 v[170:173], v157
	ds_read_b128 v[176:179], v157 offset:1024
	ds_read_b128 v[180:183], v157 offset:2048
	ds_read_b128 v[184:187], v157 offset:3072
	s_add_u32 s68, s78, 0x80000
	s_addc_u32 s69, s79, 0
	s_mov_b32 m0, s57
	v_lshl_add_u64 v[228:229], s[68:69], 0, v[134:135]
	ds_read_b128 v[188:191], v156 offset:32768
	ds_read_b128 v[192:195], v156 offset:33792
	ds_read_b128 v[196:199], v156 offset:34816
	ds_read_b128 v[200:203], v156 offset:35840
	ds_read_b128 v[204:207], v156 offset:36864
	ds_read_b128 v[208:211], v156 offset:37888
	ds_read_b128 v[212:215], v156 offset:38912
	ds_read_b128 v[216:219], v156 offset:39936
	global_load_lds_dwordx4 v[228:229], off
	v_lshl_add_u64 v[228:229], s[68:69], 0, v[130:131]
	s_mov_b32 m0, s63
	s_nop 0
	global_load_lds_dwordx4 v[228:229], off
	s_waitcnt vmcnt(8)
	s_waitcnt lgkmcnt(0)
	s_barrier
	s_waitcnt lgkmcnt(0)
	v_mfma_f32_16x16x32_bf16 v[124:127], v[144:147], v[188:191], v[124:127]
	v_mfma_f32_16x16x32_bf16 v[120:123], v[162:165], v[188:191], v[120:123]
	v_mfma_f32_16x16x32_bf16 v[116:119], v[144:147], v[196:199], v[116:119]
	v_mfma_f32_16x16x32_bf16 v[108:111], v[162:165], v[196:199], v[108:111]
	v_mfma_f32_16x16x32_bf16 v[100:103], v[144:147], v[204:207], v[100:103]
	v_mfma_f32_16x16x32_bf16 v[92:95], v[162:165], v[204:207], v[92:95]
	v_mfma_f32_16x16x32_bf16 v[84:87], v[144:147], v[212:215], v[84:87]
	v_mfma_f32_16x16x32_bf16 v[76:79], v[162:165], v[212:215], v[76:79]
	v_mfma_f32_16x16x32_bf16 v[124:127], v[158:161], v[192:195], v[124:127]
	v_mfma_f32_16x16x32_bf16 v[120:123], v[166:169], v[192:195], v[120:123]
	v_mfma_f32_16x16x32_bf16 v[116:119], v[158:161], v[200:203], v[116:119]
	v_mfma_f32_16x16x32_bf16 v[108:111], v[166:169], v[200:203], v[108:111]
	v_mfma_f32_16x16x32_bf16 v[100:103], v[158:161], v[208:211], v[100:103]
	v_mfma_f32_16x16x32_bf16 v[92:95], v[166:169], v[208:211], v[92:95]
	v_mfma_f32_16x16x32_bf16 v[84:87], v[158:161], v[216:219], v[84:87]
	v_mfma_f32_16x16x32_bf16 v[76:79], v[166:169], v[216:219], v[76:79]
	v_mfma_f32_16x16x32_bf16 v[112:115], v[170:173], v[188:191], v[112:115]
	v_mfma_f32_16x16x32_bf16 v[104:107], v[180:183], v[188:191], v[104:107]
	v_mfma_f32_16x16x32_bf16 v[96:99], v[170:173], v[196:199], v[96:99]
	v_mfma_f32_16x16x32_bf16 v[88:91], v[180:183], v[196:199], v[88:91]
	v_mfma_f32_16x16x32_bf16 v[80:83], v[170:173], v[204:207], v[80:83]
	v_mfma_f32_16x16x32_bf16 v[72:75], v[180:183], v[204:207], v[72:75]
	v_mfma_f32_16x16x32_bf16 v[68:71], v[170:173], v[212:215], v[68:71]
	v_mfma_f32_16x16x32_bf16 v[64:67], v[180:183], v[212:215], v[64:67]
	v_mfma_f32_16x16x32_bf16 v[112:115], v[176:179], v[192:195], v[112:115]
	v_mfma_f32_16x16x32_bf16 v[104:107], v[184:187], v[192:195], v[104:107]
	v_mfma_f32_16x16x32_bf16 v[96:99], v[176:179], v[200:203], v[96:99]
	v_mfma_f32_16x16x32_bf16 v[88:91], v[184:187], v[200:203], v[88:91]
	v_mfma_f32_16x16x32_bf16 v[80:83], v[176:179], v[208:211], v[80:83]
	v_mfma_f32_16x16x32_bf16 v[72:75], v[184:187], v[208:211], v[72:75]
	v_mfma_f32_16x16x32_bf16 v[68:71], v[176:179], v[216:219], v[68:71]
	v_mfma_f32_16x16x32_bf16 v[64:67], v[184:187], v[216:219], v[64:67]
	s_barrier
; #define PG8_STAGE(bufoff, gbase, voff) do { _Pragma("unroll") for (int _i = 0; _i < 2; ++_i) \
;         __builtin_amdgcn_global_load_lds((const unsigned*)((const char*)(gbase) + (voff)[_i]), (PG8_LAS unsigned*)(lds + (bufoff) + ldsw + _i * 8192), 16, 0, 0); } while (0)
; #define PG8_LDA(dst, b, h) do { _Pragma("unroll") for (int m = 0; m < 4; ++m) _Pragma("unroll") for (int k = 0; k < 2; ++k) dst[m][k] = *(const PG8_LAS bf16x8*)(lds + PG8_SA(b, h) + aoff + m * 2048 + k * 1024); } while (0)
; #define PG8_LDB(dst, b, h) do { _Pragma("unroll") for (int n = 0; n < 2; ++n) _Pragma("unroll") for (int k = 0; k < 2; ++k) dst[n][k] = *(const PG8_LAS bf16x8*)(lds + PG8_SB(b, h) + boff + n * 2048 + k * 1024); } while (0)
; #define PG8_MMA(ai, bj, At, Bt) do { __builtin_amdgcn_s_setprio(1); _Pragma("unroll") for (int m = 0; m < 4; ++m) _Pragma("unroll") for (int n = 0; n < 2; ++n) _Pragma("unroll") for (int k = 0; k < 2; ++k) \
;         acc[ai][bj][m][n] = __builtin_amdgcn_mfma_f32_16x16x32_bf16(Bt[n][k], At[m][k], acc[ai][bj][m][n], 0, 0, 0); __builtin_amdgcn_s_setprio(0); } while (0)
; #define PG8_WAIT_V(n) asm volatile("s_waitcnt vmcnt(" #n ")" ::: "memory")
; template <class Epi, class Sched, bool ALIGN_EPI = false, bool SP2 = false>
; __device__ __forceinline__ void gemm_phase(PG8_LAS unsigned char* lds, const Gemm g, const Sched& S, const Epi& E) {
;     ...
;             PG8_LDB(B0, 0, 0); PG8_LDB(B1, 0, 1); PG8_SCHED; PG8_LDA(At, 0, 0); PG8_STAGE(PG8_SA(1, 1), a1 + hstep, voffA);
;             PG8_WAIT_V(8); PG8_WAIT_L(0); PG8_BAR; PG8_MMA(0, 0, At, B0); PG8_MMA(0, 1, At, B1); PG8_BAR; PG8_SCHED;
;             PG8_LDA(At, 0, 1); PG8_STAGE(PG8_SB(0, 0), b2, voffB); PG8_STAGE(PG8_SB(0, 1), b2 + hstep, voffB); PG8_STAGE(PG8_SA(0, 0), a2, voffA);
;             PG8_WAIT_V(8); PG8_WAIT_L(0); PG8_BAR; PG8_MMA(1, 0, At, B0); PG8_MMA(1, 1, At, B1); PG8_BAR; PG8_SCHED;
;             PG8_LDB(B0, 1, 0); PG8_LDB(B1, 1, 1); PG8_SCHED; PG8_LDA(At, 1, 0); PG8_STAGE(PG8_SA(0, 1), a2 + hstep, voffA);
;             PG8_WAIT_V(8); PG8_WAIT_L(0); PG8_BAR; PG8_MMA(0, 0, At, B0); PG8_MMA(0, 1, At, B1); PG8_BAR; PG8_SCHED;
;             PG8_LDA(At, 1, 1); PG8_STAGE(PG8_SB(1, 0), b3, voffB); PG8_STAGE(PG8_SB(1, 1), b3 + hstep, voffB); PG8_STAGE(PG8_SA(1, 0), a3, voffA);
;             PG8_WAIT_V(8); PG8_WAIT_L(0); PG8_BAR; PG8_MMA(1, 0, At, B0); PG8_MMA(1, 1, At, B1); PG8_BAR; PG8_SCHED;
	s_add_i32 s68, s70, s29
	v_lshl_add_u64 v[220:221], v[220:221], 0, s[10:11]
	s_mov_b32 m0, s68
	ds_read_b128 v[188:191], v156 offset:49152
	ds_read_b128 v[192:195], v156 offset:50176
	ds_read_b128 v[196:199], v156 offset:51200
	ds_read_b128 v[200:203], v156 offset:52224
	ds_read_b128 v[204:207], v156 offset:53248
	ds_read_b128 v[208:211], v156 offset:54272
	ds_read_b128 v[212:215], v156 offset:55296
	ds_read_b128 v[216:219], v156 offset:56320
	global_load_lds_dwordx4 v[220:221], off
	s_add_i32 m0, s68, 0x2000
	s_add_u32 s68, s76, 0x80080
	v_lshl_add_u64 v[220:221], v[222:223], 0, s[10:11]
	s_addc_u32 s69, s77, 0
	s_add_i32 s70, s71, s29
	global_load_lds_dwordx4 v[220:221], off
	v_lshl_add_u64 v[220:221], s[68:69], 0, v[132:133]
	s_mov_b32 m0, s70
	s_nop 0
	global_load_lds_dwordx4 v[220:221], off
	v_lshl_add_u64 v[220:221], s[68:69], 0, v[128:129]
	s_add_i32 m0, s70, 0x2000
	s_nop 0
	global_load_lds_dwordx4 v[220:221], off
	v_lshl_add_u64 v[220:221], v[224:225], 0, s[10:11]
	s_mov_b32 m0, s65
	s_nop 0
	global_load_lds_dwordx4 v[220:221], off
	v_lshl_add_u64 v[220:221], v[226:227], 0, s[10:11]
	s_mov_b32 m0, s66
	s_nop 0
	global_load_lds_dwordx4 v[220:221], off
	s_waitcnt vmcnt(8)
	s_waitcnt lgkmcnt(0)
	s_barrier
	s_waitcnt lgkmcnt(0)
	v_mfma_f32_16x16x32_bf16 v[60:63], v[144:147], v[188:191], v[60:63]
	v_mfma_f32_16x16x32_bf16 v[56:59], v[162:165], v[188:191], v[56:59]
	v_mfma_f32_16x16x32_bf16 v[52:55], v[144:147], v[196:199], v[52:55]
	v_mfma_f32_16x16x32_bf16 v[44:47], v[162:165], v[196:199], v[44:47]
	v_mfma_f32_16x16x32_bf16 v[36:39], v[144:147], v[204:207], v[36:39]
	v_mfma_f32_16x16x32_bf16 v[28:31], v[162:165], v[204:207], v[28:31]
	v_mfma_f32_16x16x32_bf16 v[20:23], v[144:147], v[212:215], v[20:23]
	v_mfma_f32_16x16x32_bf16 v[12:15], v[162:165], v[212:215], v[12:15]
	v_mfma_f32_16x16x32_bf16 v[60:63], v[158:161], v[192:195], v[60:63]
	v_mfma_f32_16x16x32_bf16 v[56:59], v[166:169], v[192:195], v[56:59]
	v_mfma_f32_16x16x32_bf16 v[52:55], v[158:161], v[200:203], v[52:55]
	v_mfma_f32_16x16x32_bf16 v[44:47], v[166:169], v[200:203], v[44:47]
	v_mfma_f32_16x16x32_bf16 v[36:39], v[158:161], v[208:211], v[36:39]
	v_mfma_f32_16x16x32_bf16 v[28:31], v[166:169], v[208:211], v[28:31]
	v_mfma_f32_16x16x32_bf16 v[20:23], v[158:161], v[216:219], v[20:23]
	v_mfma_f32_16x16x32_bf16 v[12:15], v[166:169], v[216:219], v[12:15]
	v_mfma_f32_16x16x32_bf16 v[48:51], v[170:173], v[188:191], v[48:51]
	v_mfma_f32_16x16x32_bf16 v[40:43], v[180:183], v[188:191], v[40:43]
	v_mfma_f32_16x16x32_bf16 v[32:35], v[170:173], v[196:199], v[32:35]
	v_mfma_f32_16x16x32_bf16 v[24:27], v[180:183], v[196:199], v[24:27]
	v_mfma_f32_16x16x32_bf16 v[16:19], v[170:173], v[204:207], v[16:19]
	v_mfma_f32_16x16x32_bf16 v[8:11], v[180:183], v[204:207], v[8:11]
	v_mfma_f32_16x16x32_bf16 v[4:7], v[170:173], v[212:215], v[4:7]
	v_mfma_f32_16x16x32_bf16 v[0:3], v[180:183], v[212:215], v[0:3]
	v_mfma_f32_16x16x32_bf16 v[48:51], v[176:179], v[192:195], v[48:51]
	v_mfma_f32_16x16x32_bf16 v[40:43], v[184:187], v[192:195], v[40:43]
	v_mfma_f32_16x16x32_bf16 v[32:35], v[176:179], v[200:203], v[32:35]
	v_mfma_f32_16x16x32_bf16 v[24:27], v[184:187], v[200:203], v[24:27]
	v_mfma_f32_16x16x32_bf16 v[16:19], v[176:179], v[208:211], v[16:19]
	v_mfma_f32_16x16x32_bf16 v[8:11], v[184:187], v[208:211], v[8:11]
	v_mfma_f32_16x16x32_bf16 v[4:7], v[176:179], v[216:219], v[4:7]
	v_mfma_f32_16x16x32_bf16 v[0:3], v[184:187], v[216:219], v[0:3]
	s_barrier
	s_add_i32 s91, s91, 2
	s_add_u32 s84, s84, 0x100
	s_addc_u32 s85, s85, 0
	s_add_u32 s86, s86, 0x100
	s_addc_u32 s87, s87, 0
	s_cmp_gt_u32 s91, 29
	s_cbranch_scc0 .LBB0_123
	s_and_b64 vcc, exec, s[30:31]
	s_cbranch_vccz .LBB0_126
	s_barrier

; #define PG8_STAGE(bufoff, gbase, voff) do { _Pragma("unroll") for (int _i = 0; _i < 2; ++_i) \
;         __builtin_amdgcn_global_load_lds((const unsigned*)((const char*)(gbase) + (voff)[_i]), (PG8_LAS unsigned*)(lds + (bufoff) + ldsw + _i * 8192), 16, 0, 0); } while (0)
; #define PG8_LDA(dst, b, h) do { _Pragma("unroll") for (int m = 0; m < 4; ++m) _Pragma("unroll") for (int k = 0; k < 2; ++k) dst[m][k] = *(const PG8_LAS bf16x8*)(lds + PG8_SA(b, h) + aoff + m * 2048 + k * 1024); } while (0)
; #define PG8_LDB(dst, b, h) do { _Pragma("unroll") for (int n = 0; n < 2; ++n) _Pragma("unroll") for (int k = 0; k < 2; ++k) dst[n][k] = *(const PG8_LAS bf16x8*)(lds + PG8_SB(b, h) + boff + n * 2048 + k * 1024); } while (0)
; #define PG8_MMA(ai, bj, At, Bt) do { __builtin_amdgcn_s_setprio(1); _Pragma("unroll") for (int m = 0; m < 4; ++m) _Pragma("unroll") for (int n = 0; n < 2; ++n) _Pragma("unroll") for (int k = 0; k < 2; ++k) \
;         acc[ai][bj][m][n] = __builtin_amdgcn_mfma_f32_16x16x32_bf16(Bt[n][k], At[m][k], acc[ai][bj][m][n], 0, 0, 0); __builtin_amdgcn_s_setprio(0); } while (0)
; #define PG8_WAIT_V(n) asm volatile("s_waitcnt vmcnt(" #n ")" ::: "memory")
; template <class Epi, class Sched, bool ALIGN_EPI = false, bool SP2 = false>
; __device__ __forceinline__ void gemm_phase(PG8_LAS unsigned char* lds, const Gemm g, const Sched& S, const Epi& E) {
;     ...
;             PG8_LDB(B0, 0, 0); PG8_LDB(B1, 0, 1); PG8_SCHED; PG8_LDA(At, 0, 0); PG8_STAGE(PG8_SA(1, 1), a1 + hstep, voffA);
;             PG8_WAIT_V(8); PG8_WAIT_L(0); PG8_BAR; PG8_MMA(0, 0, At, B0); PG8_MMA(0, 1, At, B1); PG8_BAR; PG8_SCHED;
;             PG8_LDA(At, 0, 1); PG8_STAGE(PG8_SB(0, 0), b2, voffB); PG8_STAGE(PG8_SB(0, 1), b2 + hstep, voffB); PG8_STAGE(PG8_SA(0, 0), a2, voffA);
;             PG8_WAIT_V(8); PG8_WAIT_L(0); PG8_BAR; PG8_MMA(1, 0, At, B0); PG8_MMA(1, 1, At, B1); PG8_BAR; PG8_SCHED;
;             PG8_LDB(B0, 1, 0); PG8_LDB(B1, 1, 1); PG8_SCHED; PG8_LDA(At, 1, 0); PG8_STAGE(PG8_SA(0, 1), a2 + hstep, voffA);
;             PG8_WAIT_V(8); PG8_WAIT_L(0); PG8_BAR; PG8_MMA(0, 0, At, B0); PG8_MMA(0, 1, At, B1); PG8_BAR; PG8_SCHED;
;             PG8_LDA(At, 1, 1); PG8_STAGE(PG8_SB(1, 0), b3, voffB); PG8_STAGE(PG8_SB(1, 1), b3 + hstep, voffB); PG8_STAGE(PG8_SA(1, 0), a3, voffA);
;             PG8_WAIT_V(8); PG8_WAIT_L(0); PG8_BAR; PG8_MMA(1, 0, At, B0); PG8_MMA(1, 1, At, B1); PG8_BAR; PG8_SCHED;
.LBB0_139:
	ds_read_b128 v[158:161], v155
	ds_read_b128 v[162:165], v155 offset:1024
	ds_read_b128 v[166:169], v155 offset:2048
	ds_read_b128 v[170:173], v155 offset:3072
	ds_read_b128 v[176:179], v156
	ds_read_b128 v[180:183], v156 offset:1024
	ds_read_b128 v[184:187], v156 offset:2048
	ds_read_b128 v[188:191], v156 offset:3072
	s_add_u32 s68, s90, 0xfff80080
	s_addc_u32 s69, s91, -1
	s_cmp_eq_u32 s80, 4
	s_cselect_b32 s79, s9, s69
	s_cselect_b32 s78, s59, s68
	s_cselect_b32 s77, s61, s67
	s_cselect_b32 s76, s63, s66
	v_lshl_add_u64 v[224:225], s[90:91], 0, v[148:149]
	s_add_i32 m0, s11, 0xc000
	ds_read_b128 v[192:195], v154
	ds_read_b128 v[196:199], v154 offset:1024
	ds_read_b128 v[200:203], v154 offset:2048
	ds_read_b128 v[204:207], v154 offset:3072
	ds_read_b128 v[208:211], v154 offset:4096
	ds_read_b128 v[212:215], v154 offset:5120
	ds_read_b128 v[216:219], v154 offset:6144
	ds_read_b128 v[220:223], v154 offset:7168
	global_load_lds_dwordx4 v[224:225], off
	v_lshl_add_u64 v[224:225], s[90:91], 0, v[150:151]
	s_add_i32 m0, s11, 0xe000
	s_nop 0
	global_load_lds_dwordx4 v[224:225], off
	s_waitcnt vmcnt(8)
	s_waitcnt lgkmcnt(0)
	s_barrier
	s_waitcnt lgkmcnt(0)
	v_mfma_f32_16x16x32_bf16 v[124:127], v[158:161], v[192:195], v[124:127]
	v_mfma_f32_16x16x32_bf16 v[116:119], v[166:169], v[192:195], v[116:119]
	v_mfma_f32_16x16x32_bf16 v[120:123], v[158:161], v[200:203], v[120:123]
	v_mfma_f32_16x16x32_bf16 v[108:111], v[166:169], v[200:203], v[108:111]
	v_mfma_f32_16x16x32_bf16 v[112:115], v[158:161], v[208:211], v[112:115]
	v_mfma_f32_16x16x32_bf16 v[100:103], v[166:169], v[208:211], v[100:103]
	v_mfma_f32_16x16x32_bf16 v[104:107], v[158:161], v[216:219], v[104:107]
	v_mfma_f32_16x16x32_bf16 v[96:99], v[166:169], v[216:219], v[96:99]
	v_mfma_f32_16x16x32_bf16 v[124:127], v[162:165], v[196:199], v[124:127]
	v_mfma_f32_16x16x32_bf16 v[116:119], v[170:173], v[196:199], v[116:119]
	v_mfma_f32_16x16x32_bf16 v[120:123], v[162:165], v[204:207], v[120:123]
	v_mfma_f32_16x16x32_bf16 v[108:111], v[170:173], v[204:207], v[108:111]
	v_mfma_f32_16x16x32_bf16 v[112:115], v[162:165], v[212:215], v[112:115]
	v_mfma_f32_16x16x32_bf16 v[100:103], v[170:173], v[212:215], v[100:103]
	v_mfma_f32_16x16x32_bf16 v[104:107], v[162:165], v[220:223], v[104:107]
	v_mfma_f32_16x16x32_bf16 v[96:99], v[170:173], v[220:223], v[96:99]
	v_mfma_f32_16x16x32_bf16 v[92:95], v[176:179], v[192:195], v[92:95]
	v_mfma_f32_16x16x32_bf16 v[84:87], v[184:187], v[192:195], v[84:87]
	v_mfma_f32_16x16x32_bf16 v[88:91], v[176:179], v[200:203], v[88:91]
	v_mfma_f32_16x16x32_bf16 v[72:75], v[184:187], v[200:203], v[72:75]
	v_mfma_f32_16x16x32_bf16 v[76:79], v[176:179], v[208:211], v[76:79]
	v_mfma_f32_16x16x32_bf16 v[60:63], v[184:187], v[208:211], v[60:63]
	v_mfma_f32_16x16x32_bf16 v[68:71], v[176:179], v[216:219], v[68:71]
	v_mfma_f32_16x16x32_bf16 v[48:51], v[184:187], v[216:219], v[48:51]
	v_mfma_f32_16x16x32_bf16 v[92:95], v[180:183], v[196:199], v[92:95]
	v_mfma_f32_16x16x32_bf16 v[84:87], v[188:191], v[196:199], v[84:87]
	v_mfma_f32_16x16x32_bf16 v[88:91], v[180:183], v[204:207], v[88:91]
	v_mfma_f32_16x16x32_bf16 v[72:75], v[188:191], v[204:207], v[72:75]
	v_mfma_f32_16x16x32_bf16 v[76:79], v[180:183], v[212:215], v[76:79]
	v_mfma_f32_16x16x32_bf16 v[60:63], v[188:191], v[212:215], v[60:63]
	v_mfma_f32_16x16x32_bf16 v[68:71], v[180:183], v[220:223], v[68:71]
	v_mfma_f32_16x16x32_bf16 v[48:51], v[188:191], v[220:223], v[48:51]
	s_barrier
	s_add_i32 s68, s64, s29
	v_lshl_add_u64 v[224:225], s[76:77], 0, v[130:131]
	s_mov_b32 m0, s68
	ds_read_b128 v[192:195], v154 offset:16384
	ds_read_b128 v[196:199], v154 offset:17408
	ds_read_b128 v[200:203], v154 offset:18432
	ds_read_b128 v[204:207], v154 offset:19456
	ds_read_b128 v[208:211], v154 offset:20480
	ds_read_b128 v[212:215], v154 offset:21504
	ds_read_b128 v[216:219], v154 offset:22528
	ds_read_b128 v[220:223], v154 offset:23552
	global_load_lds_dwordx4 v[224:225], off
	s_add_i32 m0, s68, 0x2000
	s_add_u32 s68, s76, 0x80000
	v_lshl_add_u64 v[226:227], s[76:77], 0, v[128:129]
	s_addc_u32 s69, s77, 0
	s_add_i32 s70, s65, s29
	global_load_lds_dwordx4 v[226:227], off
	v_lshl_add_u64 v[228:229], s[68:69], 0, v[130:131]
	s_mov_b32 m0, s70
	v_lshl_add_u64 v[230:231], s[78:79], 0, v[128:129]
	global_load_lds_dwordx4 v[228:229], off
	v_lshl_add_u64 v[228:229], s[68:69], 0, v[128:129]
	s_add_i32 m0, s70, 0x2000
	s_nop 0
	global_load_lds_dwordx4 v[228:229], off
	v_lshl_add_u64 v[228:229], s[78:79], 0, v[130:131]
	s_mov_b32 m0, s11
	s_nop 0
	global_load_lds_dwordx4 v[228:229], off
	s_mov_b32 m0, s31
	s_nop 0
	global_load_lds_dwordx4 v[230:231], off
	s_waitcnt vmcnt(8)
	s_waitcnt lgkmcnt(0)
	s_barrier
; #define PG8_STAGE(bufoff, gbase, voff) do { _Pragma("unroll") for (int _i = 0; _i < 2; ++_i) \
;         __builtin_amdgcn_global_load_lds((const unsigned*)((const char*)(gbase) + (voff)[_i]), (PG8_LAS unsigned*)(lds + (bufoff) + ldsw + _i * 8192), 16, 0, 0); } while (0)
; #define PG8_LDA(dst, b, h) do { _Pragma("unroll") for (int m = 0; m < 4; ++m) _Pragma("unroll") for (int k = 0; k < 2; ++k) dst[m][k] = *(const PG8_LAS bf16x8*)(lds + PG8_SA(b, h) + aoff + m * 2048 + k * 1024); } while (0)
; #define PG8_LDB(dst, b, h) do { _Pragma("unroll") for (int n = 0; n < 2; ++n) _Pragma("unroll") for (int k = 0; k < 2; ++k) dst[n][k] = *(const PG8_LAS bf16x8*)(lds + PG8_SB(b, h) + boff + n * 2048 + k * 1024); } while (0)
; #define PG8_MMA(ai, bj, At, Bt) do { __builtin_amdgcn_s_setprio(1); _Pragma("unroll") for (int m = 0; m < 4; ++m) _Pragma("unroll") for (int n = 0; n < 2; ++n) _Pragma("unroll") for (int k = 0; k < 2; ++k) \
;         acc[ai][bj][m][n] = __builtin_amdgcn_mfma_f32_16x16x32_bf16(Bt[n][k], At[m][k], acc[ai][bj][m][n], 0, 0, 0); __builtin_amdgcn_s_setprio(0); } while (0)
; #define PG8_WAIT_V(n) asm volatile("s_waitcnt vmcnt(" #n ")" ::: "memory")
; template <class Epi, class Sched, bool ALIGN_EPI = false, bool SP2 = false>
; __device__ __forceinline__ void gemm_phase(PG8_LAS unsigned char* lds, const Gemm g, const Sched& S, const Epi& E) {
;     ...
;             PG8_LDB(B0, 0, 0); PG8_LDB(B1, 0, 1); PG8_SCHED; PG8_LDA(At, 0, 0); PG8_STAGE(PG8_SA(1, 1), a1 + hstep, voffA);
;             PG8_WAIT_V(8); PG8_WAIT_L(0); PG8_BAR; PG8_MMA(0, 0, At, B0); PG8_MMA(0, 1, At, B1); PG8_BAR; PG8_SCHED;
;             PG8_LDA(At, 0, 1); PG8_STAGE(PG8_SB(0, 0), b2, voffB); PG8_STAGE(PG8_SB(0, 1), b2 + hstep, voffB); PG8_STAGE(PG8_SA(0, 0), a2, voffA);
;             PG8_WAIT_V(8); PG8_WAIT_L(0); PG8_BAR; PG8_MMA(1, 0, At, B0); PG8_MMA(1, 1, At, B1); PG8_BAR; PG8_SCHED;
;             PG8_LDB(B0, 1, 0); PG8_LDB(B1, 1, 1); PG8_SCHED; PG8_LDA(At, 1, 0); PG8_STAGE(PG8_SA(0, 1), a2 + hstep, voffA);
;             PG8_WAIT_V(8); PG8_WAIT_L(0); PG8_BAR; PG8_MMA(0, 0, At, B0); PG8_MMA(0, 1, At, B1); PG8_BAR; PG8_SCHED;
;             PG8_LDA(At, 1, 1); PG8_STAGE(PG8_SB(1, 0), b3, voffB); PG8_STAGE(PG8_SB(1, 1), b3 + hstep, voffB); PG8_STAGE(PG8_SA(1, 0), a3, voffA);
;             PG8_WAIT_V(8); PG8_WAIT_L(0); PG8_BAR; PG8_MMA(1, 0, At, B0); PG8_MMA(1, 1, At, B1); PG8_BAR; PG8_SCHED;
	s_waitcnt lgkmcnt(0)
	v_mfma_f32_16x16x32_bf16 v[80:83], v[158:161], v[192:195], v[80:83]
	v_mfma_f32_16x16x32_bf16 v[56:59], v[166:169], v[192:195], v[56:59]
	v_mfma_f32_16x16x32_bf16 v[64:67], v[158:161], v[200:203], v[64:67]
	v_mfma_f32_16x16x32_bf16 v[44:47], v[166:169], v[200:203], v[44:47]
	v_mfma_f32_16x16x32_bf16 v[52:55], v[158:161], v[208:211], v[52:55]
	v_mfma_f32_16x16x32_bf16 v[36:39], v[166:169], v[208:211], v[36:39]
	v_mfma_f32_16x16x32_bf16 v[40:43], v[158:161], v[216:219], v[40:43]
	v_mfma_f32_16x16x32_bf16 v[32:35], v[166:169], v[216:219], v[32:35]
	v_mfma_f32_16x16x32_bf16 v[80:83], v[162:165], v[196:199], v[80:83]
	v_mfma_f32_16x16x32_bf16 v[56:59], v[170:173], v[196:199], v[56:59]
	v_mfma_f32_16x16x32_bf16 v[64:67], v[162:165], v[204:207], v[64:67]
	v_mfma_f32_16x16x32_bf16 v[44:47], v[170:173], v[204:207], v[44:47]
	v_mfma_f32_16x16x32_bf16 v[52:55], v[162:165], v[212:215], v[52:55]
	v_mfma_f32_16x16x32_bf16 v[36:39], v[170:173], v[212:215], v[36:39]
	v_mfma_f32_16x16x32_bf16 v[40:43], v[162:165], v[220:223], v[40:43]
	v_mfma_f32_16x16x32_bf16 v[32:35], v[170:173], v[220:223], v[32:35]
	v_mfma_f32_16x16x32_bf16 v[28:31], v[176:179], v[192:195], v[28:31]
	v_mfma_f32_16x16x32_bf16 v[20:23], v[184:187], v[192:195], v[20:23]
	v_mfma_f32_16x16x32_bf16 v[24:27], v[176:179], v[200:203], v[24:27]
	v_mfma_f32_16x16x32_bf16 v[12:15], v[184:187], v[200:203], v[12:15]
	v_mfma_f32_16x16x32_bf16 v[16:19], v[176:179], v[208:211], v[16:19]
	v_mfma_f32_16x16x32_bf16 v[4:7], v[184:187], v[208:211], v[4:7]
	v_mfma_f32_16x16x32_bf16 v[8:11], v[176:179], v[216:219], v[8:11]
	v_mfma_f32_16x16x32_bf16 v[0:3], v[184:187], v[216:219], v[0:3]
	v_mfma_f32_16x16x32_bf16 v[28:31], v[180:183], v[196:199], v[28:31]
	v_mfma_f32_16x16x32_bf16 v[20:23], v[188:191], v[196:199], v[20:23]
	v_mfma_f32_16x16x32_bf16 v[24:27], v[180:183], v[204:207], v[24:27]
	v_mfma_f32_16x16x32_bf16 v[12:15], v[188:191], v[204:207], v[12:15]
	v_mfma_f32_16x16x32_bf16 v[16:19], v[180:183], v[212:215], v[16:19]
	v_mfma_f32_16x16x32_bf16 v[4:7], v[188:191], v[212:215], v[4:7]
	v_mfma_f32_16x16x32_bf16 v[8:11], v[180:183], v[220:223], v[8:11]
	v_mfma_f32_16x16x32_bf16 v[0:3], v[188:191], v[220:223], v[0:3]
	s_barrier
	s_add_i32 s70, 0, 0x18000
	v_add_u32_e32 v157, s70, v152
	s_add_i32 s71, 0, 0x1c000
	ds_read_b128 v[158:161], v157
	ds_read_b128 v[162:165], v157 offset:1024
	ds_read_b128 v[166:169], v157 offset:2048
	ds_read_b128 v[170:173], v157 offset:3072
	v_add_u32_e32 v157, s71, v152
	ds_read_b128 v[176:179], v157
	ds_read_b128 v[180:183], v157 offset:1024
	ds_read_b128 v[184:187], v157 offset:2048
	ds_read_b128 v[188:191], v157 offset:3072
	s_add_u32 s68, s78, 0x80000
	s_addc_u32 s69, s79, 0
	s_mov_b32 m0, s33
	v_lshl_add_u64 v[232:233], s[68:69], 0, v[130:131]
	ds_read_b128 v[192:195], v154 offset:32768
	ds_read_b128 v[196:199], v154 offset:33792
	ds_read_b128 v[200:203], v154 offset:34816
	ds_read_b128 v[204:207], v154 offset:35840
	ds_read_b128 v[208:211], v154 offset:36864
	ds_read_b128 v[212:215], v154 offset:37888
	ds_read_b128 v[216:219], v154 offset:38912
	ds_read_b128 v[220:223], v154 offset:39936
	global_load_lds_dwordx4 v[232:233], off
	v_lshl_add_u64 v[232:233], s[68:69], 0, v[128:129]
	s_mov_b32 m0, s52
	s_nop 0
	global_load_lds_dwordx4 v[232:233], off
	s_waitcnt vmcnt(8)
	s_waitcnt lgkmcnt(0)
	s_barrier
	s_waitcnt lgkmcnt(0)
	v_mfma_f32_16x16x32_bf16 v[124:127], v[158:161], v[192:195], v[124:127]
	v_mfma_f32_16x16x32_bf16 v[116:119], v[166:169], v[192:195], v[116:119]
	v_mfma_f32_16x16x32_bf16 v[120:123], v[158:161], v[200:203], v[120:123]
	v_mfma_f32_16x16x32_bf16 v[108:111], v[166:169], v[200:203], v[108:111]
	v_mfma_f32_16x16x32_bf16 v[112:115], v[158:161], v[208:211], v[112:115]
	v_mfma_f32_16x16x32_bf16 v[100:103], v[166:169], v[208:211], v[100:103]
	v_mfma_f32_16x16x32_bf16 v[104:107], v[158:161], v[216:219], v[104:107]
	v_mfma_f32_16x16x32_bf16 v[96:99], v[166:169], v[216:219], v[96:99]
	v_mfma_f32_16x16x32_bf16 v[124:127], v[162:165], v[196:199], v[124:127]
	v_mfma_f32_16x16x32_bf16 v[116:119], v[170:173], v[196:199], v[116:119]
	v_mfma_f32_16x16x32_bf16 v[120:123], v[162:165], v[204:207], v[120:123]
	v_mfma_f32_16x16x32_bf16 v[108:111], v[170:173], v[204:207], v[108:111]
	v_mfma_f32_16x16x32_bf16 v[112:115], v[162:165], v[212:215], v[112:115]
	v_mfma_f32_16x16x32_bf16 v[100:103], v[170:173], v[212:215], v[100:103]
	v_mfma_f32_16x16x32_bf16 v[104:107], v[162:165], v[220:223], v[104:107]
	v_mfma_f32_16x16x32_bf16 v[96:99], v[170:173], v[220:223], v[96:99]
	v_mfma_f32_16x16x32_bf16 v[92:95], v[176:179], v[192:195], v[92:95]
	v_mfma_f32_16x16x32_bf16 v[84:87], v[184:187], v[192:195], v[84:87]
	v_mfma_f32_16x16x32_bf16 v[88:91], v[176:179], v[200:203], v[88:91]
	v_mfma_f32_16x16x32_bf16 v[72:75], v[184:187], v[200:203], v[72:75]
	v_mfma_f32_16x16x32_bf16 v[76:79], v[176:179], v[208:211], v[76:79]
	v_mfma_f32_16x16x32_bf16 v[60:63], v[184:187], v[208:211], v[60:63]
	v_mfma_f32_16x16x32_bf16 v[68:71], v[176:179], v[216:219], v[68:71]
	v_mfma_f32_16x16x32_bf16 v[48:51], v[184:187], v[216:219], v[48:51]
	v_mfma_f32_16x16x32_bf16 v[92:95], v[180:183], v[196:199], v[92:95]
	v_mfma_f32_16x16x32_bf16 v[84:87], v[188:191], v[196:199], v[84:87]
	v_mfma_f32_16x16x32_bf16 v[88:91], v[180:183], v[204:207], v[88:91]
	v_mfma_f32_16x16x32_bf16 v[72:75], v[188:191], v[204:207], v[72:75]
	v_mfma_f32_16x16x32_bf16 v[76:79], v[180:183], v[212:215], v[76:79]
	v_mfma_f32_16x16x32_bf16 v[60:63], v[188:191], v[212:215], v[60:63]
	v_mfma_f32_16x16x32_bf16 v[68:71], v[180:183], v[220:223], v[68:71]
	v_mfma_f32_16x16x32_bf16 v[48:51], v[188:191], v[220:223], v[48:51]
	s_barrier
; #define PG8_STAGE(bufoff, gbase, voff) do { _Pragma("unroll") for (int _i = 0; _i < 2; ++_i) \
;         __builtin_amdgcn_global_load_lds((const unsigned*)((const char*)(gbase) + (voff)[_i]), (PG8_LAS unsigned*)(lds + (bufoff) + ldsw + _i * 8192), 16, 0, 0); } while (0)
; #define PG8_LDA(dst, b, h) do { _Pragma("unroll") for (int m = 0; m < 4; ++m) _Pragma("unroll") for (int k = 0; k < 2; ++k) dst[m][k] = *(const PG8_LAS bf16x8*)(lds + PG8_SA(b, h) + aoff + m * 2048 + k * 1024); } while (0)
; #define PG8_LDB(dst, b, h) do { _Pragma("unroll") for (int n = 0; n < 2; ++n) _Pragma("unroll") for (int k = 0; k < 2; ++k) dst[n][k] = *(const PG8_LAS bf16x8*)(lds + PG8_SB(b, h) + boff + n * 2048 + k * 1024); } while (0)
; #define PG8_MMA(ai, bj, At, Bt) do { __builtin_amdgcn_s_setprio(1); _Pragma("unroll") for (int m = 0; m < 4; ++m) _Pragma("unroll") for (int n = 0; n < 2; ++n) _Pragma("unroll") for (int k = 0; k < 2; ++k) \
;         acc[ai][bj][m][n] = __builtin_amdgcn_mfma_f32_16x16x32_bf16(Bt[n][k], At[m][k], acc[ai][bj][m][n], 0, 0, 0); __builtin_amdgcn_s_setprio(0); } while (0)
; #define PG8_WAIT_V(n) asm volatile("s_waitcnt vmcnt(" #n ")" ::: "memory")
; template <class Epi, class Sched, bool ALIGN_EPI = false, bool SP2 = false>
; __device__ __forceinline__ void gemm_phase(PG8_LAS unsigned char* lds, const Gemm g, const Sched& S, const Epi& E) {
;     ...
;             PG8_LDB(B0, 0, 0); PG8_LDB(B1, 0, 1); PG8_SCHED; PG8_LDA(At, 0, 0); PG8_STAGE(PG8_SA(1, 1), a1 + hstep, voffA);
;             PG8_WAIT_V(8); PG8_WAIT_L(0); PG8_BAR; PG8_MMA(0, 0, At, B0); PG8_MMA(0, 1, At, B1); PG8_BAR; PG8_SCHED;
;             PG8_LDA(At, 0, 1); PG8_STAGE(PG8_SB(0, 0), b2, voffB); PG8_STAGE(PG8_SB(0, 1), b2 + hstep, voffB); PG8_STAGE(PG8_SA(0, 0), a2, voffA);
;             PG8_WAIT_V(8); PG8_WAIT_L(0); PG8_BAR; PG8_MMA(1, 0, At, B0); PG8_MMA(1, 1, At, B1); PG8_BAR; PG8_SCHED;
;             PG8_LDB(B0, 1, 0); PG8_LDB(B1, 1, 1); PG8_SCHED; PG8_LDA(At, 1, 0); PG8_STAGE(PG8_SA(0, 1), a2 + hstep, voffA);
;             PG8_WAIT_V(8); PG8_WAIT_L(0); PG8_BAR; PG8_MMA(0, 0, At, B0); PG8_MMA(0, 1, At, B1); PG8_BAR; PG8_SCHED;
;             PG8_LDA(At, 1, 1); PG8_STAGE(PG8_SB(1, 0), b3, voffB); PG8_STAGE(PG8_SB(1, 1), b3 + hstep, voffB); PG8_STAGE(PG8_SA(1, 0), a3, voffA);
;             PG8_WAIT_V(8); PG8_WAIT_L(0); PG8_BAR; PG8_MMA(1, 0, At, B0); PG8_MMA(1, 1, At, B1); PG8_BAR; PG8_SCHED;
	s_add_i32 s68, s70, s29
	v_lshl_add_u64 v[224:225], v[224:225], 0, s[34:35]
	s_mov_b32 m0, s68
	ds_read_b128 v[192:195], v154 offset:49152
	ds_read_b128 v[196:199], v154 offset:50176
	ds_read_b128 v[200:203], v154 offset:51200
	ds_read_b128 v[204:207], v154 offset:52224
	ds_read_b128 v[208:211], v154 offset:53248
	ds_read_b128 v[212:215], v154 offset:54272
	ds_read_b128 v[216:219], v154 offset:55296
	ds_read_b128 v[220:223], v154 offset:56320
	global_load_lds_dwordx4 v[224:225], off
	s_add_i32 m0, s68, 0x2000
	s_add_u32 s68, s76, 0x80080
	v_lshl_add_u64 v[224:225], v[226:227], 0, s[34:35]
	s_addc_u32 s69, s77, 0
	s_add_i32 s70, s71, s29
	global_load_lds_dwordx4 v[224:225], off
	v_lshl_add_u64 v[224:225], s[68:69], 0, v[130:131]
	s_mov_b32 m0, s70
	s_nop 0
	global_load_lds_dwordx4 v[224:225], off
	v_lshl_add_u64 v[224:225], s[68:69], 0, v[128:129]
	s_add_i32 m0, s70, 0x2000
	s_nop 0
	global_load_lds_dwordx4 v[224:225], off
	v_lshl_add_u64 v[224:225], v[228:229], 0, s[34:35]
	s_mov_b32 m0, s56
	s_nop 0
	global_load_lds_dwordx4 v[224:225], off
	v_lshl_add_u64 v[224:225], v[230:231], 0, s[34:35]
	s_mov_b32 m0, s57
	s_nop 0
	global_load_lds_dwordx4 v[224:225], off
	s_waitcnt vmcnt(8)
	s_waitcnt lgkmcnt(0)
	s_barrier
	s_waitcnt lgkmcnt(0)
	v_mfma_f32_16x16x32_bf16 v[80:83], v[158:161], v[192:195], v[80:83]
	v_mfma_f32_16x16x32_bf16 v[56:59], v[166:169], v[192:195], v[56:59]
	v_mfma_f32_16x16x32_bf16 v[64:67], v[158:161], v[200:203], v[64:67]
	v_mfma_f32_16x16x32_bf16 v[44:47], v[166:169], v[200:203], v[44:47]
	v_mfma_f32_16x16x32_bf16 v[52:55], v[158:161], v[208:211], v[52:55]
	v_mfma_f32_16x16x32_bf16 v[36:39], v[166:169], v[208:211], v[36:39]
	v_mfma_f32_16x16x32_bf16 v[40:43], v[158:161], v[216:219], v[40:43]
	v_mfma_f32_16x16x32_bf16 v[32:35], v[166:169], v[216:219], v[32:35]
	v_mfma_f32_16x16x32_bf16 v[80:83], v[162:165], v[196:199], v[80:83]
	v_mfma_f32_16x16x32_bf16 v[56:59], v[170:173], v[196:199], v[56:59]
	v_mfma_f32_16x16x32_bf16 v[64:67], v[162:165], v[204:207], v[64:67]
	v_mfma_f32_16x16x32_bf16 v[44:47], v[170:173], v[204:207], v[44:47]
	v_mfma_f32_16x16x32_bf16 v[52:55], v[162:165], v[212:215], v[52:55]
	v_mfma_f32_16x16x32_bf16 v[36:39], v[170:173], v[212:215], v[36:39]
	v_mfma_f32_16x16x32_bf16 v[40:43], v[162:165], v[220:223], v[40:43]
	v_mfma_f32_16x16x32_bf16 v[32:35], v[170:173], v[220:223], v[32:35]
	v_mfma_f32_16x16x32_bf16 v[28:31], v[176:179], v[192:195], v[28:31]
	v_mfma_f32_16x16x32_bf16 v[20:23], v[184:187], v[192:195], v[20:23]
	v_mfma_f32_16x16x32_bf16 v[24:27], v[176:179], v[200:203], v[24:27]
	v_mfma_f32_16x16x32_bf16 v[12:15], v[184:187], v[200:203], v[12:15]
	v_mfma_f32_16x16x32_bf16 v[16:19], v[176:179], v[208:211], v[16:19]
	v_mfma_f32_16x16x32_bf16 v[4:7], v[184:187], v[208:211], v[4:7]
	v_mfma_f32_16x16x32_bf16 v[8:11], v[176:179], v[216:219], v[8:11]
	v_mfma_f32_16x16x32_bf16 v[0:3], v[184:187], v[216:219], v[0:3]
	v_mfma_f32_16x16x32_bf16 v[28:31], v[180:183], v[196:199], v[28:31]
	v_mfma_f32_16x16x32_bf16 v[20:23], v[188:191], v[196:199], v[20:23]
	v_mfma_f32_16x16x32_bf16 v[24:27], v[180:183], v[204:207], v[24:27]
	v_mfma_f32_16x16x32_bf16 v[12:15], v[188:191], v[204:207], v[12:15]
	v_mfma_f32_16x16x32_bf16 v[16:19], v[180:183], v[212:215], v[16:19]
	v_mfma_f32_16x16x32_bf16 v[4:7], v[188:191], v[212:215], v[4:7]
	v_mfma_f32_16x16x32_bf16 v[8:11], v[180:183], v[220:223], v[8:11]
	v_mfma_f32_16x16x32_bf16 v[0:3], v[188:191], v[220:223], v[0:3]
	s_barrier
	s_add_i32 s80, s80, 2
	s_add_u32 s90, s90, 0x100
	s_addc_u32 s91, s91, 0
	s_add_u32 s66, s66, 0x100
	s_addc_u32 s67, s67, 0
	s_cmp_gt_u32 s80, 5
	s_cbranch_scc0 .LBB0_139
	s_and_b64 vcc, exec, s[54:55]
	s_cbranch_vccz .LBB0_142
	s_barrier

; __device__ __forceinline__ void rwkv_proj_phase(const bf16* Z, const float* shift, const float* w0, const float* a0, const float* kkp, const float* kap, const float* rkp, ...
;     for (int it = blockIdx.x; it < 132 * 3; it += gridDim.x) {
;         int fr = lane & 15, g = lane >> 4;
;         asm volatile("" : "+v"(fr), "+v"(g));
;         const int tt = it / 3, hg = it % 3;
;         const int m = tt * 128 + wave * 16 + fr;
;         int b, tpos, len, s;
;         if (m < ML) { b = m >> 13; tpos = m & 8191; len = SEQ; s = CTXL + tpos; } else { b = (m - ML) >> 8; tpos = (m - ML) & 255; len = CTXL; s = tpos; }
;         const bool hp = tpos > 0, hn = tpos < len - 1;
;         const long offm = hp ? -(long)INCP : 0, offp = hn ? (long)INCP : 0; const float fm = hp ? 1.f : 0.f, fn = hn ? 1.f : 0.f;
;         const bf16* zr = Z + (size_t)m * INCP + ZB0;
;     ...
;             rwkv_proj_phase(Z, in.p[9] + (size_t)l * 3 * BCOLS, in.p[10] + (size_t)l * 2 * BW, in.p[12] + (size_t)l * 2 * BW, in.p[15] + (size_t)l * BW, in.p[16] + (size_t)l * BW,
.LBB0_255:
	s_setprio 0
	s_cmp_lt_i32 s72, 4
	s_cselect_b64 s[0:1], -1, 0
	s_cmp_gt_i32 s73, 3
	s_cselect_b64 s[4:5], -1, 0
	s_and_b64 s[0:1], s[0:1], s[4:5]
	s_andn2_b64 vcc, exec, s[0:1]
	s_cbranch_vccnz .LBB0_400
	v_readfirstlane_b32 s3, v174
	s_lshr_b32 s55, s3, 6
	s_add_u32 s30, s70, 0xa900000
	v_and_b32_e32 v103, 63, v174
	s_addc_u32 s31, s71, 0
	v_readlane_b32 s0, v246, 0
	s_cmpk_gt_i32 s0, 0x18b
	v_lshrrev_b32_e32 v158, 4, v103
	s_cbranch_scc1 .LBB0_267
	v_readlane_b32 s60, v246, 31
	v_readlane_b32 s62, v246, 33
	v_readlane_b32 s63, v246, 34
	s_add_u32 s4, s62, 0x16f00000
	s_addc_u32 s5, s63, 0
	s_add_u32 s0, s62, 0x28000000
	s_addc_u32 s1, s63, 0
	s_add_u32 s6, s62, 0x29900000
	s_addc_u32 s7, s63, 0
	s_lshl_b32 s58, s55, 4
	v_and_b32_e32 v159, 15, v174
	s_add_u32 s8, s38, 0x2a00
	s_addc_u32 s9, s39, 0
	v_lshlrev_b32_e32 v88, 4, v159
	v_mov_b32_e32 v89, 0
	s_add_u32 s10, s38, 0x5400
	v_lshl_add_u64 v[0:1], s[62:63], 0, v[88:89]
	s_mov_b64 s[28:29], 0x6160000
	s_addc_u32 s11, s39, 0
	v_lshl_add_u64 v[90:91], v[0:1], 0, s[28:29]
	s_add_i32 s59, 0, 0x15800
	v_and_b32_e32 v0, 7, v174
	v_add_u32_e32 v2, s59, v88
	v_lshlrev_b32_e32 v88, 4, v0
	v_lshl_add_u64 v[0:1], s[62:63], 0, v[88:89]
	s_mov_b64 s[28:29], 0x6100000
	v_readlane_b32 s61, v246, 32
	v_bfe_u32 v160, v174, 3, 6
	v_lshrrev_b32_e32 v3, 9, v174
	v_lshl_add_u64 v[92:93], v[0:1], 0, s[28:29]
	s_mov_b64 s[28:29], 0x6130000
	s_add_i32 s62, 0, 0x11000
	v_mul_u32_u24_e32 v161, 0x300, v3
	v_lshl_or_b32 v4, v3, 6, v160
	s_movk_i32 s61, 0x90
	v_xor_b32_e32 v3, 1, v3
	v_lshl_add_u64 v[94:95], v[0:1], 0, s[28:29]
	v_mov_b32_e32 v0, s62
	v_mad_u32_u24 v5, v4, s61, 0
	v_mul_u32_u24_e32 v162, 0x300, v3
	v_lshl_or_b32 v3, v3, 6, v160
	v_mad_u32_u24 v1, v4, s61, v0
	v_add_u32_e32 v4, 0x200, v174
	v_mad_u32_u24 v0, v3, s61, v0
	v_lshrrev_b32_e32 v163, 4, v174
	v_lshrrev_b32_e32 v164, 4, v4
	v_mad_u32_u24 v6, v3, s61, 0
	v_mul_u32_u24_e32 v3, 0x110, v163
	v_mul_u32_u24_e32 v4, 0x110, v164
	v_add_u32_e32 v170, v0, v88
	v_mbcnt_lo_u32_b32 v0, -1, 0
	s_movk_i32 s60, 0x300
	v_mov_b32_e32 v165, 0xffffd000
	s_movk_i32 s63, 0x3000
	v_mov_b32_e32 v166, 0x3000
	v_mov_b64_e32 v[96:97], s[30:31]
	s_mov_b64 s[34:35], 0x800
	s_mov_b32 s76, 0xffff0000
	s_movk_i32 s77, 0x7fff
	s_movk_i32 s78, 0x600
	v_mov_b64_e32 v[98:99], s[0:1]
	v_mov_b64_e32 v[100:101], s[6:7]
	s_mov_b32 s79, 0xaaaaaaab
	s_movk_i32 s80, 0x4000
	s_movk_i32 s81, 0x190
	v_add_u32_e32 v167, v5, v88
	v_add_u32_e32 v168, v6, v88
	v_add_u32_e32 v169, v1, v88
	v_add_u32_e32 v171, v2, v3
	v_add_u32_e32 v172, v2, v4
	s_mov_b32 s54, 0xbf1b4598
	s_add_i32 s82, 0, 0xc800
	v_mov_b32_e32 v173, 0xff
	v_mov_b32_e32 v175, 0x1fff
	v_mbcnt_hi_u32_b32 v176, -1, v0
	v_mov_b32_e32 v177, 1
	v_readlane_b32 s83, v246, 0
	v_readlane_b32 s64, v246, 35
	v_readlane_b32 s65, v246, 36
	v_readlane_b32 s66, v246, 37
	v_readlane_b32 s67, v246, 38

; template <class Epi, class Sched, bool ALIGN_EPI = false, bool SP2 = false>
; __device__ __forceinline__ void gemm_phase(PG8_LAS unsigned char* lds, const Gemm g, const Sched& S, const Epi& E) {
;     const int tid = threadIdx.x, wid = __builtin_amdgcn_readfirstlane(tid >> 6), lane = tid & 63, wr = wid >> 2, wc = wid & 3, fr = lane & 15, fq = lane >> 4;
;     const int K = g.K, nt = K / BK, LD = g.ld ? g.ld : g.K;
;     unsigned voffA[2], voffB[2];
; #pragma unroll
;     for (int i = 0; i < 2; ++i) { int R, C; stage_rc(tid * 16 + i * 8192, R, C); const int Rb = Epi::PERM ? ((R & ~31) + perm32(R & 31)) : R;
;         voffA[i] = (unsigned)(R * LD + C) * 2u; voffB[i] = (unsigned)(Rb * LD + C) * 2u; }
;     const size_t kstep = (size_t)(BK * 2);
;     const size_t hstep = (size_t)HALF * LD * 2;
;     const size_t tstep = 2 * hstep;
;     const unsigned ldsw = (unsigned)wid * 1024u;
;     const int aoff = lds_byte(wr * 64 + fr, fq * 8), boff = lds_byte(wc * 32 + fr, fq * 8);
;     ...
;             pg8::Gemm g{AC, (bf16*)(ws + WS_WOUT), ML, D, D}; pg8::StaticOrder S; S.init(ML, D, (int)gridDim.x, (int)blockIdx.x, WGM_N2048);
;             EpiRes E{(l == 0) ? in.p[0] : (const float*)XL, (l == 0) ? in.p[2] : (const float*)XC, XL, XC, modl + 2 * D};
;             pg8::gemm_phase<EpiRes, pg8::StaticOrder, true, true>(lds, g, S, E); }
.LBB0_692:
	s_cmp_lt_i32 s72, 7
	s_cselect_b64 s[0:1], -1, 0
	s_cmp_gt_i32 s73, 6
	s_cselect_b64 s[4:5], -1, 0
	s_and_b64 s[0:1], s[0:1], s[4:5]
	s_andn2_b64 vcc, exec, s[0:1]
	s_cbranch_vccnz .LBB0_791
	v_readfirstlane_b32 vcc_lo, v174
	s_bitcmp1_b32 vcc_lo, 8
	s_cbranch_scc0 .Lsp_2
	s_setprio 1
.Lsp_2:
	v_lshlrev_b32_e32 v0, 4, v174
	v_and_b32_e32 v1, 32, v174
	s_waitcnt vmcnt(3)
	v_bfe_u32 v10, v174, 2, 4
	v_lshrrev_b32_e32 v2, 3, v174
	s_movk_i32 s0, 0x70
	v_add_u32_e32 v11, 0x2000, v0
	v_bitop3_b32 v8, v0, v1, 48 bitop3:0x6c
	v_and_b32_e32 v9, 64, v174
	v_and_or_b32 v2, v2, s0, v10
	v_lshrrev_b32_e32 v0, 7, v11
	s_movk_i32 s0, 0xf0
	v_or_b32_e32 v1, v8, v9
	v_and_or_b32 v0, v0, s0, v10
	s_add_u32 s2, s70, 0x1900000
	v_bfe_u32 v176, v174, 4, 2
	v_lshl_or_b32 v144, v2, 12, v1
	v_lshl_or_b32 v146, v0, 12, v1
	v_lshlrev_b32_e32 v0, 6, v174
	v_lshlrev_b32_e32 v1, 2, v174
	s_addc_u32 s82, s71, 0
	v_lshlrev_b32_e32 v178, 4, v176
	v_and_b32_e32 v0, 0x3c0, v0
	v_and_b32_e32 v1, 32, v1
	v_readlane_b32 s1, v246, 0
	v_readfirstlane_b32 s4, v174
	v_and_b32_e32 v177, 15, v174
	s_cmpk_gt_i32 s1, 0x1ff
	v_bitop3_b32 v179, v178, v1, v0 bitop3:0x36
	s_cbranch_scc1 .LBB0_721
	s_ashr_i32 s6, s1, 31
	s_lshr_b32 s0, s6, 29
	s_add_i32 s5, s1, s0
	s_and_b32 s0, s5, -8
	s_sub_i32 s7, s1, s0
	s_cmp_gt_i32 s7, -1
	s_cbranch_scc0 .LBB0_696
	s_lshl_b32 s8, s7, 6
	s_cbranch_execz .LBB0_697
	s_branch .LBB0_698

; #define PG8_STAGE(bufoff, gbase, voff) do { _Pragma("unroll") for (int _i = 0; _i < 2; ++_i) \
;         __builtin_amdgcn_global_load_lds((const unsigned*)((const char*)(gbase) + (voff)[_i]), (PG8_LAS unsigned*)(lds + (bufoff) + ldsw + _i * 8192), 16, 0, 0); } while (0)
; #define PG8_LDA(dst, b, h) do { _Pragma("unroll") for (int m = 0; m < 4; ++m) _Pragma("unroll") for (int k = 0; k < 2; ++k) dst[m][k] = *(const PG8_LAS bf16x8*)(lds + PG8_SA(b, h) + aoff + m * 2048 + k * 1024); } while (0)
; #define PG8_LDB(dst, b, h) do { _Pragma("unroll") for (int n = 0; n < 2; ++n) _Pragma("unroll") for (int k = 0; k < 2; ++k) dst[n][k] = *(const PG8_LAS bf16x8*)(lds + PG8_SB(b, h) + boff + n * 2048 + k * 1024); } while (0)
; #define PG8_MMA(ai, bj, At, Bt) do { __builtin_amdgcn_s_setprio(1); _Pragma("unroll") for (int m = 0; m < 4; ++m) _Pragma("unroll") for (int n = 0; n < 2; ++n) _Pragma("unroll") for (int k = 0; k < 2; ++k) \
;         acc[ai][bj][m][n] = __builtin_amdgcn_mfma_f32_16x16x32_bf16(Bt[n][k], At[m][k], acc[ai][bj][m][n], 0, 0, 0); __builtin_amdgcn_s_setprio(0); } while (0)
; #define PG8_WAIT_V(n) asm volatile("s_waitcnt vmcnt(" #n ")" ::: "memory")
; template <class Epi, class Sched, bool ALIGN_EPI = false, bool SP2 = false>
; __device__ __forceinline__ void gemm_phase(PG8_LAS unsigned char* lds, const Gemm g, const Sched& S, const Epi& E) {
;     ...
;             PG8_LDB(B0, 0, 0); PG8_LDB(B1, 0, 1); PG8_SCHED; PG8_LDA(At, 0, 0); PG8_STAGE(PG8_SA(1, 1), a1 + hstep, voffA);
;             PG8_WAIT_V(8); PG8_WAIT_L(0); PG8_BAR; PG8_MMA(0, 0, At, B0); PG8_MMA(0, 1, At, B1); PG8_BAR; PG8_SCHED;
;             PG8_LDA(At, 0, 1); PG8_STAGE(PG8_SB(0, 0), b2, voffB); PG8_STAGE(PG8_SB(0, 1), b2 + hstep, voffB); PG8_STAGE(PG8_SA(0, 0), a2, voffA);
;             PG8_WAIT_V(8); PG8_WAIT_L(0); PG8_BAR; PG8_MMA(1, 0, At, B0); PG8_MMA(1, 1, At, B1); PG8_BAR; PG8_SCHED;
;             PG8_LDB(B0, 1, 0); PG8_LDB(B1, 1, 1); PG8_SCHED; PG8_LDA(At, 1, 0); PG8_STAGE(PG8_SA(0, 1), a2 + hstep, voffA);
;             PG8_WAIT_V(8); PG8_WAIT_L(0); PG8_BAR; PG8_MMA(0, 0, At, B0); PG8_MMA(0, 1, At, B1); PG8_BAR; PG8_SCHED;
;             PG8_LDA(At, 1, 1); PG8_STAGE(PG8_SB(1, 0), b3, voffB); PG8_STAGE(PG8_SB(1, 1), b3 + hstep, voffB); PG8_STAGE(PG8_SA(1, 0), a3, voffA);
;             PG8_WAIT_V(8); PG8_WAIT_L(0); PG8_BAR; PG8_MMA(1, 0, At, B0); PG8_MMA(1, 1, At, B1); PG8_BAR; PG8_SCHED;
.LBB0_710:
	ds_read_b128 v[128:131], v182
	ds_read_b128 v[132:135], v182 offset:1024
	ds_read_b128 v[136:139], v182 offset:2048
	ds_read_b128 v[140:143], v182 offset:3072
	ds_read_b128 v[186:189], v183
	ds_read_b128 v[190:193], v183 offset:1024
	ds_read_b128 v[194:197], v183 offset:2048
	ds_read_b128 v[198:201], v183 offset:3072
	s_add_u32 s66, s86, 0xfff80080
	s_addc_u32 s67, s87, -1
	s_cmp_eq_u32 s65, 28
	s_cselect_b32 s79, s4, s67
	s_cselect_b32 s78, s56, s66
	s_cselect_b32 s77, s55, s64
	s_cselect_b32 s76, s57, s59
	v_lshl_add_u64 v[172:173], s[86:87], 0, v[164:165]
	s_add_i32 m0, s33, 0xc000
	ds_read_b128 v[202:205], v184
	ds_read_b128 v[206:209], v184 offset:1024
	ds_read_b128 v[210:213], v184 offset:2048
	ds_read_b128 v[214:217], v184 offset:3072
	ds_read_b128 v[218:221], v184 offset:4096
	ds_read_b128 v[222:225], v184 offset:5120
	ds_read_b128 v[226:229], v184 offset:6144
	ds_read_b128 v[230:233], v184 offset:7168
	global_load_lds_dwordx4 v[172:173], off
	v_lshl_add_u64 v[172:173], s[86:87], 0, v[166:167]
	s_add_i32 m0, s33, 0xe000
	s_nop 0
	global_load_lds_dwordx4 v[172:173], off
	s_waitcnt vmcnt(8)
	s_waitcnt lgkmcnt(0)
	s_barrier
	s_waitcnt lgkmcnt(0)
	v_mfma_f32_16x16x32_bf16 v[124:127], v[128:131], v[202:205], v[124:127]
	v_mfma_f32_16x16x32_bf16 v[120:123], v[136:139], v[202:205], v[120:123]
	v_mfma_f32_16x16x32_bf16 v[112:115], v[128:131], v[210:213], v[112:115]
	v_mfma_f32_16x16x32_bf16 v[104:107], v[136:139], v[210:213], v[104:107]
	v_mfma_f32_16x16x32_bf16 v[96:99], v[128:131], v[218:221], v[96:99]
	v_mfma_f32_16x16x32_bf16 v[88:91], v[136:139], v[218:221], v[88:91]
	v_mfma_f32_16x16x32_bf16 v[80:83], v[128:131], v[226:229], v[80:83]
	v_mfma_f32_16x16x32_bf16 v[72:75], v[136:139], v[226:229], v[72:75]
	v_mfma_f32_16x16x32_bf16 v[124:127], v[132:135], v[206:209], v[124:127]
	v_mfma_f32_16x16x32_bf16 v[120:123], v[140:143], v[206:209], v[120:123]
	v_mfma_f32_16x16x32_bf16 v[112:115], v[132:135], v[214:217], v[112:115]
	v_mfma_f32_16x16x32_bf16 v[104:107], v[140:143], v[214:217], v[104:107]
	v_mfma_f32_16x16x32_bf16 v[96:99], v[132:135], v[222:225], v[96:99]
	v_mfma_f32_16x16x32_bf16 v[88:91], v[140:143], v[222:225], v[88:91]
	v_mfma_f32_16x16x32_bf16 v[80:83], v[132:135], v[230:233], v[80:83]
	v_mfma_f32_16x16x32_bf16 v[72:75], v[140:143], v[230:233], v[72:75]
	v_mfma_f32_16x16x32_bf16 v[116:119], v[186:189], v[202:205], v[116:119]
	v_mfma_f32_16x16x32_bf16 v[108:111], v[194:197], v[202:205], v[108:111]
	v_mfma_f32_16x16x32_bf16 v[100:103], v[186:189], v[210:213], v[100:103]
	v_mfma_f32_16x16x32_bf16 v[92:95], v[194:197], v[210:213], v[92:95]
	v_mfma_f32_16x16x32_bf16 v[84:87], v[186:189], v[218:221], v[84:87]
	v_mfma_f32_16x16x32_bf16 v[76:79], v[194:197], v[218:221], v[76:79]
	v_mfma_f32_16x16x32_bf16 v[68:71], v[186:189], v[226:229], v[68:71]
	v_mfma_f32_16x16x32_bf16 v[64:67], v[194:197], v[226:229], v[64:67]
	v_mfma_f32_16x16x32_bf16 v[116:119], v[190:193], v[206:209], v[116:119]
	v_mfma_f32_16x16x32_bf16 v[108:111], v[198:201], v[206:209], v[108:111]
	v_mfma_f32_16x16x32_bf16 v[100:103], v[190:193], v[214:217], v[100:103]
	v_mfma_f32_16x16x32_bf16 v[92:95], v[198:201], v[214:217], v[92:95]
	v_mfma_f32_16x16x32_bf16 v[84:87], v[190:193], v[222:225], v[84:87]
	v_mfma_f32_16x16x32_bf16 v[76:79], v[198:201], v[222:225], v[76:79]
	v_mfma_f32_16x16x32_bf16 v[68:71], v[190:193], v[230:233], v[68:71]
	v_mfma_f32_16x16x32_bf16 v[64:67], v[198:201], v[230:233], v[64:67]
	s_barrier
	s_add_i32 s66, s96, s29
	v_lshl_add_u64 v[172:173], s[76:77], 0, v[144:145]
	s_mov_b32 m0, s66
	ds_read_b128 v[202:205], v184 offset:16384
	ds_read_b128 v[206:209], v184 offset:17408
	ds_read_b128 v[210:213], v184 offset:18432
	ds_read_b128 v[214:217], v184 offset:19456
	ds_read_b128 v[218:221], v184 offset:20480
	ds_read_b128 v[222:225], v184 offset:21504
	ds_read_b128 v[226:229], v184 offset:22528
	ds_read_b128 v[230:233], v184 offset:23552
	global_load_lds_dwordx4 v[172:173], off
	s_add_i32 m0, s66, 0x2000
	s_add_u32 s66, s76, 0x80000
	v_lshl_add_u64 v[234:235], s[76:77], 0, v[146:147]
	s_addc_u32 s67, s77, 0
	s_add_i32 s68, s97, s29
	global_load_lds_dwordx4 v[234:235], off
	v_lshl_add_u64 v[236:237], s[66:67], 0, v[144:145]
	s_mov_b32 m0, s68
	v_lshl_add_u64 v[238:239], s[78:79], 0, v[146:147]
	global_load_lds_dwordx4 v[236:237], off
	v_lshl_add_u64 v[236:237], s[66:67], 0, v[146:147]
	s_add_i32 m0, s68, 0x2000
	s_nop 0
	global_load_lds_dwordx4 v[236:237], off
	v_lshl_add_u64 v[236:237], s[78:79], 0, v[144:145]
	s_mov_b32 m0, s33
	s_nop 0
	global_load_lds_dwordx4 v[236:237], off
	s_mov_b32 m0, s35
	s_nop 0
	global_load_lds_dwordx4 v[238:239], off
	s_waitcnt vmcnt(8)
	s_waitcnt lgkmcnt(0)
	s_barrier
; #define PG8_STAGE(bufoff, gbase, voff) do { _Pragma("unroll") for (int _i = 0; _i < 2; ++_i) \
;         __builtin_amdgcn_global_load_lds((const unsigned*)((const char*)(gbase) + (voff)[_i]), (PG8_LAS unsigned*)(lds + (bufoff) + ldsw + _i * 8192), 16, 0, 0); } while (0)
; #define PG8_LDA(dst, b, h) do { _Pragma("unroll") for (int m = 0; m < 4; ++m) _Pragma("unroll") for (int k = 0; k < 2; ++k) dst[m][k] = *(const PG8_LAS bf16x8*)(lds + PG8_SA(b, h) + aoff + m * 2048 + k * 1024); } while (0)
; #define PG8_LDB(dst, b, h) do { _Pragma("unroll") for (int n = 0; n < 2; ++n) _Pragma("unroll") for (int k = 0; k < 2; ++k) dst[n][k] = *(const PG8_LAS bf16x8*)(lds + PG8_SB(b, h) + boff + n * 2048 + k * 1024); } while (0)
; #define PG8_MMA(ai, bj, At, Bt) do { __builtin_amdgcn_s_setprio(1); _Pragma("unroll") for (int m = 0; m < 4; ++m) _Pragma("unroll") for (int n = 0; n < 2; ++n) _Pragma("unroll") for (int k = 0; k < 2; ++k) \
;         acc[ai][bj][m][n] = __builtin_amdgcn_mfma_f32_16x16x32_bf16(Bt[n][k], At[m][k], acc[ai][bj][m][n], 0, 0, 0); __builtin_amdgcn_s_setprio(0); } while (0)
; #define PG8_WAIT_V(n) asm volatile("s_waitcnt vmcnt(" #n ")" ::: "memory")
; template <class Epi, class Sched, bool ALIGN_EPI = false, bool SP2 = false>
; __device__ __forceinline__ void gemm_phase(PG8_LAS unsigned char* lds, const Gemm g, const Sched& S, const Epi& E) {
;     ...
;             PG8_LDB(B0, 0, 0); PG8_LDB(B1, 0, 1); PG8_SCHED; PG8_LDA(At, 0, 0); PG8_STAGE(PG8_SA(1, 1), a1 + hstep, voffA);
;             PG8_WAIT_V(8); PG8_WAIT_L(0); PG8_BAR; PG8_MMA(0, 0, At, B0); PG8_MMA(0, 1, At, B1); PG8_BAR; PG8_SCHED;
;             PG8_LDA(At, 0, 1); PG8_STAGE(PG8_SB(0, 0), b2, voffB); PG8_STAGE(PG8_SB(0, 1), b2 + hstep, voffB); PG8_STAGE(PG8_SA(0, 0), a2, voffA);
;             PG8_WAIT_V(8); PG8_WAIT_L(0); PG8_BAR; PG8_MMA(1, 0, At, B0); PG8_MMA(1, 1, At, B1); PG8_BAR; PG8_SCHED;
;             PG8_LDB(B0, 1, 0); PG8_LDB(B1, 1, 1); PG8_SCHED; PG8_LDA(At, 1, 0); PG8_STAGE(PG8_SA(0, 1), a2 + hstep, voffA);
;             PG8_WAIT_V(8); PG8_WAIT_L(0); PG8_BAR; PG8_MMA(0, 0, At, B0); PG8_MMA(0, 1, At, B1); PG8_BAR; PG8_SCHED;
;             PG8_LDA(At, 1, 1); PG8_STAGE(PG8_SB(1, 0), b3, voffB); PG8_STAGE(PG8_SB(1, 1), b3 + hstep, voffB); PG8_STAGE(PG8_SA(1, 0), a3, voffA);
;             PG8_WAIT_V(8); PG8_WAIT_L(0); PG8_BAR; PG8_MMA(1, 0, At, B0); PG8_MMA(1, 1, At, B1); PG8_BAR; PG8_SCHED;
	s_waitcnt lgkmcnt(0)
	v_mfma_f32_16x16x32_bf16 v[60:63], v[128:131], v[202:205], v[60:63]
	v_mfma_f32_16x16x32_bf16 v[56:59], v[136:139], v[202:205], v[56:59]
	v_mfma_f32_16x16x32_bf16 v[48:51], v[128:131], v[210:213], v[48:51]
	v_mfma_f32_16x16x32_bf16 v[40:43], v[136:139], v[210:213], v[40:43]
	v_mfma_f32_16x16x32_bf16 v[32:35], v[128:131], v[218:221], v[32:35]
	v_mfma_f32_16x16x32_bf16 v[24:27], v[136:139], v[218:221], v[24:27]
	v_mfma_f32_16x16x32_bf16 v[16:19], v[128:131], v[226:229], v[16:19]
	v_mfma_f32_16x16x32_bf16 v[8:11], v[136:139], v[226:229], v[8:11]
	v_mfma_f32_16x16x32_bf16 v[60:63], v[132:135], v[206:209], v[60:63]
	v_mfma_f32_16x16x32_bf16 v[56:59], v[140:143], v[206:209], v[56:59]
	v_mfma_f32_16x16x32_bf16 v[48:51], v[132:135], v[214:217], v[48:51]
	v_mfma_f32_16x16x32_bf16 v[40:43], v[140:143], v[214:217], v[40:43]
	v_mfma_f32_16x16x32_bf16 v[32:35], v[132:135], v[222:225], v[32:35]
	v_mfma_f32_16x16x32_bf16 v[24:27], v[140:143], v[222:225], v[24:27]
	v_mfma_f32_16x16x32_bf16 v[16:19], v[132:135], v[230:233], v[16:19]
	v_mfma_f32_16x16x32_bf16 v[8:11], v[140:143], v[230:233], v[8:11]
	v_mfma_f32_16x16x32_bf16 v[52:55], v[186:189], v[202:205], v[52:55]
	v_mfma_f32_16x16x32_bf16 v[44:47], v[194:197], v[202:205], v[44:47]
	v_mfma_f32_16x16x32_bf16 v[36:39], v[186:189], v[210:213], v[36:39]
	v_mfma_f32_16x16x32_bf16 v[28:31], v[194:197], v[210:213], v[28:31]
	v_mfma_f32_16x16x32_bf16 v[20:23], v[186:189], v[218:221], v[20:23]
	v_mfma_f32_16x16x32_bf16 v[12:15], v[194:197], v[218:221], v[12:15]
	v_mfma_f32_16x16x32_bf16 v[4:7], v[186:189], v[226:229], v[4:7]
	v_mfma_f32_16x16x32_bf16 v[0:3], v[194:197], v[226:229], v[0:3]
	v_mfma_f32_16x16x32_bf16 v[52:55], v[190:193], v[206:209], v[52:55]
	v_mfma_f32_16x16x32_bf16 v[44:47], v[198:201], v[206:209], v[44:47]
	v_mfma_f32_16x16x32_bf16 v[36:39], v[190:193], v[214:217], v[36:39]
	v_mfma_f32_16x16x32_bf16 v[28:31], v[198:201], v[214:217], v[28:31]
	v_mfma_f32_16x16x32_bf16 v[20:23], v[190:193], v[222:225], v[20:23]
	v_mfma_f32_16x16x32_bf16 v[12:15], v[198:201], v[222:225], v[12:15]
	v_mfma_f32_16x16x32_bf16 v[4:7], v[190:193], v[230:233], v[4:7]
	v_mfma_f32_16x16x32_bf16 v[0:3], v[198:201], v[230:233], v[0:3]
	s_barrier
	s_add_i32 s68, 0, 0x18000
	s_add_i32 s69, 0, 0x1c000
	v_add_u32_e32 v140, s68, v180
	v_add_u32_e32 v185, s69, v180
	ds_read_b128 v[128:131], v140
	ds_read_b128 v[132:135], v140 offset:1024
	ds_read_b128 v[136:139], v140 offset:2048
	ds_read_b128 v[140:143], v140 offset:3072
	ds_read_b128 v[186:189], v185
	ds_read_b128 v[190:193], v185 offset:1024
	ds_read_b128 v[194:197], v185 offset:2048
	ds_read_b128 v[198:201], v185 offset:3072
	s_add_u32 s66, s78, 0x80000
	s_addc_u32 s67, s79, 0
	s_mov_b32 m0, s80
	v_lshl_add_u64 v[240:241], s[66:67], 0, v[144:145]
	ds_read_b128 v[202:205], v184 offset:32768
	ds_read_b128 v[206:209], v184 offset:33792
	ds_read_b128 v[210:213], v184 offset:34816
	ds_read_b128 v[214:217], v184 offset:35840
	ds_read_b128 v[218:221], v184 offset:36864
	ds_read_b128 v[222:225], v184 offset:37888
	ds_read_b128 v[226:229], v184 offset:38912
	ds_read_b128 v[230:233], v184 offset:39936
	global_load_lds_dwordx4 v[240:241], off
	v_lshl_add_u64 v[240:241], s[66:67], 0, v[146:147]
	s_mov_b32 m0, s81
	s_nop 0
	global_load_lds_dwordx4 v[240:241], off
	s_waitcnt vmcnt(8)
	s_waitcnt lgkmcnt(0)
	s_barrier
	s_waitcnt lgkmcnt(0)
	v_mfma_f32_16x16x32_bf16 v[124:127], v[128:131], v[202:205], v[124:127]
	v_mfma_f32_16x16x32_bf16 v[120:123], v[136:139], v[202:205], v[120:123]
	v_mfma_f32_16x16x32_bf16 v[112:115], v[128:131], v[210:213], v[112:115]
	v_mfma_f32_16x16x32_bf16 v[104:107], v[136:139], v[210:213], v[104:107]
	v_mfma_f32_16x16x32_bf16 v[96:99], v[128:131], v[218:221], v[96:99]
	v_mfma_f32_16x16x32_bf16 v[88:91], v[136:139], v[218:221], v[88:91]
	v_mfma_f32_16x16x32_bf16 v[80:83], v[128:131], v[226:229], v[80:83]
	v_mfma_f32_16x16x32_bf16 v[72:75], v[136:139], v[226:229], v[72:75]
	v_mfma_f32_16x16x32_bf16 v[124:127], v[132:135], v[206:209], v[124:127]
	v_mfma_f32_16x16x32_bf16 v[120:123], v[140:143], v[206:209], v[120:123]
	v_mfma_f32_16x16x32_bf16 v[112:115], v[132:135], v[214:217], v[112:115]
	v_mfma_f32_16x16x32_bf16 v[104:107], v[140:143], v[214:217], v[104:107]
	v_mfma_f32_16x16x32_bf16 v[96:99], v[132:135], v[222:225], v[96:99]
	v_mfma_f32_16x16x32_bf16 v[88:91], v[140:143], v[222:225], v[88:91]
	v_mfma_f32_16x16x32_bf16 v[80:83], v[132:135], v[230:233], v[80:83]
	v_mfma_f32_16x16x32_bf16 v[72:75], v[140:143], v[230:233], v[72:75]
	v_mfma_f32_16x16x32_bf16 v[116:119], v[186:189], v[202:205], v[116:119]
	v_mfma_f32_16x16x32_bf16 v[108:111], v[194:197], v[202:205], v[108:111]
	v_mfma_f32_16x16x32_bf16 v[100:103], v[186:189], v[210:213], v[100:103]
	v_mfma_f32_16x16x32_bf16 v[92:95], v[194:197], v[210:213], v[92:95]
	v_mfma_f32_16x16x32_bf16 v[84:87], v[186:189], v[218:221], v[84:87]
	v_mfma_f32_16x16x32_bf16 v[76:79], v[194:197], v[218:221], v[76:79]
	v_mfma_f32_16x16x32_bf16 v[68:71], v[186:189], v[226:229], v[68:71]
	v_mfma_f32_16x16x32_bf16 v[64:67], v[194:197], v[226:229], v[64:67]
	v_mfma_f32_16x16x32_bf16 v[116:119], v[190:193], v[206:209], v[116:119]
	v_mfma_f32_16x16x32_bf16 v[108:111], v[198:201], v[206:209], v[108:111]
	v_mfma_f32_16x16x32_bf16 v[100:103], v[190:193], v[214:217], v[100:103]
	v_mfma_f32_16x16x32_bf16 v[92:95], v[198:201], v[214:217], v[92:95]
	v_mfma_f32_16x16x32_bf16 v[84:87], v[190:193], v[222:225], v[84:87]
	v_mfma_f32_16x16x32_bf16 v[76:79], v[198:201], v[222:225], v[76:79]
	v_mfma_f32_16x16x32_bf16 v[68:71], v[190:193], v[230:233], v[68:71]
	v_mfma_f32_16x16x32_bf16 v[64:67], v[198:201], v[230:233], v[64:67]
	s_barrier
; #define PG8_STAGE(bufoff, gbase, voff) do { _Pragma("unroll") for (int _i = 0; _i < 2; ++_i) \
;         __builtin_amdgcn_global_load_lds((const unsigned*)((const char*)(gbase) + (voff)[_i]), (PG8_LAS unsigned*)(lds + (bufoff) + ldsw + _i * 8192), 16, 0, 0); } while (0)
; #define PG8_LDA(dst, b, h) do { _Pragma("unroll") for (int m = 0; m < 4; ++m) _Pragma("unroll") for (int k = 0; k < 2; ++k) dst[m][k] = *(const PG8_LAS bf16x8*)(lds + PG8_SA(b, h) + aoff + m * 2048 + k * 1024); } while (0)
; #define PG8_LDB(dst, b, h) do { _Pragma("unroll") for (int n = 0; n < 2; ++n) _Pragma("unroll") for (int k = 0; k < 2; ++k) dst[n][k] = *(const PG8_LAS bf16x8*)(lds + PG8_SB(b, h) + boff + n * 2048 + k * 1024); } while (0)
; #define PG8_MMA(ai, bj, At, Bt) do { __builtin_amdgcn_s_setprio(1); _Pragma("unroll") for (int m = 0; m < 4; ++m) _Pragma("unroll") for (int n = 0; n < 2; ++n) _Pragma("unroll") for (int k = 0; k < 2; ++k) \
;         acc[ai][bj][m][n] = __builtin_amdgcn_mfma_f32_16x16x32_bf16(Bt[n][k], At[m][k], acc[ai][bj][m][n], 0, 0, 0); __builtin_amdgcn_s_setprio(0); } while (0)
; #define PG8_WAIT_V(n) asm volatile("s_waitcnt vmcnt(" #n ")" ::: "memory")
; template <class Epi, class Sched, bool ALIGN_EPI = false, bool SP2 = false>
; __device__ __forceinline__ void gemm_phase(PG8_LAS unsigned char* lds, const Gemm g, const Sched& S, const Epi& E) {
;     ...
;             PG8_LDB(B0, 0, 0); PG8_LDB(B1, 0, 1); PG8_SCHED; PG8_LDA(At, 0, 0); PG8_STAGE(PG8_SA(1, 1), a1 + hstep, voffA);
;             PG8_WAIT_V(8); PG8_WAIT_L(0); PG8_BAR; PG8_MMA(0, 0, At, B0); PG8_MMA(0, 1, At, B1); PG8_BAR; PG8_SCHED;
;             PG8_LDA(At, 0, 1); PG8_STAGE(PG8_SB(0, 0), b2, voffB); PG8_STAGE(PG8_SB(0, 1), b2 + hstep, voffB); PG8_STAGE(PG8_SA(0, 0), a2, voffA);
;             PG8_WAIT_V(8); PG8_WAIT_L(0); PG8_BAR; PG8_MMA(1, 0, At, B0); PG8_MMA(1, 1, At, B1); PG8_BAR; PG8_SCHED;
;             PG8_LDB(B0, 1, 0); PG8_LDB(B1, 1, 1); PG8_SCHED; PG8_LDA(At, 1, 0); PG8_STAGE(PG8_SA(0, 1), a2 + hstep, voffA);
;             PG8_WAIT_V(8); PG8_WAIT_L(0); PG8_BAR; PG8_MMA(0, 0, At, B0); PG8_MMA(0, 1, At, B1); PG8_BAR; PG8_SCHED;
;             PG8_LDA(At, 1, 1); PG8_STAGE(PG8_SB(1, 0), b3, voffB); PG8_STAGE(PG8_SB(1, 1), b3 + hstep, voffB); PG8_STAGE(PG8_SA(1, 0), a3, voffA);
;             PG8_WAIT_V(8); PG8_WAIT_L(0); PG8_BAR; PG8_MMA(1, 0, At, B0); PG8_MMA(1, 1, At, B1); PG8_BAR; PG8_SCHED;
	s_add_i32 s66, s68, s29
	v_lshl_add_u64 v[172:173], v[172:173], 0, s[10:11]
	s_mov_b32 m0, s66
	ds_read_b128 v[202:205], v184 offset:49152
	ds_read_b128 v[206:209], v184 offset:50176
	ds_read_b128 v[210:213], v184 offset:51200
	ds_read_b128 v[214:217], v184 offset:52224
	ds_read_b128 v[218:221], v184 offset:53248
	ds_read_b128 v[222:225], v184 offset:54272
	ds_read_b128 v[226:229], v184 offset:55296
	ds_read_b128 v[230:233], v184 offset:56320
	global_load_lds_dwordx4 v[172:173], off
	s_add_i32 m0, s66, 0x2000
	s_add_u32 s66, s76, 0x80080
	v_lshl_add_u64 v[172:173], v[234:235], 0, s[10:11]
	s_addc_u32 s67, s77, 0
	s_add_i32 s68, s69, s29
	global_load_lds_dwordx4 v[172:173], off
	v_lshl_add_u64 v[172:173], s[66:67], 0, v[144:145]
	s_mov_b32 m0, s68
	s_nop 0
	global_load_lds_dwordx4 v[172:173], off
	v_lshl_add_u64 v[172:173], s[66:67], 0, v[146:147]
	s_add_i32 m0, s68, 0x2000
	s_nop 0
	global_load_lds_dwordx4 v[172:173], off
	v_lshl_add_u64 v[172:173], v[236:237], 0, s[10:11]
	s_mov_b32 m0, s92
	s_nop 0
	global_load_lds_dwordx4 v[172:173], off
	v_lshl_add_u64 v[172:173], v[238:239], 0, s[10:11]
	s_mov_b32 m0, s93
	s_nop 0
	global_load_lds_dwordx4 v[172:173], off
	s_waitcnt vmcnt(8)
	s_waitcnt lgkmcnt(0)
	s_barrier
	s_waitcnt lgkmcnt(0)
	v_mfma_f32_16x16x32_bf16 v[60:63], v[128:131], v[202:205], v[60:63]
	v_mfma_f32_16x16x32_bf16 v[56:59], v[136:139], v[202:205], v[56:59]
	v_mfma_f32_16x16x32_bf16 v[48:51], v[128:131], v[210:213], v[48:51]
	v_mfma_f32_16x16x32_bf16 v[40:43], v[136:139], v[210:213], v[40:43]
	v_mfma_f32_16x16x32_bf16 v[32:35], v[128:131], v[218:221], v[32:35]
	v_mfma_f32_16x16x32_bf16 v[24:27], v[136:139], v[218:221], v[24:27]
	v_mfma_f32_16x16x32_bf16 v[16:19], v[128:131], v[226:229], v[16:19]
	v_mfma_f32_16x16x32_bf16 v[8:11], v[136:139], v[226:229], v[8:11]
	v_mfma_f32_16x16x32_bf16 v[60:63], v[132:135], v[206:209], v[60:63]
	v_mfma_f32_16x16x32_bf16 v[56:59], v[140:143], v[206:209], v[56:59]
	v_mfma_f32_16x16x32_bf16 v[48:51], v[132:135], v[214:217], v[48:51]
	v_mfma_f32_16x16x32_bf16 v[40:43], v[140:143], v[214:217], v[40:43]
	v_mfma_f32_16x16x32_bf16 v[32:35], v[132:135], v[222:225], v[32:35]
	v_mfma_f32_16x16x32_bf16 v[24:27], v[140:143], v[222:225], v[24:27]
	v_mfma_f32_16x16x32_bf16 v[16:19], v[132:135], v[230:233], v[16:19]
	v_mfma_f32_16x16x32_bf16 v[8:11], v[140:143], v[230:233], v[8:11]
	v_mfma_f32_16x16x32_bf16 v[52:55], v[186:189], v[202:205], v[52:55]
	v_mfma_f32_16x16x32_bf16 v[44:47], v[194:197], v[202:205], v[44:47]
	v_mfma_f32_16x16x32_bf16 v[36:39], v[186:189], v[210:213], v[36:39]
	v_mfma_f32_16x16x32_bf16 v[28:31], v[194:197], v[210:213], v[28:31]
	v_mfma_f32_16x16x32_bf16 v[20:23], v[186:189], v[218:221], v[20:23]
	v_mfma_f32_16x16x32_bf16 v[12:15], v[194:197], v[218:221], v[12:15]
	v_mfma_f32_16x16x32_bf16 v[4:7], v[186:189], v[226:229], v[4:7]
	v_mfma_f32_16x16x32_bf16 v[0:3], v[194:197], v[226:229], v[0:3]
	v_mfma_f32_16x16x32_bf16 v[52:55], v[190:193], v[206:209], v[52:55]
	v_mfma_f32_16x16x32_bf16 v[44:47], v[198:201], v[206:209], v[44:47]
	v_mfma_f32_16x16x32_bf16 v[36:39], v[190:193], v[214:217], v[36:39]
	v_mfma_f32_16x16x32_bf16 v[28:31], v[198:201], v[214:217], v[28:31]
	v_mfma_f32_16x16x32_bf16 v[20:23], v[190:193], v[222:225], v[20:23]
	v_mfma_f32_16x16x32_bf16 v[12:15], v[198:201], v[222:225], v[12:15]
	v_mfma_f32_16x16x32_bf16 v[4:7], v[190:193], v[230:233], v[4:7]
	v_mfma_f32_16x16x32_bf16 v[0:3], v[198:201], v[230:233], v[0:3]
	s_barrier
	s_add_i32 s65, s65, 2
	s_add_u32 s86, s86, 0x100
	s_addc_u32 s87, s87, 0
	s_add_u32 s59, s59, 0x100
	s_addc_u32 s64, s64, 0
	s_cmp_gt_u32 s65, 29
	s_cbranch_scc0 .LBB0_710
	s_and_b64 vcc, exec, s[30:31]
	s_cbranch_vccz .LBB0_713
	s_barrier

; #define PG8_STAGE(bufoff, gbase, voff) do { _Pragma("unroll") for (int _i = 0; _i < 2; ++_i) \
;         __builtin_amdgcn_global_load_lds((const unsigned*)((const char*)(gbase) + (voff)[_i]), (PG8_LAS unsigned*)(lds + (bufoff) + ldsw + _i * 8192), 16, 0, 0); } while (0)
; #define PG8_LDA(dst, b, h) do { _Pragma("unroll") for (int m = 0; m < 4; ++m) _Pragma("unroll") for (int k = 0; k < 2; ++k) dst[m][k] = *(const PG8_LAS bf16x8*)(lds + PG8_SA(b, h) + aoff + m * 2048 + k * 1024); } while (0)
; #define PG8_LDB(dst, b, h) do { _Pragma("unroll") for (int n = 0; n < 2; ++n) _Pragma("unroll") for (int k = 0; k < 2; ++k) dst[n][k] = *(const PG8_LAS bf16x8*)(lds + PG8_SB(b, h) + boff + n * 2048 + k * 1024); } while (0)
; #define PG8_MMA(ai, bj, At, Bt) do { __builtin_amdgcn_s_setprio(1); _Pragma("unroll") for (int m = 0; m < 4; ++m) _Pragma("unroll") for (int n = 0; n < 2; ++n) _Pragma("unroll") for (int k = 0; k < 2; ++k) \
;         acc[ai][bj][m][n] = __builtin_amdgcn_mfma_f32_16x16x32_bf16(Bt[n][k], At[m][k], acc[ai][bj][m][n], 0, 0, 0); __builtin_amdgcn_s_setprio(0); } while (0)
; #define PG8_WAIT_V(n) asm volatile("s_waitcnt vmcnt(" #n ")" ::: "memory")
; template <class Epi, class Sched, bool ALIGN_EPI = false, bool SP2 = false>
; __device__ __forceinline__ void gemm_phase(PG8_LAS unsigned char* lds, const Gemm g, const Sched& S, const Epi& E) {
;     ...
;             PG8_LDB(B0, 0, 0); PG8_LDB(B1, 0, 1); PG8_SCHED; PG8_LDA(At, 0, 0); PG8_STAGE(PG8_SA(1, 1), a1 + hstep, voffA);
;             PG8_WAIT_V(8); PG8_WAIT_L(0); PG8_BAR; PG8_MMA(0, 0, At, B0); PG8_MMA(0, 1, At, B1); PG8_BAR; PG8_SCHED;
;             PG8_LDA(At, 0, 1); PG8_STAGE(PG8_SB(0, 0), b2, voffB); PG8_STAGE(PG8_SB(0, 1), b2 + hstep, voffB); PG8_STAGE(PG8_SA(0, 0), a2, voffA);
;             PG8_WAIT_V(8); PG8_WAIT_L(0); PG8_BAR; PG8_MMA(1, 0, At, B0); PG8_MMA(1, 1, At, B1); PG8_BAR; PG8_SCHED;
;             PG8_LDB(B0, 1, 0); PG8_LDB(B1, 1, 1); PG8_SCHED; PG8_LDA(At, 1, 0); PG8_STAGE(PG8_SA(0, 1), a2 + hstep, voffA);
;             PG8_WAIT_V(8); PG8_WAIT_L(0); PG8_BAR; PG8_MMA(0, 0, At, B0); PG8_MMA(0, 1, At, B1); PG8_BAR; PG8_SCHED;
;             PG8_LDA(At, 1, 1); PG8_STAGE(PG8_SB(1, 0), b3, voffB); PG8_STAGE(PG8_SB(1, 1), b3 + hstep, voffB); PG8_STAGE(PG8_SA(1, 0), a3, voffA);
;             PG8_WAIT_V(8); PG8_WAIT_L(0); PG8_BAR; PG8_MMA(1, 0, At, B0); PG8_MMA(1, 1, At, B1); PG8_BAR; PG8_SCHED;
.LBB0_730:
	s_add_u32 s68, s90, s76
	s_addc_u32 s69, s91, 0
	s_add_u32 s70, s68, 0x100
	s_addc_u32 s71, s69, 0
	s_and_b64 s[0:1], s[94:95], exec
	s_cselect_b32 vcc_hi, s31, s71
	s_cselect_b32 vcc_lo, s35, s70
	s_add_u32 s0, s88, s76
	s_addc_u32 s1, s89, 0
	s_add_u32 s70, s0, 0x100
	s_addc_u32 s71, s1, 0
	s_and_b64 s[0:1], s[94:95], exec
	s_cselect_b32 s77, s53, s71
	s_cselect_b32 s76, s61, s70
	s_add_u32 s80, s68, 0x80080
	ds_read_b128 v[128:131], v154
	ds_read_b128 v[158:161], v154 offset:1024
	ds_read_b128 v[162:165], v154 offset:2048
	ds_read_b128 v[166:169], v154 offset:3072
	ds_read_b128 v[170:173], v155
	ds_read_b128 v[176:179], v155 offset:1024
	ds_read_b128 v[180:183], v155 offset:2048
	ds_read_b128 v[184:187], v155 offset:3072
	s_addc_u32 s81, s69, 0
	s_add_i32 s75, s85, s28
	s_add_i32 m0, s3, 0xc000
	s_add_i32 s29, s3, 0xe000
	s_add_i32 s72, s75, 0x2000
	s_add_u32 s78, s76, 0x80000
	s_addc_u32 s79, s77, 0
	s_add_i32 s74, s87, s28
	s_add_i32 s73, s74, 0x2000
	s_add_i32 s71, 0, 0x18000
	s_add_i32 s70, 0, 0x1c000
	s_add_u32 s96, vcc_lo, 0x80000
	s_addc_u32 s97, vcc_hi, 0
	s_add_i32 s69, s71, s28
	s_add_i32 s1, s69, 0x2000
	s_add_u32 s94, s76, 0x80080
	s_addc_u32 s95, s77, 0
	s_add_i32 s0, s70, s28
	s_add_i32 s68, s0, 0x2000
	v_lshl_add_u64 v[220:221], s[80:81], 0, v[144:145]
	ds_read_b128 v[188:191], v156
	ds_read_b128 v[192:195], v156 offset:1024
	ds_read_b128 v[196:199], v156 offset:2048
	ds_read_b128 v[200:203], v156 offset:3072
	ds_read_b128 v[204:207], v156 offset:4096
	ds_read_b128 v[208:211], v156 offset:5120
	ds_read_b128 v[212:215], v156 offset:6144
	ds_read_b128 v[216:219], v156 offset:7168
	global_load_lds_dwordx4 v[220:221], off
	v_lshl_add_u64 v[220:221], s[80:81], 0, v[146:147]
	s_mov_b32 m0, s29
	s_nop 0
	global_load_lds_dwordx4 v[220:221], off
	s_waitcnt vmcnt(8)
	s_waitcnt lgkmcnt(0)
	s_barrier
	s_waitcnt lgkmcnt(0)
	v_mfma_f32_16x16x32_bf16 v[124:127], v[128:131], v[188:191], v[124:127]
	v_mfma_f32_16x16x32_bf16 v[116:119], v[162:165], v[188:191], v[116:119]
	v_mfma_f32_16x16x32_bf16 v[120:123], v[128:131], v[196:199], v[120:123]
	v_mfma_f32_16x16x32_bf16 v[108:111], v[162:165], v[196:199], v[108:111]
	v_mfma_f32_16x16x32_bf16 v[112:115], v[128:131], v[204:207], v[112:115]
	v_mfma_f32_16x16x32_bf16 v[100:103], v[162:165], v[204:207], v[100:103]
	v_mfma_f32_16x16x32_bf16 v[104:107], v[128:131], v[212:215], v[104:107]
	v_mfma_f32_16x16x32_bf16 v[96:99], v[162:165], v[212:215], v[96:99]
	v_mfma_f32_16x16x32_bf16 v[124:127], v[158:161], v[192:195], v[124:127]
	v_mfma_f32_16x16x32_bf16 v[116:119], v[166:169], v[192:195], v[116:119]
	v_mfma_f32_16x16x32_bf16 v[120:123], v[158:161], v[200:203], v[120:123]
	v_mfma_f32_16x16x32_bf16 v[108:111], v[166:169], v[200:203], v[108:111]
	v_mfma_f32_16x16x32_bf16 v[112:115], v[158:161], v[208:211], v[112:115]
	v_mfma_f32_16x16x32_bf16 v[100:103], v[166:169], v[208:211], v[100:103]
	v_mfma_f32_16x16x32_bf16 v[104:107], v[158:161], v[216:219], v[104:107]
	v_mfma_f32_16x16x32_bf16 v[96:99], v[166:169], v[216:219], v[96:99]
	v_mfma_f32_16x16x32_bf16 v[92:95], v[170:173], v[188:191], v[92:95]
	v_mfma_f32_16x16x32_bf16 v[52:55], v[180:183], v[188:191], v[52:55]
	v_mfma_f32_16x16x32_bf16 v[84:87], v[170:173], v[196:199], v[84:87]
	v_mfma_f32_16x16x32_bf16 v[40:43], v[180:183], v[196:199], v[40:43]
	v_mfma_f32_16x16x32_bf16 v[76:79], v[170:173], v[204:207], v[76:79]
	v_mfma_f32_16x16x32_bf16 v[36:39], v[180:183], v[204:207], v[36:39]
	v_mfma_f32_16x16x32_bf16 v[64:67], v[170:173], v[212:215], v[64:67]
	v_mfma_f32_16x16x32_bf16 v[28:31], v[180:183], v[212:215], v[28:31]
	v_mfma_f32_16x16x32_bf16 v[92:95], v[176:179], v[192:195], v[92:95]
	v_mfma_f32_16x16x32_bf16 v[52:55], v[184:187], v[192:195], v[52:55]
	v_mfma_f32_16x16x32_bf16 v[84:87], v[176:179], v[200:203], v[84:87]
	v_mfma_f32_16x16x32_bf16 v[40:43], v[184:187], v[200:203], v[40:43]
	v_mfma_f32_16x16x32_bf16 v[76:79], v[176:179], v[208:211], v[76:79]
	v_mfma_f32_16x16x32_bf16 v[36:39], v[184:187], v[208:211], v[36:39]
	v_mfma_f32_16x16x32_bf16 v[64:67], v[176:179], v[216:219], v[64:67]
	v_mfma_f32_16x16x32_bf16 v[28:31], v[184:187], v[216:219], v[28:31]
	s_barrier
	s_mov_b32 m0, s75
	v_lshl_add_u64 v[220:221], s[76:77], 0, v[144:145]
	ds_read_b128 v[188:191], v156 offset:16384
	ds_read_b128 v[192:195], v156 offset:17408
	ds_read_b128 v[196:199], v156 offset:18432
	ds_read_b128 v[200:203], v156 offset:19456
	ds_read_b128 v[204:207], v156 offset:20480
	ds_read_b128 v[208:211], v156 offset:21504
	ds_read_b128 v[212:215], v156 offset:22528
	ds_read_b128 v[216:219], v156 offset:23552
	global_load_lds_dwordx4 v[220:221], off
	v_lshl_add_u64 v[222:223], s[76:77], 0, v[146:147]
	s_mov_b32 m0, s72
	v_lshl_add_u64 v[224:225], s[78:79], 0, v[144:145]
	global_load_lds_dwordx4 v[222:223], off
	s_mov_b32 m0, s74
	v_lshl_add_u64 v[226:227], vcc, 0, v[146:147]
	global_load_lds_dwordx4 v[224:225], off
	v_lshl_add_u64 v[224:225], s[78:79], 0, v[146:147]
	s_mov_b32 m0, s73
	s_nop 0
	global_load_lds_dwordx4 v[224:225], off
	v_lshl_add_u64 v[224:225], vcc, 0, v[144:145]
	s_mov_b32 m0, s3
	s_nop 0
	global_load_lds_dwordx4 v[224:225], off
	s_mov_b32 m0, s33
	s_nop 0
	global_load_lds_dwordx4 v[226:227], off
	s_waitcnt vmcnt(8)
	s_waitcnt lgkmcnt(0)
	s_barrier
; #define PG8_STAGE(bufoff, gbase, voff) do { _Pragma("unroll") for (int _i = 0; _i < 2; ++_i) \
;         __builtin_amdgcn_global_load_lds((const unsigned*)((const char*)(gbase) + (voff)[_i]), (PG8_LAS unsigned*)(lds + (bufoff) + ldsw + _i * 8192), 16, 0, 0); } while (0)
; #define PG8_LDA(dst, b, h) do { _Pragma("unroll") for (int m = 0; m < 4; ++m) _Pragma("unroll") for (int k = 0; k < 2; ++k) dst[m][k] = *(const PG8_LAS bf16x8*)(lds + PG8_SA(b, h) + aoff + m * 2048 + k * 1024); } while (0)
; #define PG8_LDB(dst, b, h) do { _Pragma("unroll") for (int n = 0; n < 2; ++n) _Pragma("unroll") for (int k = 0; k < 2; ++k) dst[n][k] = *(const PG8_LAS bf16x8*)(lds + PG8_SB(b, h) + boff + n * 2048 + k * 1024); } while (0)
; #define PG8_MMA(ai, bj, At, Bt) do { __builtin_amdgcn_s_setprio(1); _Pragma("unroll") for (int m = 0; m < 4; ++m) _Pragma("unroll") for (int n = 0; n < 2; ++n) _Pragma("unroll") for (int k = 0; k < 2; ++k) \
;         acc[ai][bj][m][n] = __builtin_amdgcn_mfma_f32_16x16x32_bf16(Bt[n][k], At[m][k], acc[ai][bj][m][n], 0, 0, 0); __builtin_amdgcn_s_setprio(0); } while (0)
; #define PG8_WAIT_V(n) asm volatile("s_waitcnt vmcnt(" #n ")" ::: "memory")
; template <class Epi, class Sched, bool ALIGN_EPI = false, bool SP2 = false>
; __device__ __forceinline__ void gemm_phase(PG8_LAS unsigned char* lds, const Gemm g, const Sched& S, const Epi& E) {
;     ...
;             PG8_LDB(B0, 0, 0); PG8_LDB(B1, 0, 1); PG8_SCHED; PG8_LDA(At, 0, 0); PG8_STAGE(PG8_SA(1, 1), a1 + hstep, voffA);
;             PG8_WAIT_V(8); PG8_WAIT_L(0); PG8_BAR; PG8_MMA(0, 0, At, B0); PG8_MMA(0, 1, At, B1); PG8_BAR; PG8_SCHED;
;             PG8_LDA(At, 0, 1); PG8_STAGE(PG8_SB(0, 0), b2, voffB); PG8_STAGE(PG8_SB(0, 1), b2 + hstep, voffB); PG8_STAGE(PG8_SA(0, 0), a2, voffA);
;             PG8_WAIT_V(8); PG8_WAIT_L(0); PG8_BAR; PG8_MMA(1, 0, At, B0); PG8_MMA(1, 1, At, B1); PG8_BAR; PG8_SCHED;
;             PG8_LDB(B0, 1, 0); PG8_LDB(B1, 1, 1); PG8_SCHED; PG8_LDA(At, 1, 0); PG8_STAGE(PG8_SA(0, 1), a2 + hstep, voffA);
;             PG8_WAIT_V(8); PG8_WAIT_L(0); PG8_BAR; PG8_MMA(0, 0, At, B0); PG8_MMA(0, 1, At, B1); PG8_BAR; PG8_SCHED;
;             PG8_LDA(At, 1, 1); PG8_STAGE(PG8_SB(1, 0), b3, voffB); PG8_STAGE(PG8_SB(1, 1), b3 + hstep, voffB); PG8_STAGE(PG8_SA(1, 0), a3, voffA);
;             PG8_WAIT_V(8); PG8_WAIT_L(0); PG8_BAR; PG8_MMA(1, 0, At, B0); PG8_MMA(1, 1, At, B1); PG8_BAR; PG8_SCHED;
	s_waitcnt lgkmcnt(0)
	v_mfma_f32_16x16x32_bf16 v[88:91], v[128:131], v[188:191], v[88:91]
	v_mfma_f32_16x16x32_bf16 v[72:75], v[162:165], v[188:191], v[72:75]
	v_mfma_f32_16x16x32_bf16 v[80:83], v[128:131], v[196:199], v[80:83]
	v_mfma_f32_16x16x32_bf16 v[60:63], v[162:165], v[196:199], v[60:63]
	v_mfma_f32_16x16x32_bf16 v[68:71], v[128:131], v[204:207], v[68:71]
	v_mfma_f32_16x16x32_bf16 v[48:51], v[162:165], v[204:207], v[48:51]
	v_mfma_f32_16x16x32_bf16 v[56:59], v[128:131], v[212:215], v[56:59]
	v_mfma_f32_16x16x32_bf16 v[44:47], v[162:165], v[212:215], v[44:47]
	v_mfma_f32_16x16x32_bf16 v[88:91], v[158:161], v[192:195], v[88:91]
	v_mfma_f32_16x16x32_bf16 v[72:75], v[166:169], v[192:195], v[72:75]
	v_mfma_f32_16x16x32_bf16 v[80:83], v[158:161], v[200:203], v[80:83]
	v_mfma_f32_16x16x32_bf16 v[60:63], v[166:169], v[200:203], v[60:63]
	v_mfma_f32_16x16x32_bf16 v[68:71], v[158:161], v[208:211], v[68:71]
	v_mfma_f32_16x16x32_bf16 v[48:51], v[166:169], v[208:211], v[48:51]
	v_mfma_f32_16x16x32_bf16 v[56:59], v[158:161], v[216:219], v[56:59]
	v_mfma_f32_16x16x32_bf16 v[44:47], v[166:169], v[216:219], v[44:47]
	v_mfma_f32_16x16x32_bf16 v[32:35], v[170:173], v[188:191], v[32:35]
	v_mfma_f32_16x16x32_bf16 v[12:15], v[180:183], v[188:191], v[12:15]
	v_mfma_f32_16x16x32_bf16 v[24:27], v[170:173], v[196:199], v[24:27]
	v_mfma_f32_16x16x32_bf16 v[8:11], v[180:183], v[196:199], v[8:11]
	v_mfma_f32_16x16x32_bf16 v[20:23], v[170:173], v[204:207], v[20:23]
	v_mfma_f32_16x16x32_bf16 v[4:7], v[180:183], v[204:207], v[4:7]
	v_mfma_f32_16x16x32_bf16 v[16:19], v[170:173], v[212:215], v[16:19]
	v_mfma_f32_16x16x32_bf16 v[0:3], v[180:183], v[212:215], v[0:3]
	v_mfma_f32_16x16x32_bf16 v[32:35], v[176:179], v[192:195], v[32:35]
	v_mfma_f32_16x16x32_bf16 v[12:15], v[184:187], v[192:195], v[12:15]
	v_mfma_f32_16x16x32_bf16 v[24:27], v[176:179], v[200:203], v[24:27]
	v_mfma_f32_16x16x32_bf16 v[8:11], v[184:187], v[200:203], v[8:11]
	v_mfma_f32_16x16x32_bf16 v[20:23], v[176:179], v[208:211], v[20:23]
	v_mfma_f32_16x16x32_bf16 v[4:7], v[184:187], v[208:211], v[4:7]
	v_mfma_f32_16x16x32_bf16 v[16:19], v[176:179], v[216:219], v[16:19]
	v_mfma_f32_16x16x32_bf16 v[0:3], v[184:187], v[216:219], v[0:3]
	s_barrier
	v_add_u32_e32 v157, s71, v152
	ds_read_b128 v[128:131], v157
	ds_read_b128 v[158:161], v157 offset:1024
	ds_read_b128 v[162:165], v157 offset:2048
	ds_read_b128 v[166:169], v157 offset:3072
	v_add_u32_e32 v157, s70, v152
	ds_read_b128 v[170:173], v157
	ds_read_b128 v[176:179], v157 offset:1024
	ds_read_b128 v[180:183], v157 offset:2048
	ds_read_b128 v[184:187], v157 offset:3072
	s_mov_b32 m0, s56
	v_lshl_add_u64 v[228:229], s[96:97], 0, v[144:145]
	ds_read_b128 v[188:191], v156 offset:32768
	ds_read_b128 v[192:195], v156 offset:33792
	ds_read_b128 v[196:199], v156 offset:34816
	ds_read_b128 v[200:203], v156 offset:35840
	ds_read_b128 v[204:207], v156 offset:36864
	ds_read_b128 v[208:211], v156 offset:37888
	ds_read_b128 v[212:215], v156 offset:38912
	ds_read_b128 v[216:219], v156 offset:39936
	global_load_lds_dwordx4 v[228:229], off
	v_lshl_add_u64 v[228:229], s[96:97], 0, v[146:147]
	s_mov_b32 m0, s57
	s_nop 0
	global_load_lds_dwordx4 v[228:229], off
	s_waitcnt vmcnt(8)
	s_waitcnt lgkmcnt(0)
	s_barrier
	s_waitcnt lgkmcnt(0)
	v_mfma_f32_16x16x32_bf16 v[124:127], v[128:131], v[188:191], v[124:127]
	v_mfma_f32_16x16x32_bf16 v[116:119], v[162:165], v[188:191], v[116:119]
	v_mfma_f32_16x16x32_bf16 v[120:123], v[128:131], v[196:199], v[120:123]
	v_mfma_f32_16x16x32_bf16 v[108:111], v[162:165], v[196:199], v[108:111]
	v_mfma_f32_16x16x32_bf16 v[112:115], v[128:131], v[204:207], v[112:115]
	v_mfma_f32_16x16x32_bf16 v[100:103], v[162:165], v[204:207], v[100:103]
	v_mfma_f32_16x16x32_bf16 v[104:107], v[128:131], v[212:215], v[104:107]
	v_mfma_f32_16x16x32_bf16 v[96:99], v[162:165], v[212:215], v[96:99]
	v_mfma_f32_16x16x32_bf16 v[124:127], v[158:161], v[192:195], v[124:127]
	v_mfma_f32_16x16x32_bf16 v[116:119], v[166:169], v[192:195], v[116:119]
	v_mfma_f32_16x16x32_bf16 v[120:123], v[158:161], v[200:203], v[120:123]
	v_mfma_f32_16x16x32_bf16 v[108:111], v[166:169], v[200:203], v[108:111]
	v_mfma_f32_16x16x32_bf16 v[112:115], v[158:161], v[208:211], v[112:115]
	v_mfma_f32_16x16x32_bf16 v[100:103], v[166:169], v[208:211], v[100:103]
	v_mfma_f32_16x16x32_bf16 v[104:107], v[158:161], v[216:219], v[104:107]
	v_mfma_f32_16x16x32_bf16 v[96:99], v[166:169], v[216:219], v[96:99]
	v_mfma_f32_16x16x32_bf16 v[92:95], v[170:173], v[188:191], v[92:95]
	v_mfma_f32_16x16x32_bf16 v[52:55], v[180:183], v[188:191], v[52:55]
	v_mfma_f32_16x16x32_bf16 v[84:87], v[170:173], v[196:199], v[84:87]
	v_mfma_f32_16x16x32_bf16 v[40:43], v[180:183], v[196:199], v[40:43]
	v_mfma_f32_16x16x32_bf16 v[76:79], v[170:173], v[204:207], v[76:79]
	v_mfma_f32_16x16x32_bf16 v[36:39], v[180:183], v[204:207], v[36:39]
	v_mfma_f32_16x16x32_bf16 v[64:67], v[170:173], v[212:215], v[64:67]
	v_mfma_f32_16x16x32_bf16 v[28:31], v[180:183], v[212:215], v[28:31]
	v_mfma_f32_16x16x32_bf16 v[92:95], v[176:179], v[192:195], v[92:95]
	v_mfma_f32_16x16x32_bf16 v[52:55], v[184:187], v[192:195], v[52:55]
	v_mfma_f32_16x16x32_bf16 v[84:87], v[176:179], v[200:203], v[84:87]
	v_mfma_f32_16x16x32_bf16 v[40:43], v[184:187], v[200:203], v[40:43]
	v_mfma_f32_16x16x32_bf16 v[76:79], v[176:179], v[208:211], v[76:79]
	v_mfma_f32_16x16x32_bf16 v[36:39], v[184:187], v[208:211], v[36:39]
	v_mfma_f32_16x16x32_bf16 v[64:67], v[176:179], v[216:219], v[64:67]
	v_mfma_f32_16x16x32_bf16 v[28:31], v[184:187], v[216:219], v[28:31]
	s_barrier
; #define PG8_STAGE(bufoff, gbase, voff) do { _Pragma("unroll") for (int _i = 0; _i < 2; ++_i) \
;         __builtin_amdgcn_global_load_lds((const unsigned*)((const char*)(gbase) + (voff)[_i]), (PG8_LAS unsigned*)(lds + (bufoff) + ldsw + _i * 8192), 16, 0, 0); } while (0)
; #define PG8_LDA(dst, b, h) do { _Pragma("unroll") for (int m = 0; m < 4; ++m) _Pragma("unroll") for (int k = 0; k < 2; ++k) dst[m][k] = *(const PG8_LAS bf16x8*)(lds + PG8_SA(b, h) + aoff + m * 2048 + k * 1024); } while (0)
; #define PG8_LDB(dst, b, h) do { _Pragma("unroll") for (int n = 0; n < 2; ++n) _Pragma("unroll") for (int k = 0; k < 2; ++k) dst[n][k] = *(const PG8_LAS bf16x8*)(lds + PG8_SB(b, h) + boff + n * 2048 + k * 1024); } while (0)
; #define PG8_MMA(ai, bj, At, Bt) do { __builtin_amdgcn_s_setprio(1); _Pragma("unroll") for (int m = 0; m < 4; ++m) _Pragma("unroll") for (int n = 0; n < 2; ++n) _Pragma("unroll") for (int k = 0; k < 2; ++k) \
;         acc[ai][bj][m][n] = __builtin_amdgcn_mfma_f32_16x16x32_bf16(Bt[n][k], At[m][k], acc[ai][bj][m][n], 0, 0, 0); __builtin_amdgcn_s_setprio(0); } while (0)
; #define PG8_WAIT_V(n) asm volatile("s_waitcnt vmcnt(" #n ")" ::: "memory")
; template <class Epi, class Sched, bool ALIGN_EPI = false, bool SP2 = false>
; __device__ __forceinline__ void gemm_phase(PG8_LAS unsigned char* lds, const Gemm g, const Sched& S, const Epi& E) {
;     ...
;             PG8_LDB(B0, 0, 0); PG8_LDB(B1, 0, 1); PG8_SCHED; PG8_LDA(At, 0, 0); PG8_STAGE(PG8_SA(1, 1), a1 + hstep, voffA);
;             PG8_WAIT_V(8); PG8_WAIT_L(0); PG8_BAR; PG8_MMA(0, 0, At, B0); PG8_MMA(0, 1, At, B1); PG8_BAR; PG8_SCHED;
;             PG8_LDA(At, 0, 1); PG8_STAGE(PG8_SB(0, 0), b2, voffB); PG8_STAGE(PG8_SB(0, 1), b2 + hstep, voffB); PG8_STAGE(PG8_SA(0, 0), a2, voffA);
;             PG8_WAIT_V(8); PG8_WAIT_L(0); PG8_BAR; PG8_MMA(1, 0, At, B0); PG8_MMA(1, 1, At, B1); PG8_BAR; PG8_SCHED;
;             PG8_LDB(B0, 1, 0); PG8_LDB(B1, 1, 1); PG8_SCHED; PG8_LDA(At, 1, 0); PG8_STAGE(PG8_SA(0, 1), a2 + hstep, voffA);
;             PG8_WAIT_V(8); PG8_WAIT_L(0); PG8_BAR; PG8_MMA(0, 0, At, B0); PG8_MMA(0, 1, At, B1); PG8_BAR; PG8_SCHED;
;             PG8_LDA(At, 1, 1); PG8_STAGE(PG8_SB(1, 0), b3, voffB); PG8_STAGE(PG8_SB(1, 1), b3 + hstep, voffB); PG8_STAGE(PG8_SA(1, 0), a3, voffA);
;             PG8_WAIT_V(8); PG8_WAIT_L(0); PG8_BAR; PG8_MMA(1, 0, At, B0); PG8_MMA(1, 1, At, B1); PG8_BAR; PG8_SCHED;
	s_mov_b32 m0, s69
	v_lshl_add_u64 v[220:221], v[220:221], 0, s[8:9]
	ds_read_b128 v[188:191], v156 offset:49152
	ds_read_b128 v[192:195], v156 offset:50176
	ds_read_b128 v[196:199], v156 offset:51200
	ds_read_b128 v[200:203], v156 offset:52224
	ds_read_b128 v[204:207], v156 offset:53248
	ds_read_b128 v[208:211], v156 offset:54272
	ds_read_b128 v[212:215], v156 offset:55296
	ds_read_b128 v[216:219], v156 offset:56320
	global_load_lds_dwordx4 v[220:221], off
	v_lshl_add_u64 v[220:221], v[222:223], 0, s[8:9]
	s_mov_b32 m0, s1
	s_nop 0
	global_load_lds_dwordx4 v[220:221], off
	v_lshl_add_u64 v[220:221], s[94:95], 0, v[144:145]
	s_mov_b32 m0, s0
	s_nop 0
	global_load_lds_dwordx4 v[220:221], off
	v_lshl_add_u64 v[220:221], s[94:95], 0, v[146:147]
	s_mov_b32 m0, s68
	s_nop 0
	global_load_lds_dwordx4 v[220:221], off
	v_lshl_add_u64 v[220:221], v[224:225], 0, s[8:9]
	s_mov_b32 m0, s67
	s_nop 0
	global_load_lds_dwordx4 v[220:221], off
	v_lshl_add_u64 v[220:221], v[226:227], 0, s[8:9]
	s_mov_b32 m0, s83
	s_nop 0
	global_load_lds_dwordx4 v[220:221], off
	s_waitcnt vmcnt(8)
	s_waitcnt lgkmcnt(0)
	s_barrier
	s_waitcnt lgkmcnt(0)
	v_mfma_f32_16x16x32_bf16 v[88:91], v[128:131], v[188:191], v[88:91]
	v_mfma_f32_16x16x32_bf16 v[72:75], v[162:165], v[188:191], v[72:75]
	v_mfma_f32_16x16x32_bf16 v[80:83], v[128:131], v[196:199], v[80:83]
	v_mfma_f32_16x16x32_bf16 v[60:63], v[162:165], v[196:199], v[60:63]
	v_mfma_f32_16x16x32_bf16 v[68:71], v[128:131], v[204:207], v[68:71]
	v_mfma_f32_16x16x32_bf16 v[48:51], v[162:165], v[204:207], v[48:51]
	v_mfma_f32_16x16x32_bf16 v[56:59], v[128:131], v[212:215], v[56:59]
	v_mfma_f32_16x16x32_bf16 v[44:47], v[162:165], v[212:215], v[44:47]
	v_mfma_f32_16x16x32_bf16 v[88:91], v[158:161], v[192:195], v[88:91]
	v_mfma_f32_16x16x32_bf16 v[72:75], v[166:169], v[192:195], v[72:75]
	v_mfma_f32_16x16x32_bf16 v[80:83], v[158:161], v[200:203], v[80:83]
	v_mfma_f32_16x16x32_bf16 v[60:63], v[166:169], v[200:203], v[60:63]
	v_mfma_f32_16x16x32_bf16 v[68:71], v[158:161], v[208:211], v[68:71]
	v_mfma_f32_16x16x32_bf16 v[48:51], v[166:169], v[208:211], v[48:51]
	v_mfma_f32_16x16x32_bf16 v[56:59], v[158:161], v[216:219], v[56:59]
	v_mfma_f32_16x16x32_bf16 v[44:47], v[166:169], v[216:219], v[44:47]
	v_mfma_f32_16x16x32_bf16 v[32:35], v[170:173], v[188:191], v[32:35]
	v_mfma_f32_16x16x32_bf16 v[12:15], v[180:183], v[188:191], v[12:15]
	v_mfma_f32_16x16x32_bf16 v[24:27], v[170:173], v[196:199], v[24:27]
	v_mfma_f32_16x16x32_bf16 v[8:11], v[180:183], v[196:199], v[8:11]
	v_mfma_f32_16x16x32_bf16 v[20:23], v[170:173], v[204:207], v[20:23]
	v_mfma_f32_16x16x32_bf16 v[4:7], v[180:183], v[204:207], v[4:7]
	v_mfma_f32_16x16x32_bf16 v[16:19], v[170:173], v[212:215], v[16:19]
	v_mfma_f32_16x16x32_bf16 v[0:3], v[180:183], v[212:215], v[0:3]
	v_mfma_f32_16x16x32_bf16 v[32:35], v[176:179], v[192:195], v[32:35]
	v_mfma_f32_16x16x32_bf16 v[12:15], v[184:187], v[192:195], v[12:15]
	v_mfma_f32_16x16x32_bf16 v[24:27], v[176:179], v[200:203], v[24:27]
	v_mfma_f32_16x16x32_bf16 v[8:11], v[184:187], v[200:203], v[8:11]
	v_mfma_f32_16x16x32_bf16 v[20:23], v[176:179], v[208:211], v[20:23]
	v_mfma_f32_16x16x32_bf16 v[4:7], v[184:187], v[208:211], v[4:7]
	v_mfma_f32_16x16x32_bf16 v[16:19], v[176:179], v[216:219], v[16:19]
	v_mfma_f32_16x16x32_bf16 v[0:3], v[184:187], v[216:219], v[0:3]
	s_barrier
	s_movk_i32 s76, 0x100
	s_andn2_b64 vcc, exec, s[92:93]
	s_mov_b64 s[94:95], -1
	s_mov_b64 s[92:93], 0
	s_cbranch_vccz .LBB0_730
	s_and_b64 vcc, exec, s[10:11]
	s_cbranch_vccz .LBB0_733
	s_barrier

;     f32x4 nv[8];
;     if (gw < nrows) { const float* s0_ = (gw < ML) ? srcL + (size_t)gw * D : srcC + (size_t)(gw - ML) * D;
; #pragma unroll
;         for (int j = 0; j < 8; ++j) nv[j] = *(const f32x4*)(s0_ + lane * 4 + 256 * j); }
;     for (int m = gw; m < nrows; m += NGW) {
;         float* dst; int mv;
;         if (m < ML) { dst = dstL + (size_t)m * D; mv = (m >= SEQ) ? 1 : 0; }
;         else { dst = dstC + (size_t)(m - ML) * D; mv = 2; }
;         f32x4 v[8];
; #pragma unroll
;         for (int j = 0; j < 8; ++j) v[j] = nv[j];
;         { const int mn = m + NGW;
;           if (mn < nrows) { const float* s1_ = (mn < ML) ? srcL + (size_t)mn * D : srcC + (size_t)(mn - ML) * D;
; #pragma unroll
;               for (int j = 0; j < 8; ++j) nv[j] = *(const f32x4*)(s1_ + lane * 4 + 256 * j); } }
;         if (nslab > 0 && m >= ML) {
; #pragma unroll
;             for (int j = 0; j < 8; ++j) v[j] = v[j] * ALPHA;
;             for (int sidx = 0; sidx < nslab; ++sidx) { const float* sp = slab + ((size_t)sidx * (2 * CTXL) + (m - ML)) * D + lane * 4;
; #pragma unroll
;                 for (int j = 0; j < 8; ++j) v[j] += *(const f32x4*)(sp + 256 * j); }
;         }
;         if (do_ln) {
;             float s = 0.f;
; #pragma unroll
;             for (int j = 0; j < 8; ++j) s += (v[j].x + v[j].y) + (v[j].z + v[j].w);
;             const float mean = wave_sum(s) * (1.f / D); float s2 = 0.f;
; #pragma unroll
;             for (int j = 0; j < 8; ++j) { v[j] = v[j] - mean; s2 += (v[j].x * v[j].x + v[j].y * v[j].y) + (v[j].z * v[j].z + v[j].w * v[j].w); }
;             const float rstd = rsqrtf(wave_sum(s2) * (1.f / D) + LN_EPS);
; #pragma unroll
;             for (int j = 0; j < 8; ++j) { const f32x4 gg = *(const f32x4*)(lng + lane * 4 + 256 * j), bb = *(const f32x4*)(lnb + lane * 4 + 256 * j);
;                 v[j] = v[j] * rstd * gg + bb; *(f32x4*)(dst + lane * 4 + 256 * j) = v[j]; }
;     ...
;             rowwise(gw, NGW, lane, Mrows, XL, (l == 0) ? in.p[2] : (const float*)XC, XL, XC, true, in.p[22] + (size_t)l * D, in.p[23] + (size_t)l * D, true, modl, 3, 4, AC, (const float*)(ws + WS_SLAB), (l == 0) ? 8 : 0); }
.LBB0_791:
	s_setprio 0
	s_cmp_lt_i32 s72, 8
	s_cselect_b64 s[0:1], -1, 0
	s_cmp_gt_i32 s73, 7
	s_cselect_b64 s[4:5], -1, 0
	s_and_b64 s[0:1], s[0:1], s[4:5]
	s_andn2_b64 vcc, exec, s[0:1]
	s_cbranch_vccnz .LBB0_858
	v_readfirstlane_b32 s0, v174
	v_readlane_b32 s1, v246, 0
	s_lshr_b32 s0, s0, 6
	s_lshl_b32 s1, s1, 3
	s_add_i32 s84, s0, s1
	s_cmpk_gt_i32 s84, 0x3fff
	s_cbranch_scc1 .LBB0_804
	v_readlane_b32 s52, v246, 31
	v_readlane_b32 s58, v246, 37
	v_readlane_b32 s54, v246, 33
	s_lshl_b32 s0, s58, 3
	v_readlane_b32 s55, v246, 34
	v_readlane_b32 s56, v246, 35
	v_readlane_b32 s57, v246, 36
	v_readlane_b32 s59, v246, 38
	s_add_u32 s3, s54, 0x6300000
	s_addc_u32 s35, s55, 0
	s_add_i32 s1, s84, 0xffffc000
	s_ashr_i32 s85, s84, 31
	v_readlane_b32 s56, v246, 15
	s_cmpk_lt_i32 s84, 0x4000
	v_readlane_b32 s60, v246, 19
	v_readlane_b32 s61, v246, 20
	v_readlane_b32 s53, v246, 32
	s_cselect_b32 s7, s85, 0
	s_cselect_b32 s6, s84, s1
	s_mov_b64 s[8:9], s[60:61]
	s_cselect_b32 s1, s53, s9
	s_cselect_b32 s2, s52, s8
	s_lshl_b64 s[6:7], s[6:7], 13
	v_lshlrev_b32_e32 v0, 2, v174
	s_add_u32 s6, s2, s6
	s_waitcnt vmcnt(4)
	v_and_b32_e32 v70, 0xfc, v0
	s_addc_u32 s7, s1, s7
	v_mov_b32_e32 v73, 0
	v_lshlrev_b32_e32 v72, 2, v70
	v_lshl_add_u64 v[0:1], s[6:7], 0, v[72:73]
	s_movk_i32 s76, 0x1000
	v_add_co_u32_e32 v0, vcc, s76, v0
	global_load_dwordx4 v[56:59], v72, s[6:7]
	global_load_dwordx4 v[60:63], v72, s[6:7] offset:1024
	global_load_dwordx4 v[32:35], v72, s[6:7] offset:2048
	global_load_dwordx4 v[36:39], v72, s[6:7] offset:3072
	v_addc_co_u32_e32 v1, vcc, 0, v1, vcc
	global_load_dwordx4 v[48:51], v[0:1], off
	global_load_dwordx4 v[44:47], v[0:1], off offset:1024
	global_load_dwordx4 v[40:43], v[0:1], off offset:2048
	global_load_dwordx4 v[52:55], v[0:1], off offset:3072
	v_lshl_add_u64 v[0:1], s[54:55], 0, v[72:73]
	s_mov_b64 s[6:7], 0x1b800000
	v_lshl_add_u64 v[74:75], v[0:1], 0, s[6:7]
	v_mbcnt_lo_u32_b32 v0, -1, 0
	v_mbcnt_hi_u32_b32 v0, -1, v0
	v_and_b32_e32 v1, 64, v0
	v_add_u32_e32 v1, 64, v1
	v_xor_b32_e32 v2, 1, v0
	v_cmp_lt_i32_e32 vcc, v2, v1
	v_readlane_b32 s8, v246, 39
	v_readlane_b32 s20, v246, 51
	v_cndmask_b32_e32 v2, v0, v2, vcc
	v_lshlrev_b32_e32 v71, 2, v2
	v_xor_b32_e32 v2, 2, v0
	v_cmp_lt_i32_e32 vcc, v2, v1
	v_readlane_b32 s21, v246, 52
	v_readlane_b32 s22, v246, 53
	v_cndmask_b32_e32 v2, v0, v2, vcc
	v_lshlrev_b32_e32 v105, 2, v2
	v_xor_b32_e32 v2, 4, v0
	v_cmp_lt_i32_e32 vcc, v2, v1
	v_readlane_b32 s23, v246, 54
	v_lshl_add_u64 v[76:77], s[20:21], 0, v[72:73]
	v_cndmask_b32_e32 v2, v0, v2, vcc
	v_lshlrev_b32_e32 v108, 2, v2
	v_xor_b32_e32 v2, 8, v0
	v_lshl_add_u64 v[78:79], s[22:23], 0, v[72:73]
	s_mov_b64 s[6:7], 0x1000
	v_cmp_lt_i32_e32 vcc, v2, v1
	v_lshl_add_u64 v[80:81], v[76:77], 0, s[6:7]
	v_lshl_add_u64 v[82:83], v[78:79], 0, s[6:7]
	s_mov_b64 s[6:7], 0x1400
	v_cndmask_b32_e32 v2, v0, v2, vcc
	v_lshl_add_u64 v[84:85], v[76:77], 0, s[6:7]
	v_lshl_add_u64 v[86:87], v[78:79], 0, s[6:7]
	s_mov_b64 s[6:7], 0x1800
	v_lshlrev_b32_e32 v109, 2, v2
	v_xor_b32_e32 v2, 16, v0
	v_lshl_add_u64 v[88:89], v[76:77], 0, s[6:7]
	v_lshl_add_u64 v[90:91], v[78:79], 0, s[6:7]
	s_mov_b64 s[6:7], 0x1c00
	v_cmp_lt_i32_e32 vcc, v2, v1
	v_lshl_add_u64 v[92:93], v[76:77], 0, s[6:7]
	v_lshl_add_u64 v[94:95], v[78:79], 0, s[6:7]
	v_cndmask_b32_e32 v2, v0, v2, vcc
	s_lshl_b64 s[6:7], s[84:85], 13
	v_readlane_b32 s9, v246, 40
	v_lshlrev_b32_e32 v110, 2, v2
	v_xor_b32_e32 v2, 32, v0
	s_add_u32 s8, s52, s6
	v_readlane_b32 s10, v246, 41
	v_readlane_b32 s11, v246, 42
	v_cmp_lt_i32_e32 vcc, v2, v1
	s_addc_u32 s9, s53, s7
	s_ashr_i32 s1, s0, 31
	v_cndmask_b32_e32 v0, v0, v2, vcc
	s_lshl_b64 s[10:11], s[0:1], 13
	s_lshl_b64 s[6:7], s[84:85], 12
	v_lshlrev_b32_e32 v111, 2, v0
	v_and_b32_e32 v0, 63, v174
	s_add_u32 s6, s54, s6
	v_lshlrev_b32_e32 v72, 3, v0
	s_addc_u32 s7, s55, s7
	v_lshl_add_u64 v[0:1], s[6:7], 0, v[72:73]
	s_mov_b64 s[6:7], 0x6700000
	s_add_i32 s77, s84, s0
	s_mov_b32 s5, 0
	v_lshl_add_u64 v[96:97], v[0:1], 0, s[6:7]
	s_lshl_b64 s[30:31], s[0:1], 12
	s_ashr_i32 s78, s77, 31
	s_mov_b32 s34, 0x3fb504f3
	s_mov_b32 s79, 0x800000
	s_mov_b32 s80, 0x1800000
	s_mov_b32 s81, 0x1801000
	s_mov_b32 s82, 0x1c00000
	s_mov_b32 s83, 0x1c01000
	v_mov_b32_e32 v112, 0x3727c5ac
	s_mov_b64 s[52:53], 0x8000
	s_mov_b64 s[54:55], 0x6000
	s_movk_i32 s85, 0x7fff
	s_mov_b32 s86, 0xffff0000
	s_mov_b32 s87, 0x9000
	s_movk_i32 s88, 0x7000
	v_readlane_b32 s57, v246, 16
	v_readlane_b32 s58, v246, 17
	v_readlane_b32 s59, v246, 18
	v_readlane_b32 s62, v246, 21
	v_readlane_b32 s63, v246, 22
	v_readlane_b32 s64, v246, 23
	v_readlane_b32 s65, v246, 24
	v_readlane_b32 s66, v246, 25
	v_readlane_b32 s67, v246, 26
	v_readlane_b32 s68, v246, 27
	v_readlane_b32 s69, v246, 28
	v_readlane_b32 s70, v246, 29
	v_readlane_b32 s71, v246, 30
	v_readlane_b32 s12, v246, 43
	v_readlane_b32 s13, v246, 44
	v_readlane_b32 s14, v246, 45
	v_readlane_b32 s15, v246, 46
	v_readlane_b32 s16, v246, 47
	v_readlane_b32 s17, v246, 48
	v_readlane_b32 s18, v246, 49
	v_readlane_b32 s19, v246, 50
	s_branch .LBB0_796

;     __host__ __device__ bool next(int i, Unit& u) const {
;         const long L = (long)i * G + c; if (L >= nwg) return false;
;         int wgid = (int)L; { const int q = nwg / NXCD, r = nwg % NXCD, xcd = wgid % NXCD, off = wgid / NXCD; wgid = (xcd < r ? xcd * (q + 1) : r * (q + 1) + (xcd - r) * q) + off; }
; template <class Epi, class Sched, bool ALIGN_EPI = false, bool SP2 = false>
; __device__ __forceinline__ void gemm_phase(PG8_LAS unsigned char* lds, const Gemm g, const Sched& S, const Epi& E) {
;     const int tid = threadIdx.x, wid = __builtin_amdgcn_readfirstlane(tid >> 6), lane = tid & 63, wr = wid >> 2, wc = wid & 3, fr = lane & 15, fq = lane >> 4;
;     const int K = g.K, nt = K / BK, LD = g.ld ? g.ld : g.K;
;     unsigned voffA[2], voffB[2];
; #pragma unroll
;     for (int i = 0; i < 2; ++i) { int R, C; stage_rc(tid * 16 + i * 8192, R, C); const int Rb = Epi::PERM ? ((R & ~31) + perm32(R & 31)) : R;
;         voffA[i] = (unsigned)(R * LD + C) * 2u; voffB[i] = (unsigned)(Rb * LD + C) * 2u; }
;     const size_t kstep = (size_t)(BK * 2);
;     const size_t hstep = (size_t)HALF * LD * 2;
;     const size_t tstep = 2 * hstep;
;     const unsigned ldsw = (unsigned)wid * 1024u;
;     const int aoff = lds_byte(wr * 64 + fr, fq * 8), boff = lds_byte(wc * 32 + fr, fq * 8);
;     ...
;     Unit cur, nxt; int ui = 0;
;     if (!S.next(0, cur)) return;
;     f32x4 acc[2][2][4][2];
; #pragma unroll
;     for (int a = 0; a < 2; ++a)
; #pragma unroll
;         for (int b = 0; b < 2; ++b)
; #pragma unroll
;             for (int m = 0; m < 4; ++m)
; #pragma unroll
;                 for (int n = 0; n < 2; ++n) acc[a][b][m][n] = (f32x4){0.f, 0.f, 0.f, 0.f};
;     bf16x8 At[4][2], B0[2][2], B1[2][2];
;     const char* cA = (const char*)g.A + (size_t)cur.pm * tstep + (size_t)cur.ks * K * 2; const char* cB = (const char*)g.Bt + (size_t)cur.pn * tstep + (size_t)cur.ks * K * 2;
;     S.a_ready(cur);
;     if constexpr (SP2) {
;         PG8_STAGE(PG8_SB(0, 0), cB, voffB); PG8_STAGE(PG8_SB(0, 1), cB + hstep, voffB); PG8_STAGE(PG8_SA(0, 0), cA, voffA); PG8_STAGE(PG8_SA(0, 1), cA + hstep, voffA);
;         if (wr == 1) PG8_BAR;
;         PG8_WAIT_V(2); PG8_BAR;
;         PG8_STAGE(PG8_SB(1, 0), cB + kstep, voffB); PG8_STAGE(PG8_SA(1, 0), cA + kstep, voffA); PG8_STAGE(PG8_SB(1, 1), cB + hstep + kstep, voffB);
;         PG8_WAIT_V(6); PG8_BAR;
.LBB0_858:
	s_cmp_lt_i32 s72, 9
	s_cselect_b64 s[0:1], -1, 0
	s_cmp_gt_i32 s73, 8
	s_cselect_b64 s[4:5], -1, 0
	s_and_b64 s[0:1], s[0:1], s[4:5]
	s_andn2_b64 vcc, exec, s[0:1]
	s_cbranch_vccnz .LBB0_929
	v_readfirstlane_b32 vcc_lo, v174
	s_bitcmp1_b32 vcc_lo, 8
	s_cbranch_scc0 .Lsp_3
	s_setprio 1
.Lsp_3:
	v_readlane_b32 s0, v246, 0
	s_cmpk_gt_i32 s0, 0x83f
	v_readfirstlane_b32 s1, v174
	s_cbranch_scc1 .LBB0_875
	v_lshrrev_b32_e32 v0, 5, v174
	v_lshrrev_b32_e32 v2, 1, v174
	v_and_b32_e32 v0, 4, v0
	v_bfe_u32 v1, v174, 2, 2
	s_waitcnt vmcnt(3)
	v_and_b32_e32 v11, 24, v2
	v_or3_b32 v0, v0, v1, v11
	v_lshlrev_b32_e32 v1, 4, v174
	v_add_u32_e32 v8, 0x2000, v1
	v_lshrrev_b32_e32 v2, 7, v8
	s_movk_i32 s0, 0xe0
	v_and_b32_e32 v4, 32, v174
	s_add_u32 s3, s70, 0x6700000
	v_and_or_b32 v3, v2, s0, v0
	v_bitop3_b32 v9, v1, v4, 48 bitop3:0x6c
	v_and_b32_e32 v10, 64, v174
	s_waitcnt vmcnt(2)
	v_bfe_u32 v12, v174, 2, 4
	s_movk_i32 s0, 0xf0
	s_addc_u32 s6, s71, 0
	v_or_b32_e32 v1, v9, v10
	v_and_or_b32 v2, v2, s0, v12
	s_add_u32 s7, s70, 0x2100000
	v_lshl_or_b32 v130, v2, 12, v1
	v_lshrrev_b32_e32 v2, 3, v174
	s_movk_i32 s0, 0x60
	v_readlane_b32 s4, v246, 0
	s_addc_u32 s28, s71, 0
	v_and_or_b32 v0, v2, s0, v0
	s_movk_i32 s0, 0x70
	s_ashr_i32 s33, s4, 31
	v_lshl_or_b32 v132, v0, 12, v1
	v_and_or_b32 v0, v2, s0, v12
	s_lshr_b32 s0, s33, 29
	s_add_i32 s0, s4, s0
	s_lshr_b32 s10, s1, 6
	s_ashr_i32 s2, s0, 3
	s_and_b32 s0, s0, -8
	s_lshr_b32 s30, s1, 8
	s_lshl_b32 s29, s10, 10
	s_sub_i32 s0, s4, s0
	s_cmp_lt_i32 s0, 0
	s_movk_i32 s78, 0x109
	s_cselect_b32 s4, s78, 0x108
	s_mul_i32 s0, s4, s0
	s_add_i32 s0, s0, s2
	s_ashr_i32 s2, s0, 31
	s_lshr_b32 s2, s2, 25
	s_add_i32 s2, s0, s2
	s_ashr_i32 s2, s2, 7
	s_lshl_b32 s8, s2, 2
	s_sub_i32 s4, 0x42, s8
	s_lshl_b32 s2, s2, 7
	s_min_u32 s9, s4, 4
	s_sub_i32 s2, s0, s2
	v_lshl_or_b32 v128, v3, 12, v1
	s_sext_i32_i8 s0, s2
	v_cvt_f32_ubyte0_e32 v3, s9
	v_cvt_f32_i32_e32 v2, s0
	v_rcp_iflag_f32_e32 v4, v3
	v_lshl_or_b32 v134, v0, 12, v1
	s_ashr_i32 s0, s0, 30
	s_or_b32 s0, s0, 1
	v_mul_f32_e32 v0, v2, v4
	v_trunc_f32_e32 v0, v0
	v_fma_f32 v1, -v0, v3, v2
	v_cvt_i32_f32_e32 v0, v0
	v_cmp_ge_f32_e64 s[4:5], |v1|, v3
	s_and_b64 s[4:5], s[4:5], exec
	s_cselect_b32 s0, s0, 0
	v_readfirstlane_b32 s4, v0
	s_add_i32 s0, s4, s0
	s_mul_i32 s4, s0, s9
	s_sub_i32 s2, s2, s4
	s_sext_i32_i8 s2, s2
	s_add_i32 s58, s8, s2
	s_ashr_i32 s59, s58, 31
	s_bfe_i64 s[8:9], s[0:1], 0x80000
	s_lshl_b64 s[4:5], s[58:59], 20
	s_lshl_b64 s[8:9], s[8:9], 20
	s_add_u32 s62, s7, s8
	s_addc_u32 s63, s28, s9
	s_add_i32 s59, s29, 0
	s_add_i32 m0, s59, 0x10000
	v_mov_b32_e32 v133, 0
	global_load_lds_dwordx4 v132, s[62:63]
	s_add_i32 m0, s59, 0x12000
	s_add_u32 s8, s62, 0x80000
	global_load_lds_dwordx4 v128, s[62:63]
	s_addc_u32 s9, s63, 0
	s_add_i32 m0, s59, 0x14000
	v_mov_b32_e32 v129, v133
	global_load_lds_dwordx4 v132, s[8:9]
	s_add_i32 m0, s59, 0x16000
	s_add_u32 s60, s3, s4
	s_addc_u32 s61, s6, s5
	s_add_i32 s79, s59, 0x2000
	global_load_lds_dwordx4 v128, s[8:9]
	s_mov_b32 m0, s59
	s_add_u32 s4, s60, 0x80000
	global_load_lds_dwordx4 v134, s[60:61]
	s_mov_b32 m0, s79
	s_addc_u32 s5, s61, 0
	s_add_i32 s80, s59, 0x4000
	global_load_lds_dwordx4 v130, s[60:61]
	s_mov_b32 m0, s80
	s_add_i32 s81, s59, 0x6000
	global_load_lds_dwordx4 v134, s[4:5]
	s_mov_b32 m0, s81
	v_mov_b32_e32 v135, v133
	global_load_lds_dwordx4 v130, s[4:5]
	v_mov_b32_e32 v131, v133
	s_cmp_eq_u32 s30, 1
	s_mov_b32 s82, 0
	v_lshl_add_u64 v[6:7], s[62:63], 0, v[132:133]
	v_lshl_add_u64 v[4:5], s[62:63], 0, v[128:129]
	v_lshl_add_u64 v[0:1], s[60:61], 0, v[134:135]
	s_cselect_b64 s[4:5], -1, 0
	s_cmp_lg_u32 s30, 1
	v_lshl_add_u64 v[2:3], s[60:61], 0, v[130:131]
	s_cbranch_scc1 .LBB0_862
	s_barrier

; #define PG8_STAGE(bufoff, gbase, voff) do { _Pragma("unroll") for (int _i = 0; _i < 2; ++_i) \
;         __builtin_amdgcn_global_load_lds((const unsigned*)((const char*)(gbase) + (voff)[_i]), (PG8_LAS unsigned*)(lds + (bufoff) + ldsw + _i * 8192), 16, 0, 0); } while (0)
; #define PG8_LDA(dst, b, h) do { _Pragma("unroll") for (int m = 0; m < 4; ++m) _Pragma("unroll") for (int k = 0; k < 2; ++k) dst[m][k] = *(const PG8_LAS bf16x8*)(lds + PG8_SA(b, h) + aoff + m * 2048 + k * 1024); } while (0)
; #define PG8_LDB(dst, b, h) do { _Pragma("unroll") for (int n = 0; n < 2; ++n) _Pragma("unroll") for (int k = 0; k < 2; ++k) dst[n][k] = *(const PG8_LAS bf16x8*)(lds + PG8_SB(b, h) + boff + n * 2048 + k * 1024); } while (0)
; #define PG8_MMA(ai, bj, At, Bt) do { __builtin_amdgcn_s_setprio(1); _Pragma("unroll") for (int m = 0; m < 4; ++m) _Pragma("unroll") for (int n = 0; n < 2; ++n) _Pragma("unroll") for (int k = 0; k < 2; ++k) \
;         acc[ai][bj][m][n] = __builtin_amdgcn_mfma_f32_16x16x32_bf16(Bt[n][k], At[m][k], acc[ai][bj][m][n], 0, 0, 0); __builtin_amdgcn_s_setprio(0); } while (0)
; #define PG8_WAIT_V(n) asm volatile("s_waitcnt vmcnt(" #n ")" ::: "memory")
; #define PG8_WAIT_L(n) asm volatile("s_waitcnt lgkmcnt(" #n ")" ::: "memory")
; #define PG8_BAR __builtin_amdgcn_s_barrier()
; #define PG8_SCHED __builtin_amdgcn_sched_barrier(0)
; template <class Epi, class Sched, bool ALIGN_EPI = false, bool SP2 = false>
; __device__ __forceinline__ void gemm_phase(PG8_LAS unsigned char* lds, const Gemm g, const Sched& S, const Epi& E) {
;     ...
;             const bool last = (t == nt - 2);
;             const char* a1 = cA + (size_t)(t + 1) * kstep;
;             const char* a2 = last ? nA : cA + (size_t)(t + 2) * kstep; const char* b2 = last ? nB : cB + (size_t)(t + 2) * kstep;
;             const char* a3 = a2 + kstep; const char* b3 = b2 + kstep;
;             if (last && has_next) S.a_ready(nxt);
;             if constexpr (SP2) {
;             PG8_LDB(B0, 0, 0); PG8_LDB(B1, 0, 1); PG8_SCHED; PG8_LDA(At, 0, 0); PG8_STAGE(PG8_SA(1, 1), a1 + hstep, voffA);
;             PG8_WAIT_V(8); PG8_WAIT_L(0); PG8_BAR; PG8_MMA(0, 0, At, B0); PG8_MMA(0, 1, At, B1); PG8_BAR; PG8_SCHED;
;             PG8_LDA(At, 0, 1); PG8_STAGE(PG8_SB(0, 0), b2, voffB); PG8_STAGE(PG8_SB(0, 1), b2 + hstep, voffB); PG8_STAGE(PG8_SA(0, 0), a2, voffA);
.LBB0_868:
	ds_read_b128 v[152:155], v149
	ds_read_b128 v[156:159], v149 offset:1024
	ds_read_b128 v[160:163], v149 offset:2048
	ds_read_b128 v[164:167], v149 offset:3072
	ds_read_b128 v[168:171], v150
	ds_read_b128 v[176:179], v150 offset:1024
	ds_read_b128 v[180:183], v150 offset:2048
	ds_read_b128 v[184:187], v150 offset:3072
	s_add_u32 s2, s60, 0xfff80080
	s_addc_u32 s62, s61, -1
	s_cmp_eq_u32 s90, 28
	s_cselect_b32 s77, s53, s62
	s_cselect_b32 s76, s86, s2
	s_cselect_b32 s63, s35, s89
	s_cselect_b32 s62, s87, s88
	v_lshl_add_u64 v[144:145], s[60:61], 0, v[136:137]
	s_add_i32 m0, s59, 0xc000
	ds_read_b128 v[188:191], v151
	ds_read_b128 v[192:195], v151 offset:1024
	ds_read_b128 v[196:199], v151 offset:2048
	ds_read_b128 v[200:203], v151 offset:3072
	ds_read_b128 v[204:207], v151 offset:4096
	ds_read_b128 v[208:211], v151 offset:5120
	ds_read_b128 v[212:215], v151 offset:6144
	ds_read_b128 v[216:219], v151 offset:7168
	global_load_lds_dwordx4 v[144:145], off
	v_lshl_add_u64 v[144:145], s[60:61], 0, v[138:139]
	s_add_i32 m0, s59, 0xe000
	s_nop 0
	global_load_lds_dwordx4 v[144:145], off
	s_waitcnt vmcnt(8)
	s_waitcnt lgkmcnt(0)
	s_barrier
	s_waitcnt lgkmcnt(0)
	v_mfma_f32_16x16x32_bf16 v[124:127], v[152:155], v[188:191], v[124:127]
	v_mfma_f32_16x16x32_bf16 v[120:123], v[160:163], v[188:191], v[120:123]
	v_mfma_f32_16x16x32_bf16 v[108:111], v[152:155], v[196:199], v[108:111]
	v_mfma_f32_16x16x32_bf16 v[104:107], v[160:163], v[196:199], v[104:107]
	v_mfma_f32_16x16x32_bf16 v[92:95], v[152:155], v[204:207], v[92:95]
	v_mfma_f32_16x16x32_bf16 v[88:91], v[160:163], v[204:207], v[88:91]
	v_mfma_f32_16x16x32_bf16 v[76:79], v[152:155], v[212:215], v[76:79]
	v_mfma_f32_16x16x32_bf16 v[72:75], v[160:163], v[212:215], v[72:75]
	v_mfma_f32_16x16x32_bf16 v[124:127], v[156:159], v[192:195], v[124:127]
	v_mfma_f32_16x16x32_bf16 v[120:123], v[164:167], v[192:195], v[120:123]
	v_mfma_f32_16x16x32_bf16 v[108:111], v[156:159], v[200:203], v[108:111]
	v_mfma_f32_16x16x32_bf16 v[104:107], v[164:167], v[200:203], v[104:107]
	v_mfma_f32_16x16x32_bf16 v[92:95], v[156:159], v[208:211], v[92:95]
	v_mfma_f32_16x16x32_bf16 v[88:91], v[164:167], v[208:211], v[88:91]
	v_mfma_f32_16x16x32_bf16 v[76:79], v[156:159], v[216:219], v[76:79]
	v_mfma_f32_16x16x32_bf16 v[72:75], v[164:167], v[216:219], v[72:75]
	v_mfma_f32_16x16x32_bf16 v[116:119], v[168:171], v[188:191], v[116:119]
	v_mfma_f32_16x16x32_bf16 v[112:115], v[180:183], v[188:191], v[112:115]
	v_mfma_f32_16x16x32_bf16 v[100:103], v[168:171], v[196:199], v[100:103]
	v_mfma_f32_16x16x32_bf16 v[96:99], v[180:183], v[196:199], v[96:99]
	v_mfma_f32_16x16x32_bf16 v[84:87], v[168:171], v[204:207], v[84:87]
	v_mfma_f32_16x16x32_bf16 v[80:83], v[180:183], v[204:207], v[80:83]
	v_mfma_f32_16x16x32_bf16 v[68:71], v[168:171], v[212:215], v[68:71]
	v_mfma_f32_16x16x32_bf16 v[64:67], v[180:183], v[212:215], v[64:67]
	v_mfma_f32_16x16x32_bf16 v[116:119], v[176:179], v[192:195], v[116:119]
	v_mfma_f32_16x16x32_bf16 v[112:115], v[184:187], v[192:195], v[112:115]
	v_mfma_f32_16x16x32_bf16 v[100:103], v[176:179], v[200:203], v[100:103]
	v_mfma_f32_16x16x32_bf16 v[96:99], v[184:187], v[200:203], v[96:99]
	v_mfma_f32_16x16x32_bf16 v[84:87], v[176:179], v[208:211], v[84:87]
	v_mfma_f32_16x16x32_bf16 v[80:83], v[184:187], v[208:211], v[80:83]
	v_mfma_f32_16x16x32_bf16 v[68:71], v[176:179], v[216:219], v[68:71]
	v_mfma_f32_16x16x32_bf16 v[64:67], v[184:187], v[216:219], v[64:67]
	s_barrier
	s_add_i32 s2, s66, s29
	v_lshl_add_u64 v[144:145], s[62:63], 0, v[132:133]
	s_mov_b32 m0, s2
	ds_read_b128 v[188:191], v151 offset:16384
	ds_read_b128 v[192:195], v151 offset:17408
	ds_read_b128 v[196:199], v151 offset:18432
	ds_read_b128 v[200:203], v151 offset:19456
	ds_read_b128 v[204:207], v151 offset:20480
	ds_read_b128 v[208:211], v151 offset:21504
	ds_read_b128 v[212:215], v151 offset:22528
	ds_read_b128 v[216:219], v151 offset:23552
	global_load_lds_dwordx4 v[144:145], off
	s_add_i32 m0, s2, 0x2000
	s_add_u32 s68, s62, 0x80000
	v_lshl_add_u64 v[172:173], s[62:63], 0, v[128:129]
	s_addc_u32 s69, s63, 0
	s_add_i32 s2, s67, s29
	global_load_lds_dwordx4 v[172:173], off
	v_lshl_add_u64 v[220:221], s[68:69], 0, v[132:133]
	s_mov_b32 m0, s2
	v_lshl_add_u64 v[222:223], s[76:77], 0, v[130:131]
	global_load_lds_dwordx4 v[220:221], off
	v_lshl_add_u64 v[220:221], s[68:69], 0, v[128:129]
	s_add_i32 m0, s2, 0x2000
	s_nop 0
	global_load_lds_dwordx4 v[220:221], off
	v_lshl_add_u64 v[220:221], s[76:77], 0, v[134:135]
	s_mov_b32 m0, s59
	s_nop 0
	global_load_lds_dwordx4 v[220:221], off
	s_mov_b32 m0, s79
	s_nop 0
	global_load_lds_dwordx4 v[222:223], off
	s_waitcnt vmcnt(8)
	s_waitcnt lgkmcnt(0)
	s_barrier
; #define PG8_STAGE(bufoff, gbase, voff) do { _Pragma("unroll") for (int _i = 0; _i < 2; ++_i) \
;         __builtin_amdgcn_global_load_lds((const unsigned*)((const char*)(gbase) + (voff)[_i]), (PG8_LAS unsigned*)(lds + (bufoff) + ldsw + _i * 8192), 16, 0, 0); } while (0)
; #define PG8_LDA(dst, b, h) do { _Pragma("unroll") for (int m = 0; m < 4; ++m) _Pragma("unroll") for (int k = 0; k < 2; ++k) dst[m][k] = *(const PG8_LAS bf16x8*)(lds + PG8_SA(b, h) + aoff + m * 2048 + k * 1024); } while (0)
; #define PG8_LDB(dst, b, h) do { _Pragma("unroll") for (int n = 0; n < 2; ++n) _Pragma("unroll") for (int k = 0; k < 2; ++k) dst[n][k] = *(const PG8_LAS bf16x8*)(lds + PG8_SB(b, h) + boff + n * 2048 + k * 1024); } while (0)
; #define PG8_MMA(ai, bj, At, Bt) do { __builtin_amdgcn_s_setprio(1); _Pragma("unroll") for (int m = 0; m < 4; ++m) _Pragma("unroll") for (int n = 0; n < 2; ++n) _Pragma("unroll") for (int k = 0; k < 2; ++k) \
;         acc[ai][bj][m][n] = __builtin_amdgcn_mfma_f32_16x16x32_bf16(Bt[n][k], At[m][k], acc[ai][bj][m][n], 0, 0, 0); __builtin_amdgcn_s_setprio(0); } while (0)
; #define PG8_WAIT_V(n) asm volatile("s_waitcnt vmcnt(" #n ")" ::: "memory")
; #define PG8_WAIT_L(n) asm volatile("s_waitcnt lgkmcnt(" #n ")" ::: "memory")
; #define PG8_BAR __builtin_amdgcn_s_barrier()
; #define PG8_SCHED __builtin_amdgcn_sched_barrier(0)
; template <class Epi, class Sched, bool ALIGN_EPI = false, bool SP2 = false>
; __device__ __forceinline__ void gemm_phase(PG8_LAS unsigned char* lds, const Gemm g, const Sched& S, const Epi& E) {
;     ...
;             PG8_WAIT_V(8); PG8_WAIT_L(0); PG8_BAR; PG8_MMA(1, 0, At, B0); PG8_MMA(1, 1, At, B1); PG8_BAR; PG8_SCHED;
;             PG8_LDB(B0, 1, 0); PG8_LDB(B1, 1, 1); PG8_SCHED; PG8_LDA(At, 1, 0); PG8_STAGE(PG8_SA(0, 1), a2 + hstep, voffA);
;             PG8_WAIT_V(8); PG8_WAIT_L(0); PG8_BAR; PG8_MMA(0, 0, At, B0); PG8_MMA(0, 1, At, B1); PG8_BAR; PG8_SCHED;
	s_waitcnt lgkmcnt(0)
	v_mfma_f32_16x16x32_bf16 v[60:63], v[152:155], v[188:191], v[60:63]
	v_mfma_f32_16x16x32_bf16 v[56:59], v[160:163], v[188:191], v[56:59]
	v_mfma_f32_16x16x32_bf16 v[44:47], v[152:155], v[196:199], v[44:47]
	v_mfma_f32_16x16x32_bf16 v[40:43], v[160:163], v[196:199], v[40:43]
	v_mfma_f32_16x16x32_bf16 v[28:31], v[152:155], v[204:207], v[28:31]
	v_mfma_f32_16x16x32_bf16 v[24:27], v[160:163], v[204:207], v[24:27]
	v_mfma_f32_16x16x32_bf16 v[12:15], v[152:155], v[212:215], v[12:15]
	v_mfma_f32_16x16x32_bf16 v[8:11], v[160:163], v[212:215], v[8:11]
	v_mfma_f32_16x16x32_bf16 v[60:63], v[156:159], v[192:195], v[60:63]
	v_mfma_f32_16x16x32_bf16 v[56:59], v[164:167], v[192:195], v[56:59]
	v_mfma_f32_16x16x32_bf16 v[44:47], v[156:159], v[200:203], v[44:47]
	v_mfma_f32_16x16x32_bf16 v[40:43], v[164:167], v[200:203], v[40:43]
	v_mfma_f32_16x16x32_bf16 v[28:31], v[156:159], v[208:211], v[28:31]
	v_mfma_f32_16x16x32_bf16 v[24:27], v[164:167], v[208:211], v[24:27]
	v_mfma_f32_16x16x32_bf16 v[12:15], v[156:159], v[216:219], v[12:15]
	v_mfma_f32_16x16x32_bf16 v[8:11], v[164:167], v[216:219], v[8:11]
	v_mfma_f32_16x16x32_bf16 v[52:55], v[168:171], v[188:191], v[52:55]
	v_mfma_f32_16x16x32_bf16 v[48:51], v[180:183], v[188:191], v[48:51]
	v_mfma_f32_16x16x32_bf16 v[36:39], v[168:171], v[196:199], v[36:39]
	v_mfma_f32_16x16x32_bf16 v[32:35], v[180:183], v[196:199], v[32:35]
	v_mfma_f32_16x16x32_bf16 v[20:23], v[168:171], v[204:207], v[20:23]
	v_mfma_f32_16x16x32_bf16 v[16:19], v[180:183], v[204:207], v[16:19]
	v_mfma_f32_16x16x32_bf16 v[4:7], v[168:171], v[212:215], v[4:7]
	v_mfma_f32_16x16x32_bf16 v[0:3], v[180:183], v[212:215], v[0:3]
	v_mfma_f32_16x16x32_bf16 v[52:55], v[176:179], v[192:195], v[52:55]
	v_mfma_f32_16x16x32_bf16 v[48:51], v[184:187], v[192:195], v[48:51]
	v_mfma_f32_16x16x32_bf16 v[36:39], v[176:179], v[200:203], v[36:39]
	v_mfma_f32_16x16x32_bf16 v[32:35], v[184:187], v[200:203], v[32:35]
	v_mfma_f32_16x16x32_bf16 v[20:23], v[176:179], v[208:211], v[20:23]
	v_mfma_f32_16x16x32_bf16 v[16:19], v[184:187], v[208:211], v[16:19]
	v_mfma_f32_16x16x32_bf16 v[4:7], v[176:179], v[216:219], v[4:7]
	v_mfma_f32_16x16x32_bf16 v[0:3], v[184:187], v[216:219], v[0:3]
	s_barrier
	s_add_i32 s2, 0, 0x18000
	s_add_i32 s70, 0, 0x1c000
	v_add_u32_e32 v164, s2, v147
	v_add_u32_e32 v184, s70, v147
	ds_read_b128 v[152:155], v164
	ds_read_b128 v[156:159], v164 offset:1024
	ds_read_b128 v[160:163], v164 offset:2048
	ds_read_b128 v[164:167], v164 offset:3072
	ds_read_b128 v[168:171], v184
	ds_read_b128 v[176:179], v184 offset:1024
	ds_read_b128 v[180:183], v184 offset:2048
	ds_read_b128 v[184:187], v184 offset:3072
	s_add_u32 s68, s76, 0x80000
	s_addc_u32 s69, s77, 0
	s_mov_b32 m0, s80
	v_lshl_add_u64 v[224:225], s[68:69], 0, v[134:135]
	ds_read_b128 v[188:191], v151 offset:32768
	ds_read_b128 v[192:195], v151 offset:33792
	ds_read_b128 v[196:199], v151 offset:34816
	ds_read_b128 v[200:203], v151 offset:35840
	ds_read_b128 v[204:207], v151 offset:36864
	ds_read_b128 v[208:211], v151 offset:37888
	ds_read_b128 v[212:215], v151 offset:38912
	ds_read_b128 v[216:219], v151 offset:39936
	global_load_lds_dwordx4 v[224:225], off
	v_lshl_add_u64 v[224:225], s[68:69], 0, v[130:131]
	s_mov_b32 m0, s81
	s_nop 0
	global_load_lds_dwordx4 v[224:225], off
	s_waitcnt vmcnt(8)
	s_waitcnt lgkmcnt(0)
	s_barrier
	s_waitcnt lgkmcnt(0)
	v_mfma_f32_16x16x32_bf16 v[124:127], v[152:155], v[188:191], v[124:127]
	v_mfma_f32_16x16x32_bf16 v[120:123], v[160:163], v[188:191], v[120:123]
	v_mfma_f32_16x16x32_bf16 v[108:111], v[152:155], v[196:199], v[108:111]
	v_mfma_f32_16x16x32_bf16 v[104:107], v[160:163], v[196:199], v[104:107]
	v_mfma_f32_16x16x32_bf16 v[92:95], v[152:155], v[204:207], v[92:95]
	v_mfma_f32_16x16x32_bf16 v[88:91], v[160:163], v[204:207], v[88:91]
	v_mfma_f32_16x16x32_bf16 v[76:79], v[152:155], v[212:215], v[76:79]
	v_mfma_f32_16x16x32_bf16 v[72:75], v[160:163], v[212:215], v[72:75]
	v_mfma_f32_16x16x32_bf16 v[124:127], v[156:159], v[192:195], v[124:127]
	v_mfma_f32_16x16x32_bf16 v[120:123], v[164:167], v[192:195], v[120:123]
	v_mfma_f32_16x16x32_bf16 v[108:111], v[156:159], v[200:203], v[108:111]
	v_mfma_f32_16x16x32_bf16 v[104:107], v[164:167], v[200:203], v[104:107]
	v_mfma_f32_16x16x32_bf16 v[92:95], v[156:159], v[208:211], v[92:95]
	v_mfma_f32_16x16x32_bf16 v[88:91], v[164:167], v[208:211], v[88:91]
	v_mfma_f32_16x16x32_bf16 v[76:79], v[156:159], v[216:219], v[76:79]
	v_mfma_f32_16x16x32_bf16 v[72:75], v[164:167], v[216:219], v[72:75]
	v_mfma_f32_16x16x32_bf16 v[116:119], v[168:171], v[188:191], v[116:119]
	v_mfma_f32_16x16x32_bf16 v[112:115], v[180:183], v[188:191], v[112:115]
	v_mfma_f32_16x16x32_bf16 v[100:103], v[168:171], v[196:199], v[100:103]
	v_mfma_f32_16x16x32_bf16 v[96:99], v[180:183], v[196:199], v[96:99]
	v_mfma_f32_16x16x32_bf16 v[84:87], v[168:171], v[204:207], v[84:87]
	v_mfma_f32_16x16x32_bf16 v[80:83], v[180:183], v[204:207], v[80:83]
	v_mfma_f32_16x16x32_bf16 v[68:71], v[168:171], v[212:215], v[68:71]
	v_mfma_f32_16x16x32_bf16 v[64:67], v[180:183], v[212:215], v[64:67]
	v_mfma_f32_16x16x32_bf16 v[116:119], v[176:179], v[192:195], v[116:119]
	v_mfma_f32_16x16x32_bf16 v[112:115], v[184:187], v[192:195], v[112:115]
	v_mfma_f32_16x16x32_bf16 v[100:103], v[176:179], v[200:203], v[100:103]
	v_mfma_f32_16x16x32_bf16 v[96:99], v[184:187], v[200:203], v[96:99]
	v_mfma_f32_16x16x32_bf16 v[84:87], v[176:179], v[208:211], v[84:87]
	v_mfma_f32_16x16x32_bf16 v[80:83], v[184:187], v[208:211], v[80:83]
	v_mfma_f32_16x16x32_bf16 v[68:71], v[176:179], v[216:219], v[68:71]
	v_mfma_f32_16x16x32_bf16 v[64:67], v[184:187], v[216:219], v[64:67]
	s_barrier
; #define PG8_STAGE(bufoff, gbase, voff) do { _Pragma("unroll") for (int _i = 0; _i < 2; ++_i) \
;         __builtin_amdgcn_global_load_lds((const unsigned*)((const char*)(gbase) + (voff)[_i]), (PG8_LAS unsigned*)(lds + (bufoff) + ldsw + _i * 8192), 16, 0, 0); } while (0)
; #define PG8_LDA(dst, b, h) do { _Pragma("unroll") for (int m = 0; m < 4; ++m) _Pragma("unroll") for (int k = 0; k < 2; ++k) dst[m][k] = *(const PG8_LAS bf16x8*)(lds + PG8_SA(b, h) + aoff + m * 2048 + k * 1024); } while (0)
; #define PG8_MMA(ai, bj, At, Bt) do { __builtin_amdgcn_s_setprio(1); _Pragma("unroll") for (int m = 0; m < 4; ++m) _Pragma("unroll") for (int n = 0; n < 2; ++n) _Pragma("unroll") for (int k = 0; k < 2; ++k) \
;         acc[ai][bj][m][n] = __builtin_amdgcn_mfma_f32_16x16x32_bf16(Bt[n][k], At[m][k], acc[ai][bj][m][n], 0, 0, 0); __builtin_amdgcn_s_setprio(0); } while (0)
; #define PG8_WAIT_V(n) asm volatile("s_waitcnt vmcnt(" #n ")" ::: "memory")
; #define PG8_WAIT_L(n) asm volatile("s_waitcnt lgkmcnt(" #n ")" ::: "memory")
; #define PG8_BAR __builtin_amdgcn_s_barrier()
; #define PG8_SCHED __builtin_amdgcn_sched_barrier(0)
; template <class Epi, class Sched, bool ALIGN_EPI = false, bool SP2 = false>
; __device__ __forceinline__ void gemm_phase(PG8_LAS unsigned char* lds, const Gemm g, const Sched& S, const Epi& E) {
;     ...
;             PG8_LDA(At, 1, 1); PG8_STAGE(PG8_SB(1, 0), b3, voffB); PG8_STAGE(PG8_SB(1, 1), b3 + hstep, voffB); PG8_STAGE(PG8_SA(1, 0), a3, voffA);
;             PG8_WAIT_V(8); PG8_WAIT_L(0); PG8_BAR; PG8_MMA(1, 0, At, B0); PG8_MMA(1, 1, At, B1); PG8_BAR; PG8_SCHED;
	s_add_i32 s2, s2, s29
	v_lshl_add_u64 v[144:145], v[144:145], 0, s[10:11]
	s_mov_b32 m0, s2
	ds_read_b128 v[188:191], v151 offset:49152
	ds_read_b128 v[192:195], v151 offset:50176
	ds_read_b128 v[196:199], v151 offset:51200
	ds_read_b128 v[200:203], v151 offset:52224
	ds_read_b128 v[204:207], v151 offset:53248
	ds_read_b128 v[208:211], v151 offset:54272
	ds_read_b128 v[212:215], v151 offset:55296
	ds_read_b128 v[216:219], v151 offset:56320
	global_load_lds_dwordx4 v[144:145], off
	s_add_i32 m0, s2, 0x2000
	s_add_u32 s62, s62, 0x80080
	v_lshl_add_u64 v[144:145], v[172:173], 0, s[10:11]
	s_addc_u32 s63, s63, 0
	s_add_i32 s2, s70, s29
	global_load_lds_dwordx4 v[144:145], off
	v_lshl_add_u64 v[144:145], s[62:63], 0, v[132:133]
	s_mov_b32 m0, s2
	s_nop 0
	global_load_lds_dwordx4 v[144:145], off
	v_lshl_add_u64 v[144:145], s[62:63], 0, v[128:129]
	s_add_i32 m0, s2, 0x2000
	s_nop 0
	global_load_lds_dwordx4 v[144:145], off
	v_lshl_add_u64 v[144:145], v[220:221], 0, s[10:11]
	s_mov_b32 m0, s83
	s_nop 0
	global_load_lds_dwordx4 v[144:145], off
	v_lshl_add_u64 v[144:145], v[222:223], 0, s[10:11]
	s_mov_b32 m0, s84
	s_nop 0
	global_load_lds_dwordx4 v[144:145], off
	s_waitcnt vmcnt(8)
	s_waitcnt lgkmcnt(0)
	s_barrier
	s_waitcnt lgkmcnt(0)
	v_mfma_f32_16x16x32_bf16 v[60:63], v[152:155], v[188:191], v[60:63]
	v_mfma_f32_16x16x32_bf16 v[56:59], v[160:163], v[188:191], v[56:59]
	v_mfma_f32_16x16x32_bf16 v[44:47], v[152:155], v[196:199], v[44:47]
	v_mfma_f32_16x16x32_bf16 v[40:43], v[160:163], v[196:199], v[40:43]
	v_mfma_f32_16x16x32_bf16 v[28:31], v[152:155], v[204:207], v[28:31]
	v_mfma_f32_16x16x32_bf16 v[24:27], v[160:163], v[204:207], v[24:27]
	v_mfma_f32_16x16x32_bf16 v[12:15], v[152:155], v[212:215], v[12:15]
	v_mfma_f32_16x16x32_bf16 v[8:11], v[160:163], v[212:215], v[8:11]
	v_mfma_f32_16x16x32_bf16 v[60:63], v[156:159], v[192:195], v[60:63]
	v_mfma_f32_16x16x32_bf16 v[56:59], v[164:167], v[192:195], v[56:59]
	v_mfma_f32_16x16x32_bf16 v[44:47], v[156:159], v[200:203], v[44:47]
	v_mfma_f32_16x16x32_bf16 v[40:43], v[164:167], v[200:203], v[40:43]
	v_mfma_f32_16x16x32_bf16 v[28:31], v[156:159], v[208:211], v[28:31]
	v_mfma_f32_16x16x32_bf16 v[24:27], v[164:167], v[208:211], v[24:27]
	v_mfma_f32_16x16x32_bf16 v[12:15], v[156:159], v[216:219], v[12:15]
	v_mfma_f32_16x16x32_bf16 v[8:11], v[164:167], v[216:219], v[8:11]
	v_mfma_f32_16x16x32_bf16 v[52:55], v[168:171], v[188:191], v[52:55]
	v_mfma_f32_16x16x32_bf16 v[48:51], v[180:183], v[188:191], v[48:51]
	v_mfma_f32_16x16x32_bf16 v[36:39], v[168:171], v[196:199], v[36:39]
	v_mfma_f32_16x16x32_bf16 v[32:35], v[180:183], v[196:199], v[32:35]
	v_mfma_f32_16x16x32_bf16 v[20:23], v[168:171], v[204:207], v[20:23]
	v_mfma_f32_16x16x32_bf16 v[16:19], v[180:183], v[204:207], v[16:19]
	v_mfma_f32_16x16x32_bf16 v[4:7], v[168:171], v[212:215], v[4:7]
	v_mfma_f32_16x16x32_bf16 v[0:3], v[180:183], v[212:215], v[0:3]
	v_mfma_f32_16x16x32_bf16 v[52:55], v[176:179], v[192:195], v[52:55]
	v_mfma_f32_16x16x32_bf16 v[48:51], v[184:187], v[192:195], v[48:51]
	v_mfma_f32_16x16x32_bf16 v[36:39], v[176:179], v[200:203], v[36:39]
	v_mfma_f32_16x16x32_bf16 v[32:35], v[184:187], v[200:203], v[32:35]
	v_mfma_f32_16x16x32_bf16 v[20:23], v[176:179], v[208:211], v[20:23]
	v_mfma_f32_16x16x32_bf16 v[16:19], v[184:187], v[208:211], v[16:19]
	v_mfma_f32_16x16x32_bf16 v[4:7], v[176:179], v[216:219], v[4:7]
	v_mfma_f32_16x16x32_bf16 v[0:3], v[184:187], v[216:219], v[0:3]
	s_barrier
	s_add_i32 s90, s90, 2
	s_add_u32 s60, s60, 0x100
	s_addc_u32 s61, s61, 0
	s_add_u32 s88, s88, 0x100
	s_addc_u32 s89, s89, 0
	s_cmp_gt_u32 s90, 29
	s_cbranch_scc0 .LBB0_868
	s_and_b64 vcc, exec, s[30:31]
	s_cbranch_vccz .LBB0_871
	s_barrier

;     __host__ __device__ bool next(int i, Unit& u) const {
;         const long L = (long)i * G + c; if (L >= nwg) return false;
;         int wgid = (int)L; { const int q = nwg / NXCD, r = nwg % NXCD, xcd = wgid % NXCD, off = wgid / NXCD; wgid = (xcd < r ? xcd * (q + 1) : r * (q + 1) + (xcd - r) * q) + off; }
; template <class Epi, class Sched, bool ALIGN_EPI = false, bool SP2 = false>
; __device__ __forceinline__ void gemm_phase(PG8_LAS unsigned char* lds, const Gemm g, const Sched& S, const Epi& E) {
;     const int tid = threadIdx.x, wid = __builtin_amdgcn_readfirstlane(tid >> 6), lane = tid & 63, wr = wid >> 2, wc = wid & 3, fr = lane & 15, fq = lane >> 4;
;     const int K = g.K, nt = K / BK, LD = g.ld ? g.ld : g.K;
;     unsigned voffA[2], voffB[2];
; #pragma unroll
;     for (int i = 0; i < 2; ++i) { int R, C; stage_rc(tid * 16 + i * 8192, R, C); const int Rb = Epi::PERM ? ((R & ~31) + perm32(R & 31)) : R;
;         voffA[i] = (unsigned)(R * LD + C) * 2u; voffB[i] = (unsigned)(Rb * LD + C) * 2u; }
;     const size_t kstep = (size_t)(BK * 2);
;     const size_t hstep = (size_t)HALF * LD * 2;
;     const size_t tstep = 2 * hstep;
;     const unsigned ldsw = (unsigned)wid * 1024u;
;     const int aoff = lds_byte(wr * 64 + fr, fq * 8), boff = lds_byte(wc * 32 + fr, fq * 8);
.LBB0_929:
	s_setprio 0
	s_cmp_lt_i32 s72, 10
	s_cselect_b64 s[0:1], -1, 0
	s_cmp_gt_i32 s73, 9
	s_cselect_b64 s[4:5], -1, 0
	s_and_b64 s[0:1], s[0:1], s[4:5]
	s_andn2_b64 vcc, exec, s[0:1]
	s_cbranch_vccnz .LBB0_1028
	v_readfirstlane_b32 vcc_lo, v174
	s_bitcmp1_b32 vcc_lo, 8
	s_cbranch_scc0 .Lsp_4
	s_setprio 1
.Lsp_4:
	v_lshlrev_b32_e32 v0, 4, v174
	v_and_b32_e32 v1, 32, v174
	v_bfe_u32 v179, v174, 2, 4
	v_lshrrev_b32_e32 v2, 3, v174
	s_movk_i32 s0, 0x70
	v_add_u32_e32 v180, 0x2000, v0
	v_bitop3_b32 v176, v0, v1, 48 bitop3:0x6c
	v_and_b32_e32 v177, 64, v174
	v_and_or_b32 v2, v2, s0, v179
	v_lshrrev_b32_e32 v0, 7, v180
	s_movk_i32 s0, 0xf0
	v_or_b32_e32 v1, v176, v177
	v_and_or_b32 v0, v0, s0, v179
	s_add_u32 s3, s70, 0x4100000
	v_bfe_u32 v178, v174, 4, 2
	v_lshl_or_b32 v144, v2, 14, v1
	v_lshl_or_b32 v146, v0, 14, v1
	v_lshlrev_b32_e32 v0, 6, v174
	v_lshlrev_b32_e32 v1, 2, v174
	s_addc_u32 s80, s71, 0
	v_lshlrev_b32_e32 v182, 4, v178
	v_and_b32_e32 v0, 0x3c0, v0
	v_and_b32_e32 v1, 32, v1
	v_readlane_b32 s1, v246, 0
	v_readfirstlane_b32 s4, v174
	v_and_b32_e32 v181, 15, v174
	s_cmpk_gt_i32 s1, 0x1ff
	v_bitop3_b32 v183, v182, v1, v0 bitop3:0x36
	s_cbranch_scc1 .LBB0_958
	s_ashr_i32 s6, s1, 31
	s_lshr_b32 s0, s6, 29
	s_add_i32 s5, s1, s0
	s_and_b32 s0, s5, -8
	s_sub_i32 s7, s1, s0
	s_cmp_gt_i32 s7, -1
	s_cbranch_scc0 .LBB0_933
	s_lshl_b32 s8, s7, 6
	s_cbranch_execz .LBB0_934
	s_branch .LBB0_935

; #define PG8_STAGE(bufoff, gbase, voff) do { _Pragma("unroll") for (int _i = 0; _i < 2; ++_i) \
;         __builtin_amdgcn_global_load_lds((const unsigned*)((const char*)(gbase) + (voff)[_i]), (PG8_LAS unsigned*)(lds + (bufoff) + ldsw + _i * 8192), 16, 0, 0); } while (0)
; #define PG8_LDA(dst, b, h) do { _Pragma("unroll") for (int m = 0; m < 4; ++m) _Pragma("unroll") for (int k = 0; k < 2; ++k) dst[m][k] = *(const PG8_LAS bf16x8*)(lds + PG8_SA(b, h) + aoff + m * 2048 + k * 1024); } while (0)
; #define PG8_LDB(dst, b, h) do { _Pragma("unroll") for (int n = 0; n < 2; ++n) _Pragma("unroll") for (int k = 0; k < 2; ++k) dst[n][k] = *(const PG8_LAS bf16x8*)(lds + PG8_SB(b, h) + boff + n * 2048 + k * 1024); } while (0)
; #define PG8_MMA(ai, bj, At, Bt) do { __builtin_amdgcn_s_setprio(1); _Pragma("unroll") for (int m = 0; m < 4; ++m) _Pragma("unroll") for (int n = 0; n < 2; ++n) _Pragma("unroll") for (int k = 0; k < 2; ++k) \
;         acc[ai][bj][m][n] = __builtin_amdgcn_mfma_f32_16x16x32_bf16(Bt[n][k], At[m][k], acc[ai][bj][m][n], 0, 0, 0); __builtin_amdgcn_s_setprio(0); } while (0)
; #define PG8_WAIT_V(n) asm volatile("s_waitcnt vmcnt(" #n ")" ::: "memory")
; #define PG8_WAIT_L(n) asm volatile("s_waitcnt lgkmcnt(" #n ")" ::: "memory")
; #define PG8_BAR __builtin_amdgcn_s_barrier()
; #define PG8_SCHED __builtin_amdgcn_sched_barrier(0)
; template <class Epi, class Sched, bool ALIGN_EPI = false, bool SP2 = false>
; __device__ __forceinline__ void gemm_phase(PG8_LAS unsigned char* lds, const Gemm g, const Sched& S, const Epi& E) {
;     ...
;             const bool last = (t == nt - 2);
;             const char* a1 = cA + (size_t)(t + 1) * kstep;
;             const char* a2 = last ? nA : cA + (size_t)(t + 2) * kstep; const char* b2 = last ? nB : cB + (size_t)(t + 2) * kstep;
;             const char* a3 = a2 + kstep; const char* b3 = b2 + kstep;
;             if (last && has_next) S.a_ready(nxt);
;             if constexpr (SP2) {
;             PG8_LDB(B0, 0, 0); PG8_LDB(B1, 0, 1); PG8_SCHED; PG8_LDA(At, 0, 0); PG8_STAGE(PG8_SA(1, 1), a1 + hstep, voffA);
;             PG8_WAIT_V(8); PG8_WAIT_L(0); PG8_BAR; PG8_MMA(0, 0, At, B0); PG8_MMA(0, 1, At, B1); PG8_BAR; PG8_SCHED;
;             PG8_LDA(At, 0, 1); PG8_STAGE(PG8_SB(0, 0), b2, voffB); PG8_STAGE(PG8_SB(0, 1), b2 + hstep, voffB); PG8_STAGE(PG8_SA(0, 0), a2, voffA);
.LBB0_947:
	ds_read_b128 v[128:131], v186
	ds_read_b128 v[132:135], v186 offset:1024
	ds_read_b128 v[136:139], v186 offset:2048
	ds_read_b128 v[140:143], v186 offset:3072
	ds_read_b128 v[190:193], v187
	ds_read_b128 v[194:197], v187 offset:1024
	ds_read_b128 v[198:201], v187 offset:2048
	ds_read_b128 v[202:205], v187 offset:3072
	s_add_u32 s2, s62, 0xffe00080
	s_addc_u32 s68, s63, -1
	s_cmpk_eq_i32 s84, 0x7c
	s_cselect_b32 s79, s4, s68
	s_cselect_b32 s78, s55, s2
	s_cselect_b32 s77, s53, s67
	s_cselect_b32 s76, s65, s66
	v_lshl_add_u64 v[172:173], s[62:63], 0, v[164:165]
	s_add_i32 m0, s33, 0xc000
	ds_read_b128 v[206:209], v188
	ds_read_b128 v[210:213], v188 offset:1024
	ds_read_b128 v[214:217], v188 offset:2048
	ds_read_b128 v[218:221], v188 offset:3072
	ds_read_b128 v[222:225], v188 offset:4096
	ds_read_b128 v[226:229], v188 offset:5120
	ds_read_b128 v[230:233], v188 offset:6144
	ds_read_b128 v[234:237], v188 offset:7168
	global_load_lds_dwordx4 v[172:173], off
	v_lshl_add_u64 v[172:173], s[62:63], 0, v[166:167]
	s_add_i32 m0, s33, 0xe000
	s_nop 0
	global_load_lds_dwordx4 v[172:173], off
	s_waitcnt vmcnt(8)
	s_waitcnt lgkmcnt(0)
	s_barrier
	s_waitcnt lgkmcnt(0)
	v_mfma_f32_16x16x32_bf16 v[124:127], v[128:131], v[206:209], v[124:127]
	v_mfma_f32_16x16x32_bf16 v[120:123], v[136:139], v[206:209], v[120:123]
	v_mfma_f32_16x16x32_bf16 v[108:111], v[128:131], v[214:217], v[108:111]
	v_mfma_f32_16x16x32_bf16 v[104:107], v[136:139], v[214:217], v[104:107]
	v_mfma_f32_16x16x32_bf16 v[92:95], v[128:131], v[222:225], v[92:95]
	v_mfma_f32_16x16x32_bf16 v[88:91], v[136:139], v[222:225], v[88:91]
	v_mfma_f32_16x16x32_bf16 v[76:79], v[128:131], v[230:233], v[76:79]
	v_mfma_f32_16x16x32_bf16 v[72:75], v[136:139], v[230:233], v[72:75]
	v_mfma_f32_16x16x32_bf16 v[124:127], v[132:135], v[210:213], v[124:127]
	v_mfma_f32_16x16x32_bf16 v[120:123], v[140:143], v[210:213], v[120:123]
	v_mfma_f32_16x16x32_bf16 v[108:111], v[132:135], v[218:221], v[108:111]
	v_mfma_f32_16x16x32_bf16 v[104:107], v[140:143], v[218:221], v[104:107]
	v_mfma_f32_16x16x32_bf16 v[92:95], v[132:135], v[226:229], v[92:95]
	v_mfma_f32_16x16x32_bf16 v[88:91], v[140:143], v[226:229], v[88:91]
	v_mfma_f32_16x16x32_bf16 v[76:79], v[132:135], v[234:237], v[76:79]
	v_mfma_f32_16x16x32_bf16 v[72:75], v[140:143], v[234:237], v[72:75]
	v_mfma_f32_16x16x32_bf16 v[116:119], v[190:193], v[206:209], v[116:119]
	v_mfma_f32_16x16x32_bf16 v[112:115], v[198:201], v[206:209], v[112:115]
	v_mfma_f32_16x16x32_bf16 v[100:103], v[190:193], v[214:217], v[100:103]
	v_mfma_f32_16x16x32_bf16 v[96:99], v[198:201], v[214:217], v[96:99]
	v_mfma_f32_16x16x32_bf16 v[84:87], v[190:193], v[222:225], v[84:87]
	v_mfma_f32_16x16x32_bf16 v[80:83], v[198:201], v[222:225], v[80:83]
	v_mfma_f32_16x16x32_bf16 v[68:71], v[190:193], v[230:233], v[68:71]
	v_mfma_f32_16x16x32_bf16 v[64:67], v[198:201], v[230:233], v[64:67]
	v_mfma_f32_16x16x32_bf16 v[116:119], v[194:197], v[210:213], v[116:119]
	v_mfma_f32_16x16x32_bf16 v[112:115], v[202:205], v[210:213], v[112:115]
	v_mfma_f32_16x16x32_bf16 v[100:103], v[194:197], v[218:221], v[100:103]
	v_mfma_f32_16x16x32_bf16 v[96:99], v[202:205], v[218:221], v[96:99]
	v_mfma_f32_16x16x32_bf16 v[84:87], v[194:197], v[226:229], v[84:87]
	v_mfma_f32_16x16x32_bf16 v[80:83], v[202:205], v[226:229], v[80:83]
	v_mfma_f32_16x16x32_bf16 v[68:71], v[194:197], v[234:237], v[68:71]
	v_mfma_f32_16x16x32_bf16 v[64:67], v[202:205], v[234:237], v[64:67]
	s_barrier
	s_add_i32 s2, s92, s29
	v_lshl_add_u64 v[172:173], s[76:77], 0, v[144:145]
	s_mov_b32 m0, s2
	ds_read_b128 v[206:209], v188 offset:16384
	ds_read_b128 v[210:213], v188 offset:17408
	ds_read_b128 v[214:217], v188 offset:18432
	ds_read_b128 v[218:221], v188 offset:19456
	ds_read_b128 v[222:225], v188 offset:20480
	ds_read_b128 v[226:229], v188 offset:21504
	ds_read_b128 v[230:233], v188 offset:22528
	ds_read_b128 v[234:237], v188 offset:23552
	global_load_lds_dwordx4 v[172:173], off
	s_add_i32 m0, s2, 0x2000
	s_add_u32 s68, s76, 0x200000
	v_lshl_add_u64 v[238:239], s[76:77], 0, v[146:147]
	s_addc_u32 s69, s77, 0
	s_add_i32 s2, s93, s29
	global_load_lds_dwordx4 v[238:239], off
	v_lshl_add_u64 v[240:241], s[68:69], 0, v[144:145]
	s_mov_b32 m0, s2
	v_lshl_add_u64 v[242:243], s[78:79], 0, v[146:147]
	global_load_lds_dwordx4 v[240:241], off
	v_lshl_add_u64 v[240:241], s[68:69], 0, v[146:147]
	s_add_i32 m0, s2, 0x2000
	s_nop 0
	global_load_lds_dwordx4 v[240:241], off
	v_lshl_add_u64 v[240:241], s[78:79], 0, v[144:145]
	s_mov_b32 m0, s33
	s_nop 0
	global_load_lds_dwordx4 v[240:241], off
	s_mov_b32 m0, s35
	s_nop 0
	global_load_lds_dwordx4 v[242:243], off
	s_waitcnt vmcnt(8)
	s_waitcnt lgkmcnt(0)
	s_barrier
; #define PG8_STAGE(bufoff, gbase, voff) do { _Pragma("unroll") for (int _i = 0; _i < 2; ++_i) \
;         __builtin_amdgcn_global_load_lds((const unsigned*)((const char*)(gbase) + (voff)[_i]), (PG8_LAS unsigned*)(lds + (bufoff) + ldsw + _i * 8192), 16, 0, 0); } while (0)
; #define PG8_LDA(dst, b, h) do { _Pragma("unroll") for (int m = 0; m < 4; ++m) _Pragma("unroll") for (int k = 0; k < 2; ++k) dst[m][k] = *(const PG8_LAS bf16x8*)(lds + PG8_SA(b, h) + aoff + m * 2048 + k * 1024); } while (0)
; #define PG8_LDB(dst, b, h) do { _Pragma("unroll") for (int n = 0; n < 2; ++n) _Pragma("unroll") for (int k = 0; k < 2; ++k) dst[n][k] = *(const PG8_LAS bf16x8*)(lds + PG8_SB(b, h) + boff + n * 2048 + k * 1024); } while (0)
; #define PG8_MMA(ai, bj, At, Bt) do { __builtin_amdgcn_s_setprio(1); _Pragma("unroll") for (int m = 0; m < 4; ++m) _Pragma("unroll") for (int n = 0; n < 2; ++n) _Pragma("unroll") for (int k = 0; k < 2; ++k) \
;         acc[ai][bj][m][n] = __builtin_amdgcn_mfma_f32_16x16x32_bf16(Bt[n][k], At[m][k], acc[ai][bj][m][n], 0, 0, 0); __builtin_amdgcn_s_setprio(0); } while (0)
; #define PG8_WAIT_V(n) asm volatile("s_waitcnt vmcnt(" #n ")" ::: "memory")
; #define PG8_WAIT_L(n) asm volatile("s_waitcnt lgkmcnt(" #n ")" ::: "memory")
; #define PG8_BAR __builtin_amdgcn_s_barrier()
; #define PG8_SCHED __builtin_amdgcn_sched_barrier(0)
; template <class Epi, class Sched, bool ALIGN_EPI = false, bool SP2 = false>
; __device__ __forceinline__ void gemm_phase(PG8_LAS unsigned char* lds, const Gemm g, const Sched& S, const Epi& E) {
;     ...
;             PG8_WAIT_V(8); PG8_WAIT_L(0); PG8_BAR; PG8_MMA(1, 0, At, B0); PG8_MMA(1, 1, At, B1); PG8_BAR; PG8_SCHED;
;             PG8_LDB(B0, 1, 0); PG8_LDB(B1, 1, 1); PG8_SCHED; PG8_LDA(At, 1, 0); PG8_STAGE(PG8_SA(0, 1), a2 + hstep, voffA);
;             PG8_WAIT_V(8); PG8_WAIT_L(0); PG8_BAR; PG8_MMA(0, 0, At, B0); PG8_MMA(0, 1, At, B1); PG8_BAR; PG8_SCHED;
	s_waitcnt lgkmcnt(0)
	v_mfma_f32_16x16x32_bf16 v[60:63], v[128:131], v[206:209], v[60:63]
	v_mfma_f32_16x16x32_bf16 v[56:59], v[136:139], v[206:209], v[56:59]
	v_mfma_f32_16x16x32_bf16 v[44:47], v[128:131], v[214:217], v[44:47]
	v_mfma_f32_16x16x32_bf16 v[40:43], v[136:139], v[214:217], v[40:43]
	v_mfma_f32_16x16x32_bf16 v[28:31], v[128:131], v[222:225], v[28:31]
	v_mfma_f32_16x16x32_bf16 v[24:27], v[136:139], v[222:225], v[24:27]
	v_mfma_f32_16x16x32_bf16 v[12:15], v[128:131], v[230:233], v[12:15]
	v_mfma_f32_16x16x32_bf16 v[8:11], v[136:139], v[230:233], v[8:11]
	v_mfma_f32_16x16x32_bf16 v[60:63], v[132:135], v[210:213], v[60:63]
	v_mfma_f32_16x16x32_bf16 v[56:59], v[140:143], v[210:213], v[56:59]
	v_mfma_f32_16x16x32_bf16 v[44:47], v[132:135], v[218:221], v[44:47]
	v_mfma_f32_16x16x32_bf16 v[40:43], v[140:143], v[218:221], v[40:43]
	v_mfma_f32_16x16x32_bf16 v[28:31], v[132:135], v[226:229], v[28:31]
	v_mfma_f32_16x16x32_bf16 v[24:27], v[140:143], v[226:229], v[24:27]
	v_mfma_f32_16x16x32_bf16 v[12:15], v[132:135], v[234:237], v[12:15]
	v_mfma_f32_16x16x32_bf16 v[8:11], v[140:143], v[234:237], v[8:11]
	v_mfma_f32_16x16x32_bf16 v[52:55], v[190:193], v[206:209], v[52:55]
	v_mfma_f32_16x16x32_bf16 v[48:51], v[198:201], v[206:209], v[48:51]
	v_mfma_f32_16x16x32_bf16 v[36:39], v[190:193], v[214:217], v[36:39]
	v_mfma_f32_16x16x32_bf16 v[32:35], v[198:201], v[214:217], v[32:35]
	v_mfma_f32_16x16x32_bf16 v[20:23], v[190:193], v[222:225], v[20:23]
	v_mfma_f32_16x16x32_bf16 v[16:19], v[198:201], v[222:225], v[16:19]
	v_mfma_f32_16x16x32_bf16 v[4:7], v[190:193], v[230:233], v[4:7]
	v_mfma_f32_16x16x32_bf16 v[0:3], v[198:201], v[230:233], v[0:3]
	v_mfma_f32_16x16x32_bf16 v[52:55], v[194:197], v[210:213], v[52:55]
	v_mfma_f32_16x16x32_bf16 v[48:51], v[202:205], v[210:213], v[48:51]
	v_mfma_f32_16x16x32_bf16 v[36:39], v[194:197], v[218:221], v[36:39]
	v_mfma_f32_16x16x32_bf16 v[32:35], v[202:205], v[218:221], v[32:35]
	v_mfma_f32_16x16x32_bf16 v[20:23], v[194:197], v[226:229], v[20:23]
	v_mfma_f32_16x16x32_bf16 v[16:19], v[202:205], v[226:229], v[16:19]
	v_mfma_f32_16x16x32_bf16 v[4:7], v[194:197], v[234:237], v[4:7]
	v_mfma_f32_16x16x32_bf16 v[0:3], v[202:205], v[234:237], v[0:3]
	s_barrier
	s_add_i32 s2, 0, 0x18000
	s_add_i32 s70, 0, 0x1c000
	v_add_u32_e32 v140, s2, v184
	v_add_u32_e32 v189, s70, v184
	ds_read_b128 v[128:131], v140
	ds_read_b128 v[132:135], v140 offset:1024
	ds_read_b128 v[136:139], v140 offset:2048
	ds_read_b128 v[140:143], v140 offset:3072
	ds_read_b128 v[190:193], v189
	ds_read_b128 v[194:197], v189 offset:1024
	ds_read_b128 v[198:201], v189 offset:2048
	ds_read_b128 v[202:205], v189 offset:3072
	s_add_u32 s68, s78, 0x200000
	s_addc_u32 s69, s79, 0
	s_mov_b32 m0, s61
	v_lshl_add_u64 v[244:245], s[68:69], 0, v[144:145]
	ds_read_b128 v[206:209], v188 offset:32768
	ds_read_b128 v[210:213], v188 offset:33792
	ds_read_b128 v[214:217], v188 offset:34816
	ds_read_b128 v[218:221], v188 offset:35840
	ds_read_b128 v[222:225], v188 offset:36864
	ds_read_b128 v[226:229], v188 offset:37888
	ds_read_b128 v[230:233], v188 offset:38912
	ds_read_b128 v[234:237], v188 offset:39936
	global_load_lds_dwordx4 v[244:245], off
	v_lshl_add_u64 v[244:245], s[68:69], 0, v[146:147]
	s_mov_b32 m0, s81
	s_nop 0
	global_load_lds_dwordx4 v[244:245], off
	s_waitcnt vmcnt(8)
	s_waitcnt lgkmcnt(0)
	s_barrier
	s_waitcnt lgkmcnt(0)
	v_mfma_f32_16x16x32_bf16 v[124:127], v[128:131], v[206:209], v[124:127]
	v_mfma_f32_16x16x32_bf16 v[120:123], v[136:139], v[206:209], v[120:123]
	v_mfma_f32_16x16x32_bf16 v[108:111], v[128:131], v[214:217], v[108:111]
	v_mfma_f32_16x16x32_bf16 v[104:107], v[136:139], v[214:217], v[104:107]
	v_mfma_f32_16x16x32_bf16 v[92:95], v[128:131], v[222:225], v[92:95]
	v_mfma_f32_16x16x32_bf16 v[88:91], v[136:139], v[222:225], v[88:91]
	v_mfma_f32_16x16x32_bf16 v[76:79], v[128:131], v[230:233], v[76:79]
	v_mfma_f32_16x16x32_bf16 v[72:75], v[136:139], v[230:233], v[72:75]
	v_mfma_f32_16x16x32_bf16 v[124:127], v[132:135], v[210:213], v[124:127]
	v_mfma_f32_16x16x32_bf16 v[120:123], v[140:143], v[210:213], v[120:123]
	v_mfma_f32_16x16x32_bf16 v[108:111], v[132:135], v[218:221], v[108:111]
	v_mfma_f32_16x16x32_bf16 v[104:107], v[140:143], v[218:221], v[104:107]
	v_mfma_f32_16x16x32_bf16 v[92:95], v[132:135], v[226:229], v[92:95]
	v_mfma_f32_16x16x32_bf16 v[88:91], v[140:143], v[226:229], v[88:91]
	v_mfma_f32_16x16x32_bf16 v[76:79], v[132:135], v[234:237], v[76:79]
	v_mfma_f32_16x16x32_bf16 v[72:75], v[140:143], v[234:237], v[72:75]
	v_mfma_f32_16x16x32_bf16 v[116:119], v[190:193], v[206:209], v[116:119]
	v_mfma_f32_16x16x32_bf16 v[112:115], v[198:201], v[206:209], v[112:115]
	v_mfma_f32_16x16x32_bf16 v[100:103], v[190:193], v[214:217], v[100:103]
	v_mfma_f32_16x16x32_bf16 v[96:99], v[198:201], v[214:217], v[96:99]
	v_mfma_f32_16x16x32_bf16 v[84:87], v[190:193], v[222:225], v[84:87]
	v_mfma_f32_16x16x32_bf16 v[80:83], v[198:201], v[222:225], v[80:83]
	v_mfma_f32_16x16x32_bf16 v[68:71], v[190:193], v[230:233], v[68:71]
	v_mfma_f32_16x16x32_bf16 v[64:67], v[198:201], v[230:233], v[64:67]
	v_mfma_f32_16x16x32_bf16 v[116:119], v[194:197], v[210:213], v[116:119]
	v_mfma_f32_16x16x32_bf16 v[112:115], v[202:205], v[210:213], v[112:115]
	v_mfma_f32_16x16x32_bf16 v[100:103], v[194:197], v[218:221], v[100:103]
	v_mfma_f32_16x16x32_bf16 v[96:99], v[202:205], v[218:221], v[96:99]
	v_mfma_f32_16x16x32_bf16 v[84:87], v[194:197], v[226:229], v[84:87]
	v_mfma_f32_16x16x32_bf16 v[80:83], v[202:205], v[226:229], v[80:83]
	v_mfma_f32_16x16x32_bf16 v[68:71], v[194:197], v[234:237], v[68:71]
	v_mfma_f32_16x16x32_bf16 v[64:67], v[202:205], v[234:237], v[64:67]
	s_barrier
; #define PG8_STAGE(bufoff, gbase, voff) do { _Pragma("unroll") for (int _i = 0; _i < 2; ++_i) \
;         __builtin_amdgcn_global_load_lds((const unsigned*)((const char*)(gbase) + (voff)[_i]), (PG8_LAS unsigned*)(lds + (bufoff) + ldsw + _i * 8192), 16, 0, 0); } while (0)
; #define PG8_LDA(dst, b, h) do { _Pragma("unroll") for (int m = 0; m < 4; ++m) _Pragma("unroll") for (int k = 0; k < 2; ++k) dst[m][k] = *(const PG8_LAS bf16x8*)(lds + PG8_SA(b, h) + aoff + m * 2048 + k * 1024); } while (0)
; #define PG8_MMA(ai, bj, At, Bt) do { __builtin_amdgcn_s_setprio(1); _Pragma("unroll") for (int m = 0; m < 4; ++m) _Pragma("unroll") for (int n = 0; n < 2; ++n) _Pragma("unroll") for (int k = 0; k < 2; ++k) \
;         acc[ai][bj][m][n] = __builtin_amdgcn_mfma_f32_16x16x32_bf16(Bt[n][k], At[m][k], acc[ai][bj][m][n], 0, 0, 0); __builtin_amdgcn_s_setprio(0); } while (0)
; #define PG8_WAIT_V(n) asm volatile("s_waitcnt vmcnt(" #n ")" ::: "memory")
; #define PG8_WAIT_L(n) asm volatile("s_waitcnt lgkmcnt(" #n ")" ::: "memory")
; #define PG8_BAR __builtin_amdgcn_s_barrier()
; #define PG8_SCHED __builtin_amdgcn_sched_barrier(0)
; template <class Epi, class Sched, bool ALIGN_EPI = false, bool SP2 = false>
; __device__ __forceinline__ void gemm_phase(PG8_LAS unsigned char* lds, const Gemm g, const Sched& S, const Epi& E) {
;     ...
;             PG8_LDA(At, 1, 1); PG8_STAGE(PG8_SB(1, 0), b3, voffB); PG8_STAGE(PG8_SB(1, 1), b3 + hstep, voffB); PG8_STAGE(PG8_SA(1, 0), a3, voffA);
;             PG8_WAIT_V(8); PG8_WAIT_L(0); PG8_BAR; PG8_MMA(1, 0, At, B0); PG8_MMA(1, 1, At, B1); PG8_BAR; PG8_SCHED;
	s_add_i32 s2, s2, s29
	v_lshl_add_u64 v[172:173], v[172:173], 0, s[10:11]
	s_mov_b32 m0, s2
	ds_read_b128 v[206:209], v188 offset:49152
	ds_read_b128 v[210:213], v188 offset:50176
	ds_read_b128 v[214:217], v188 offset:51200
	ds_read_b128 v[218:221], v188 offset:52224
	ds_read_b128 v[222:225], v188 offset:53248
	ds_read_b128 v[226:229], v188 offset:54272
	ds_read_b128 v[230:233], v188 offset:55296
	ds_read_b128 v[234:237], v188 offset:56320
	global_load_lds_dwordx4 v[172:173], off
	s_add_i32 m0, s2, 0x2000
	s_add_u32 s68, s76, 0x200080
	v_lshl_add_u64 v[172:173], v[238:239], 0, s[10:11]
	s_addc_u32 s69, s77, 0
	s_add_i32 s2, s70, s29
	global_load_lds_dwordx4 v[172:173], off
	v_lshl_add_u64 v[172:173], s[68:69], 0, v[144:145]
	s_mov_b32 m0, s2
	s_nop 0
	global_load_lds_dwordx4 v[172:173], off
	v_lshl_add_u64 v[172:173], s[68:69], 0, v[146:147]
	s_add_i32 m0, s2, 0x2000
	s_nop 0
	global_load_lds_dwordx4 v[172:173], off
	v_lshl_add_u64 v[172:173], v[240:241], 0, s[10:11]
	s_mov_b32 m0, s88
	s_nop 0
	global_load_lds_dwordx4 v[172:173], off
	v_lshl_add_u64 v[172:173], v[242:243], 0, s[10:11]
	s_mov_b32 m0, s89
	s_nop 0
	global_load_lds_dwordx4 v[172:173], off
	s_waitcnt vmcnt(8)
	s_waitcnt lgkmcnt(0)
	s_barrier
	s_waitcnt lgkmcnt(0)
	v_mfma_f32_16x16x32_bf16 v[60:63], v[128:131], v[206:209], v[60:63]
	v_mfma_f32_16x16x32_bf16 v[56:59], v[136:139], v[206:209], v[56:59]
	v_mfma_f32_16x16x32_bf16 v[44:47], v[128:131], v[214:217], v[44:47]
	v_mfma_f32_16x16x32_bf16 v[40:43], v[136:139], v[214:217], v[40:43]
	v_mfma_f32_16x16x32_bf16 v[28:31], v[128:131], v[222:225], v[28:31]
	v_mfma_f32_16x16x32_bf16 v[24:27], v[136:139], v[222:225], v[24:27]
	v_mfma_f32_16x16x32_bf16 v[12:15], v[128:131], v[230:233], v[12:15]
	v_mfma_f32_16x16x32_bf16 v[8:11], v[136:139], v[230:233], v[8:11]
	v_mfma_f32_16x16x32_bf16 v[60:63], v[132:135], v[210:213], v[60:63]
	v_mfma_f32_16x16x32_bf16 v[56:59], v[140:143], v[210:213], v[56:59]
	v_mfma_f32_16x16x32_bf16 v[44:47], v[132:135], v[218:221], v[44:47]
	v_mfma_f32_16x16x32_bf16 v[40:43], v[140:143], v[218:221], v[40:43]
	v_mfma_f32_16x16x32_bf16 v[28:31], v[132:135], v[226:229], v[28:31]
	v_mfma_f32_16x16x32_bf16 v[24:27], v[140:143], v[226:229], v[24:27]
	v_mfma_f32_16x16x32_bf16 v[12:15], v[132:135], v[234:237], v[12:15]
	v_mfma_f32_16x16x32_bf16 v[8:11], v[140:143], v[234:237], v[8:11]
	v_mfma_f32_16x16x32_bf16 v[52:55], v[190:193], v[206:209], v[52:55]
	v_mfma_f32_16x16x32_bf16 v[48:51], v[198:201], v[206:209], v[48:51]
	v_mfma_f32_16x16x32_bf16 v[36:39], v[190:193], v[214:217], v[36:39]
	v_mfma_f32_16x16x32_bf16 v[32:35], v[198:201], v[214:217], v[32:35]
	v_mfma_f32_16x16x32_bf16 v[20:23], v[190:193], v[222:225], v[20:23]
	v_mfma_f32_16x16x32_bf16 v[16:19], v[198:201], v[222:225], v[16:19]
	v_mfma_f32_16x16x32_bf16 v[4:7], v[190:193], v[230:233], v[4:7]
	v_mfma_f32_16x16x32_bf16 v[0:3], v[198:201], v[230:233], v[0:3]
	v_mfma_f32_16x16x32_bf16 v[52:55], v[194:197], v[210:213], v[52:55]
	v_mfma_f32_16x16x32_bf16 v[48:51], v[202:205], v[210:213], v[48:51]
	v_mfma_f32_16x16x32_bf16 v[36:39], v[194:197], v[218:221], v[36:39]
	v_mfma_f32_16x16x32_bf16 v[32:35], v[202:205], v[218:221], v[32:35]
	v_mfma_f32_16x16x32_bf16 v[20:23], v[194:197], v[226:229], v[20:23]
	v_mfma_f32_16x16x32_bf16 v[16:19], v[202:205], v[226:229], v[16:19]
	v_mfma_f32_16x16x32_bf16 v[4:7], v[194:197], v[234:237], v[4:7]
	v_mfma_f32_16x16x32_bf16 v[0:3], v[202:205], v[234:237], v[0:3]
	s_barrier
	s_add_i32 s84, s84, 2
	s_add_u32 s62, s62, 0x100
	s_addc_u32 s63, s63, 0
	s_add_u32 s66, s66, 0x100
	s_addc_u32 s67, s67, 0
	s_cmpk_gt_u32 s84, 0x7d
	s_cbranch_scc0 .LBB0_947
	s_and_b64 vcc, exec, s[30:31]
	s_cbranch_vccz .LBB0_950
	s_barrier

; #define PG8_STAGE(bufoff, gbase, voff) do { _Pragma("unroll") for (int _i = 0; _i < 2; ++_i) \
;         __builtin_amdgcn_global_load_lds((const unsigned*)((const char*)(gbase) + (voff)[_i]), (PG8_LAS unsigned*)(lds + (bufoff) + ldsw + _i * 8192), 16, 0, 0); } while (0)
; #define PG8_LDA(dst, b, h) do { _Pragma("unroll") for (int m = 0; m < 4; ++m) _Pragma("unroll") for (int k = 0; k < 2; ++k) dst[m][k] = *(const PG8_LAS bf16x8*)(lds + PG8_SA(b, h) + aoff + m * 2048 + k * 1024); } while (0)
; #define PG8_LDB(dst, b, h) do { _Pragma("unroll") for (int n = 0; n < 2; ++n) _Pragma("unroll") for (int k = 0; k < 2; ++k) dst[n][k] = *(const PG8_LAS bf16x8*)(lds + PG8_SB(b, h) + boff + n * 2048 + k * 1024); } while (0)
; #define PG8_MMA(ai, bj, At, Bt) do { __builtin_amdgcn_s_setprio(1); _Pragma("unroll") for (int m = 0; m < 4; ++m) _Pragma("unroll") for (int n = 0; n < 2; ++n) _Pragma("unroll") for (int k = 0; k < 2; ++k) \
;         acc[ai][bj][m][n] = __builtin_amdgcn_mfma_f32_16x16x32_bf16(Bt[n][k], At[m][k], acc[ai][bj][m][n], 0, 0, 0); __builtin_amdgcn_s_setprio(0); } while (0)
; #define PG8_WAIT_V(n) asm volatile("s_waitcnt vmcnt(" #n ")" ::: "memory")
; #define PG8_WAIT_L(n) asm volatile("s_waitcnt lgkmcnt(" #n ")" ::: "memory")
; #define PG8_BAR __builtin_amdgcn_s_barrier()
; #define PG8_SCHED __builtin_amdgcn_sched_barrier(0)
; template <class Epi, class Sched, bool ALIGN_EPI = false, bool SP2 = false>
; __device__ __forceinline__ void gemm_phase(PG8_LAS unsigned char* lds, const Gemm g, const Sched& S, const Epi& E) {
;     ...
;             const bool last = (t == nt - 2);
;             const char* a1 = cA + (size_t)(t + 1) * kstep;
;             const char* a2 = last ? nA : cA + (size_t)(t + 2) * kstep; const char* b2 = last ? nB : cB + (size_t)(t + 2) * kstep;
;             const char* a3 = a2 + kstep; const char* b3 = b2 + kstep;
;             if (last && has_next) S.a_ready(nxt);
;             if constexpr (SP2) {
;             PG8_LDB(B0, 0, 0); PG8_LDB(B1, 0, 1); PG8_SCHED; PG8_LDA(At, 0, 0); PG8_STAGE(PG8_SA(1, 1), a1 + hstep, voffA);
;             PG8_WAIT_V(8); PG8_WAIT_L(0); PG8_BAR; PG8_MMA(0, 0, At, B0); PG8_MMA(0, 1, At, B1); PG8_BAR; PG8_SCHED;
;             PG8_LDA(At, 0, 1); PG8_STAGE(PG8_SB(0, 0), b2, voffB); PG8_STAGE(PG8_SB(0, 1), b2 + hstep, voffB); PG8_STAGE(PG8_SA(0, 0), a2, voffA);
.LBB0_967:
	ds_read_b128 v[128:131], v158
	ds_read_b128 v[162:165], v158 offset:1024
	ds_read_b128 v[166:169], v158 offset:2048
	ds_read_b128 v[170:173], v158 offset:3072
	ds_read_b128 v[176:179], v159
	ds_read_b128 v[180:183], v159 offset:1024
	ds_read_b128 v[184:187], v159 offset:2048
	ds_read_b128 v[188:191], v159 offset:3072
	s_add_u32 s2, s86, 0xffe00080
	s_addc_u32 s68, s87, -1
	s_cmp_eq_u32 s90, 4
	s_cselect_b32 s79, s31, s68
	s_cselect_b32 s78, s35, s2
	s_cselect_b32 s77, s53, s89
	s_cselect_b32 s76, s59, s88
	v_lshl_add_u64 v[224:225], s[86:87], 0, v[152:153]
	s_add_i32 m0, s29, 0xc000
	ds_read_b128 v[192:195], v160
	ds_read_b128 v[196:199], v160 offset:1024
	ds_read_b128 v[200:203], v160 offset:2048
	ds_read_b128 v[204:207], v160 offset:3072
	ds_read_b128 v[208:211], v160 offset:4096
	ds_read_b128 v[212:215], v160 offset:5120
	ds_read_b128 v[216:219], v160 offset:6144
	ds_read_b128 v[220:223], v160 offset:7168
	global_load_lds_dwordx4 v[224:225], off
	v_lshl_add_u64 v[224:225], s[86:87], 0, v[154:155]
	s_add_i32 m0, s29, 0xe000
	s_nop 0
	global_load_lds_dwordx4 v[224:225], off
	s_waitcnt vmcnt(8)
	s_waitcnt lgkmcnt(0)
	s_barrier
	s_waitcnt lgkmcnt(0)
	v_mfma_f32_16x16x32_bf16 v[124:127], v[128:131], v[192:195], v[124:127]
	v_mfma_f32_16x16x32_bf16 v[116:119], v[166:169], v[192:195], v[116:119]
	v_mfma_f32_16x16x32_bf16 v[120:123], v[128:131], v[200:203], v[120:123]
	v_mfma_f32_16x16x32_bf16 v[108:111], v[166:169], v[200:203], v[108:111]
	v_mfma_f32_16x16x32_bf16 v[112:115], v[128:131], v[208:211], v[112:115]
	v_mfma_f32_16x16x32_bf16 v[100:103], v[166:169], v[208:211], v[100:103]
	v_mfma_f32_16x16x32_bf16 v[104:107], v[128:131], v[216:219], v[104:107]
	v_mfma_f32_16x16x32_bf16 v[96:99], v[166:169], v[216:219], v[96:99]
	v_mfma_f32_16x16x32_bf16 v[124:127], v[162:165], v[196:199], v[124:127]
	v_mfma_f32_16x16x32_bf16 v[116:119], v[170:173], v[196:199], v[116:119]
	v_mfma_f32_16x16x32_bf16 v[120:123], v[162:165], v[204:207], v[120:123]
	v_mfma_f32_16x16x32_bf16 v[108:111], v[170:173], v[204:207], v[108:111]
	v_mfma_f32_16x16x32_bf16 v[112:115], v[162:165], v[212:215], v[112:115]
	v_mfma_f32_16x16x32_bf16 v[100:103], v[170:173], v[212:215], v[100:103]
	v_mfma_f32_16x16x32_bf16 v[104:107], v[162:165], v[220:223], v[104:107]
	v_mfma_f32_16x16x32_bf16 v[96:99], v[170:173], v[220:223], v[96:99]
	v_mfma_f32_16x16x32_bf16 v[92:95], v[176:179], v[192:195], v[92:95]
	v_mfma_f32_16x16x32_bf16 v[52:55], v[184:187], v[192:195], v[52:55]
	v_mfma_f32_16x16x32_bf16 v[84:87], v[176:179], v[200:203], v[84:87]
	v_mfma_f32_16x16x32_bf16 v[40:43], v[184:187], v[200:203], v[40:43]
	v_mfma_f32_16x16x32_bf16 v[76:79], v[176:179], v[208:211], v[76:79]
	v_mfma_f32_16x16x32_bf16 v[36:39], v[184:187], v[208:211], v[36:39]
	v_mfma_f32_16x16x32_bf16 v[64:67], v[176:179], v[216:219], v[64:67]
	v_mfma_f32_16x16x32_bf16 v[28:31], v[184:187], v[216:219], v[28:31]
	v_mfma_f32_16x16x32_bf16 v[92:95], v[180:183], v[196:199], v[92:95]
	v_mfma_f32_16x16x32_bf16 v[52:55], v[188:191], v[196:199], v[52:55]
	v_mfma_f32_16x16x32_bf16 v[84:87], v[180:183], v[204:207], v[84:87]
	v_mfma_f32_16x16x32_bf16 v[40:43], v[188:191], v[204:207], v[40:43]
	v_mfma_f32_16x16x32_bf16 v[76:79], v[180:183], v[212:215], v[76:79]
	v_mfma_f32_16x16x32_bf16 v[36:39], v[188:191], v[212:215], v[36:39]
	v_mfma_f32_16x16x32_bf16 v[64:67], v[180:183], v[220:223], v[64:67]
	v_mfma_f32_16x16x32_bf16 v[28:31], v[188:191], v[220:223], v[28:31]
	s_barrier
	s_add_i32 s2, s83, s28
	v_lshl_add_u64 v[224:225], s[76:77], 0, v[144:145]
	s_mov_b32 m0, s2
	ds_read_b128 v[192:195], v160 offset:16384
	ds_read_b128 v[196:199], v160 offset:17408
	ds_read_b128 v[200:203], v160 offset:18432
	ds_read_b128 v[204:207], v160 offset:19456
	ds_read_b128 v[208:211], v160 offset:20480
	ds_read_b128 v[212:215], v160 offset:21504
	ds_read_b128 v[216:219], v160 offset:22528
	ds_read_b128 v[220:223], v160 offset:23552
	global_load_lds_dwordx4 v[224:225], off
	s_add_i32 m0, s2, 0x2000
	s_add_u32 s68, s76, 0x200000
	v_lshl_add_u64 v[226:227], s[76:77], 0, v[146:147]
	s_addc_u32 s69, s77, 0
	s_add_i32 s2, s85, s28
	global_load_lds_dwordx4 v[226:227], off
	v_lshl_add_u64 v[228:229], s[68:69], 0, v[144:145]
	s_mov_b32 m0, s2
	v_lshl_add_u64 v[230:231], s[78:79], 0, v[146:147]
	global_load_lds_dwordx4 v[228:229], off
	v_lshl_add_u64 v[228:229], s[68:69], 0, v[146:147]
	s_add_i32 m0, s2, 0x2000
	s_nop 0
	global_load_lds_dwordx4 v[228:229], off
	v_lshl_add_u64 v[228:229], s[78:79], 0, v[144:145]
	s_mov_b32 m0, s29
	s_nop 0
	global_load_lds_dwordx4 v[228:229], off
	s_mov_b32 m0, s33
	s_nop 0
	global_load_lds_dwordx4 v[230:231], off
	s_waitcnt vmcnt(8)
	s_waitcnt lgkmcnt(0)
	s_barrier
; #define PG8_STAGE(bufoff, gbase, voff) do { _Pragma("unroll") for (int _i = 0; _i < 2; ++_i) \
;         __builtin_amdgcn_global_load_lds((const unsigned*)((const char*)(gbase) + (voff)[_i]), (PG8_LAS unsigned*)(lds + (bufoff) + ldsw + _i * 8192), 16, 0, 0); } while (0)
; #define PG8_LDA(dst, b, h) do { _Pragma("unroll") for (int m = 0; m < 4; ++m) _Pragma("unroll") for (int k = 0; k < 2; ++k) dst[m][k] = *(const PG8_LAS bf16x8*)(lds + PG8_SA(b, h) + aoff + m * 2048 + k * 1024); } while (0)
; #define PG8_LDB(dst, b, h) do { _Pragma("unroll") for (int n = 0; n < 2; ++n) _Pragma("unroll") for (int k = 0; k < 2; ++k) dst[n][k] = *(const PG8_LAS bf16x8*)(lds + PG8_SB(b, h) + boff + n * 2048 + k * 1024); } while (0)
; #define PG8_MMA(ai, bj, At, Bt) do { __builtin_amdgcn_s_setprio(1); _Pragma("unroll") for (int m = 0; m < 4; ++m) _Pragma("unroll") for (int n = 0; n < 2; ++n) _Pragma("unroll") for (int k = 0; k < 2; ++k) \
;         acc[ai][bj][m][n] = __builtin_amdgcn_mfma_f32_16x16x32_bf16(Bt[n][k], At[m][k], acc[ai][bj][m][n], 0, 0, 0); __builtin_amdgcn_s_setprio(0); } while (0)
; #define PG8_WAIT_V(n) asm volatile("s_waitcnt vmcnt(" #n ")" ::: "memory")
; #define PG8_WAIT_L(n) asm volatile("s_waitcnt lgkmcnt(" #n ")" ::: "memory")
; #define PG8_BAR __builtin_amdgcn_s_barrier()
; #define PG8_SCHED __builtin_amdgcn_sched_barrier(0)
; template <class Epi, class Sched, bool ALIGN_EPI = false, bool SP2 = false>
; __device__ __forceinline__ void gemm_phase(PG8_LAS unsigned char* lds, const Gemm g, const Sched& S, const Epi& E) {
;     ...
;             PG8_WAIT_V(8); PG8_WAIT_L(0); PG8_BAR; PG8_MMA(1, 0, At, B0); PG8_MMA(1, 1, At, B1); PG8_BAR; PG8_SCHED;
;             PG8_LDB(B0, 1, 0); PG8_LDB(B1, 1, 1); PG8_SCHED; PG8_LDA(At, 1, 0); PG8_STAGE(PG8_SA(0, 1), a2 + hstep, voffA);
;             PG8_WAIT_V(8); PG8_WAIT_L(0); PG8_BAR; PG8_MMA(0, 0, At, B0); PG8_MMA(0, 1, At, B1); PG8_BAR; PG8_SCHED;
	s_waitcnt lgkmcnt(0)
	v_mfma_f32_16x16x32_bf16 v[88:91], v[128:131], v[192:195], v[88:91]
	v_mfma_f32_16x16x32_bf16 v[72:75], v[166:169], v[192:195], v[72:75]
	v_mfma_f32_16x16x32_bf16 v[80:83], v[128:131], v[200:203], v[80:83]
	v_mfma_f32_16x16x32_bf16 v[60:63], v[166:169], v[200:203], v[60:63]
	v_mfma_f32_16x16x32_bf16 v[68:71], v[128:131], v[208:211], v[68:71]
	v_mfma_f32_16x16x32_bf16 v[48:51], v[166:169], v[208:211], v[48:51]
	v_mfma_f32_16x16x32_bf16 v[56:59], v[128:131], v[216:219], v[56:59]
	v_mfma_f32_16x16x32_bf16 v[44:47], v[166:169], v[216:219], v[44:47]
	v_mfma_f32_16x16x32_bf16 v[88:91], v[162:165], v[196:199], v[88:91]
	v_mfma_f32_16x16x32_bf16 v[72:75], v[170:173], v[196:199], v[72:75]
	v_mfma_f32_16x16x32_bf16 v[80:83], v[162:165], v[204:207], v[80:83]
	v_mfma_f32_16x16x32_bf16 v[60:63], v[170:173], v[204:207], v[60:63]
	v_mfma_f32_16x16x32_bf16 v[68:71], v[162:165], v[212:215], v[68:71]
	v_mfma_f32_16x16x32_bf16 v[48:51], v[170:173], v[212:215], v[48:51]
	v_mfma_f32_16x16x32_bf16 v[56:59], v[162:165], v[220:223], v[56:59]
	v_mfma_f32_16x16x32_bf16 v[44:47], v[170:173], v[220:223], v[44:47]
	v_mfma_f32_16x16x32_bf16 v[32:35], v[176:179], v[192:195], v[32:35]
	v_mfma_f32_16x16x32_bf16 v[12:15], v[184:187], v[192:195], v[12:15]
	v_mfma_f32_16x16x32_bf16 v[24:27], v[176:179], v[200:203], v[24:27]
	v_mfma_f32_16x16x32_bf16 v[8:11], v[184:187], v[200:203], v[8:11]
	v_mfma_f32_16x16x32_bf16 v[20:23], v[176:179], v[208:211], v[20:23]
	v_mfma_f32_16x16x32_bf16 v[4:7], v[184:187], v[208:211], v[4:7]
	v_mfma_f32_16x16x32_bf16 v[16:19], v[176:179], v[216:219], v[16:19]
	v_mfma_f32_16x16x32_bf16 v[0:3], v[184:187], v[216:219], v[0:3]
	v_mfma_f32_16x16x32_bf16 v[32:35], v[180:183], v[196:199], v[32:35]
	v_mfma_f32_16x16x32_bf16 v[12:15], v[188:191], v[196:199], v[12:15]
	v_mfma_f32_16x16x32_bf16 v[24:27], v[180:183], v[204:207], v[24:27]
	v_mfma_f32_16x16x32_bf16 v[8:11], v[188:191], v[204:207], v[8:11]
	v_mfma_f32_16x16x32_bf16 v[20:23], v[180:183], v[212:215], v[20:23]
	v_mfma_f32_16x16x32_bf16 v[4:7], v[188:191], v[212:215], v[4:7]
	v_mfma_f32_16x16x32_bf16 v[16:19], v[180:183], v[220:223], v[16:19]
	v_mfma_f32_16x16x32_bf16 v[0:3], v[188:191], v[220:223], v[0:3]
	s_barrier
	s_add_i32 s2, 0, 0x18000
	v_add_u32_e32 v161, s2, v156
	s_add_i32 s70, 0, 0x1c000
	ds_read_b128 v[128:131], v161
	ds_read_b128 v[162:165], v161 offset:1024
	ds_read_b128 v[166:169], v161 offset:2048
	ds_read_b128 v[170:173], v161 offset:3072
	v_add_u32_e32 v161, s70, v156
	ds_read_b128 v[176:179], v161
	ds_read_b128 v[180:183], v161 offset:1024
	ds_read_b128 v[184:187], v161 offset:2048
	ds_read_b128 v[188:191], v161 offset:3072
	s_add_u32 s68, s78, 0x200000
	s_addc_u32 s69, s79, 0
	s_mov_b32 m0, s61
	v_lshl_add_u64 v[232:233], s[68:69], 0, v[144:145]
	ds_read_b128 v[192:195], v160 offset:32768
	ds_read_b128 v[196:199], v160 offset:33792
	ds_read_b128 v[200:203], v160 offset:34816
	ds_read_b128 v[204:207], v160 offset:35840
	ds_read_b128 v[208:211], v160 offset:36864
	ds_read_b128 v[212:215], v160 offset:37888
	ds_read_b128 v[216:219], v160 offset:38912
	ds_read_b128 v[220:223], v160 offset:39936
	global_load_lds_dwordx4 v[232:233], off
	v_lshl_add_u64 v[232:233], s[68:69], 0, v[146:147]
	s_mov_b32 m0, s64
	s_nop 0
	global_load_lds_dwordx4 v[232:233], off
	s_waitcnt vmcnt(8)
	s_waitcnt lgkmcnt(0)
	s_barrier
	s_waitcnt lgkmcnt(0)
	v_mfma_f32_16x16x32_bf16 v[124:127], v[128:131], v[192:195], v[124:127]
	v_mfma_f32_16x16x32_bf16 v[116:119], v[166:169], v[192:195], v[116:119]
	v_mfma_f32_16x16x32_bf16 v[120:123], v[128:131], v[200:203], v[120:123]
	v_mfma_f32_16x16x32_bf16 v[108:111], v[166:169], v[200:203], v[108:111]
	v_mfma_f32_16x16x32_bf16 v[112:115], v[128:131], v[208:211], v[112:115]
	v_mfma_f32_16x16x32_bf16 v[100:103], v[166:169], v[208:211], v[100:103]
	v_mfma_f32_16x16x32_bf16 v[104:107], v[128:131], v[216:219], v[104:107]
	v_mfma_f32_16x16x32_bf16 v[96:99], v[166:169], v[216:219], v[96:99]
	v_mfma_f32_16x16x32_bf16 v[124:127], v[162:165], v[196:199], v[124:127]
	v_mfma_f32_16x16x32_bf16 v[116:119], v[170:173], v[196:199], v[116:119]
	v_mfma_f32_16x16x32_bf16 v[120:123], v[162:165], v[204:207], v[120:123]
	v_mfma_f32_16x16x32_bf16 v[108:111], v[170:173], v[204:207], v[108:111]
	v_mfma_f32_16x16x32_bf16 v[112:115], v[162:165], v[212:215], v[112:115]
	v_mfma_f32_16x16x32_bf16 v[100:103], v[170:173], v[212:215], v[100:103]
	v_mfma_f32_16x16x32_bf16 v[104:107], v[162:165], v[220:223], v[104:107]
	v_mfma_f32_16x16x32_bf16 v[96:99], v[170:173], v[220:223], v[96:99]
	v_mfma_f32_16x16x32_bf16 v[92:95], v[176:179], v[192:195], v[92:95]
	v_mfma_f32_16x16x32_bf16 v[52:55], v[184:187], v[192:195], v[52:55]
	v_mfma_f32_16x16x32_bf16 v[84:87], v[176:179], v[200:203], v[84:87]
	v_mfma_f32_16x16x32_bf16 v[40:43], v[184:187], v[200:203], v[40:43]
	v_mfma_f32_16x16x32_bf16 v[76:79], v[176:179], v[208:211], v[76:79]
	v_mfma_f32_16x16x32_bf16 v[36:39], v[184:187], v[208:211], v[36:39]
	v_mfma_f32_16x16x32_bf16 v[64:67], v[176:179], v[216:219], v[64:67]
	v_mfma_f32_16x16x32_bf16 v[28:31], v[184:187], v[216:219], v[28:31]
	v_mfma_f32_16x16x32_bf16 v[92:95], v[180:183], v[196:199], v[92:95]
	v_mfma_f32_16x16x32_bf16 v[52:55], v[188:191], v[196:199], v[52:55]
	v_mfma_f32_16x16x32_bf16 v[84:87], v[180:183], v[204:207], v[84:87]
	v_mfma_f32_16x16x32_bf16 v[40:43], v[188:191], v[204:207], v[40:43]
	v_mfma_f32_16x16x32_bf16 v[76:79], v[180:183], v[212:215], v[76:79]
	v_mfma_f32_16x16x32_bf16 v[36:39], v[188:191], v[212:215], v[36:39]
	v_mfma_f32_16x16x32_bf16 v[64:67], v[180:183], v[220:223], v[64:67]
	v_mfma_f32_16x16x32_bf16 v[28:31], v[188:191], v[220:223], v[28:31]
	s_barrier
; #define PG8_STAGE(bufoff, gbase, voff) do { _Pragma("unroll") for (int _i = 0; _i < 2; ++_i) \
;         __builtin_amdgcn_global_load_lds((const unsigned*)((const char*)(gbase) + (voff)[_i]), (PG8_LAS unsigned*)(lds + (bufoff) + ldsw + _i * 8192), 16, 0, 0); } while (0)
; #define PG8_LDA(dst, b, h) do { _Pragma("unroll") for (int m = 0; m < 4; ++m) _Pragma("unroll") for (int k = 0; k < 2; ++k) dst[m][k] = *(const PG8_LAS bf16x8*)(lds + PG8_SA(b, h) + aoff + m * 2048 + k * 1024); } while (0)
; #define PG8_MMA(ai, bj, At, Bt) do { __builtin_amdgcn_s_setprio(1); _Pragma("unroll") for (int m = 0; m < 4; ++m) _Pragma("unroll") for (int n = 0; n < 2; ++n) _Pragma("unroll") for (int k = 0; k < 2; ++k) \
;         acc[ai][bj][m][n] = __builtin_amdgcn_mfma_f32_16x16x32_bf16(Bt[n][k], At[m][k], acc[ai][bj][m][n], 0, 0, 0); __builtin_amdgcn_s_setprio(0); } while (0)
; #define PG8_WAIT_V(n) asm volatile("s_waitcnt vmcnt(" #n ")" ::: "memory")
; #define PG8_WAIT_L(n) asm volatile("s_waitcnt lgkmcnt(" #n ")" ::: "memory")
; #define PG8_BAR __builtin_amdgcn_s_barrier()
; #define PG8_SCHED __builtin_amdgcn_sched_barrier(0)
; template <class Epi, class Sched, bool ALIGN_EPI = false, bool SP2 = false>
; __device__ __forceinline__ void gemm_phase(PG8_LAS unsigned char* lds, const Gemm g, const Sched& S, const Epi& E) {
;     ...
;             PG8_LDA(At, 1, 1); PG8_STAGE(PG8_SB(1, 0), b3, voffB); PG8_STAGE(PG8_SB(1, 1), b3 + hstep, voffB); PG8_STAGE(PG8_SA(1, 0), a3, voffA);
;             PG8_WAIT_V(8); PG8_WAIT_L(0); PG8_BAR; PG8_MMA(1, 0, At, B0); PG8_MMA(1, 1, At, B1); PG8_BAR; PG8_SCHED;
	s_add_i32 s2, s2, s28
	v_lshl_add_u64 v[224:225], v[224:225], 0, s[8:9]
	s_mov_b32 m0, s2
	ds_read_b128 v[192:195], v160 offset:49152
	ds_read_b128 v[196:199], v160 offset:50176
	ds_read_b128 v[200:203], v160 offset:51200
	ds_read_b128 v[204:207], v160 offset:52224
	ds_read_b128 v[208:211], v160 offset:53248
	ds_read_b128 v[212:215], v160 offset:54272
	ds_read_b128 v[216:219], v160 offset:55296
	ds_read_b128 v[220:223], v160 offset:56320
	global_load_lds_dwordx4 v[224:225], off
	s_add_i32 m0, s2, 0x2000
	s_add_u32 s68, s76, 0x200080
	v_lshl_add_u64 v[224:225], v[226:227], 0, s[8:9]
	s_addc_u32 s69, s77, 0
	s_add_i32 s2, s70, s28
	global_load_lds_dwordx4 v[224:225], off
	v_lshl_add_u64 v[224:225], s[68:69], 0, v[144:145]
	s_mov_b32 m0, s2
	s_nop 0
	global_load_lds_dwordx4 v[224:225], off
	v_lshl_add_u64 v[224:225], s[68:69], 0, v[146:147]
	s_add_i32 m0, s2, 0x2000
	s_nop 0
	global_load_lds_dwordx4 v[224:225], off
	v_lshl_add_u64 v[224:225], v[228:229], 0, s[8:9]
	s_mov_b32 m0, s81
	s_nop 0
	global_load_lds_dwordx4 v[224:225], off
	v_lshl_add_u64 v[224:225], v[230:231], 0, s[8:9]
	s_mov_b32 m0, s82
	s_nop 0
	global_load_lds_dwordx4 v[224:225], off
	s_waitcnt vmcnt(8)
	s_waitcnt lgkmcnt(0)
	s_barrier
	s_waitcnt lgkmcnt(0)
	v_mfma_f32_16x16x32_bf16 v[88:91], v[128:131], v[192:195], v[88:91]
	v_mfma_f32_16x16x32_bf16 v[72:75], v[166:169], v[192:195], v[72:75]
	v_mfma_f32_16x16x32_bf16 v[80:83], v[128:131], v[200:203], v[80:83]
	v_mfma_f32_16x16x32_bf16 v[60:63], v[166:169], v[200:203], v[60:63]
	v_mfma_f32_16x16x32_bf16 v[68:71], v[128:131], v[208:211], v[68:71]
	v_mfma_f32_16x16x32_bf16 v[48:51], v[166:169], v[208:211], v[48:51]
	v_mfma_f32_16x16x32_bf16 v[56:59], v[128:131], v[216:219], v[56:59]
	v_mfma_f32_16x16x32_bf16 v[44:47], v[166:169], v[216:219], v[44:47]
	v_mfma_f32_16x16x32_bf16 v[88:91], v[162:165], v[196:199], v[88:91]
	v_mfma_f32_16x16x32_bf16 v[72:75], v[170:173], v[196:199], v[72:75]
	v_mfma_f32_16x16x32_bf16 v[80:83], v[162:165], v[204:207], v[80:83]
	v_mfma_f32_16x16x32_bf16 v[60:63], v[170:173], v[204:207], v[60:63]
	v_mfma_f32_16x16x32_bf16 v[68:71], v[162:165], v[212:215], v[68:71]
	v_mfma_f32_16x16x32_bf16 v[48:51], v[170:173], v[212:215], v[48:51]
	v_mfma_f32_16x16x32_bf16 v[56:59], v[162:165], v[220:223], v[56:59]
	v_mfma_f32_16x16x32_bf16 v[44:47], v[170:173], v[220:223], v[44:47]
	v_mfma_f32_16x16x32_bf16 v[32:35], v[176:179], v[192:195], v[32:35]
	v_mfma_f32_16x16x32_bf16 v[12:15], v[184:187], v[192:195], v[12:15]
	v_mfma_f32_16x16x32_bf16 v[24:27], v[176:179], v[200:203], v[24:27]
	v_mfma_f32_16x16x32_bf16 v[8:11], v[184:187], v[200:203], v[8:11]
	v_mfma_f32_16x16x32_bf16 v[20:23], v[176:179], v[208:211], v[20:23]
	v_mfma_f32_16x16x32_bf16 v[4:7], v[184:187], v[208:211], v[4:7]
	v_mfma_f32_16x16x32_bf16 v[16:19], v[176:179], v[216:219], v[16:19]
	v_mfma_f32_16x16x32_bf16 v[0:3], v[184:187], v[216:219], v[0:3]
	v_mfma_f32_16x16x32_bf16 v[32:35], v[180:183], v[196:199], v[32:35]
	v_mfma_f32_16x16x32_bf16 v[12:15], v[188:191], v[196:199], v[12:15]
	v_mfma_f32_16x16x32_bf16 v[24:27], v[180:183], v[204:207], v[24:27]
	v_mfma_f32_16x16x32_bf16 v[8:11], v[188:191], v[204:207], v[8:11]
	v_mfma_f32_16x16x32_bf16 v[20:23], v[180:183], v[212:215], v[20:23]
	v_mfma_f32_16x16x32_bf16 v[4:7], v[188:191], v[212:215], v[4:7]
	v_mfma_f32_16x16x32_bf16 v[16:19], v[180:183], v[220:223], v[16:19]
	v_mfma_f32_16x16x32_bf16 v[0:3], v[188:191], v[220:223], v[0:3]
	s_barrier
	s_add_i32 s90, s90, 2
	s_add_u32 s86, s86, 0x100
	s_addc_u32 s87, s87, 0
	s_add_u32 s88, s88, 0x100
	s_addc_u32 s89, s89, 0
	s_cmp_gt_u32 s90, 5
	s_cbranch_scc0 .LBB0_967
	s_and_b64 vcc, exec, s[10:11]
	s_cbranch_vccz .LBB0_970
	s_barrier

;     f32x4 nv[8];
;     if (gw < nrows) { const float* s0_ = (gw < ML) ? srcL + (size_t)gw * D : srcC + (size_t)(gw - ML) * D;
; #pragma unroll
;         for (int j = 0; j < 8; ++j) nv[j] = *(const f32x4*)(s0_ + lane * 4 + 256 * j); }
;     for (int m = gw; m < nrows; m += NGW) {
;         float* dst; int mv;
;         if (m < ML) { dst = dstL + (size_t)m * D; mv = (m >= SEQ) ? 1 : 0; }
;         else { dst = dstC + (size_t)(m - ML) * D; mv = 2; }
;         f32x4 v[8];
; #pragma unroll
;         for (int j = 0; j < 8; ++j) v[j] = nv[j];
;         { const int mn = m + NGW;
;           if (mn < nrows) { const float* s1_ = (mn < ML) ? srcL + (size_t)mn * D : srcC + (size_t)(mn - ML) * D;
; #pragma unroll
;               for (int j = 0; j < 8; ++j) nv[j] = *(const f32x4*)(s1_ + lane * 4 + 256 * j); } }
;         if (nslab > 0 && m >= ML) {
; #pragma unroll
;             for (int j = 0; j < 8; ++j) v[j] = v[j] * ALPHA;
;             for (int sidx = 0; sidx < nslab; ++sidx) { const float* sp = slab + ((size_t)sidx * (2 * CTXL) + (m - ML)) * D + lane * 4;
; #pragma unroll
;                 for (int j = 0; j < 8; ++j) v[j] += *(const f32x4*)(sp + 256 * j); }
;         }
;         if (do_ln) {
;             float s = 0.f;
; #pragma unroll
;             for (int j = 0; j < 8; ++j) s += (v[j].x + v[j].y) + (v[j].z + v[j].w);
;             const float mean = wave_sum(s) * (1.f / D); float s2 = 0.f;
; #pragma unroll
;             for (int j = 0; j < 8; ++j) { v[j] = v[j] - mean; s2 += (v[j].x * v[j].x + v[j].y * v[j].y) + (v[j].z * v[j].z + v[j].w * v[j].w); }
;             const float rstd = rsqrtf(wave_sum(s2) * (1.f / D) + LN_EPS);
; #pragma unroll
;             for (int j = 0; j < 8; ++j) { const f32x4 gg = *(const f32x4*)(lng + lane * 4 + 256 * j), bb = *(const f32x4*)(lnb + lane * 4 + 256 * j);
;                 v[j] = v[j] * rstd * gg + bb; *(f32x4*)(dst + lane * 4 + 256 * j) = v[j]; }
.LBB0_1028:
	s_setprio 0
	s_cmp_lt_i32 s72, 11
	s_cselect_b64 s[0:1], -1, 0
	s_cmp_gt_i32 s73, 10
	s_cselect_b64 s[4:5], -1, 0
	s_and_b64 s[0:1], s[0:1], s[4:5]
	s_andn2_b64 vcc, exec, s[0:1]
	s_cbranch_vccnz .LBB0_1123
	v_readfirstlane_b32 s0, v174
	s_lshr_b32 s7, s0, 6
	v_readlane_b32 s0, v246, 0
	s_lshl_b32 s0, s0, 3
	s_add_i32 s3, s7, s0
	s_lshl_b32 s6, s74, 3
	s_cmpk_gt_i32 s3, 0x3fff
	s_waitcnt vmcnt(0)
	v_and_b32_e32 v71, 63, v174
	s_cbranch_scc1 .LBB0_1041
	s_add_u32 s9, s70, 0x6300000
	s_addc_u32 s28, s71, 0
	s_add_u32 s29, s70, 0x24000
	s_addc_u32 s33, s71, 0
	s_add_i32 s0, s3, 0xffffc000
	s_ashr_i32 s1, s3, 31
	s_cmpk_lt_i32 s3, 0x4000
	s_cselect_b32 s5, s1, 0
	s_cselect_b32 s4, s3, s0
	s_cselect_b32 s1, s69, s28
	s_cselect_b32 s2, s68, s9
	s_lshl_b64 s[4:5], s[4:5], 13
	s_add_u32 s4, s2, s4
	s_addc_u32 s5, s1, s5
	v_mov_b32_e32 v69, 0
	v_lshlrev_b32_e32 v68, 4, v71
	v_lshl_add_u64 v[0:1], s[4:5], 0, v[68:69]
	s_movk_i32 s58, 0x1000
	v_add_co_u32_e32 v0, vcc, s58, v0
	global_load_dwordx4 v[60:63], v68, s[4:5]
	global_load_dwordx4 v[56:59], v68, s[4:5] offset:1024
	global_load_dwordx4 v[52:55], v68, s[4:5] offset:2048
	global_load_dwordx4 v[48:51], v68, s[4:5] offset:3072
	v_addc_co_u32_e32 v1, vcc, 0, v1, vcc
	global_load_dwordx4 v[44:47], v[0:1], off
	global_load_dwordx4 v[40:43], v[0:1], off offset:1024
	global_load_dwordx4 v[36:39], v[0:1], off offset:2048
	global_load_dwordx4 v[32:35], v[0:1], off offset:3072
	v_lshlrev_b32_e32 v0, 3, v71
	v_mov_b32_e32 v1, v69
	v_lshl_add_u64 v[0:1], s[70:71], 0, v[0:1]
	s_mov_b64 s[10:11], 0x6700000
	v_lshl_add_u64 v[76:77], v[0:1], 0, s[10:11]
	v_mbcnt_lo_u32_b32 v0, -1, 0
	v_mbcnt_hi_u32_b32 v0, -1, v0
	v_and_b32_e32 v1, 64, v0
	v_add_u32_e32 v1, 64, v1
	v_xor_b32_e32 v2, 1, v0
	v_cmp_lt_i32_e32 vcc, v2, v1
	v_readlane_b32 s60, v246, 1
	v_readlane_b32 s64, v246, 5
	v_cndmask_b32_e32 v2, v0, v2, vcc
	v_lshlrev_b32_e32 v98, 2, v2
	v_xor_b32_e32 v2, 2, v0
	v_cmp_lt_i32_e32 vcc, v2, v1
	v_readlane_b32 s65, v246, 6
	v_readlane_b32 s66, v246, 7
	v_cndmask_b32_e32 v2, v0, v2, vcc
	v_lshlrev_b32_e32 v99, 2, v2
	v_xor_b32_e32 v2, 4, v0
	v_cmp_lt_i32_e32 vcc, v2, v1
	v_readlane_b32 s67, v246, 8
	v_lshl_add_u64 v[72:73], s[64:65], 0, v[68:69]
	v_cndmask_b32_e32 v2, v0, v2, vcc
	v_lshlrev_b32_e32 v100, 2, v2
	v_xor_b32_e32 v2, 8, v0
	v_cmp_lt_i32_e32 vcc, v2, v1
	v_lshl_add_u64 v[74:75], s[66:67], 0, v[68:69]
	s_mov_b64 s[10:11], 0x1000
	v_cndmask_b32_e32 v2, v0, v2, vcc
	v_lshlrev_b32_e32 v101, 2, v2
	v_xor_b32_e32 v2, 16, v0
	v_cmp_lt_i32_e32 vcc, v2, v1
	v_lshl_add_u64 v[78:79], v[72:73], 0, s[10:11]
	v_lshl_add_u64 v[80:81], v[74:75], 0, s[10:11]
	v_cndmask_b32_e32 v2, v0, v2, vcc
	s_mov_b64 s[10:11], 0x1400
	v_lshlrev_b32_e32 v102, 2, v2
	v_xor_b32_e32 v2, 32, v0
	v_lshl_add_u64 v[82:83], v[72:73], 0, s[10:11]
	v_lshl_add_u64 v[84:85], v[74:75], 0, s[10:11]
	s_mov_b64 s[10:11], 0x1800
	v_cmp_lt_i32_e32 vcc, v2, v1
	v_readlane_b32 s61, v246, 2
	v_readlane_b32 s62, v246, 3
	v_readlane_b32 s63, v246, 4
	v_lshl_add_u64 v[86:87], v[72:73], 0, s[10:11]
	v_lshl_add_u64 v[88:89], v[74:75], 0, s[10:11]
	s_mov_b64 s[10:11], 0x1c00
	v_cndmask_b32_e32 v0, v0, v2, vcc
	s_mov_b32 s5, 0
	v_lshlrev_b32_e32 v70, 2, v71
	v_lshl_add_u64 v[90:91], v[72:73], 0, s[10:11]
	v_lshl_add_u64 v[92:93], v[74:75], 0, s[10:11]
	v_lshlrev_b32_e32 v103, 2, v0
	v_lshl_add_u64 v[94:95], s[70:71], 0, v[68:69]
	s_movk_i32 s59, 0x3000
	s_mov_b32 s8, 0x3fb504f3
	s_mov_b32 s60, 0x1b800000
	s_mov_b32 s61, 0x1b801000
	s_mov_b32 s62, 0x1bc00000
	s_mov_b32 s63, 0x1bc01000
	s_brev_b32 s64, 56
	s_mov_b32 s65, 0x1c001000
	s_mov_b32 s66, 0x1c400000
	s_mov_b32 s67, 0x1c401000
	v_mov_b32_e32 v104, 0x3727c5ac
	s_mov_b32 s76, 0x800000
	s_mov_b64 s[10:11], 0x2000
	s_movk_i32 s77, 0x7fff
	s_mov_b32 s78, 0xffff0000
	s_mov_b32 s34, s3
	s_branch .LBB0_1032

; #define PG8_WAIT_V(n) asm volatile("s_waitcnt vmcnt(" #n ")" ::: "memory")
; template <class Epi, class Sched, bool ALIGN_EPI = false, bool SP2 = false>
; __device__ __forceinline__ void gemm_phase(PG8_LAS unsigned char* lds, const Gemm g, const Sched& S, const Epi& E) {
;     const int tid = threadIdx.x, wid = __builtin_amdgcn_readfirstlane(tid >> 6), lane = tid & 63, wr = wid >> 2, wc = wid & 3, fr = lane & 15, fq = lane >> 4;
;     const int K = g.K, nt = K / BK, LD = g.ld ? g.ld : g.K;
;     unsigned voffA[2], voffB[2];
; #pragma unroll
;     for (int i = 0; i < 2; ++i) { int R, C; stage_rc(tid * 16 + i * 8192, R, C); const int Rb = Epi::PERM ? ((R & ~31) + perm32(R & 31)) : R;
;         voffA[i] = (unsigned)(R * LD + C) * 2u; voffB[i] = (unsigned)(Rb * LD + C) * 2u; }
;     const size_t kstep = (size_t)(BK * 2);
;     const size_t hstep = (size_t)HALF * LD * 2;
;     const size_t tstep = 2 * hstep;
;     const unsigned ldsw = (unsigned)wid * 1024u;
;     const int aoff = lds_byte(wr * 64 + fr, fq * 8), boff = lds_byte(wc * 32 + fr, fq * 8);
;     ...
;     Unit cur, nxt; int ui = 0;
;     if (!S.next(0, cur)) return;
;     f32x4 acc[2][2][4][2];
; #pragma unroll
;     for (int a = 0; a < 2; ++a)
; #pragma unroll
;         for (int b = 0; b < 2; ++b)
; #pragma unroll
;             for (int m = 0; m < 4; ++m)
; #pragma unroll
;                 for (int n = 0; n < 2; ++n) acc[a][b][m][n] = (f32x4){0.f, 0.f, 0.f, 0.f};
;     bf16x8 At[4][2], B0[2][2], B1[2][2];
;     const char* cA = (const char*)g.A + (size_t)cur.pm * tstep + (size_t)cur.ks * K * 2; const char* cB = (const char*)g.Bt + (size_t)cur.pn * tstep + (size_t)cur.ks * K * 2;
;     S.a_ready(cur);
;     if constexpr (SP2) {
;         PG8_STAGE(PG8_SB(0, 0), cB, voffB); PG8_STAGE(PG8_SB(0, 1), cB + hstep, voffB); PG8_STAGE(PG8_SA(0, 0), cA, voffA); PG8_STAGE(PG8_SA(0, 1), cA + hstep, voffA);
;         if (wr == 1) PG8_BAR;
;         PG8_WAIT_V(2); PG8_BAR;
;         PG8_STAGE(PG8_SB(1, 0), cB + kstep, voffB); PG8_STAGE(PG8_SA(1, 0), cA + kstep, voffA); PG8_STAGE(PG8_SB(1, 1), cB + hstep + kstep, voffB);
;         PG8_WAIT_V(6); PG8_BAR;
;     ...
;             pg8::Gemm g{AC, (bf16*)(ws + WS_WIN), ML, INCP, D}; pg8::StaticOrder S; S.init(ML, INCP, (int)gridDim.x, (int)blockIdx.x);
;             EpiStoreBf16<0> E{Z, INCP};
;             pg8::gemm_phase<EpiStoreBf16<0>, pg8::StaticOrder, true, true>(lds, g, S, E); }
.LBB0_1177:
	s_cmp_lt_i32 s72, 13
	s_cselect_b64 s[0:1], -1, 0
	s_cmp_gt_i32 s73, 12
	s_cselect_b64 s[4:5], -1, 0
	s_and_b64 s[0:1], s[0:1], s[4:5]
	s_andn2_b64 vcc, exec, s[0:1]
	s_cbranch_vccnz .LBB0_1319
	v_readfirstlane_b32 vcc_lo, v174
	s_bitcmp1_b32 vcc_lo, 8
	s_cbranch_scc0 .Lsp_5
	s_setprio 1
.Lsp_5:
	s_add_u32 s3, s70, 0x100000
	v_lshlrev_b32_e32 v0, 6, v174
	s_addc_u32 s6, s71, 0
	v_and_b32_e32 v148, 0x3c0, v0
	v_lshlrev_b32_e32 v0, 2, v174
	v_readlane_b32 s4, v246, 0
	v_readfirstlane_b32 s1, v174
	v_and_b32_e32 v149, 15, v174
	s_cmpk_gt_i32 s4, 0x5ff
	v_and_b32_e32 v150, 32, v0
	s_cbranch_scc1 .LBB0_1194
	v_lshrrev_b32_e32 v0, 5, v174
	v_lshrrev_b32_e32 v2, 1, v174
	v_and_b32_e32 v0, 4, v0
	v_bfe_u32 v1, v174, 2, 2
	s_waitcnt vmcnt(0)
	v_and_b32_e32 v11, 24, v2
	v_or3_b32 v0, v0, v1, v11
	v_lshlrev_b32_e32 v1, 4, v174
	v_add_u32_e32 v8, 0x2000, v1
	v_lshrrev_b32_e32 v2, 7, v8
	s_movk_i32 s0, 0xe0
	v_and_b32_e32 v4, 32, v174
	v_and_or_b32 v3, v2, s0, v0
	v_bitop3_b32 v9, v1, v4, 48 bitop3:0x6c
	v_and_b32_e32 v10, 64, v174
	v_bfe_u32 v12, v174, 2, 4
	s_movk_i32 s0, 0xf0
	v_or_b32_e32 v1, v9, v10
	v_and_or_b32 v2, v2, s0, v12
	s_add_u32 s7, s70, 0x6700000
	v_lshl_or_b32 v130, v2, 12, v1
	v_lshrrev_b32_e32 v2, 3, v174
	s_movk_i32 s0, 0x60
	s_addc_u32 s28, s71, 0
	v_and_or_b32 v0, v2, s0, v0
	s_movk_i32 s0, 0x70
	s_ashr_i32 s33, s4, 31
	v_lshl_or_b32 v132, v0, 12, v1
	v_and_or_b32 v0, v2, s0, v12
	s_lshr_b32 s0, s33, 29
	s_add_i32 s0, s4, s0
	s_lshr_b32 s10, s1, 6
	s_ashr_i32 s2, s0, 3
	s_and_b32 s0, s0, -8
	s_lshr_b32 s30, s1, 8
	s_lshl_b32 s29, s10, 10
	s_sub_i32 s0, s4, s0
	s_cmp_lt_i32 s0, 0
	s_movk_i32 s60, 0xc1
	s_cselect_b32 s4, s60, 0xc0
	s_mul_i32 s0, s4, s0
	s_add_i32 s0, s0, s2
	s_mul_hi_i32 s2, s0, 0x2aaaaaab
	s_lshr_b32 s4, s2, 31
	s_ashr_i32 s2, s2, 5
	s_add_i32 s2, s2, s4
	s_lshl_b32 s4, s2, 3
	s_mulk_i32 s2, 0xc0
	s_sub_i32 s2, s0, s2
	s_sext_i32_i16 s0, s2
	s_bfe_u32 s0, s0, 0x3001c
	s_add_i32 s5, s2, s0
	s_sext_i32_i16 s0, s5
	s_and_b32 s5, s5, 0xfff8
	s_sub_i32 s2, s2, s5
	s_sext_i32_i16 s2, s2
	s_lshr_b32 s0, s0, 3
	s_add_i32 s52, s4, s2
	s_ashr_i32 s53, s52, 31
	s_bfe_i64 s[8:9], s[0:1], 0x100000
	s_lshl_b64 s[4:5], s[52:53], 20
	s_lshl_b64 s[8:9], s[8:9], 20
	s_add_u32 s56, s3, s8
	s_addc_u32 s57, s6, s9
	s_add_i32 s53, s29, 0
	s_add_i32 m0, s53, 0x10000
	v_lshl_or_b32 v128, v3, 12, v1
	global_load_lds_dwordx4 v132, s[56:57]
	s_add_i32 m0, s53, 0x12000
	s_add_u32 s8, s56, 0x80000
	global_load_lds_dwordx4 v128, s[56:57]
	s_addc_u32 s9, s57, 0
	s_add_i32 m0, s53, 0x14000
	v_lshl_or_b32 v134, v0, 12, v1
	global_load_lds_dwordx4 v132, s[8:9]
	s_add_i32 m0, s53, 0x16000
	s_add_u32 s54, s7, s4
	s_addc_u32 s55, s28, s5
	s_add_i32 s61, s53, 0x2000
	global_load_lds_dwordx4 v128, s[8:9]
	s_mov_b32 m0, s53
	s_add_u32 s4, s54, 0x80000
	global_load_lds_dwordx4 v134, s[54:55]
	s_mov_b32 m0, s61
	s_addc_u32 s5, s55, 0
	s_add_i32 s62, s53, 0x4000
	global_load_lds_dwordx4 v130, s[54:55]
	s_mov_b32 m0, s62
	s_add_i32 s63, s53, 0x6000
	global_load_lds_dwordx4 v134, s[4:5]
	s_mov_b32 m0, s63
	v_mov_b32_e32 v133, 0
	global_load_lds_dwordx4 v130, s[4:5]
	v_mov_b32_e32 v129, v133
	v_mov_b32_e32 v135, v133
	v_mov_b32_e32 v131, v133
	s_cmp_eq_u32 s30, 1
	s_mov_b32 s64, 0
	v_lshl_add_u64 v[6:7], s[56:57], 0, v[132:133]
	v_lshl_add_u64 v[4:5], s[56:57], 0, v[128:129]
	v_lshl_add_u64 v[0:1], s[54:55], 0, v[134:135]
	s_cselect_b64 s[4:5], -1, 0
	s_cmp_lg_u32 s30, 1
	v_lshl_add_u64 v[2:3], s[54:55], 0, v[130:131]
	s_cbranch_scc1 .LBB0_1181
	s_barrier

; #define PG8_STAGE(bufoff, gbase, voff) do { _Pragma("unroll") for (int _i = 0; _i < 2; ++_i) \
;         __builtin_amdgcn_global_load_lds((const unsigned*)((const char*)(gbase) + (voff)[_i]), (PG8_LAS unsigned*)(lds + (bufoff) + ldsw + _i * 8192), 16, 0, 0); } while (0)
; #define PG8_LDA(dst, b, h) do { _Pragma("unroll") for (int m = 0; m < 4; ++m) _Pragma("unroll") for (int k = 0; k < 2; ++k) dst[m][k] = *(const PG8_LAS bf16x8*)(lds + PG8_SA(b, h) + aoff + m * 2048 + k * 1024); } while (0)
; #define PG8_LDB(dst, b, h) do { _Pragma("unroll") for (int n = 0; n < 2; ++n) _Pragma("unroll") for (int k = 0; k < 2; ++k) dst[n][k] = *(const PG8_LAS bf16x8*)(lds + PG8_SB(b, h) + boff + n * 2048 + k * 1024); } while (0)
; #define PG8_MMA(ai, bj, At, Bt) do { __builtin_amdgcn_s_setprio(1); _Pragma("unroll") for (int m = 0; m < 4; ++m) _Pragma("unroll") for (int n = 0; n < 2; ++n) _Pragma("unroll") for (int k = 0; k < 2; ++k) \
;         acc[ai][bj][m][n] = __builtin_amdgcn_mfma_f32_16x16x32_bf16(Bt[n][k], At[m][k], acc[ai][bj][m][n], 0, 0, 0); __builtin_amdgcn_s_setprio(0); } while (0)
; #define PG8_WAIT_V(n) asm volatile("s_waitcnt vmcnt(" #n ")" ::: "memory")
; #define PG8_WAIT_L(n) asm volatile("s_waitcnt lgkmcnt(" #n ")" ::: "memory")
; #define PG8_BAR __builtin_amdgcn_s_barrier()
; #define PG8_SCHED __builtin_amdgcn_sched_barrier(0)
; template <class Epi, class Sched, bool ALIGN_EPI = false, bool SP2 = false>
; __device__ __forceinline__ void gemm_phase(PG8_LAS unsigned char* lds, const Gemm g, const Sched& S, const Epi& E) {
;     ...
;             const bool last = (t == nt - 2);
;             const char* a1 = cA + (size_t)(t + 1) * kstep;
;             const char* a2 = last ? nA : cA + (size_t)(t + 2) * kstep; const char* b2 = last ? nB : cB + (size_t)(t + 2) * kstep;
;             const char* a3 = a2 + kstep; const char* b3 = b2 + kstep;
;             if (last && has_next) S.a_ready(nxt);
;             if constexpr (SP2) {
;             PG8_LDB(B0, 0, 0); PG8_LDB(B1, 0, 1); PG8_SCHED; PG8_LDA(At, 0, 0); PG8_STAGE(PG8_SA(1, 1), a1 + hstep, voffA);
;             PG8_WAIT_V(8); PG8_WAIT_L(0); PG8_BAR; PG8_MMA(0, 0, At, B0); PG8_MMA(0, 1, At, B1); PG8_BAR; PG8_SCHED;
;             PG8_LDA(At, 0, 1); PG8_STAGE(PG8_SB(0, 0), b2, voffB); PG8_STAGE(PG8_SB(0, 1), b2 + hstep, voffB); PG8_STAGE(PG8_SA(0, 0), a2, voffA);
.LBB0_1187:
	ds_read_b128 v[144:147], v154
	ds_read_b128 v[158:161], v154 offset:1024
	ds_read_b128 v[162:165], v154 offset:2048
	ds_read_b128 v[166:169], v154 offset:3072
	ds_read_b128 v[170:173], v155
	ds_read_b128 v[176:179], v155 offset:1024
	ds_read_b128 v[180:183], v155 offset:2048
	ds_read_b128 v[184:187], v155 offset:3072
	s_add_u32 s2, s54, 0xfff80080
	s_addc_u32 s56, s55, -1
	s_cmp_eq_u32 s85, 28
	s_cselect_b32 s59, s43, s56
	s_cselect_b32 s58, s81, s2
	s_cselect_b32 s57, s35, s84
	s_cselect_b32 s56, s82, s83
	v_lshl_add_u64 v[220:221], s[54:55], 0, v[136:137]
	s_add_i32 m0, s53, 0xc000
	ds_read_b128 v[188:191], v156
	ds_read_b128 v[192:195], v156 offset:1024
	ds_read_b128 v[196:199], v156 offset:2048
	ds_read_b128 v[200:203], v156 offset:3072
	ds_read_b128 v[204:207], v156 offset:4096
	ds_read_b128 v[208:211], v156 offset:5120
	ds_read_b128 v[212:215], v156 offset:6144
	ds_read_b128 v[216:219], v156 offset:7168
	global_load_lds_dwordx4 v[220:221], off
	v_lshl_add_u64 v[220:221], s[54:55], 0, v[138:139]
	s_add_i32 m0, s53, 0xe000
	s_nop 0
	global_load_lds_dwordx4 v[220:221], off
	s_waitcnt vmcnt(8)
	s_waitcnt lgkmcnt(0)
	s_barrier
	s_waitcnt lgkmcnt(0)
	v_mfma_f32_16x16x32_bf16 v[124:127], v[144:147], v[188:191], v[124:127]
	v_mfma_f32_16x16x32_bf16 v[120:123], v[162:165], v[188:191], v[120:123]
	v_mfma_f32_16x16x32_bf16 v[116:119], v[144:147], v[196:199], v[116:119]
	v_mfma_f32_16x16x32_bf16 v[108:111], v[162:165], v[196:199], v[108:111]
	v_mfma_f32_16x16x32_bf16 v[100:103], v[144:147], v[204:207], v[100:103]
	v_mfma_f32_16x16x32_bf16 v[92:95], v[162:165], v[204:207], v[92:95]
	v_mfma_f32_16x16x32_bf16 v[84:87], v[144:147], v[212:215], v[84:87]
	v_mfma_f32_16x16x32_bf16 v[76:79], v[162:165], v[212:215], v[76:79]
	v_mfma_f32_16x16x32_bf16 v[124:127], v[158:161], v[192:195], v[124:127]
	v_mfma_f32_16x16x32_bf16 v[120:123], v[166:169], v[192:195], v[120:123]
	v_mfma_f32_16x16x32_bf16 v[116:119], v[158:161], v[200:203], v[116:119]
	v_mfma_f32_16x16x32_bf16 v[108:111], v[166:169], v[200:203], v[108:111]
	v_mfma_f32_16x16x32_bf16 v[100:103], v[158:161], v[208:211], v[100:103]
	v_mfma_f32_16x16x32_bf16 v[92:95], v[166:169], v[208:211], v[92:95]
	v_mfma_f32_16x16x32_bf16 v[84:87], v[158:161], v[216:219], v[84:87]
	v_mfma_f32_16x16x32_bf16 v[76:79], v[166:169], v[216:219], v[76:79]
	v_mfma_f32_16x16x32_bf16 v[112:115], v[170:173], v[188:191], v[112:115]
	v_mfma_f32_16x16x32_bf16 v[104:107], v[180:183], v[188:191], v[104:107]
	v_mfma_f32_16x16x32_bf16 v[96:99], v[170:173], v[196:199], v[96:99]
	v_mfma_f32_16x16x32_bf16 v[88:91], v[180:183], v[196:199], v[88:91]
	v_mfma_f32_16x16x32_bf16 v[80:83], v[170:173], v[204:207], v[80:83]
	v_mfma_f32_16x16x32_bf16 v[72:75], v[180:183], v[204:207], v[72:75]
	v_mfma_f32_16x16x32_bf16 v[68:71], v[170:173], v[212:215], v[68:71]
	v_mfma_f32_16x16x32_bf16 v[64:67], v[180:183], v[212:215], v[64:67]
	v_mfma_f32_16x16x32_bf16 v[112:115], v[176:179], v[192:195], v[112:115]
	v_mfma_f32_16x16x32_bf16 v[104:107], v[184:187], v[192:195], v[104:107]
	v_mfma_f32_16x16x32_bf16 v[96:99], v[176:179], v[200:203], v[96:99]
	v_mfma_f32_16x16x32_bf16 v[88:91], v[184:187], v[200:203], v[88:91]
	v_mfma_f32_16x16x32_bf16 v[80:83], v[176:179], v[208:211], v[80:83]
	v_mfma_f32_16x16x32_bf16 v[72:75], v[184:187], v[208:211], v[72:75]
	v_mfma_f32_16x16x32_bf16 v[68:71], v[176:179], v[216:219], v[68:71]
	v_mfma_f32_16x16x32_bf16 v[64:67], v[184:187], v[216:219], v[64:67]
	s_barrier
	s_add_i32 s2, s77, s29
	v_lshl_add_u64 v[220:221], s[56:57], 0, v[132:133]
	s_mov_b32 m0, s2
	ds_read_b128 v[188:191], v156 offset:16384
	ds_read_b128 v[192:195], v156 offset:17408
	ds_read_b128 v[196:199], v156 offset:18432
	ds_read_b128 v[200:203], v156 offset:19456
	ds_read_b128 v[204:207], v156 offset:20480
	ds_read_b128 v[208:211], v156 offset:21504
	ds_read_b128 v[212:215], v156 offset:22528
	ds_read_b128 v[216:219], v156 offset:23552
	global_load_lds_dwordx4 v[220:221], off
	s_add_i32 m0, s2, 0x2000
	s_add_u32 s68, s56, 0x80000
	v_lshl_add_u64 v[222:223], s[56:57], 0, v[128:129]
	s_addc_u32 s69, s57, 0
	s_add_i32 s2, s78, s29
	global_load_lds_dwordx4 v[222:223], off
	v_lshl_add_u64 v[224:225], s[68:69], 0, v[132:133]
	s_mov_b32 m0, s2
	v_lshl_add_u64 v[226:227], s[58:59], 0, v[130:131]
	global_load_lds_dwordx4 v[224:225], off
	v_lshl_add_u64 v[224:225], s[68:69], 0, v[128:129]
	s_add_i32 m0, s2, 0x2000
	s_nop 0
	global_load_lds_dwordx4 v[224:225], off
	v_lshl_add_u64 v[224:225], s[58:59], 0, v[134:135]
	s_mov_b32 m0, s53
	s_nop 0
	global_load_lds_dwordx4 v[224:225], off
	s_mov_b32 m0, s61
	s_nop 0
	global_load_lds_dwordx4 v[226:227], off
	s_waitcnt vmcnt(8)
	s_waitcnt lgkmcnt(0)
	s_barrier
; #define PG8_STAGE(bufoff, gbase, voff) do { _Pragma("unroll") for (int _i = 0; _i < 2; ++_i) \
;         __builtin_amdgcn_global_load_lds((const unsigned*)((const char*)(gbase) + (voff)[_i]), (PG8_LAS unsigned*)(lds + (bufoff) + ldsw + _i * 8192), 16, 0, 0); } while (0)
; #define PG8_LDA(dst, b, h) do { _Pragma("unroll") for (int m = 0; m < 4; ++m) _Pragma("unroll") for (int k = 0; k < 2; ++k) dst[m][k] = *(const PG8_LAS bf16x8*)(lds + PG8_SA(b, h) + aoff + m * 2048 + k * 1024); } while (0)
; #define PG8_LDB(dst, b, h) do { _Pragma("unroll") for (int n = 0; n < 2; ++n) _Pragma("unroll") for (int k = 0; k < 2; ++k) dst[n][k] = *(const PG8_LAS bf16x8*)(lds + PG8_SB(b, h) + boff + n * 2048 + k * 1024); } while (0)
; #define PG8_MMA(ai, bj, At, Bt) do { __builtin_amdgcn_s_setprio(1); _Pragma("unroll") for (int m = 0; m < 4; ++m) _Pragma("unroll") for (int n = 0; n < 2; ++n) _Pragma("unroll") for (int k = 0; k < 2; ++k) \
;         acc[ai][bj][m][n] = __builtin_amdgcn_mfma_f32_16x16x32_bf16(Bt[n][k], At[m][k], acc[ai][bj][m][n], 0, 0, 0); __builtin_amdgcn_s_setprio(0); } while (0)
; #define PG8_WAIT_V(n) asm volatile("s_waitcnt vmcnt(" #n ")" ::: "memory")
; #define PG8_WAIT_L(n) asm volatile("s_waitcnt lgkmcnt(" #n ")" ::: "memory")
; #define PG8_BAR __builtin_amdgcn_s_barrier()
; #define PG8_SCHED __builtin_amdgcn_sched_barrier(0)
; template <class Epi, class Sched, bool ALIGN_EPI = false, bool SP2 = false>
; __device__ __forceinline__ void gemm_phase(PG8_LAS unsigned char* lds, const Gemm g, const Sched& S, const Epi& E) {
;     ...
;             PG8_WAIT_V(8); PG8_WAIT_L(0); PG8_BAR; PG8_MMA(1, 0, At, B0); PG8_MMA(1, 1, At, B1); PG8_BAR; PG8_SCHED;
;             PG8_LDB(B0, 1, 0); PG8_LDB(B1, 1, 1); PG8_SCHED; PG8_LDA(At, 1, 0); PG8_STAGE(PG8_SA(0, 1), a2 + hstep, voffA);
;             PG8_WAIT_V(8); PG8_WAIT_L(0); PG8_BAR; PG8_MMA(0, 0, At, B0); PG8_MMA(0, 1, At, B1); PG8_BAR; PG8_SCHED;
	s_waitcnt lgkmcnt(0)
	v_mfma_f32_16x16x32_bf16 v[60:63], v[144:147], v[188:191], v[60:63]
	v_mfma_f32_16x16x32_bf16 v[56:59], v[162:165], v[188:191], v[56:59]
	v_mfma_f32_16x16x32_bf16 v[52:55], v[144:147], v[196:199], v[52:55]
	v_mfma_f32_16x16x32_bf16 v[44:47], v[162:165], v[196:199], v[44:47]
	v_mfma_f32_16x16x32_bf16 v[36:39], v[144:147], v[204:207], v[36:39]
	v_mfma_f32_16x16x32_bf16 v[28:31], v[162:165], v[204:207], v[28:31]
	v_mfma_f32_16x16x32_bf16 v[20:23], v[144:147], v[212:215], v[20:23]
	v_mfma_f32_16x16x32_bf16 v[12:15], v[162:165], v[212:215], v[12:15]
	v_mfma_f32_16x16x32_bf16 v[60:63], v[158:161], v[192:195], v[60:63]
	v_mfma_f32_16x16x32_bf16 v[56:59], v[166:169], v[192:195], v[56:59]
	v_mfma_f32_16x16x32_bf16 v[52:55], v[158:161], v[200:203], v[52:55]
	v_mfma_f32_16x16x32_bf16 v[44:47], v[166:169], v[200:203], v[44:47]
	v_mfma_f32_16x16x32_bf16 v[36:39], v[158:161], v[208:211], v[36:39]
	v_mfma_f32_16x16x32_bf16 v[28:31], v[166:169], v[208:211], v[28:31]
	v_mfma_f32_16x16x32_bf16 v[20:23], v[158:161], v[216:219], v[20:23]
	v_mfma_f32_16x16x32_bf16 v[12:15], v[166:169], v[216:219], v[12:15]
	v_mfma_f32_16x16x32_bf16 v[48:51], v[170:173], v[188:191], v[48:51]
	v_mfma_f32_16x16x32_bf16 v[40:43], v[180:183], v[188:191], v[40:43]
	v_mfma_f32_16x16x32_bf16 v[32:35], v[170:173], v[196:199], v[32:35]
	v_mfma_f32_16x16x32_bf16 v[24:27], v[180:183], v[196:199], v[24:27]
	v_mfma_f32_16x16x32_bf16 v[16:19], v[170:173], v[204:207], v[16:19]
	v_mfma_f32_16x16x32_bf16 v[8:11], v[180:183], v[204:207], v[8:11]
	v_mfma_f32_16x16x32_bf16 v[4:7], v[170:173], v[212:215], v[4:7]
	v_mfma_f32_16x16x32_bf16 v[0:3], v[180:183], v[212:215], v[0:3]
	v_mfma_f32_16x16x32_bf16 v[48:51], v[176:179], v[192:195], v[48:51]
	v_mfma_f32_16x16x32_bf16 v[40:43], v[184:187], v[192:195], v[40:43]
	v_mfma_f32_16x16x32_bf16 v[32:35], v[176:179], v[200:203], v[32:35]
	v_mfma_f32_16x16x32_bf16 v[24:27], v[184:187], v[200:203], v[24:27]
	v_mfma_f32_16x16x32_bf16 v[16:19], v[176:179], v[208:211], v[16:19]
	v_mfma_f32_16x16x32_bf16 v[8:11], v[184:187], v[208:211], v[8:11]
	v_mfma_f32_16x16x32_bf16 v[4:7], v[176:179], v[216:219], v[4:7]
	v_mfma_f32_16x16x32_bf16 v[0:3], v[184:187], v[216:219], v[0:3]
	s_barrier
	s_add_i32 s2, 0, 0x18000
	v_add_u32_e32 v157, s2, v152
	s_add_i32 s68, 0, 0x1c000
	ds_read_b128 v[144:147], v157
	ds_read_b128 v[158:161], v157 offset:1024
	ds_read_b128 v[162:165], v157 offset:2048
	ds_read_b128 v[166:169], v157 offset:3072
	v_add_u32_e32 v157, s68, v152
	ds_read_b128 v[170:173], v157
	ds_read_b128 v[176:179], v157 offset:1024
	ds_read_b128 v[180:183], v157 offset:2048
	ds_read_b128 v[184:187], v157 offset:3072
	s_add_u32 s58, s58, 0x80000
	s_addc_u32 s59, s59, 0
	s_mov_b32 m0, s62
	v_lshl_add_u64 v[228:229], s[58:59], 0, v[134:135]
	ds_read_b128 v[188:191], v156 offset:32768
	ds_read_b128 v[192:195], v156 offset:33792
	ds_read_b128 v[196:199], v156 offset:34816
	ds_read_b128 v[200:203], v156 offset:35840
	ds_read_b128 v[204:207], v156 offset:36864
	ds_read_b128 v[208:211], v156 offset:37888
	ds_read_b128 v[212:215], v156 offset:38912
	ds_read_b128 v[216:219], v156 offset:39936
	global_load_lds_dwordx4 v[228:229], off
	v_lshl_add_u64 v[228:229], s[58:59], 0, v[130:131]
	s_mov_b32 m0, s63
	s_nop 0
	global_load_lds_dwordx4 v[228:229], off
	s_waitcnt vmcnt(8)
	s_waitcnt lgkmcnt(0)
	s_barrier
	s_waitcnt lgkmcnt(0)
	v_mfma_f32_16x16x32_bf16 v[124:127], v[144:147], v[188:191], v[124:127]
	v_mfma_f32_16x16x32_bf16 v[120:123], v[162:165], v[188:191], v[120:123]
	v_mfma_f32_16x16x32_bf16 v[116:119], v[144:147], v[196:199], v[116:119]
	v_mfma_f32_16x16x32_bf16 v[108:111], v[162:165], v[196:199], v[108:111]
	v_mfma_f32_16x16x32_bf16 v[100:103], v[144:147], v[204:207], v[100:103]
	v_mfma_f32_16x16x32_bf16 v[92:95], v[162:165], v[204:207], v[92:95]
	v_mfma_f32_16x16x32_bf16 v[84:87], v[144:147], v[212:215], v[84:87]
	v_mfma_f32_16x16x32_bf16 v[76:79], v[162:165], v[212:215], v[76:79]
	v_mfma_f32_16x16x32_bf16 v[124:127], v[158:161], v[192:195], v[124:127]
	v_mfma_f32_16x16x32_bf16 v[120:123], v[166:169], v[192:195], v[120:123]
	v_mfma_f32_16x16x32_bf16 v[116:119], v[158:161], v[200:203], v[116:119]
	v_mfma_f32_16x16x32_bf16 v[108:111], v[166:169], v[200:203], v[108:111]
	v_mfma_f32_16x16x32_bf16 v[100:103], v[158:161], v[208:211], v[100:103]
	v_mfma_f32_16x16x32_bf16 v[92:95], v[166:169], v[208:211], v[92:95]
	v_mfma_f32_16x16x32_bf16 v[84:87], v[158:161], v[216:219], v[84:87]
	v_mfma_f32_16x16x32_bf16 v[76:79], v[166:169], v[216:219], v[76:79]
	v_mfma_f32_16x16x32_bf16 v[112:115], v[170:173], v[188:191], v[112:115]
	v_mfma_f32_16x16x32_bf16 v[104:107], v[180:183], v[188:191], v[104:107]
	v_mfma_f32_16x16x32_bf16 v[96:99], v[170:173], v[196:199], v[96:99]
	v_mfma_f32_16x16x32_bf16 v[88:91], v[180:183], v[196:199], v[88:91]
	v_mfma_f32_16x16x32_bf16 v[80:83], v[170:173], v[204:207], v[80:83]
	v_mfma_f32_16x16x32_bf16 v[72:75], v[180:183], v[204:207], v[72:75]
	v_mfma_f32_16x16x32_bf16 v[68:71], v[170:173], v[212:215], v[68:71]
	v_mfma_f32_16x16x32_bf16 v[64:67], v[180:183], v[212:215], v[64:67]
	v_mfma_f32_16x16x32_bf16 v[112:115], v[176:179], v[192:195], v[112:115]
	v_mfma_f32_16x16x32_bf16 v[104:107], v[184:187], v[192:195], v[104:107]
	v_mfma_f32_16x16x32_bf16 v[96:99], v[176:179], v[200:203], v[96:99]
	v_mfma_f32_16x16x32_bf16 v[88:91], v[184:187], v[200:203], v[88:91]
	v_mfma_f32_16x16x32_bf16 v[80:83], v[176:179], v[208:211], v[80:83]
	v_mfma_f32_16x16x32_bf16 v[72:75], v[184:187], v[208:211], v[72:75]
	v_mfma_f32_16x16x32_bf16 v[68:71], v[176:179], v[216:219], v[68:71]
	v_mfma_f32_16x16x32_bf16 v[64:67], v[184:187], v[216:219], v[64:67]
	s_barrier
; #define PG8_STAGE(bufoff, gbase, voff) do { _Pragma("unroll") for (int _i = 0; _i < 2; ++_i) \
;         __builtin_amdgcn_global_load_lds((const unsigned*)((const char*)(gbase) + (voff)[_i]), (PG8_LAS unsigned*)(lds + (bufoff) + ldsw + _i * 8192), 16, 0, 0); } while (0)
; #define PG8_LDA(dst, b, h) do { _Pragma("unroll") for (int m = 0; m < 4; ++m) _Pragma("unroll") for (int k = 0; k < 2; ++k) dst[m][k] = *(const PG8_LAS bf16x8*)(lds + PG8_SA(b, h) + aoff + m * 2048 + k * 1024); } while (0)
; #define PG8_MMA(ai, bj, At, Bt) do { __builtin_amdgcn_s_setprio(1); _Pragma("unroll") for (int m = 0; m < 4; ++m) _Pragma("unroll") for (int n = 0; n < 2; ++n) _Pragma("unroll") for (int k = 0; k < 2; ++k) \
;         acc[ai][bj][m][n] = __builtin_amdgcn_mfma_f32_16x16x32_bf16(Bt[n][k], At[m][k], acc[ai][bj][m][n], 0, 0, 0); __builtin_amdgcn_s_setprio(0); } while (0)
; #define PG8_WAIT_V(n) asm volatile("s_waitcnt vmcnt(" #n ")" ::: "memory")
; #define PG8_WAIT_L(n) asm volatile("s_waitcnt lgkmcnt(" #n ")" ::: "memory")
; #define PG8_BAR __builtin_amdgcn_s_barrier()
; #define PG8_SCHED __builtin_amdgcn_sched_barrier(0)
; template <class Epi, class Sched, bool ALIGN_EPI = false, bool SP2 = false>
; __device__ __forceinline__ void gemm_phase(PG8_LAS unsigned char* lds, const Gemm g, const Sched& S, const Epi& E) {
;     ...
;             PG8_LDA(At, 1, 1); PG8_STAGE(PG8_SB(1, 0), b3, voffB); PG8_STAGE(PG8_SB(1, 1), b3 + hstep, voffB); PG8_STAGE(PG8_SA(1, 0), a3, voffA);
;             PG8_WAIT_V(8); PG8_WAIT_L(0); PG8_BAR; PG8_MMA(1, 0, At, B0); PG8_MMA(1, 1, At, B1); PG8_BAR; PG8_SCHED;
	s_add_i32 s2, s2, s29
	v_lshl_add_u64 v[220:221], v[220:221], 0, s[10:11]
	s_mov_b32 m0, s2
	ds_read_b128 v[188:191], v156 offset:49152
	ds_read_b128 v[192:195], v156 offset:50176
	ds_read_b128 v[196:199], v156 offset:51200
	ds_read_b128 v[200:203], v156 offset:52224
	ds_read_b128 v[204:207], v156 offset:53248
	ds_read_b128 v[208:211], v156 offset:54272
	ds_read_b128 v[212:215], v156 offset:55296
	ds_read_b128 v[216:219], v156 offset:56320
	global_load_lds_dwordx4 v[220:221], off
	s_add_i32 m0, s2, 0x2000
	s_add_u32 s56, s56, 0x80080
	v_lshl_add_u64 v[220:221], v[222:223], 0, s[10:11]
	s_addc_u32 s57, s57, 0
	s_add_i32 s2, s68, s29
	global_load_lds_dwordx4 v[220:221], off
	v_lshl_add_u64 v[220:221], s[56:57], 0, v[132:133]
	s_mov_b32 m0, s2
	s_nop 0
	global_load_lds_dwordx4 v[220:221], off
	v_lshl_add_u64 v[220:221], s[56:57], 0, v[128:129]
	s_add_i32 m0, s2, 0x2000
	s_nop 0
	global_load_lds_dwordx4 v[220:221], off
	v_lshl_add_u64 v[220:221], v[224:225], 0, s[10:11]
	s_mov_b32 m0, s65
	s_nop 0
	global_load_lds_dwordx4 v[220:221], off
	v_lshl_add_u64 v[220:221], v[226:227], 0, s[10:11]
	s_mov_b32 m0, s66
	s_nop 0
	global_load_lds_dwordx4 v[220:221], off
	s_waitcnt vmcnt(8)
	s_waitcnt lgkmcnt(0)
	s_barrier
	s_waitcnt lgkmcnt(0)
	v_mfma_f32_16x16x32_bf16 v[60:63], v[144:147], v[188:191], v[60:63]
	v_mfma_f32_16x16x32_bf16 v[56:59], v[162:165], v[188:191], v[56:59]
	v_mfma_f32_16x16x32_bf16 v[52:55], v[144:147], v[196:199], v[52:55]
	v_mfma_f32_16x16x32_bf16 v[44:47], v[162:165], v[196:199], v[44:47]
	v_mfma_f32_16x16x32_bf16 v[36:39], v[144:147], v[204:207], v[36:39]
	v_mfma_f32_16x16x32_bf16 v[28:31], v[162:165], v[204:207], v[28:31]
	v_mfma_f32_16x16x32_bf16 v[20:23], v[144:147], v[212:215], v[20:23]
	v_mfma_f32_16x16x32_bf16 v[12:15], v[162:165], v[212:215], v[12:15]
	v_mfma_f32_16x16x32_bf16 v[60:63], v[158:161], v[192:195], v[60:63]
	v_mfma_f32_16x16x32_bf16 v[56:59], v[166:169], v[192:195], v[56:59]
	v_mfma_f32_16x16x32_bf16 v[52:55], v[158:161], v[200:203], v[52:55]
	v_mfma_f32_16x16x32_bf16 v[44:47], v[166:169], v[200:203], v[44:47]
	v_mfma_f32_16x16x32_bf16 v[36:39], v[158:161], v[208:211], v[36:39]
	v_mfma_f32_16x16x32_bf16 v[28:31], v[166:169], v[208:211], v[28:31]
	v_mfma_f32_16x16x32_bf16 v[20:23], v[158:161], v[216:219], v[20:23]
	v_mfma_f32_16x16x32_bf16 v[12:15], v[166:169], v[216:219], v[12:15]
	v_mfma_f32_16x16x32_bf16 v[48:51], v[170:173], v[188:191], v[48:51]
	v_mfma_f32_16x16x32_bf16 v[40:43], v[180:183], v[188:191], v[40:43]
	v_mfma_f32_16x16x32_bf16 v[32:35], v[170:173], v[196:199], v[32:35]
	v_mfma_f32_16x16x32_bf16 v[24:27], v[180:183], v[196:199], v[24:27]
	v_mfma_f32_16x16x32_bf16 v[16:19], v[170:173], v[204:207], v[16:19]
	v_mfma_f32_16x16x32_bf16 v[8:11], v[180:183], v[204:207], v[8:11]
	v_mfma_f32_16x16x32_bf16 v[4:7], v[170:173], v[212:215], v[4:7]
	v_mfma_f32_16x16x32_bf16 v[0:3], v[180:183], v[212:215], v[0:3]
	v_mfma_f32_16x16x32_bf16 v[48:51], v[176:179], v[192:195], v[48:51]
	v_mfma_f32_16x16x32_bf16 v[40:43], v[184:187], v[192:195], v[40:43]
	v_mfma_f32_16x16x32_bf16 v[32:35], v[176:179], v[200:203], v[32:35]
	v_mfma_f32_16x16x32_bf16 v[24:27], v[184:187], v[200:203], v[24:27]
	v_mfma_f32_16x16x32_bf16 v[16:19], v[176:179], v[208:211], v[16:19]
	v_mfma_f32_16x16x32_bf16 v[8:11], v[184:187], v[208:211], v[8:11]
	v_mfma_f32_16x16x32_bf16 v[4:7], v[176:179], v[216:219], v[4:7]
	v_mfma_f32_16x16x32_bf16 v[0:3], v[184:187], v[216:219], v[0:3]
	s_barrier
	s_add_i32 s85, s85, 2
	s_add_u32 s54, s54, 0x100
	s_addc_u32 s55, s55, 0
	s_add_u32 s83, s83, 0x100
	s_addc_u32 s84, s84, 0
	s_cmp_gt_u32 s85, 29
	s_cbranch_scc0 .LBB0_1187
	s_and_b64 vcc, exec, s[30:31]
	s_cbranch_vccz .LBB0_1190
	s_barrier

; #define PG8_STAGE(bufoff, gbase, voff) do { _Pragma("unroll") for (int _i = 0; _i < 2; ++_i) \
;         __builtin_amdgcn_global_load_lds((const unsigned*)((const char*)(gbase) + (voff)[_i]), (PG8_LAS unsigned*)(lds + (bufoff) + ldsw + _i * 8192), 16, 0, 0); } while (0)
; #define PG8_LDA(dst, b, h) do { _Pragma("unroll") for (int m = 0; m < 4; ++m) _Pragma("unroll") for (int k = 0; k < 2; ++k) dst[m][k] = *(const PG8_LAS bf16x8*)(lds + PG8_SA(b, h) + aoff + m * 2048 + k * 1024); } while (0)
; #define PG8_LDB(dst, b, h) do { _Pragma("unroll") for (int n = 0; n < 2; ++n) _Pragma("unroll") for (int k = 0; k < 2; ++k) dst[n][k] = *(const PG8_LAS bf16x8*)(lds + PG8_SB(b, h) + boff + n * 2048 + k * 1024); } while (0)
; #define PG8_MMA(ai, bj, At, Bt) do { __builtin_amdgcn_s_setprio(1); _Pragma("unroll") for (int m = 0; m < 4; ++m) _Pragma("unroll") for (int n = 0; n < 2; ++n) _Pragma("unroll") for (int k = 0; k < 2; ++k) \
;         acc[ai][bj][m][n] = __builtin_amdgcn_mfma_f32_16x16x32_bf16(Bt[n][k], At[m][k], acc[ai][bj][m][n], 0, 0, 0); __builtin_amdgcn_s_setprio(0); } while (0)
; #define PG8_WAIT_V(n) asm volatile("s_waitcnt vmcnt(" #n ")" ::: "memory")
; #define PG8_WAIT_L(n) asm volatile("s_waitcnt lgkmcnt(" #n ")" ::: "memory")
; #define PG8_BAR __builtin_amdgcn_s_barrier()
; #define PG8_SCHED __builtin_amdgcn_sched_barrier(0)
; template <class Epi, class Sched, bool ALIGN_EPI = false, bool SP2 = false>
; __device__ __forceinline__ void gemm_phase(PG8_LAS unsigned char* lds, const Gemm g, const Sched& S, const Epi& E) {
;     ...
;             const bool last = (t == nt - 2);
;             const char* a1 = cA + (size_t)(t + 1) * kstep;
;             const char* a2 = last ? nA : cA + (size_t)(t + 2) * kstep; const char* b2 = last ? nB : cB + (size_t)(t + 2) * kstep;
;             const char* a3 = a2 + kstep; const char* b3 = b2 + kstep;
;             if (last && has_next) S.a_ready(nxt);
;             if constexpr (SP2) {
;             PG8_LDB(B0, 0, 0); PG8_LDB(B1, 0, 1); PG8_SCHED; PG8_LDA(At, 0, 0); PG8_STAGE(PG8_SA(1, 1), a1 + hstep, voffA);
;             PG8_WAIT_V(8); PG8_WAIT_L(0); PG8_BAR; PG8_MMA(0, 0, At, B0); PG8_MMA(0, 1, At, B1); PG8_BAR; PG8_SCHED;
;             PG8_LDA(At, 0, 1); PG8_STAGE(PG8_SB(0, 0), b2, voffB); PG8_STAGE(PG8_SB(0, 1), b2 + hstep, voffB); PG8_STAGE(PG8_SA(0, 0), a2, voffA);
.LBB0_1203:
	ds_read_b128 v[158:161], v155
	ds_read_b128 v[162:165], v155 offset:1024
	ds_read_b128 v[166:169], v155 offset:2048
	ds_read_b128 v[170:173], v155 offset:3072
	ds_read_b128 v[176:179], v156
	ds_read_b128 v[180:183], v156 offset:1024
	ds_read_b128 v[184:187], v156 offset:2048
	ds_read_b128 v[188:191], v156 offset:3072
	s_add_u32 s2, s60, 0xfff80080
	s_addc_u32 s62, s61, -1
	s_cmp_eq_u32 s82, 4
	s_cselect_b32 s65, s9, s62
	s_cselect_b32 s64, s47, s2
	s_cselect_b32 s63, s49, s81
	s_cselect_b32 s62, s53, s80
	v_lshl_add_u64 v[224:225], s[60:61], 0, v[148:149]
	s_add_i32 m0, s11, 0xc000
	ds_read_b128 v[192:195], v154
	ds_read_b128 v[196:199], v154 offset:1024
	ds_read_b128 v[200:203], v154 offset:2048
	ds_read_b128 v[204:207], v154 offset:3072
	ds_read_b128 v[208:211], v154 offset:4096
	ds_read_b128 v[212:215], v154 offset:5120
	ds_read_b128 v[216:219], v154 offset:6144
	ds_read_b128 v[220:223], v154 offset:7168
	global_load_lds_dwordx4 v[224:225], off
	v_lshl_add_u64 v[224:225], s[60:61], 0, v[150:151]
	s_add_i32 m0, s11, 0xe000
	s_nop 0
	global_load_lds_dwordx4 v[224:225], off
	s_waitcnt vmcnt(8)
	s_waitcnt lgkmcnt(0)
	s_barrier
	s_waitcnt lgkmcnt(0)
	v_mfma_f32_16x16x32_bf16 v[124:127], v[158:161], v[192:195], v[124:127]
	v_mfma_f32_16x16x32_bf16 v[116:119], v[166:169], v[192:195], v[116:119]
	v_mfma_f32_16x16x32_bf16 v[120:123], v[158:161], v[200:203], v[120:123]
	v_mfma_f32_16x16x32_bf16 v[108:111], v[166:169], v[200:203], v[108:111]
	v_mfma_f32_16x16x32_bf16 v[112:115], v[158:161], v[208:211], v[112:115]
	v_mfma_f32_16x16x32_bf16 v[100:103], v[166:169], v[208:211], v[100:103]
	v_mfma_f32_16x16x32_bf16 v[104:107], v[158:161], v[216:219], v[104:107]
	v_mfma_f32_16x16x32_bf16 v[96:99], v[166:169], v[216:219], v[96:99]
	v_mfma_f32_16x16x32_bf16 v[124:127], v[162:165], v[196:199], v[124:127]
	v_mfma_f32_16x16x32_bf16 v[116:119], v[170:173], v[196:199], v[116:119]
	v_mfma_f32_16x16x32_bf16 v[120:123], v[162:165], v[204:207], v[120:123]
	v_mfma_f32_16x16x32_bf16 v[108:111], v[170:173], v[204:207], v[108:111]
	v_mfma_f32_16x16x32_bf16 v[112:115], v[162:165], v[212:215], v[112:115]
	v_mfma_f32_16x16x32_bf16 v[100:103], v[170:173], v[212:215], v[100:103]
	v_mfma_f32_16x16x32_bf16 v[104:107], v[162:165], v[220:223], v[104:107]
	v_mfma_f32_16x16x32_bf16 v[96:99], v[170:173], v[220:223], v[96:99]
	v_mfma_f32_16x16x32_bf16 v[92:95], v[176:179], v[192:195], v[92:95]
	v_mfma_f32_16x16x32_bf16 v[84:87], v[184:187], v[192:195], v[84:87]
	v_mfma_f32_16x16x32_bf16 v[88:91], v[176:179], v[200:203], v[88:91]
	v_mfma_f32_16x16x32_bf16 v[72:75], v[184:187], v[200:203], v[72:75]
	v_mfma_f32_16x16x32_bf16 v[76:79], v[176:179], v[208:211], v[76:79]
	v_mfma_f32_16x16x32_bf16 v[60:63], v[184:187], v[208:211], v[60:63]
	v_mfma_f32_16x16x32_bf16 v[68:71], v[176:179], v[216:219], v[68:71]
	v_mfma_f32_16x16x32_bf16 v[48:51], v[184:187], v[216:219], v[48:51]
	v_mfma_f32_16x16x32_bf16 v[92:95], v[180:183], v[196:199], v[92:95]
	v_mfma_f32_16x16x32_bf16 v[84:87], v[188:191], v[196:199], v[84:87]
	v_mfma_f32_16x16x32_bf16 v[88:91], v[180:183], v[204:207], v[88:91]
	v_mfma_f32_16x16x32_bf16 v[72:75], v[188:191], v[204:207], v[72:75]
	v_mfma_f32_16x16x32_bf16 v[76:79], v[180:183], v[212:215], v[76:79]
	v_mfma_f32_16x16x32_bf16 v[60:63], v[188:191], v[212:215], v[60:63]
	v_mfma_f32_16x16x32_bf16 v[68:71], v[180:183], v[220:223], v[68:71]
	v_mfma_f32_16x16x32_bf16 v[48:51], v[188:191], v[220:223], v[48:51]
	s_barrier
	s_add_i32 s2, s78, s29
	v_lshl_add_u64 v[224:225], s[62:63], 0, v[130:131]
	s_mov_b32 m0, s2
	ds_read_b128 v[192:195], v154 offset:16384
	ds_read_b128 v[196:199], v154 offset:17408
	ds_read_b128 v[200:203], v154 offset:18432
	ds_read_b128 v[204:207], v154 offset:19456
	ds_read_b128 v[208:211], v154 offset:20480
	ds_read_b128 v[212:215], v154 offset:21504
	ds_read_b128 v[216:219], v154 offset:22528
	ds_read_b128 v[220:223], v154 offset:23552
	global_load_lds_dwordx4 v[224:225], off
	s_add_i32 m0, s2, 0x2000
	s_add_u32 s68, s62, 0x80000
	v_lshl_add_u64 v[226:227], s[62:63], 0, v[128:129]
	s_addc_u32 s69, s63, 0
	s_add_i32 s2, s79, s29
	global_load_lds_dwordx4 v[226:227], off
	v_lshl_add_u64 v[228:229], s[68:69], 0, v[130:131]
	s_mov_b32 m0, s2
	v_lshl_add_u64 v[230:231], s[64:65], 0, v[128:129]
	global_load_lds_dwordx4 v[228:229], off
	v_lshl_add_u64 v[228:229], s[68:69], 0, v[128:129]
	s_add_i32 m0, s2, 0x2000
	s_nop 0
	global_load_lds_dwordx4 v[228:229], off
	v_lshl_add_u64 v[228:229], s[64:65], 0, v[130:131]
	s_mov_b32 m0, s11
	s_nop 0
	global_load_lds_dwordx4 v[228:229], off
	s_mov_b32 m0, s31
	s_nop 0
	global_load_lds_dwordx4 v[230:231], off
	s_waitcnt vmcnt(8)
	s_waitcnt lgkmcnt(0)
	s_barrier
; #define PG8_STAGE(bufoff, gbase, voff) do { _Pragma("unroll") for (int _i = 0; _i < 2; ++_i) \
;         __builtin_amdgcn_global_load_lds((const unsigned*)((const char*)(gbase) + (voff)[_i]), (PG8_LAS unsigned*)(lds + (bufoff) + ldsw + _i * 8192), 16, 0, 0); } while (0)
; #define PG8_LDA(dst, b, h) do { _Pragma("unroll") for (int m = 0; m < 4; ++m) _Pragma("unroll") for (int k = 0; k < 2; ++k) dst[m][k] = *(const PG8_LAS bf16x8*)(lds + PG8_SA(b, h) + aoff + m * 2048 + k * 1024); } while (0)
; #define PG8_LDB(dst, b, h) do { _Pragma("unroll") for (int n = 0; n < 2; ++n) _Pragma("unroll") for (int k = 0; k < 2; ++k) dst[n][k] = *(const PG8_LAS bf16x8*)(lds + PG8_SB(b, h) + boff + n * 2048 + k * 1024); } while (0)
; #define PG8_MMA(ai, bj, At, Bt) do { __builtin_amdgcn_s_setprio(1); _Pragma("unroll") for (int m = 0; m < 4; ++m) _Pragma("unroll") for (int n = 0; n < 2; ++n) _Pragma("unroll") for (int k = 0; k < 2; ++k) \
;         acc[ai][bj][m][n] = __builtin_amdgcn_mfma_f32_16x16x32_bf16(Bt[n][k], At[m][k], acc[ai][bj][m][n], 0, 0, 0); __builtin_amdgcn_s_setprio(0); } while (0)
; #define PG8_WAIT_V(n) asm volatile("s_waitcnt vmcnt(" #n ")" ::: "memory")
; #define PG8_WAIT_L(n) asm volatile("s_waitcnt lgkmcnt(" #n ")" ::: "memory")
; #define PG8_BAR __builtin_amdgcn_s_barrier()
; #define PG8_SCHED __builtin_amdgcn_sched_barrier(0)
; template <class Epi, class Sched, bool ALIGN_EPI = false, bool SP2 = false>
; __device__ __forceinline__ void gemm_phase(PG8_LAS unsigned char* lds, const Gemm g, const Sched& S, const Epi& E) {
;     ...
;             PG8_WAIT_V(8); PG8_WAIT_L(0); PG8_BAR; PG8_MMA(1, 0, At, B0); PG8_MMA(1, 1, At, B1); PG8_BAR; PG8_SCHED;
;             PG8_LDB(B0, 1, 0); PG8_LDB(B1, 1, 1); PG8_SCHED; PG8_LDA(At, 1, 0); PG8_STAGE(PG8_SA(0, 1), a2 + hstep, voffA);
;             PG8_WAIT_V(8); PG8_WAIT_L(0); PG8_BAR; PG8_MMA(0, 0, At, B0); PG8_MMA(0, 1, At, B1); PG8_BAR; PG8_SCHED;
	s_waitcnt lgkmcnt(0)
	v_mfma_f32_16x16x32_bf16 v[80:83], v[158:161], v[192:195], v[80:83]
	v_mfma_f32_16x16x32_bf16 v[56:59], v[166:169], v[192:195], v[56:59]
	v_mfma_f32_16x16x32_bf16 v[64:67], v[158:161], v[200:203], v[64:67]
	v_mfma_f32_16x16x32_bf16 v[44:47], v[166:169], v[200:203], v[44:47]
	v_mfma_f32_16x16x32_bf16 v[52:55], v[158:161], v[208:211], v[52:55]
	v_mfma_f32_16x16x32_bf16 v[36:39], v[166:169], v[208:211], v[36:39]
	v_mfma_f32_16x16x32_bf16 v[40:43], v[158:161], v[216:219], v[40:43]
	v_mfma_f32_16x16x32_bf16 v[32:35], v[166:169], v[216:219], v[32:35]
	v_mfma_f32_16x16x32_bf16 v[80:83], v[162:165], v[196:199], v[80:83]
	v_mfma_f32_16x16x32_bf16 v[56:59], v[170:173], v[196:199], v[56:59]
	v_mfma_f32_16x16x32_bf16 v[64:67], v[162:165], v[204:207], v[64:67]
	v_mfma_f32_16x16x32_bf16 v[44:47], v[170:173], v[204:207], v[44:47]
	v_mfma_f32_16x16x32_bf16 v[52:55], v[162:165], v[212:215], v[52:55]
	v_mfma_f32_16x16x32_bf16 v[36:39], v[170:173], v[212:215], v[36:39]
	v_mfma_f32_16x16x32_bf16 v[40:43], v[162:165], v[220:223], v[40:43]
	v_mfma_f32_16x16x32_bf16 v[32:35], v[170:173], v[220:223], v[32:35]
	v_mfma_f32_16x16x32_bf16 v[28:31], v[176:179], v[192:195], v[28:31]
	v_mfma_f32_16x16x32_bf16 v[20:23], v[184:187], v[192:195], v[20:23]
	v_mfma_f32_16x16x32_bf16 v[24:27], v[176:179], v[200:203], v[24:27]
	v_mfma_f32_16x16x32_bf16 v[12:15], v[184:187], v[200:203], v[12:15]
	v_mfma_f32_16x16x32_bf16 v[16:19], v[176:179], v[208:211], v[16:19]
	v_mfma_f32_16x16x32_bf16 v[4:7], v[184:187], v[208:211], v[4:7]
	v_mfma_f32_16x16x32_bf16 v[8:11], v[176:179], v[216:219], v[8:11]
	v_mfma_f32_16x16x32_bf16 v[0:3], v[184:187], v[216:219], v[0:3]
	v_mfma_f32_16x16x32_bf16 v[28:31], v[180:183], v[196:199], v[28:31]
	v_mfma_f32_16x16x32_bf16 v[20:23], v[188:191], v[196:199], v[20:23]
	v_mfma_f32_16x16x32_bf16 v[24:27], v[180:183], v[204:207], v[24:27]
	v_mfma_f32_16x16x32_bf16 v[12:15], v[188:191], v[204:207], v[12:15]
	v_mfma_f32_16x16x32_bf16 v[16:19], v[180:183], v[212:215], v[16:19]
	v_mfma_f32_16x16x32_bf16 v[4:7], v[188:191], v[212:215], v[4:7]
	v_mfma_f32_16x16x32_bf16 v[8:11], v[180:183], v[220:223], v[8:11]
	v_mfma_f32_16x16x32_bf16 v[0:3], v[188:191], v[220:223], v[0:3]
	s_barrier
	s_add_i32 s2, 0, 0x18000
	v_add_u32_e32 v157, s2, v152
	s_add_i32 s68, 0, 0x1c000
	ds_read_b128 v[158:161], v157
	ds_read_b128 v[162:165], v157 offset:1024
	ds_read_b128 v[166:169], v157 offset:2048
	ds_read_b128 v[170:173], v157 offset:3072
	v_add_u32_e32 v157, s68, v152
	ds_read_b128 v[176:179], v157
	ds_read_b128 v[180:183], v157 offset:1024
	ds_read_b128 v[184:187], v157 offset:2048
	ds_read_b128 v[188:191], v157 offset:3072
	s_add_u32 s64, s64, 0x80000
	s_addc_u32 s65, s65, 0
	s_mov_b32 m0, s33
	v_lshl_add_u64 v[232:233], s[64:65], 0, v[130:131]
	ds_read_b128 v[192:195], v154 offset:32768
	ds_read_b128 v[196:199], v154 offset:33792
	ds_read_b128 v[200:203], v154 offset:34816
	ds_read_b128 v[204:207], v154 offset:35840
	ds_read_b128 v[208:211], v154 offset:36864
	ds_read_b128 v[212:215], v154 offset:37888
	ds_read_b128 v[216:219], v154 offset:38912
	ds_read_b128 v[220:223], v154 offset:39936
	global_load_lds_dwordx4 v[232:233], off
	v_lshl_add_u64 v[232:233], s[64:65], 0, v[128:129]
	s_mov_b32 m0, s66
	s_nop 0
	global_load_lds_dwordx4 v[232:233], off
	s_waitcnt vmcnt(8)
	s_waitcnt lgkmcnt(0)
	s_barrier
	s_waitcnt lgkmcnt(0)
	v_mfma_f32_16x16x32_bf16 v[124:127], v[158:161], v[192:195], v[124:127]
	v_mfma_f32_16x16x32_bf16 v[116:119], v[166:169], v[192:195], v[116:119]
	v_mfma_f32_16x16x32_bf16 v[120:123], v[158:161], v[200:203], v[120:123]
	v_mfma_f32_16x16x32_bf16 v[108:111], v[166:169], v[200:203], v[108:111]
	v_mfma_f32_16x16x32_bf16 v[112:115], v[158:161], v[208:211], v[112:115]
	v_mfma_f32_16x16x32_bf16 v[100:103], v[166:169], v[208:211], v[100:103]
	v_mfma_f32_16x16x32_bf16 v[104:107], v[158:161], v[216:219], v[104:107]
	v_mfma_f32_16x16x32_bf16 v[96:99], v[166:169], v[216:219], v[96:99]
	v_mfma_f32_16x16x32_bf16 v[124:127], v[162:165], v[196:199], v[124:127]
	v_mfma_f32_16x16x32_bf16 v[116:119], v[170:173], v[196:199], v[116:119]
	v_mfma_f32_16x16x32_bf16 v[120:123], v[162:165], v[204:207], v[120:123]
	v_mfma_f32_16x16x32_bf16 v[108:111], v[170:173], v[204:207], v[108:111]
	v_mfma_f32_16x16x32_bf16 v[112:115], v[162:165], v[212:215], v[112:115]
	v_mfma_f32_16x16x32_bf16 v[100:103], v[170:173], v[212:215], v[100:103]
	v_mfma_f32_16x16x32_bf16 v[104:107], v[162:165], v[220:223], v[104:107]
	v_mfma_f32_16x16x32_bf16 v[96:99], v[170:173], v[220:223], v[96:99]
	v_mfma_f32_16x16x32_bf16 v[92:95], v[176:179], v[192:195], v[92:95]
	v_mfma_f32_16x16x32_bf16 v[84:87], v[184:187], v[192:195], v[84:87]
	v_mfma_f32_16x16x32_bf16 v[88:91], v[176:179], v[200:203], v[88:91]
	v_mfma_f32_16x16x32_bf16 v[72:75], v[184:187], v[200:203], v[72:75]
	v_mfma_f32_16x16x32_bf16 v[76:79], v[176:179], v[208:211], v[76:79]
	v_mfma_f32_16x16x32_bf16 v[60:63], v[184:187], v[208:211], v[60:63]
	v_mfma_f32_16x16x32_bf16 v[68:71], v[176:179], v[216:219], v[68:71]
	v_mfma_f32_16x16x32_bf16 v[48:51], v[184:187], v[216:219], v[48:51]
	v_mfma_f32_16x16x32_bf16 v[92:95], v[180:183], v[196:199], v[92:95]
	v_mfma_f32_16x16x32_bf16 v[84:87], v[188:191], v[196:199], v[84:87]
	v_mfma_f32_16x16x32_bf16 v[88:91], v[180:183], v[204:207], v[88:91]
	v_mfma_f32_16x16x32_bf16 v[72:75], v[188:191], v[204:207], v[72:75]
	v_mfma_f32_16x16x32_bf16 v[76:79], v[180:183], v[212:215], v[76:79]
	v_mfma_f32_16x16x32_bf16 v[60:63], v[188:191], v[212:215], v[60:63]
	v_mfma_f32_16x16x32_bf16 v[68:71], v[180:183], v[220:223], v[68:71]
	v_mfma_f32_16x16x32_bf16 v[48:51], v[188:191], v[220:223], v[48:51]
	s_barrier
; #define PG8_STAGE(bufoff, gbase, voff) do { _Pragma("unroll") for (int _i = 0; _i < 2; ++_i) \
;         __builtin_amdgcn_global_load_lds((const unsigned*)((const char*)(gbase) + (voff)[_i]), (PG8_LAS unsigned*)(lds + (bufoff) + ldsw + _i * 8192), 16, 0, 0); } while (0)
; #define PG8_LDA(dst, b, h) do { _Pragma("unroll") for (int m = 0; m < 4; ++m) _Pragma("unroll") for (int k = 0; k < 2; ++k) dst[m][k] = *(const PG8_LAS bf16x8*)(lds + PG8_SA(b, h) + aoff + m * 2048 + k * 1024); } while (0)
; #define PG8_MMA(ai, bj, At, Bt) do { __builtin_amdgcn_s_setprio(1); _Pragma("unroll") for (int m = 0; m < 4; ++m) _Pragma("unroll") for (int n = 0; n < 2; ++n) _Pragma("unroll") for (int k = 0; k < 2; ++k) \
;         acc[ai][bj][m][n] = __builtin_amdgcn_mfma_f32_16x16x32_bf16(Bt[n][k], At[m][k], acc[ai][bj][m][n], 0, 0, 0); __builtin_amdgcn_s_setprio(0); } while (0)
; #define PG8_WAIT_V(n) asm volatile("s_waitcnt vmcnt(" #n ")" ::: "memory")
; #define PG8_WAIT_L(n) asm volatile("s_waitcnt lgkmcnt(" #n ")" ::: "memory")
; #define PG8_BAR __builtin_amdgcn_s_barrier()
; #define PG8_SCHED __builtin_amdgcn_sched_barrier(0)
; template <class Epi, class Sched, bool ALIGN_EPI = false, bool SP2 = false>
; __device__ __forceinline__ void gemm_phase(PG8_LAS unsigned char* lds, const Gemm g, const Sched& S, const Epi& E) {
;     ...
;             PG8_LDA(At, 1, 1); PG8_STAGE(PG8_SB(1, 0), b3, voffB); PG8_STAGE(PG8_SB(1, 1), b3 + hstep, voffB); PG8_STAGE(PG8_SA(1, 0), a3, voffA);
;             PG8_WAIT_V(8); PG8_WAIT_L(0); PG8_BAR; PG8_MMA(1, 0, At, B0); PG8_MMA(1, 1, At, B1); PG8_BAR; PG8_SCHED;
	s_add_i32 s2, s2, s29
	v_lshl_add_u64 v[224:225], v[224:225], 0, s[34:35]
	s_mov_b32 m0, s2
	ds_read_b128 v[192:195], v154 offset:49152
	ds_read_b128 v[196:199], v154 offset:50176
	ds_read_b128 v[200:203], v154 offset:51200
	ds_read_b128 v[204:207], v154 offset:52224
	ds_read_b128 v[208:211], v154 offset:53248
	ds_read_b128 v[212:215], v154 offset:54272
	ds_read_b128 v[216:219], v154 offset:55296
	ds_read_b128 v[220:223], v154 offset:56320
	global_load_lds_dwordx4 v[224:225], off
	s_add_i32 m0, s2, 0x2000
	s_add_u32 s62, s62, 0x80080
	v_lshl_add_u64 v[224:225], v[226:227], 0, s[34:35]
	s_addc_u32 s63, s63, 0
	s_add_i32 s2, s68, s29
	global_load_lds_dwordx4 v[224:225], off
	v_lshl_add_u64 v[224:225], s[62:63], 0, v[130:131]
	s_mov_b32 m0, s2
	s_nop 0
	global_load_lds_dwordx4 v[224:225], off
	v_lshl_add_u64 v[224:225], s[62:63], 0, v[128:129]
	s_add_i32 m0, s2, 0x2000
	s_nop 0
	global_load_lds_dwordx4 v[224:225], off
	v_lshl_add_u64 v[224:225], v[228:229], 0, s[34:35]
	s_mov_b32 m0, s76
	s_nop 0
	global_load_lds_dwordx4 v[224:225], off
	v_lshl_add_u64 v[224:225], v[230:231], 0, s[34:35]
	s_mov_b32 m0, s77
	s_nop 0
	global_load_lds_dwordx4 v[224:225], off
	s_waitcnt vmcnt(8)
	s_waitcnt lgkmcnt(0)
	s_barrier
	s_waitcnt lgkmcnt(0)
	v_mfma_f32_16x16x32_bf16 v[80:83], v[158:161], v[192:195], v[80:83]
	v_mfma_f32_16x16x32_bf16 v[56:59], v[166:169], v[192:195], v[56:59]
	v_mfma_f32_16x16x32_bf16 v[64:67], v[158:161], v[200:203], v[64:67]
	v_mfma_f32_16x16x32_bf16 v[44:47], v[166:169], v[200:203], v[44:47]
	v_mfma_f32_16x16x32_bf16 v[52:55], v[158:161], v[208:211], v[52:55]
	v_mfma_f32_16x16x32_bf16 v[36:39], v[166:169], v[208:211], v[36:39]
	v_mfma_f32_16x16x32_bf16 v[40:43], v[158:161], v[216:219], v[40:43]
	v_mfma_f32_16x16x32_bf16 v[32:35], v[166:169], v[216:219], v[32:35]
	v_mfma_f32_16x16x32_bf16 v[80:83], v[162:165], v[196:199], v[80:83]
	v_mfma_f32_16x16x32_bf16 v[56:59], v[170:173], v[196:199], v[56:59]
	v_mfma_f32_16x16x32_bf16 v[64:67], v[162:165], v[204:207], v[64:67]
	v_mfma_f32_16x16x32_bf16 v[44:47], v[170:173], v[204:207], v[44:47]
	v_mfma_f32_16x16x32_bf16 v[52:55], v[162:165], v[212:215], v[52:55]
	v_mfma_f32_16x16x32_bf16 v[36:39], v[170:173], v[212:215], v[36:39]
	v_mfma_f32_16x16x32_bf16 v[40:43], v[162:165], v[220:223], v[40:43]
	v_mfma_f32_16x16x32_bf16 v[32:35], v[170:173], v[220:223], v[32:35]
	v_mfma_f32_16x16x32_bf16 v[28:31], v[176:179], v[192:195], v[28:31]
	v_mfma_f32_16x16x32_bf16 v[20:23], v[184:187], v[192:195], v[20:23]
	v_mfma_f32_16x16x32_bf16 v[24:27], v[176:179], v[200:203], v[24:27]
	v_mfma_f32_16x16x32_bf16 v[12:15], v[184:187], v[200:203], v[12:15]
	v_mfma_f32_16x16x32_bf16 v[16:19], v[176:179], v[208:211], v[16:19]
	v_mfma_f32_16x16x32_bf16 v[4:7], v[184:187], v[208:211], v[4:7]
	v_mfma_f32_16x16x32_bf16 v[8:11], v[176:179], v[216:219], v[8:11]
	v_mfma_f32_16x16x32_bf16 v[0:3], v[184:187], v[216:219], v[0:3]
	v_mfma_f32_16x16x32_bf16 v[28:31], v[180:183], v[196:199], v[28:31]
	v_mfma_f32_16x16x32_bf16 v[20:23], v[188:191], v[196:199], v[20:23]
	v_mfma_f32_16x16x32_bf16 v[24:27], v[180:183], v[204:207], v[24:27]
	v_mfma_f32_16x16x32_bf16 v[12:15], v[188:191], v[204:207], v[12:15]
	v_mfma_f32_16x16x32_bf16 v[16:19], v[180:183], v[212:215], v[16:19]
	v_mfma_f32_16x16x32_bf16 v[4:7], v[188:191], v[212:215], v[4:7]
	v_mfma_f32_16x16x32_bf16 v[8:11], v[180:183], v[220:223], v[8:11]
	v_mfma_f32_16x16x32_bf16 v[0:3], v[188:191], v[220:223], v[0:3]
	s_barrier
	s_add_i32 s82, s82, 2
	s_add_u32 s60, s60, 0x100
	s_addc_u32 s61, s61, 0
	s_add_u32 s80, s80, 0x100
	s_addc_u32 s81, s81, 0
	s_cmp_gt_u32 s82, 5
	s_cbranch_scc0 .LBB0_1203
	s_and_b64 vcc, exec, s[42:43]
	s_cbranch_vccz .LBB0_1206
	s_barrier

; __device__ __forceinline__ void rwkv_proj_phase(const bf16* Z, const float* shift, const float* w0, const float* a0, const float* kkp, const float* kap, const float* rkp, ...
;     for (int it = blockIdx.x; it < 132 * 3; it += gridDim.x) {
;         int fr = lane & 15, g = lane >> 4;
;         asm volatile("" : "+v"(fr), "+v"(g));
;         const int tt = it / 3, hg = it % 3;
;         const int m = tt * 128 + wave * 16 + fr;
;         int b, tpos, len, s;
;         if (m < ML) { b = m >> 13; tpos = m & 8191; len = SEQ; s = CTXL + tpos; } else { b = (m - ML) >> 8; tpos = (m - ML) & 255; len = CTXL; s = tpos; }
;         const bool hp = tpos > 0, hn = tpos < len - 1;
;         const long offm = hp ? -(long)INCP : 0, offp = hn ? (long)INCP : 0; const float fm = hp ? 1.f : 0.f, fn = hn ? 1.f : 0.f;
;         const bf16* zr = Z + (size_t)m * INCP + ZB0;
;         bf16x8 xf[12];
; #pragma unroll
;         for (int ks = 0; ks < 12; ++ks) {
;             const int col = 2304 + 32 * ks + 8 * g;
;             const u32x4 c0 = *(const u32x4*)(zr + col), cm = *(const u32x4*)(zr + offm + col), cp = *(const u32x4*)(zr + offp + col);
;             float val[8];
; #pragma unroll
;             for (int q = 0; q < 2; ++q) { const f32x4 t0 = *(const f32x4*)(shift + col + 4 * q) * fm, t1 = *(const f32x4*)(shift + BCOLS + col + 4 * q), t2 = *(const f32x4*)(shift + 2 * BCOLS + col + 4 * q) * fn;
;                 const unsigned m0 = q ? cm.z : cm.x, m1 = q ? cm.w : cm.y, z0 = q ? c0.z : c0.x, z1 = q ? c0.w : c0.y, p0 = q ? cp.z : cp.x, p1 = q ? cp.w : cp.y;
;                 val[4 * q + 0] = t0.x * bflo(m0) + t1.x * bflo(z0) + t2.x * bflo(p0);
;                 val[4 * q + 1] = t0.y * bfhi(m0) + t1.y * bfhi(z0) + t2.y * bfhi(p0);
;                 val[4 * q + 2] = t0.z * bflo(m1) + t1.z * bflo(z1) + t2.z * bflo(p1);
;                 val[4 * q + 3] = t0.w * bfhi(m1) + t1.w * bfhi(z1) + t2.w * bfhi(p1); }
; #pragma unroll
;             for (int e = 0; e < 8; ++e) { if (ks < 4) val[e] = tanh_f(val[e]); else if (ks >= 8) val[e] = sigmoid_f(val[e]); }
;             u32x4 pk; pk.x = pk2(val[0], val[1]); pk.y = pk2(val[2], val[3]); pk.z = pk2(val[4], val[5]); pk.w = pk2(val[6], val[7]);
;             xf[ks] = __builtin_bit_cast(bf16x8, pk);
;             if (ks & 1) asm volatile("" ::: "memory");
;         }
; #pragma unroll 1
;         for (int hh = 0; hh < 4; ++hh) {
.LBB0_1319:
	s_setprio 0
	s_cmp_lt_i32 s72, 14
	s_cselect_b64 s[0:1], -1, 0
	s_cmp_gt_i32 s73, 13
	s_cselect_b64 s[4:5], -1, 0
	s_and_b64 s[0:1], s[0:1], s[4:5]
	s_andn2_b64 vcc, exec, s[0:1]
	s_cbranch_vccnz .LBB0_1464
	v_readfirstlane_b32 s3, v174
	s_lshr_b32 s49, s3, 6
	s_add_u32 s30, s70, 0xa900000
	v_and_b32_e32 v103, 63, v174
	s_addc_u32 s31, s71, 0
	v_readlane_b32 s0, v246, 0
	s_cmpk_gt_i32 s0, 0x18b
	v_lshrrev_b32_e32 v152, 4, v103
	s_cbranch_scc1 .LBB0_1331
	s_add_u32 s4, s38, 0x7e00
	s_addc_u32 s5, s39, 0
	s_add_u32 s8, s40, 0x1800
	s_addc_u32 s9, s41, 0
	s_add_u32 s10, s44, 0x1800
	s_addc_u32 s11, s45, 0
	s_add_u32 s34, s70, 0x16f00000
	s_addc_u32 s35, s71, 0
	s_add_u32 s0, s70, 0x28000000
	s_addc_u32 s1, s71, 0
	s_add_u32 s6, s70, 0x29900000
	s_addc_u32 s7, s71, 0
	s_lshl_b32 s52, s49, 4
	s_add_u32 s42, s38, 0xa800
	v_and_b32_e32 v153, 15, v174
	s_addc_u32 s43, s39, 0
	s_add_u32 s38, s38, 0xd200
	v_lshlrev_b32_e32 v88, 4, v153
	v_mov_b32_e32 v89, 0
	s_addc_u32 s39, s39, 0
	v_lshl_add_u64 v[0:1], s[70:71], 0, v[88:89]
	s_mov_b64 s[28:29], 0x6160000
	s_add_i32 s53, 0, 0x15800
	v_lshl_add_u64 v[90:91], v[0:1], 0, s[28:29]
	v_and_b32_e32 v0, 7, v174
	s_add_u32 s40, s40, 0x2400
	v_add_u32_e32 v2, s53, v88
	v_lshlrev_b32_e32 v88, 4, v0
	s_addc_u32 s41, s41, 0
	s_add_u32 s44, s44, 0x2400
	v_lshl_add_u64 v[0:1], s[70:71], 0, v[88:89]
	s_mov_b64 s[28:29], 0x6100000
	v_bfe_u32 v154, v174, 3, 6
	s_addc_u32 s45, s45, 0
	v_lshrrev_b32_e32 v3, 9, v174
	v_lshl_add_u64 v[92:93], v[0:1], 0, s[28:29]
	s_mov_b64 s[28:29], 0x6130000
	s_add_i32 s56, 0, 0x11000
	v_mul_u32_u24_e32 v155, 0x300, v3
	v_lshl_or_b32 v4, v3, 6, v154
	s_movk_i32 s55, 0x90
	v_xor_b32_e32 v3, 1, v3
	v_lshl_add_u64 v[94:95], v[0:1], 0, s[28:29]
	v_mov_b32_e32 v0, s56
	v_mad_u32_u24 v5, v4, s55, 0
	v_mul_u32_u24_e32 v156, 0x300, v3
	v_lshl_or_b32 v3, v3, 6, v154
	v_mad_u32_u24 v1, v4, s55, v0
	v_add_u32_e32 v4, 0x200, v174
	v_mad_u32_u24 v0, v3, s55, v0
	v_lshrrev_b32_e32 v157, 4, v174
	v_lshrrev_b32_e32 v158, 4, v4
	v_mad_u32_u24 v6, v3, s55, 0
	v_mul_u32_u24_e32 v3, 0x110, v157
	v_mul_u32_u24_e32 v4, 0x110, v158
	v_add_u32_e32 v164, v0, v88
	v_mbcnt_lo_u32_b32 v0, -1, 0
	s_movk_i32 s54, 0x300
	s_movk_i32 s57, 0x110
	s_movk_i32 s58, 0x3fff
	v_mov_b32_e32 v159, 0xffffd000
	s_movk_i32 s59, 0x3000
	v_mov_b32_e32 v160, 0x3000
	v_mov_b64_e32 v[96:97], s[30:31]
	s_mov_b64 s[46:47], 0x800
	s_mov_b32 s60, 0xffff0000
	s_movk_i32 s61, 0x7fff
	s_movk_i32 s62, 0x600
	v_mov_b64_e32 v[98:99], s[0:1]
	v_mov_b64_e32 v[100:101], s[6:7]
	s_mov_b32 s63, 0xaaaaaaab
	s_movk_i32 s64, 0x4000
	s_movk_i32 s65, 0x190
	v_add_u32_e32 v161, v5, v88
	v_add_u32_e32 v162, v6, v88
	v_add_u32_e32 v163, v1, v88
	v_add_u32_e32 v165, v2, v3
	v_add_u32_e32 v166, v2, v4
	s_movk_i32 s66, 0x2100
	s_movk_i32 s67, 0x480
	s_mov_b32 s48, 0xbf1b4598
	s_add_i32 s76, 0, 0xc800
	v_mov_b32_e32 v167, 0xff
	v_mov_b32_e32 v168, 0x1fff
	v_mbcnt_hi_u32_b32 v169, -1, v0
	v_mov_b32_e32 v170, 1
	v_readlane_b32 s77, v246, 0

;     __device__ __forceinline__ bool next(int i, pg8::Unit& u) const { const int L = i * G + c; if (L >= nM * nN * nS) return false; u.ks = L % nS; const int t = L / nS; u.pm = t % nM; u.pn = t / nM; return true; }
;     __host__ __device__ bool next(int i, Unit& u) const {
;         const long L = (long)i * G + c; if (L >= nwg) return false;
;         int wgid = (int)L; { const int q = nwg / NXCD, r = nwg % NXCD, xcd = wgid % NXCD, off = wgid / NXCD; wgid = (xcd < r ? xcd * (q + 1) : r * (q + 1) + (xcd - r) * q) + off; }
;     ...
;             pg8::Gemm g{AC, (bf16*)(ws + WS_WOUT), ML, D, D}; pg8::StaticOrder S; S.init(ML, D, (int)gridDim.x, (int)blockIdx.x, WGM_N2048);
;             EpiRes E{(l == 0) ? in.p[0] : (const float*)XL, (l == 0) ? in.p[2] : (const float*)XC, XL, XC, modl + 2 * D};
;             pg8::gemm_phase<EpiRes, pg8::StaticOrder, true, true>(lds, g, S, E); }
.LBB0_1747:
	s_cmp_lt_i32 s72, 17
	s_cselect_b64 s[0:1], -1, 0
	s_cmp_gt_i32 s73, 16
	s_cselect_b64 s[4:5], -1, 0
	s_and_b64 s[0:1], s[0:1], s[4:5]
	s_andn2_b64 vcc, exec, s[0:1]
	s_cbranch_vccnz .LBB0_1830
	v_readfirstlane_b32 vcc_lo, v174
	s_bitcmp1_b32 vcc_lo, 8
	s_cbranch_scc0 .Lsp_6
	s_setprio 1
.Lsp_6:
	v_readlane_b32 s0, v246, 0
	s_cmpk_gt_i32 s0, 0x1ff
	v_readfirstlane_b32 s4, v174
	s_cbranch_scc1 .LBB0_1776
	v_readlane_b32 s1, v246, 0
	s_ashr_i32 s3, s1, 31
	s_lshr_b32 s0, s3, 29
	s_add_i32 s6, s1, s0
	s_and_b32 s0, s6, -8
	s_sub_i32 s7, s1, s0
	s_cmp_gt_i32 s7, -1
	s_cbranch_scc0 .LBB0_1751
	s_lshl_b32 s5, s7, 6
	s_cbranch_execz .LBB0_1752
	s_branch .LBB0_1753

; #define PG8_STAGE(bufoff, gbase, voff) do { _Pragma("unroll") for (int _i = 0; _i < 2; ++_i) \
;         __builtin_amdgcn_global_load_lds((const unsigned*)((const char*)(gbase) + (voff)[_i]), (PG8_LAS unsigned*)(lds + (bufoff) + ldsw + _i * 8192), 16, 0, 0); } while (0)
; #define PG8_LDA(dst, b, h) do { _Pragma("unroll") for (int m = 0; m < 4; ++m) _Pragma("unroll") for (int k = 0; k < 2; ++k) dst[m][k] = *(const PG8_LAS bf16x8*)(lds + PG8_SA(b, h) + aoff + m * 2048 + k * 1024); } while (0)
; #define PG8_LDB(dst, b, h) do { _Pragma("unroll") for (int n = 0; n < 2; ++n) _Pragma("unroll") for (int k = 0; k < 2; ++k) dst[n][k] = *(const PG8_LAS bf16x8*)(lds + PG8_SB(b, h) + boff + n * 2048 + k * 1024); } while (0)
; #define PG8_MMA(ai, bj, At, Bt) do { __builtin_amdgcn_s_setprio(1); _Pragma("unroll") for (int m = 0; m < 4; ++m) _Pragma("unroll") for (int n = 0; n < 2; ++n) _Pragma("unroll") for (int k = 0; k < 2; ++k) \
;         acc[ai][bj][m][n] = __builtin_amdgcn_mfma_f32_16x16x32_bf16(Bt[n][k], At[m][k], acc[ai][bj][m][n], 0, 0, 0); __builtin_amdgcn_s_setprio(0); } while (0)
; #define PG8_WAIT_V(n) asm volatile("s_waitcnt vmcnt(" #n ")" ::: "memory")
; #define PG8_WAIT_L(n) asm volatile("s_waitcnt lgkmcnt(" #n ")" ::: "memory")
; #define PG8_BAR __builtin_amdgcn_s_barrier()
; #define PG8_SCHED __builtin_amdgcn_sched_barrier(0)
; template <class Epi, class Sched, bool ALIGN_EPI = false, bool SP2 = false>
; __device__ __forceinline__ void gemm_phase(PG8_LAS unsigned char* lds, const Gemm g, const Sched& S, const Epi& E) {
;     ...
;             const bool last = (t == nt - 2);
;             const char* a1 = cA + (size_t)(t + 1) * kstep;
;             const char* a2 = last ? nA : cA + (size_t)(t + 2) * kstep; const char* b2 = last ? nB : cB + (size_t)(t + 2) * kstep;
;             const char* a3 = a2 + kstep; const char* b3 = b2 + kstep;
;             if (last && has_next) S.a_ready(nxt);
;             if constexpr (SP2) {
;             PG8_LDB(B0, 0, 0); PG8_LDB(B1, 0, 1); PG8_SCHED; PG8_LDA(At, 0, 0); PG8_STAGE(PG8_SA(1, 1), a1 + hstep, voffA);
;             PG8_WAIT_V(8); PG8_WAIT_L(0); PG8_BAR; PG8_MMA(0, 0, At, B0); PG8_MMA(0, 1, At, B1); PG8_BAR; PG8_SCHED;
;             PG8_LDA(At, 0, 1); PG8_STAGE(PG8_SB(0, 0), b2, voffB); PG8_STAGE(PG8_SB(0, 1), b2 + hstep, voffB); PG8_STAGE(PG8_SA(0, 0), a2, voffA);
.LBB0_1765:
	ds_read_b128 v[128:131], v177
	ds_read_b128 v[132:135], v177 offset:1024
	ds_read_b128 v[136:139], v177 offset:2048
	ds_read_b128 v[140:143], v177 offset:3072
	ds_read_b128 v[180:183], v178
	ds_read_b128 v[184:187], v178 offset:1024
	ds_read_b128 v[188:191], v178 offset:2048
	ds_read_b128 v[192:195], v178 offset:3072
	s_add_u32 s2, s34, 0xfff80080
	s_addc_u32 s36, s35, -1
	s_cmp_eq_u32 s57, 28
	s_cselect_b32 s39, s4, s36
	s_cselect_b32 s38, s19, s2
	s_cselect_b32 s37, s17, s56
	s_cselect_b32 s36, s54, s55
	v_lshl_add_u64 v[172:173], s[34:35], 0, v[164:165]
	s_add_i32 m0, s31, 0xc000
	ds_read_b128 v[196:199], v179
	ds_read_b128 v[200:203], v179 offset:1024
	ds_read_b128 v[204:207], v179 offset:2048
	ds_read_b128 v[208:211], v179 offset:3072
	ds_read_b128 v[212:215], v179 offset:4096
	ds_read_b128 v[216:219], v179 offset:5120
	ds_read_b128 v[220:223], v179 offset:6144
	ds_read_b128 v[224:227], v179 offset:7168
	global_load_lds_dwordx4 v[172:173], off
	v_lshl_add_u64 v[172:173], s[34:35], 0, v[166:167]
	s_add_i32 m0, s31, 0xe000
	s_nop 0
	global_load_lds_dwordx4 v[172:173], off
	s_waitcnt vmcnt(8)
	s_waitcnt lgkmcnt(0)
	s_barrier
	s_waitcnt lgkmcnt(0)
	v_mfma_f32_16x16x32_bf16 v[124:127], v[128:131], v[196:199], v[124:127]
	v_mfma_f32_16x16x32_bf16 v[120:123], v[136:139], v[196:199], v[120:123]
	v_mfma_f32_16x16x32_bf16 v[108:111], v[128:131], v[204:207], v[108:111]
	v_mfma_f32_16x16x32_bf16 v[104:107], v[136:139], v[204:207], v[104:107]
	v_mfma_f32_16x16x32_bf16 v[92:95], v[128:131], v[212:215], v[92:95]
	v_mfma_f32_16x16x32_bf16 v[88:91], v[136:139], v[212:215], v[88:91]
	v_mfma_f32_16x16x32_bf16 v[76:79], v[128:131], v[220:223], v[76:79]
	v_mfma_f32_16x16x32_bf16 v[72:75], v[136:139], v[220:223], v[72:75]
	v_mfma_f32_16x16x32_bf16 v[124:127], v[132:135], v[200:203], v[124:127]
	v_mfma_f32_16x16x32_bf16 v[120:123], v[140:143], v[200:203], v[120:123]
	v_mfma_f32_16x16x32_bf16 v[108:111], v[132:135], v[208:211], v[108:111]
	v_mfma_f32_16x16x32_bf16 v[104:107], v[140:143], v[208:211], v[104:107]
	v_mfma_f32_16x16x32_bf16 v[92:95], v[132:135], v[216:219], v[92:95]
	v_mfma_f32_16x16x32_bf16 v[88:91], v[140:143], v[216:219], v[88:91]
	v_mfma_f32_16x16x32_bf16 v[76:79], v[132:135], v[224:227], v[76:79]
	v_mfma_f32_16x16x32_bf16 v[72:75], v[140:143], v[224:227], v[72:75]
	v_mfma_f32_16x16x32_bf16 v[116:119], v[180:183], v[196:199], v[116:119]
	v_mfma_f32_16x16x32_bf16 v[112:115], v[188:191], v[196:199], v[112:115]
	v_mfma_f32_16x16x32_bf16 v[100:103], v[180:183], v[204:207], v[100:103]
	v_mfma_f32_16x16x32_bf16 v[96:99], v[188:191], v[204:207], v[96:99]
	v_mfma_f32_16x16x32_bf16 v[84:87], v[180:183], v[212:215], v[84:87]
	v_mfma_f32_16x16x32_bf16 v[80:83], v[188:191], v[212:215], v[80:83]
	v_mfma_f32_16x16x32_bf16 v[68:71], v[180:183], v[220:223], v[68:71]
	v_mfma_f32_16x16x32_bf16 v[64:67], v[188:191], v[220:223], v[64:67]
	v_mfma_f32_16x16x32_bf16 v[116:119], v[184:187], v[200:203], v[116:119]
	v_mfma_f32_16x16x32_bf16 v[112:115], v[192:195], v[200:203], v[112:115]
	v_mfma_f32_16x16x32_bf16 v[100:103], v[184:187], v[208:211], v[100:103]
	v_mfma_f32_16x16x32_bf16 v[96:99], v[192:195], v[208:211], v[96:99]
	v_mfma_f32_16x16x32_bf16 v[84:87], v[184:187], v[216:219], v[84:87]
	v_mfma_f32_16x16x32_bf16 v[80:83], v[192:195], v[216:219], v[80:83]
	v_mfma_f32_16x16x32_bf16 v[68:71], v[184:187], v[224:227], v[68:71]
	v_mfma_f32_16x16x32_bf16 v[64:67], v[192:195], v[224:227], v[64:67]
	s_barrier
	s_add_i32 s2, s50, s29
	v_lshl_add_u64 v[172:173], s[36:37], 0, v[144:145]
	s_mov_b32 m0, s2
	ds_read_b128 v[196:199], v179 offset:16384
	ds_read_b128 v[200:203], v179 offset:17408
	ds_read_b128 v[204:207], v179 offset:18432
	ds_read_b128 v[208:211], v179 offset:19456
	ds_read_b128 v[212:215], v179 offset:20480
	ds_read_b128 v[216:219], v179 offset:21504
	ds_read_b128 v[220:223], v179 offset:22528
	ds_read_b128 v[224:227], v179 offset:23552
	global_load_lds_dwordx4 v[172:173], off
	s_add_i32 m0, s2, 0x2000
	s_add_u32 s58, s36, 0x80000
	v_lshl_add_u64 v[228:229], s[36:37], 0, v[146:147]
	s_addc_u32 s59, s37, 0
	s_add_i32 s2, s51, s29
	global_load_lds_dwordx4 v[228:229], off
	v_lshl_add_u64 v[230:231], s[58:59], 0, v[144:145]
	s_mov_b32 m0, s2
	v_lshl_add_u64 v[232:233], s[38:39], 0, v[146:147]
	global_load_lds_dwordx4 v[230:231], off
	v_lshl_add_u64 v[230:231], s[58:59], 0, v[146:147]
	s_add_i32 m0, s2, 0x2000
	s_nop 0
	global_load_lds_dwordx4 v[230:231], off
	v_lshl_add_u64 v[230:231], s[38:39], 0, v[144:145]
	s_mov_b32 m0, s31
	s_nop 0
	global_load_lds_dwordx4 v[230:231], off
	s_mov_b32 m0, s33
	s_nop 0
	global_load_lds_dwordx4 v[232:233], off
	s_waitcnt vmcnt(8)
	s_waitcnt lgkmcnt(0)
	s_barrier
; #define PG8_STAGE(bufoff, gbase, voff) do { _Pragma("unroll") for (int _i = 0; _i < 2; ++_i) \
;         __builtin_amdgcn_global_load_lds((const unsigned*)((const char*)(gbase) + (voff)[_i]), (PG8_LAS unsigned*)(lds + (bufoff) + ldsw + _i * 8192), 16, 0, 0); } while (0)
; #define PG8_LDA(dst, b, h) do { _Pragma("unroll") for (int m = 0; m < 4; ++m) _Pragma("unroll") for (int k = 0; k < 2; ++k) dst[m][k] = *(const PG8_LAS bf16x8*)(lds + PG8_SA(b, h) + aoff + m * 2048 + k * 1024); } while (0)
; #define PG8_LDB(dst, b, h) do { _Pragma("unroll") for (int n = 0; n < 2; ++n) _Pragma("unroll") for (int k = 0; k < 2; ++k) dst[n][k] = *(const PG8_LAS bf16x8*)(lds + PG8_SB(b, h) + boff + n * 2048 + k * 1024); } while (0)
; #define PG8_MMA(ai, bj, At, Bt) do { __builtin_amdgcn_s_setprio(1); _Pragma("unroll") for (int m = 0; m < 4; ++m) _Pragma("unroll") for (int n = 0; n < 2; ++n) _Pragma("unroll") for (int k = 0; k < 2; ++k) \
;         acc[ai][bj][m][n] = __builtin_amdgcn_mfma_f32_16x16x32_bf16(Bt[n][k], At[m][k], acc[ai][bj][m][n], 0, 0, 0); __builtin_amdgcn_s_setprio(0); } while (0)
; #define PG8_WAIT_V(n) asm volatile("s_waitcnt vmcnt(" #n ")" ::: "memory")
; #define PG8_WAIT_L(n) asm volatile("s_waitcnt lgkmcnt(" #n ")" ::: "memory")
; #define PG8_BAR __builtin_amdgcn_s_barrier()
; #define PG8_SCHED __builtin_amdgcn_sched_barrier(0)
; template <class Epi, class Sched, bool ALIGN_EPI = false, bool SP2 = false>
; __device__ __forceinline__ void gemm_phase(PG8_LAS unsigned char* lds, const Gemm g, const Sched& S, const Epi& E) {
;     ...
;             PG8_WAIT_V(8); PG8_WAIT_L(0); PG8_BAR; PG8_MMA(1, 0, At, B0); PG8_MMA(1, 1, At, B1); PG8_BAR; PG8_SCHED;
;             PG8_LDB(B0, 1, 0); PG8_LDB(B1, 1, 1); PG8_SCHED; PG8_LDA(At, 1, 0); PG8_STAGE(PG8_SA(0, 1), a2 + hstep, voffA);
;             PG8_WAIT_V(8); PG8_WAIT_L(0); PG8_BAR; PG8_MMA(0, 0, At, B0); PG8_MMA(0, 1, At, B1); PG8_BAR; PG8_SCHED;
	s_waitcnt lgkmcnt(0)
	v_mfma_f32_16x16x32_bf16 v[60:63], v[128:131], v[196:199], v[60:63]
	v_mfma_f32_16x16x32_bf16 v[56:59], v[136:139], v[196:199], v[56:59]
	v_mfma_f32_16x16x32_bf16 v[44:47], v[128:131], v[204:207], v[44:47]
	v_mfma_f32_16x16x32_bf16 v[40:43], v[136:139], v[204:207], v[40:43]
	v_mfma_f32_16x16x32_bf16 v[28:31], v[128:131], v[212:215], v[28:31]
	v_mfma_f32_16x16x32_bf16 v[24:27], v[136:139], v[212:215], v[24:27]
	v_mfma_f32_16x16x32_bf16 v[12:15], v[128:131], v[220:223], v[12:15]
	v_mfma_f32_16x16x32_bf16 v[8:11], v[136:139], v[220:223], v[8:11]
	v_mfma_f32_16x16x32_bf16 v[60:63], v[132:135], v[200:203], v[60:63]
	v_mfma_f32_16x16x32_bf16 v[56:59], v[140:143], v[200:203], v[56:59]
	v_mfma_f32_16x16x32_bf16 v[44:47], v[132:135], v[208:211], v[44:47]
	v_mfma_f32_16x16x32_bf16 v[40:43], v[140:143], v[208:211], v[40:43]
	v_mfma_f32_16x16x32_bf16 v[28:31], v[132:135], v[216:219], v[28:31]
	v_mfma_f32_16x16x32_bf16 v[24:27], v[140:143], v[216:219], v[24:27]
	v_mfma_f32_16x16x32_bf16 v[12:15], v[132:135], v[224:227], v[12:15]
	v_mfma_f32_16x16x32_bf16 v[8:11], v[140:143], v[224:227], v[8:11]
	v_mfma_f32_16x16x32_bf16 v[52:55], v[180:183], v[196:199], v[52:55]
	v_mfma_f32_16x16x32_bf16 v[48:51], v[188:191], v[196:199], v[48:51]
	v_mfma_f32_16x16x32_bf16 v[36:39], v[180:183], v[204:207], v[36:39]
	v_mfma_f32_16x16x32_bf16 v[32:35], v[188:191], v[204:207], v[32:35]
	v_mfma_f32_16x16x32_bf16 v[20:23], v[180:183], v[212:215], v[20:23]
	v_mfma_f32_16x16x32_bf16 v[16:19], v[188:191], v[212:215], v[16:19]
	v_mfma_f32_16x16x32_bf16 v[4:7], v[180:183], v[220:223], v[4:7]
	v_mfma_f32_16x16x32_bf16 v[0:3], v[188:191], v[220:223], v[0:3]
	v_mfma_f32_16x16x32_bf16 v[52:55], v[184:187], v[200:203], v[52:55]
	v_mfma_f32_16x16x32_bf16 v[48:51], v[192:195], v[200:203], v[48:51]
	v_mfma_f32_16x16x32_bf16 v[36:39], v[184:187], v[208:211], v[36:39]
	v_mfma_f32_16x16x32_bf16 v[32:35], v[192:195], v[208:211], v[32:35]
	v_mfma_f32_16x16x32_bf16 v[20:23], v[184:187], v[216:219], v[20:23]
	v_mfma_f32_16x16x32_bf16 v[16:19], v[192:195], v[216:219], v[16:19]
	v_mfma_f32_16x16x32_bf16 v[4:7], v[184:187], v[224:227], v[4:7]
	v_mfma_f32_16x16x32_bf16 v[0:3], v[192:195], v[224:227], v[0:3]
	s_barrier
	s_add_i32 s2, 0, 0x18000
	s_add_i32 s58, 0, 0x1c000
	v_add_u32_e32 v140, s2, v175
	v_add_u32_e32 v192, s58, v175
	ds_read_b128 v[128:131], v140
	ds_read_b128 v[132:135], v140 offset:1024
	ds_read_b128 v[136:139], v140 offset:2048
	ds_read_b128 v[140:143], v140 offset:3072
	ds_read_b128 v[180:183], v192
	ds_read_b128 v[184:187], v192 offset:1024
	ds_read_b128 v[188:191], v192 offset:2048
	ds_read_b128 v[192:195], v192 offset:3072
	s_add_u32 s38, s38, 0x80000
	s_addc_u32 s39, s39, 0
	s_mov_b32 m0, s40
	v_lshl_add_u64 v[234:235], s[38:39], 0, v[144:145]
	ds_read_b128 v[196:199], v179 offset:32768
	ds_read_b128 v[200:203], v179 offset:33792
	ds_read_b128 v[204:207], v179 offset:34816
	ds_read_b128 v[208:211], v179 offset:35840
	ds_read_b128 v[212:215], v179 offset:36864
	ds_read_b128 v[216:219], v179 offset:37888
	ds_read_b128 v[220:223], v179 offset:38912
	ds_read_b128 v[224:227], v179 offset:39936
	global_load_lds_dwordx4 v[234:235], off
	v_lshl_add_u64 v[234:235], s[38:39], 0, v[146:147]
	s_mov_b32 m0, s41
	s_nop 0
	global_load_lds_dwordx4 v[234:235], off
	s_waitcnt vmcnt(8)
	s_waitcnt lgkmcnt(0)
	s_barrier
	s_waitcnt lgkmcnt(0)
	v_mfma_f32_16x16x32_bf16 v[124:127], v[128:131], v[196:199], v[124:127]
	v_mfma_f32_16x16x32_bf16 v[120:123], v[136:139], v[196:199], v[120:123]
	v_mfma_f32_16x16x32_bf16 v[108:111], v[128:131], v[204:207], v[108:111]
	v_mfma_f32_16x16x32_bf16 v[104:107], v[136:139], v[204:207], v[104:107]
	v_mfma_f32_16x16x32_bf16 v[92:95], v[128:131], v[212:215], v[92:95]
	v_mfma_f32_16x16x32_bf16 v[88:91], v[136:139], v[212:215], v[88:91]
	v_mfma_f32_16x16x32_bf16 v[76:79], v[128:131], v[220:223], v[76:79]
	v_mfma_f32_16x16x32_bf16 v[72:75], v[136:139], v[220:223], v[72:75]
	v_mfma_f32_16x16x32_bf16 v[124:127], v[132:135], v[200:203], v[124:127]
	v_mfma_f32_16x16x32_bf16 v[120:123], v[140:143], v[200:203], v[120:123]
	v_mfma_f32_16x16x32_bf16 v[108:111], v[132:135], v[208:211], v[108:111]
	v_mfma_f32_16x16x32_bf16 v[104:107], v[140:143], v[208:211], v[104:107]
	v_mfma_f32_16x16x32_bf16 v[92:95], v[132:135], v[216:219], v[92:95]
	v_mfma_f32_16x16x32_bf16 v[88:91], v[140:143], v[216:219], v[88:91]
	v_mfma_f32_16x16x32_bf16 v[76:79], v[132:135], v[224:227], v[76:79]
	v_mfma_f32_16x16x32_bf16 v[72:75], v[140:143], v[224:227], v[72:75]
	v_mfma_f32_16x16x32_bf16 v[116:119], v[180:183], v[196:199], v[116:119]
	v_mfma_f32_16x16x32_bf16 v[112:115], v[188:191], v[196:199], v[112:115]
	v_mfma_f32_16x16x32_bf16 v[100:103], v[180:183], v[204:207], v[100:103]
	v_mfma_f32_16x16x32_bf16 v[96:99], v[188:191], v[204:207], v[96:99]
	v_mfma_f32_16x16x32_bf16 v[84:87], v[180:183], v[212:215], v[84:87]
	v_mfma_f32_16x16x32_bf16 v[80:83], v[188:191], v[212:215], v[80:83]
	v_mfma_f32_16x16x32_bf16 v[68:71], v[180:183], v[220:223], v[68:71]
	v_mfma_f32_16x16x32_bf16 v[64:67], v[188:191], v[220:223], v[64:67]
	v_mfma_f32_16x16x32_bf16 v[116:119], v[184:187], v[200:203], v[116:119]
	v_mfma_f32_16x16x32_bf16 v[112:115], v[192:195], v[200:203], v[112:115]
	v_mfma_f32_16x16x32_bf16 v[100:103], v[184:187], v[208:211], v[100:103]
	v_mfma_f32_16x16x32_bf16 v[96:99], v[192:195], v[208:211], v[96:99]
	v_mfma_f32_16x16x32_bf16 v[84:87], v[184:187], v[216:219], v[84:87]
	v_mfma_f32_16x16x32_bf16 v[80:83], v[192:195], v[216:219], v[80:83]
	v_mfma_f32_16x16x32_bf16 v[68:71], v[184:187], v[224:227], v[68:71]
	v_mfma_f32_16x16x32_bf16 v[64:67], v[192:195], v[224:227], v[64:67]
	s_barrier
; #define PG8_STAGE(bufoff, gbase, voff) do { _Pragma("unroll") for (int _i = 0; _i < 2; ++_i) \
;         __builtin_amdgcn_global_load_lds((const unsigned*)((const char*)(gbase) + (voff)[_i]), (PG8_LAS unsigned*)(lds + (bufoff) + ldsw + _i * 8192), 16, 0, 0); } while (0)
; #define PG8_LDA(dst, b, h) do { _Pragma("unroll") for (int m = 0; m < 4; ++m) _Pragma("unroll") for (int k = 0; k < 2; ++k) dst[m][k] = *(const PG8_LAS bf16x8*)(lds + PG8_SA(b, h) + aoff + m * 2048 + k * 1024); } while (0)
; #define PG8_MMA(ai, bj, At, Bt) do { __builtin_amdgcn_s_setprio(1); _Pragma("unroll") for (int m = 0; m < 4; ++m) _Pragma("unroll") for (int n = 0; n < 2; ++n) _Pragma("unroll") for (int k = 0; k < 2; ++k) \
;         acc[ai][bj][m][n] = __builtin_amdgcn_mfma_f32_16x16x32_bf16(Bt[n][k], At[m][k], acc[ai][bj][m][n], 0, 0, 0); __builtin_amdgcn_s_setprio(0); } while (0)
; #define PG8_WAIT_V(n) asm volatile("s_waitcnt vmcnt(" #n ")" ::: "memory")
; #define PG8_WAIT_L(n) asm volatile("s_waitcnt lgkmcnt(" #n ")" ::: "memory")
; #define PG8_BAR __builtin_amdgcn_s_barrier()
; #define PG8_SCHED __builtin_amdgcn_sched_barrier(0)
; template <class Epi, class Sched, bool ALIGN_EPI = false, bool SP2 = false>
; __device__ __forceinline__ void gemm_phase(PG8_LAS unsigned char* lds, const Gemm g, const Sched& S, const Epi& E) {
;     ...
;             PG8_LDA(At, 1, 1); PG8_STAGE(PG8_SB(1, 0), b3, voffB); PG8_STAGE(PG8_SB(1, 1), b3 + hstep, voffB); PG8_STAGE(PG8_SA(1, 0), a3, voffA);
;             PG8_WAIT_V(8); PG8_WAIT_L(0); PG8_BAR; PG8_MMA(1, 0, At, B0); PG8_MMA(1, 1, At, B1); PG8_BAR; PG8_SCHED;
	s_add_i32 s2, s2, s29
	v_lshl_add_u64 v[172:173], v[172:173], 0, s[10:11]
	s_mov_b32 m0, s2
	ds_read_b128 v[196:199], v179 offset:49152
	ds_read_b128 v[200:203], v179 offset:50176
	ds_read_b128 v[204:207], v179 offset:51200
	ds_read_b128 v[208:211], v179 offset:52224
	ds_read_b128 v[212:215], v179 offset:53248
	ds_read_b128 v[216:219], v179 offset:54272
	ds_read_b128 v[220:223], v179 offset:55296
	ds_read_b128 v[224:227], v179 offset:56320
	global_load_lds_dwordx4 v[172:173], off
	s_add_i32 m0, s2, 0x2000
	s_add_u32 s36, s36, 0x80080
	v_lshl_add_u64 v[172:173], v[228:229], 0, s[10:11]
	s_addc_u32 s37, s37, 0
	s_add_i32 s2, s58, s29
	global_load_lds_dwordx4 v[172:173], off
	v_lshl_add_u64 v[172:173], s[36:37], 0, v[144:145]
	s_mov_b32 m0, s2
	s_nop 0
	global_load_lds_dwordx4 v[172:173], off
	v_lshl_add_u64 v[172:173], s[36:37], 0, v[146:147]
	s_add_i32 m0, s2, 0x2000
	s_nop 0
	global_load_lds_dwordx4 v[172:173], off
	v_lshl_add_u64 v[172:173], v[230:231], 0, s[10:11]
	s_mov_b32 m0, s46
	s_nop 0
	global_load_lds_dwordx4 v[172:173], off
	v_lshl_add_u64 v[172:173], v[232:233], 0, s[10:11]
	s_mov_b32 m0, s47
	s_nop 0
	global_load_lds_dwordx4 v[172:173], off
	s_waitcnt vmcnt(8)
	s_waitcnt lgkmcnt(0)
	s_barrier
	s_waitcnt lgkmcnt(0)
	v_mfma_f32_16x16x32_bf16 v[60:63], v[128:131], v[196:199], v[60:63]
	v_mfma_f32_16x16x32_bf16 v[56:59], v[136:139], v[196:199], v[56:59]
	v_mfma_f32_16x16x32_bf16 v[44:47], v[128:131], v[204:207], v[44:47]
	v_mfma_f32_16x16x32_bf16 v[40:43], v[136:139], v[204:207], v[40:43]
	v_mfma_f32_16x16x32_bf16 v[28:31], v[128:131], v[212:215], v[28:31]
	v_mfma_f32_16x16x32_bf16 v[24:27], v[136:139], v[212:215], v[24:27]
	v_mfma_f32_16x16x32_bf16 v[12:15], v[128:131], v[220:223], v[12:15]
	v_mfma_f32_16x16x32_bf16 v[8:11], v[136:139], v[220:223], v[8:11]
	v_mfma_f32_16x16x32_bf16 v[60:63], v[132:135], v[200:203], v[60:63]
	v_mfma_f32_16x16x32_bf16 v[56:59], v[140:143], v[200:203], v[56:59]
	v_mfma_f32_16x16x32_bf16 v[44:47], v[132:135], v[208:211], v[44:47]
	v_mfma_f32_16x16x32_bf16 v[40:43], v[140:143], v[208:211], v[40:43]
	v_mfma_f32_16x16x32_bf16 v[28:31], v[132:135], v[216:219], v[28:31]
	v_mfma_f32_16x16x32_bf16 v[24:27], v[140:143], v[216:219], v[24:27]
	v_mfma_f32_16x16x32_bf16 v[12:15], v[132:135], v[224:227], v[12:15]
	v_mfma_f32_16x16x32_bf16 v[8:11], v[140:143], v[224:227], v[8:11]
	v_mfma_f32_16x16x32_bf16 v[52:55], v[180:183], v[196:199], v[52:55]
	v_mfma_f32_16x16x32_bf16 v[48:51], v[188:191], v[196:199], v[48:51]
	v_mfma_f32_16x16x32_bf16 v[36:39], v[180:183], v[204:207], v[36:39]
	v_mfma_f32_16x16x32_bf16 v[32:35], v[188:191], v[204:207], v[32:35]
	v_mfma_f32_16x16x32_bf16 v[20:23], v[180:183], v[212:215], v[20:23]
	v_mfma_f32_16x16x32_bf16 v[16:19], v[188:191], v[212:215], v[16:19]
	v_mfma_f32_16x16x32_bf16 v[4:7], v[180:183], v[220:223], v[4:7]
	v_mfma_f32_16x16x32_bf16 v[0:3], v[188:191], v[220:223], v[0:3]
	v_mfma_f32_16x16x32_bf16 v[52:55], v[184:187], v[200:203], v[52:55]
	v_mfma_f32_16x16x32_bf16 v[48:51], v[192:195], v[200:203], v[48:51]
	v_mfma_f32_16x16x32_bf16 v[36:39], v[184:187], v[208:211], v[36:39]
	v_mfma_f32_16x16x32_bf16 v[32:35], v[192:195], v[208:211], v[32:35]
	v_mfma_f32_16x16x32_bf16 v[20:23], v[184:187], v[216:219], v[20:23]
	v_mfma_f32_16x16x32_bf16 v[16:19], v[192:195], v[216:219], v[16:19]
	v_mfma_f32_16x16x32_bf16 v[4:7], v[184:187], v[224:227], v[4:7]
	v_mfma_f32_16x16x32_bf16 v[0:3], v[192:195], v[224:227], v[0:3]
	s_barrier
	s_add_i32 s57, s57, 2
	s_add_u32 s34, s34, 0x100
	s_addc_u32 s35, s35, 0
	s_add_u32 s55, s55, 0x100
	s_addc_u32 s56, s56, 0
	s_cmp_gt_u32 s57, 29
	s_cbranch_scc0 .LBB0_1765
	s_and_b64 vcc, exec, s[12:13]
	s_cbranch_vccz .LBB0_1768
	s_barrier

;     f32x4 nv[8];
;     if (gw < nrows) { const float* s0_ = (gw < ML) ? srcL + (size_t)gw * D : srcC + (size_t)(gw - ML) * D;
; #pragma unroll
;         for (int j = 0; j < 8; ++j) nv[j] = *(const f32x4*)(s0_ + lane * 4 + 256 * j); }
;     for (int m = gw; m < nrows; m += NGW) {
;         float* dst; int mv;
;         if (m < ML) { dst = dstL + (size_t)m * D; mv = (m >= SEQ) ? 1 : 0; }
;         else { dst = dstC + (size_t)(m - ML) * D; mv = 2; }
;         f32x4 v[8];
; #pragma unroll
;         for (int j = 0; j < 8; ++j) v[j] = nv[j];
;         { const int mn = m + NGW;
;           if (mn < nrows) { const float* s1_ = (mn < ML) ? srcL + (size_t)mn * D : srcC + (size_t)(mn - ML) * D;
; #pragma unroll
;               for (int j = 0; j < 8; ++j) nv[j] = *(const f32x4*)(s1_ + lane * 4 + 256 * j); } }
.LBB0_1830:
	s_setprio 0
	s_cmp_lt_i32 s72, 18
	s_cselect_b64 s[0:1], -1, 0
	s_cmp_gt_i32 s73, 17
	s_cselect_b64 s[4:5], -1, 0
	s_and_b64 s[0:1], s[0:1], s[4:5]
	s_andn2_b64 vcc, exec, s[0:1]
	s_cbranch_vccnz .LBB0_1890
	v_readfirstlane_b32 s0, v174
	v_readlane_b32 s1, v246, 0
	s_lshr_b32 s0, s0, 6
	s_lshl_b32 s1, s1, 3
	s_add_i32 s20, s0, s1
	s_cmpk_gt_i32 s20, 0x3fff
	s_cbranch_scc1 .LBB0_1836
	s_lshl_b32 s0, s74, 3
	s_add_u32 s3, s70, 0x24000
	s_addc_u32 s6, s71, 0
	s_ashr_i32 s21, s20, 31
	s_lshl_b64 s[4:5], s[20:21], 13
	v_lshlrev_b32_e32 v0, 2, v174
	s_add_u32 s4, s68, s4
	v_and_b32_e32 v0, 0xfc, v0
	s_addc_u32 s5, s69, s5
	s_waitcnt vmcnt(0)
	v_mov_b32_e32 v69, 0
	v_lshlrev_b32_e32 v68, 2, v0
	v_lshl_add_u64 v[2:3], s[4:5], 0, v[68:69]
	s_movk_i32 s7, 0x1000
	v_add_co_u32_e32 v2, vcc, s7, v2
	global_load_dwordx4 v[60:63], v68, s[4:5]
	global_load_dwordx4 v[56:59], v68, s[4:5] offset:1024
	global_load_dwordx4 v[52:55], v68, s[4:5] offset:2048
	global_load_dwordx4 v[48:51], v68, s[4:5] offset:3072
	v_addc_co_u32_e32 v3, vcc, 0, v3, vcc
	global_load_dwordx4 v[44:47], v[2:3], off
	global_load_dwordx4 v[40:43], v[2:3], off offset:1024
	global_load_dwordx4 v[36:39], v[2:3], off offset:2048
	global_load_dwordx4 v[32:35], v[2:3], off offset:3072
	v_readlane_b32 s36, v246, 39
	v_readlane_b32 s48, v246, 51
	v_readlane_b32 s49, v246, 52
	v_readlane_b32 s50, v246, 53
	v_readlane_b32 s51, v246, 54
	s_mov_b64 s[12:13], s[48:49]
	s_mov_b64 s[14:15], s[50:51]
	v_lshl_add_u64 v[2:3], s[12:13], 0, v[68:69]
	s_mov_b64 s[8:9], 0x2000
	v_lshl_add_u64 v[4:5], s[14:15], 0, v[68:69]
	v_lshl_add_u64 v[70:71], v[2:3], 0, s[8:9]
	v_lshl_add_u64 v[72:73], v[4:5], 0, s[8:9]
	s_mov_b64 s[8:9], 0x3000
	v_lshl_add_u64 v[74:75], v[2:3], 0, s[8:9]
	v_lshl_add_u64 v[76:77], v[4:5], 0, s[8:9]
	s_mov_b64 s[8:9], 0x3400
	v_lshl_add_u64 v[78:79], v[2:3], 0, s[8:9]
	v_lshl_add_u64 v[80:81], v[4:5], 0, s[8:9]
	s_mov_b64 s[8:9], 0x3800
	v_mbcnt_lo_u32_b32 v1, -1, 0
	v_lshl_add_u64 v[82:83], v[2:3], 0, s[8:9]
	v_lshl_add_u64 v[84:85], v[4:5], 0, s[8:9]
	s_mov_b64 s[8:9], 0x3c00
	v_mbcnt_hi_u32_b32 v1, -1, v1
	v_lshl_add_u64 v[86:87], v[2:3], 0, s[8:9]
	v_and_b32_e32 v2, 64, v1
	v_add_u32_e32 v2, 64, v2
	v_xor_b32_e32 v3, 1, v1
	v_cmp_lt_i32_e32 vcc, v3, v2
	v_lshl_add_u64 v[88:89], v[4:5], 0, s[8:9]
	s_add_i32 s8, s20, s0
	v_cndmask_b32_e32 v3, v1, v3, vcc
	v_lshlrev_b32_e32 v94, 2, v3
	v_xor_b32_e32 v3, 2, v1
	v_cmp_lt_i32_e32 vcc, v3, v2
	s_ashr_i32 s9, s8, 31
	s_lshl_b64 s[8:9], s[8:9], 13
	v_cndmask_b32_e32 v3, v1, v3, vcc
	v_lshlrev_b32_e32 v95, 2, v3
	v_xor_b32_e32 v3, 4, v1
	v_cmp_lt_i32_e32 vcc, v3, v2
	s_add_u32 s8, s68, s8
	s_addc_u32 s9, s69, s9
	v_cndmask_b32_e32 v3, v1, v3, vcc
	v_lshlrev_b32_e32 v96, 2, v3
	v_xor_b32_e32 v3, 8, v1
	v_cmp_lt_i32_e32 vcc, v3, v2
	s_ashr_i32 s1, s0, 31
	s_lshl_b64 s[10:11], s[0:1], 13
	v_cndmask_b32_e32 v3, v1, v3, vcc
	v_lshlrev_b32_e32 v97, 2, v3
	v_xor_b32_e32 v3, 16, v1
	v_cmp_lt_i32_e32 vcc, v3, v2
	s_lshl_b64 s[12:13], s[20:21], 12
	s_add_u32 s12, s70, s12
	v_cndmask_b32_e32 v3, v1, v3, vcc
	v_lshlrev_b32_e32 v98, 2, v3
	v_xor_b32_e32 v3, 32, v1
	v_cmp_lt_i32_e32 vcc, v3, v2
	s_addc_u32 s13, s71, s13
	v_mov_b32_e32 v91, v69
	v_cndmask_b32_e32 v1, v1, v3, vcc
	v_lshlrev_b32_e32 v99, 2, v1
	v_and_b32_e32 v1, 63, v174
	v_lshlrev_b32_e32 v68, 3, v1
	v_lshl_add_u64 v[2:3], s[12:13], 0, v[68:69]
	s_mov_b64 s[12:13], 0x6700000
	v_lshlrev_b32_e32 v90, 4, v1
	v_lshl_add_u64 v[92:93], v[2:3], 0, s[12:13]
	v_lshlrev_b32_e32 v68, 2, v0
	s_lshl_b64 s[12:13], s[0:1], 12
	v_mov_b32_e32 v100, 0x3727c5ac
	s_mov_b32 s1, 0x800000
	s_waitcnt vmcnt(7)
	v_mov_b64_e32 v[12:13], v[60:61]
	s_waitcnt vmcnt(6)
	v_mov_b64_e32 v[8:9], v[56:57]
	s_waitcnt vmcnt(5)
	v_mov_b64_e32 v[4:5], v[52:53]
	s_waitcnt vmcnt(3)
	v_mov_b64_e32 v[28:29], v[44:45]
	s_waitcnt vmcnt(2)
	v_mov_b64_e32 v[24:25], v[40:41]
	s_waitcnt vmcnt(1)
	v_mov_b64_e32 v[20:21], v[36:37]
	s_waitcnt vmcnt(0)
	v_mov_b64_e32 v[16:17], v[32:33]
	v_mov_b64_e32 v[0:1], v[48:49]
	s_mov_b64 s[14:15], 0x8000
	s_mov_b64 s[16:17], 0x6000
	s_movk_i32 s21, 0x7fff
	s_mov_b32 s22, 0xffff0000
	s_mov_b32 s23, 0x9000
	s_movk_i32 s24, 0x7000
	v_mov_b64_e32 v[18:19], v[34:35]
	v_mov_b64_e32 v[22:23], v[38:39]
	v_mov_b64_e32 v[26:27], v[42:43]
	v_mov_b64_e32 v[30:31], v[46:47]
	v_mov_b64_e32 v[2:3], v[50:51]
	v_mov_b64_e32 v[6:7], v[54:55]
	v_mov_b64_e32 v[10:11], v[58:59]
	v_mov_b64_e32 v[14:15], v[62:63]
	v_readlane_b32 s37, v246, 40
	v_readlane_b32 s38, v246, 41
	v_readlane_b32 s39, v246, 42
	v_readlane_b32 s40, v246, 43
	v_readlane_b32 s41, v246, 44
	v_readlane_b32 s42, v246, 45
	v_readlane_b32 s43, v246, 46
	v_readlane_b32 s44, v246, 47
	v_readlane_b32 s45, v246, 48
	v_readlane_b32 s46, v246, 49
	v_readlane_b32 s47, v246, 50
	s_branch .LBB0_1834

;     __device__ __forceinline__ bool next(int i, pg8::Unit& u) const { const int L = i * G + c; if (L >= nM * nN * nS) return false; u.ks = L % nS; const int t = L / nS; u.pm = t % nM; u.pn = t / nM; return true; }
;     __host__ __device__ bool next(int i, Unit& u) const {
;         const long L = (long)i * G + c; if (L >= nwg) return false;
;         int wgid = (int)L; { const int q = nwg / NXCD, r = nwg % NXCD, xcd = wgid % NXCD, off = wgid / NXCD; wgid = (xcd < r ? xcd * (q + 1) : r * (q + 1) + (xcd - r) * q) + off; }
;     ...
;             pg8::Gemm g{AC, (bf16*)(ws + WS_WUP), Mrows, DFF, D}; pg8::StaticOrder S; S.init(Mrows, DFF, (int)gridDim.x, (int)blockIdx.x, WGM_N8192);
;             EpiStoreBf16<1> E{(bf16*)(ws + WS_HM), DFF};
;             pg8::gemm_phase<EpiStoreBf16<1>, pg8::StaticOrder, true, true>(lds, g, S, E); }
.LBB0_1890:
	s_cmp_lt_i32 s72, 19
	s_cselect_b64 s[0:1], -1, 0
	s_cmp_gt_i32 s73, 18
	s_cselect_b64 s[4:5], -1, 0
	s_and_b64 s[0:1], s[0:1], s[4:5]
	s_andn2_b64 vcc, exec, s[0:1]
	s_cbranch_vccnz .LBB0_1969
	v_readfirstlane_b32 vcc_lo, v174
	s_bitcmp1_b32 vcc_lo, 8
	s_cbranch_scc0 .Lsp_7
	s_setprio 1
.Lsp_7:
	v_readlane_b32 s0, v246, 0
	s_cmpk_gt_i32 s0, 0x7ff
	v_readfirstlane_b32 s12, v174
	s_cbranch_scc1 .LBB0_1915
	v_readlane_b32 s1, v246, 0
	s_ashr_i32 s3, s1, 31
	s_lshr_b32 s0, s3, 29
	s_add_i32 s5, s1, s0
	s_and_b32 s0, s5, -8
	s_sub_i32 s6, s1, s0
	s_cmp_gt_i32 s6, -1
	s_cbranch_scc0 .LBB0_1894
	s_lshl_b32 s4, s6, 8
	s_cbranch_execz .LBB0_1895
	s_branch .LBB0_1896

; #define PG8_STAGE(bufoff, gbase, voff) do { _Pragma("unroll") for (int _i = 0; _i < 2; ++_i) \
;         __builtin_amdgcn_global_load_lds((const unsigned*)((const char*)(gbase) + (voff)[_i]), (PG8_LAS unsigned*)(lds + (bufoff) + ldsw + _i * 8192), 16, 0, 0); } while (0)
; #define PG8_LDA(dst, b, h) do { _Pragma("unroll") for (int m = 0; m < 4; ++m) _Pragma("unroll") for (int k = 0; k < 2; ++k) dst[m][k] = *(const PG8_LAS bf16x8*)(lds + PG8_SA(b, h) + aoff + m * 2048 + k * 1024); } while (0)
; #define PG8_LDB(dst, b, h) do { _Pragma("unroll") for (int n = 0; n < 2; ++n) _Pragma("unroll") for (int k = 0; k < 2; ++k) dst[n][k] = *(const PG8_LAS bf16x8*)(lds + PG8_SB(b, h) + boff + n * 2048 + k * 1024); } while (0)
; #define PG8_MMA(ai, bj, At, Bt) do { __builtin_amdgcn_s_setprio(1); _Pragma("unroll") for (int m = 0; m < 4; ++m) _Pragma("unroll") for (int n = 0; n < 2; ++n) _Pragma("unroll") for (int k = 0; k < 2; ++k) \
;         acc[ai][bj][m][n] = __builtin_amdgcn_mfma_f32_16x16x32_bf16(Bt[n][k], At[m][k], acc[ai][bj][m][n], 0, 0, 0); __builtin_amdgcn_s_setprio(0); } while (0)
; #define PG8_WAIT_V(n) asm volatile("s_waitcnt vmcnt(" #n ")" ::: "memory")
; #define PG8_WAIT_L(n) asm volatile("s_waitcnt lgkmcnt(" #n ")" ::: "memory")
; #define PG8_BAR __builtin_amdgcn_s_barrier()
; #define PG8_SCHED __builtin_amdgcn_sched_barrier(0)
; template <class Epi, class Sched, bool ALIGN_EPI = false, bool SP2 = false>
; __device__ __forceinline__ void gemm_phase(PG8_LAS unsigned char* lds, const Gemm g, const Sched& S, const Epi& E) {
;     ...
;             const bool last = (t == nt - 2);
;             const char* a1 = cA + (size_t)(t + 1) * kstep;
;             const char* a2 = last ? nA : cA + (size_t)(t + 2) * kstep; const char* b2 = last ? nB : cB + (size_t)(t + 2) * kstep;
;             const char* a3 = a2 + kstep; const char* b3 = b2 + kstep;
;             if (last && has_next) S.a_ready(nxt);
;             if constexpr (SP2) {
;             PG8_LDB(B0, 0, 0); PG8_LDB(B1, 0, 1); PG8_SCHED; PG8_LDA(At, 0, 0); PG8_STAGE(PG8_SA(1, 1), a1 + hstep, voffA);
;             PG8_WAIT_V(8); PG8_WAIT_L(0); PG8_BAR; PG8_MMA(0, 0, At, B0); PG8_MMA(0, 1, At, B1); PG8_BAR; PG8_SCHED;
;             PG8_LDA(At, 0, 1); PG8_STAGE(PG8_SB(0, 0), b2, voffB); PG8_STAGE(PG8_SB(0, 1), b2 + hstep, voffB); PG8_STAGE(PG8_SA(0, 0), a2, voffA);
.LBB0_1908:
	ds_read_b128 v[152:155], v149
	ds_read_b128 v[156:159], v149 offset:1024
	ds_read_b128 v[160:163], v149 offset:2048
	ds_read_b128 v[164:167], v149 offset:3072
	ds_read_b128 v[168:171], v150
	ds_read_b128 v[176:179], v150 offset:1024
	ds_read_b128 v[180:183], v150 offset:2048
	ds_read_b128 v[184:187], v150 offset:3072
	s_add_u32 s2, s36, 0xfff80080
	s_addc_u32 s38, s37, -1
	s_cmp_eq_u32 s61, 28
	s_cselect_b32 s41, s25, s38
	s_cselect_b32 s40, s57, s2
	s_cselect_b32 s39, s23, s60
	s_cselect_b32 s38, s58, s59
	v_lshl_add_u64 v[144:145], s[36:37], 0, v[136:137]
	s_add_i32 m0, s35, 0xc000
	ds_read_b128 v[188:191], v151
	ds_read_b128 v[192:195], v151 offset:1024
	ds_read_b128 v[196:199], v151 offset:2048
	ds_read_b128 v[200:203], v151 offset:3072
	ds_read_b128 v[204:207], v151 offset:4096
	ds_read_b128 v[208:211], v151 offset:5120
	ds_read_b128 v[212:215], v151 offset:6144
	ds_read_b128 v[216:219], v151 offset:7168
	global_load_lds_dwordx4 v[144:145], off
	v_lshl_add_u64 v[144:145], s[36:37], 0, v[138:139]
	s_add_i32 m0, s35, 0xe000
	s_nop 0
	global_load_lds_dwordx4 v[144:145], off
	s_waitcnt vmcnt(8)
	s_waitcnt lgkmcnt(0)
	s_barrier
	s_waitcnt lgkmcnt(0)
	v_mfma_f32_16x16x32_bf16 v[124:127], v[152:155], v[188:191], v[124:127]
	v_mfma_f32_16x16x32_bf16 v[120:123], v[160:163], v[188:191], v[120:123]
	v_mfma_f32_16x16x32_bf16 v[108:111], v[152:155], v[196:199], v[108:111]
	v_mfma_f32_16x16x32_bf16 v[104:107], v[160:163], v[196:199], v[104:107]
	v_mfma_f32_16x16x32_bf16 v[92:95], v[152:155], v[204:207], v[92:95]
	v_mfma_f32_16x16x32_bf16 v[88:91], v[160:163], v[204:207], v[88:91]
	v_mfma_f32_16x16x32_bf16 v[76:79], v[152:155], v[212:215], v[76:79]
	v_mfma_f32_16x16x32_bf16 v[72:75], v[160:163], v[212:215], v[72:75]
	v_mfma_f32_16x16x32_bf16 v[124:127], v[156:159], v[192:195], v[124:127]
	v_mfma_f32_16x16x32_bf16 v[120:123], v[164:167], v[192:195], v[120:123]
	v_mfma_f32_16x16x32_bf16 v[108:111], v[156:159], v[200:203], v[108:111]
	v_mfma_f32_16x16x32_bf16 v[104:107], v[164:167], v[200:203], v[104:107]
	v_mfma_f32_16x16x32_bf16 v[92:95], v[156:159], v[208:211], v[92:95]
	v_mfma_f32_16x16x32_bf16 v[88:91], v[164:167], v[208:211], v[88:91]
	v_mfma_f32_16x16x32_bf16 v[76:79], v[156:159], v[216:219], v[76:79]
	v_mfma_f32_16x16x32_bf16 v[72:75], v[164:167], v[216:219], v[72:75]
	v_mfma_f32_16x16x32_bf16 v[116:119], v[168:171], v[188:191], v[116:119]
	v_mfma_f32_16x16x32_bf16 v[112:115], v[180:183], v[188:191], v[112:115]
	v_mfma_f32_16x16x32_bf16 v[100:103], v[168:171], v[196:199], v[100:103]
	v_mfma_f32_16x16x32_bf16 v[96:99], v[180:183], v[196:199], v[96:99]
	v_mfma_f32_16x16x32_bf16 v[84:87], v[168:171], v[204:207], v[84:87]
	v_mfma_f32_16x16x32_bf16 v[80:83], v[180:183], v[204:207], v[80:83]
	v_mfma_f32_16x16x32_bf16 v[68:71], v[168:171], v[212:215], v[68:71]
	v_mfma_f32_16x16x32_bf16 v[64:67], v[180:183], v[212:215], v[64:67]
	v_mfma_f32_16x16x32_bf16 v[116:119], v[176:179], v[192:195], v[116:119]
	v_mfma_f32_16x16x32_bf16 v[112:115], v[184:187], v[192:195], v[112:115]
	v_mfma_f32_16x16x32_bf16 v[100:103], v[176:179], v[200:203], v[100:103]
	v_mfma_f32_16x16x32_bf16 v[96:99], v[184:187], v[200:203], v[96:99]
	v_mfma_f32_16x16x32_bf16 v[84:87], v[176:179], v[208:211], v[84:87]
	v_mfma_f32_16x16x32_bf16 v[80:83], v[184:187], v[208:211], v[80:83]
	v_mfma_f32_16x16x32_bf16 v[68:71], v[176:179], v[216:219], v[68:71]
	v_mfma_f32_16x16x32_bf16 v[64:67], v[184:187], v[216:219], v[64:67]
	s_barrier
	s_add_i32 s2, s50, s33
	v_lshl_add_u64 v[144:145], s[38:39], 0, v[130:131]
	s_mov_b32 m0, s2
	ds_read_b128 v[188:191], v151 offset:16384
	ds_read_b128 v[192:195], v151 offset:17408
	ds_read_b128 v[196:199], v151 offset:18432
	ds_read_b128 v[200:203], v151 offset:19456
	ds_read_b128 v[204:207], v151 offset:20480
	ds_read_b128 v[208:211], v151 offset:21504
	ds_read_b128 v[212:215], v151 offset:22528
	ds_read_b128 v[216:219], v151 offset:23552
	global_load_lds_dwordx4 v[144:145], off
	s_add_i32 m0, s2, 0x2000
	s_add_u32 s62, s38, 0x80000
	v_lshl_add_u64 v[172:173], s[38:39], 0, v[134:135]
	s_addc_u32 s63, s39, 0
	s_add_i32 s2, s51, s33
	global_load_lds_dwordx4 v[172:173], off
	v_lshl_add_u64 v[220:221], s[62:63], 0, v[130:131]
	s_mov_b32 m0, s2
	v_lshl_add_u64 v[222:223], s[40:41], 0, v[132:133]
	global_load_lds_dwordx4 v[220:221], off
	v_lshl_add_u64 v[220:221], s[62:63], 0, v[134:135]
	s_add_i32 m0, s2, 0x2000
	s_nop 0
	global_load_lds_dwordx4 v[220:221], off
	v_lshl_add_u64 v[220:221], s[40:41], 0, v[128:129]
	s_mov_b32 m0, s35
	s_nop 0
	global_load_lds_dwordx4 v[220:221], off
	s_mov_b32 m0, s42
	s_nop 0
	global_load_lds_dwordx4 v[222:223], off
	s_waitcnt vmcnt(8)
	s_waitcnt lgkmcnt(0)
	s_barrier
; #define PG8_STAGE(bufoff, gbase, voff) do { _Pragma("unroll") for (int _i = 0; _i < 2; ++_i) \
;         __builtin_amdgcn_global_load_lds((const unsigned*)((const char*)(gbase) + (voff)[_i]), (PG8_LAS unsigned*)(lds + (bufoff) + ldsw + _i * 8192), 16, 0, 0); } while (0)
; #define PG8_LDA(dst, b, h) do { _Pragma("unroll") for (int m = 0; m < 4; ++m) _Pragma("unroll") for (int k = 0; k < 2; ++k) dst[m][k] = *(const PG8_LAS bf16x8*)(lds + PG8_SA(b, h) + aoff + m * 2048 + k * 1024); } while (0)
; #define PG8_LDB(dst, b, h) do { _Pragma("unroll") for (int n = 0; n < 2; ++n) _Pragma("unroll") for (int k = 0; k < 2; ++k) dst[n][k] = *(const PG8_LAS bf16x8*)(lds + PG8_SB(b, h) + boff + n * 2048 + k * 1024); } while (0)
; #define PG8_MMA(ai, bj, At, Bt) do { __builtin_amdgcn_s_setprio(1); _Pragma("unroll") for (int m = 0; m < 4; ++m) _Pragma("unroll") for (int n = 0; n < 2; ++n) _Pragma("unroll") for (int k = 0; k < 2; ++k) \
;         acc[ai][bj][m][n] = __builtin_amdgcn_mfma_f32_16x16x32_bf16(Bt[n][k], At[m][k], acc[ai][bj][m][n], 0, 0, 0); __builtin_amdgcn_s_setprio(0); } while (0)
; #define PG8_WAIT_V(n) asm volatile("s_waitcnt vmcnt(" #n ")" ::: "memory")
; #define PG8_WAIT_L(n) asm volatile("s_waitcnt lgkmcnt(" #n ")" ::: "memory")
; #define PG8_BAR __builtin_amdgcn_s_barrier()
; #define PG8_SCHED __builtin_amdgcn_sched_barrier(0)
; template <class Epi, class Sched, bool ALIGN_EPI = false, bool SP2 = false>
; __device__ __forceinline__ void gemm_phase(PG8_LAS unsigned char* lds, const Gemm g, const Sched& S, const Epi& E) {
;     ...
;             PG8_WAIT_V(8); PG8_WAIT_L(0); PG8_BAR; PG8_MMA(1, 0, At, B0); PG8_MMA(1, 1, At, B1); PG8_BAR; PG8_SCHED;
;             PG8_LDB(B0, 1, 0); PG8_LDB(B1, 1, 1); PG8_SCHED; PG8_LDA(At, 1, 0); PG8_STAGE(PG8_SA(0, 1), a2 + hstep, voffA);
;             PG8_WAIT_V(8); PG8_WAIT_L(0); PG8_BAR; PG8_MMA(0, 0, At, B0); PG8_MMA(0, 1, At, B1); PG8_BAR; PG8_SCHED;
	s_waitcnt lgkmcnt(0)
	v_mfma_f32_16x16x32_bf16 v[60:63], v[152:155], v[188:191], v[60:63]
	v_mfma_f32_16x16x32_bf16 v[56:59], v[160:163], v[188:191], v[56:59]
	v_mfma_f32_16x16x32_bf16 v[44:47], v[152:155], v[196:199], v[44:47]
	v_mfma_f32_16x16x32_bf16 v[40:43], v[160:163], v[196:199], v[40:43]
	v_mfma_f32_16x16x32_bf16 v[28:31], v[152:155], v[204:207], v[28:31]
	v_mfma_f32_16x16x32_bf16 v[24:27], v[160:163], v[204:207], v[24:27]
	v_mfma_f32_16x16x32_bf16 v[12:15], v[152:155], v[212:215], v[12:15]
	v_mfma_f32_16x16x32_bf16 v[8:11], v[160:163], v[212:215], v[8:11]
	v_mfma_f32_16x16x32_bf16 v[60:63], v[156:159], v[192:195], v[60:63]
	v_mfma_f32_16x16x32_bf16 v[56:59], v[164:167], v[192:195], v[56:59]
	v_mfma_f32_16x16x32_bf16 v[44:47], v[156:159], v[200:203], v[44:47]
	v_mfma_f32_16x16x32_bf16 v[40:43], v[164:167], v[200:203], v[40:43]
	v_mfma_f32_16x16x32_bf16 v[28:31], v[156:159], v[208:211], v[28:31]
	v_mfma_f32_16x16x32_bf16 v[24:27], v[164:167], v[208:211], v[24:27]
	v_mfma_f32_16x16x32_bf16 v[12:15], v[156:159], v[216:219], v[12:15]
	v_mfma_f32_16x16x32_bf16 v[8:11], v[164:167], v[216:219], v[8:11]
	v_mfma_f32_16x16x32_bf16 v[52:55], v[168:171], v[188:191], v[52:55]
	v_mfma_f32_16x16x32_bf16 v[48:51], v[180:183], v[188:191], v[48:51]
	v_mfma_f32_16x16x32_bf16 v[36:39], v[168:171], v[196:199], v[36:39]
	v_mfma_f32_16x16x32_bf16 v[32:35], v[180:183], v[196:199], v[32:35]
	v_mfma_f32_16x16x32_bf16 v[20:23], v[168:171], v[204:207], v[20:23]
	v_mfma_f32_16x16x32_bf16 v[16:19], v[180:183], v[204:207], v[16:19]
	v_mfma_f32_16x16x32_bf16 v[4:7], v[168:171], v[212:215], v[4:7]
	v_mfma_f32_16x16x32_bf16 v[0:3], v[180:183], v[212:215], v[0:3]
	v_mfma_f32_16x16x32_bf16 v[52:55], v[176:179], v[192:195], v[52:55]
	v_mfma_f32_16x16x32_bf16 v[48:51], v[184:187], v[192:195], v[48:51]
	v_mfma_f32_16x16x32_bf16 v[36:39], v[176:179], v[200:203], v[36:39]
	v_mfma_f32_16x16x32_bf16 v[32:35], v[184:187], v[200:203], v[32:35]
	v_mfma_f32_16x16x32_bf16 v[20:23], v[176:179], v[208:211], v[20:23]
	v_mfma_f32_16x16x32_bf16 v[16:19], v[184:187], v[208:211], v[16:19]
	v_mfma_f32_16x16x32_bf16 v[4:7], v[176:179], v[216:219], v[4:7]
	v_mfma_f32_16x16x32_bf16 v[0:3], v[184:187], v[216:219], v[0:3]
	s_barrier
	s_add_i32 s2, 0, 0x18000
	s_add_i32 s62, 0, 0x1c000
	v_add_u32_e32 v164, s2, v147
	v_add_u32_e32 v175, s62, v147
	ds_read_b128 v[152:155], v164
	ds_read_b128 v[156:159], v164 offset:1024
	ds_read_b128 v[160:163], v164 offset:2048
	ds_read_b128 v[164:167], v164 offset:3072
	ds_read_b128 v[168:171], v175
	ds_read_b128 v[176:179], v175 offset:1024
	ds_read_b128 v[180:183], v175 offset:2048
	ds_read_b128 v[184:187], v175 offset:3072
	s_add_u32 s40, s40, 0x80000
	s_addc_u32 s41, s41, 0
	s_mov_b32 m0, s43
	v_lshl_add_u64 v[224:225], s[40:41], 0, v[128:129]
	ds_read_b128 v[188:191], v151 offset:32768
	ds_read_b128 v[192:195], v151 offset:33792
	ds_read_b128 v[196:199], v151 offset:34816
	ds_read_b128 v[200:203], v151 offset:35840
	ds_read_b128 v[204:207], v151 offset:36864
	ds_read_b128 v[208:211], v151 offset:37888
	ds_read_b128 v[212:215], v151 offset:38912
	ds_read_b128 v[216:219], v151 offset:39936
	global_load_lds_dwordx4 v[224:225], off
	v_lshl_add_u64 v[224:225], s[40:41], 0, v[132:133]
	s_mov_b32 m0, s44
	s_nop 0
	global_load_lds_dwordx4 v[224:225], off
	s_waitcnt vmcnt(8)
	s_waitcnt lgkmcnt(0)
	s_barrier
	s_waitcnt lgkmcnt(0)
	v_mfma_f32_16x16x32_bf16 v[124:127], v[152:155], v[188:191], v[124:127]
	v_mfma_f32_16x16x32_bf16 v[120:123], v[160:163], v[188:191], v[120:123]
	v_mfma_f32_16x16x32_bf16 v[108:111], v[152:155], v[196:199], v[108:111]
	v_mfma_f32_16x16x32_bf16 v[104:107], v[160:163], v[196:199], v[104:107]
	v_mfma_f32_16x16x32_bf16 v[92:95], v[152:155], v[204:207], v[92:95]
	v_mfma_f32_16x16x32_bf16 v[88:91], v[160:163], v[204:207], v[88:91]
	v_mfma_f32_16x16x32_bf16 v[76:79], v[152:155], v[212:215], v[76:79]
	v_mfma_f32_16x16x32_bf16 v[72:75], v[160:163], v[212:215], v[72:75]
	v_mfma_f32_16x16x32_bf16 v[124:127], v[156:159], v[192:195], v[124:127]
	v_mfma_f32_16x16x32_bf16 v[120:123], v[164:167], v[192:195], v[120:123]
	v_mfma_f32_16x16x32_bf16 v[108:111], v[156:159], v[200:203], v[108:111]
	v_mfma_f32_16x16x32_bf16 v[104:107], v[164:167], v[200:203], v[104:107]
	v_mfma_f32_16x16x32_bf16 v[92:95], v[156:159], v[208:211], v[92:95]
	v_mfma_f32_16x16x32_bf16 v[88:91], v[164:167], v[208:211], v[88:91]
	v_mfma_f32_16x16x32_bf16 v[76:79], v[156:159], v[216:219], v[76:79]
	v_mfma_f32_16x16x32_bf16 v[72:75], v[164:167], v[216:219], v[72:75]
	v_mfma_f32_16x16x32_bf16 v[116:119], v[168:171], v[188:191], v[116:119]
	v_mfma_f32_16x16x32_bf16 v[112:115], v[180:183], v[188:191], v[112:115]
	v_mfma_f32_16x16x32_bf16 v[100:103], v[168:171], v[196:199], v[100:103]
	v_mfma_f32_16x16x32_bf16 v[96:99], v[180:183], v[196:199], v[96:99]
	v_mfma_f32_16x16x32_bf16 v[84:87], v[168:171], v[204:207], v[84:87]
	v_mfma_f32_16x16x32_bf16 v[80:83], v[180:183], v[204:207], v[80:83]
	v_mfma_f32_16x16x32_bf16 v[68:71], v[168:171], v[212:215], v[68:71]
	v_mfma_f32_16x16x32_bf16 v[64:67], v[180:183], v[212:215], v[64:67]
	v_mfma_f32_16x16x32_bf16 v[116:119], v[176:179], v[192:195], v[116:119]
	v_mfma_f32_16x16x32_bf16 v[112:115], v[184:187], v[192:195], v[112:115]
	v_mfma_f32_16x16x32_bf16 v[100:103], v[176:179], v[200:203], v[100:103]
	v_mfma_f32_16x16x32_bf16 v[96:99], v[184:187], v[200:203], v[96:99]
	v_mfma_f32_16x16x32_bf16 v[84:87], v[176:179], v[208:211], v[84:87]
	v_mfma_f32_16x16x32_bf16 v[80:83], v[184:187], v[208:211], v[80:83]
	v_mfma_f32_16x16x32_bf16 v[68:71], v[176:179], v[216:219], v[68:71]
	v_mfma_f32_16x16x32_bf16 v[64:67], v[184:187], v[216:219], v[64:67]
	s_barrier
; #define PG8_STAGE(bufoff, gbase, voff) do { _Pragma("unroll") for (int _i = 0; _i < 2; ++_i) \
;         __builtin_amdgcn_global_load_lds((const unsigned*)((const char*)(gbase) + (voff)[_i]), (PG8_LAS unsigned*)(lds + (bufoff) + ldsw + _i * 8192), 16, 0, 0); } while (0)
; #define PG8_LDA(dst, b, h) do { _Pragma("unroll") for (int m = 0; m < 4; ++m) _Pragma("unroll") for (int k = 0; k < 2; ++k) dst[m][k] = *(const PG8_LAS bf16x8*)(lds + PG8_SA(b, h) + aoff + m * 2048 + k * 1024); } while (0)
; #define PG8_MMA(ai, bj, At, Bt) do { __builtin_amdgcn_s_setprio(1); _Pragma("unroll") for (int m = 0; m < 4; ++m) _Pragma("unroll") for (int n = 0; n < 2; ++n) _Pragma("unroll") for (int k = 0; k < 2; ++k) \
;         acc[ai][bj][m][n] = __builtin_amdgcn_mfma_f32_16x16x32_bf16(Bt[n][k], At[m][k], acc[ai][bj][m][n], 0, 0, 0); __builtin_amdgcn_s_setprio(0); } while (0)
; #define PG8_WAIT_V(n) asm volatile("s_waitcnt vmcnt(" #n ")" ::: "memory")
; #define PG8_WAIT_L(n) asm volatile("s_waitcnt lgkmcnt(" #n ")" ::: "memory")
; #define PG8_BAR __builtin_amdgcn_s_barrier()
; #define PG8_SCHED __builtin_amdgcn_sched_barrier(0)
; template <class Epi, class Sched, bool ALIGN_EPI = false, bool SP2 = false>
; __device__ __forceinline__ void gemm_phase(PG8_LAS unsigned char* lds, const Gemm g, const Sched& S, const Epi& E) {
;     ...
;             PG8_LDA(At, 1, 1); PG8_STAGE(PG8_SB(1, 0), b3, voffB); PG8_STAGE(PG8_SB(1, 1), b3 + hstep, voffB); PG8_STAGE(PG8_SA(1, 0), a3, voffA);
;             PG8_WAIT_V(8); PG8_WAIT_L(0); PG8_BAR; PG8_MMA(1, 0, At, B0); PG8_MMA(1, 1, At, B1); PG8_BAR; PG8_SCHED;
	s_add_i32 s2, s2, s33
	v_lshl_add_u64 v[144:145], v[144:145], 0, s[10:11]
	s_mov_b32 m0, s2
	ds_read_b128 v[188:191], v151 offset:49152
	ds_read_b128 v[192:195], v151 offset:50176
	ds_read_b128 v[196:199], v151 offset:51200
	ds_read_b128 v[200:203], v151 offset:52224
	ds_read_b128 v[204:207], v151 offset:53248
	ds_read_b128 v[208:211], v151 offset:54272
	ds_read_b128 v[212:215], v151 offset:55296
	ds_read_b128 v[216:219], v151 offset:56320
	global_load_lds_dwordx4 v[144:145], off
	s_add_i32 m0, s2, 0x2000
	s_add_u32 s38, s38, 0x80080
	v_lshl_add_u64 v[144:145], v[172:173], 0, s[10:11]
	s_addc_u32 s39, s39, 0
	s_add_i32 s2, s62, s33
	global_load_lds_dwordx4 v[144:145], off
	v_lshl_add_u64 v[144:145], s[38:39], 0, v[130:131]
	s_mov_b32 m0, s2
	s_nop 0
	global_load_lds_dwordx4 v[144:145], off
	v_lshl_add_u64 v[144:145], s[38:39], 0, v[134:135]
	s_add_i32 m0, s2, 0x2000
	s_nop 0
	global_load_lds_dwordx4 v[144:145], off
	v_lshl_add_u64 v[144:145], v[220:221], 0, s[10:11]
	s_mov_b32 m0, s46
	s_nop 0
	global_load_lds_dwordx4 v[144:145], off
	v_lshl_add_u64 v[144:145], v[222:223], 0, s[10:11]
	s_mov_b32 m0, s47
	s_nop 0
	global_load_lds_dwordx4 v[144:145], off
	s_waitcnt vmcnt(8)
	s_waitcnt lgkmcnt(0)
	s_barrier
	s_waitcnt lgkmcnt(0)
	v_mfma_f32_16x16x32_bf16 v[60:63], v[152:155], v[188:191], v[60:63]
	v_mfma_f32_16x16x32_bf16 v[56:59], v[160:163], v[188:191], v[56:59]
	v_mfma_f32_16x16x32_bf16 v[44:47], v[152:155], v[196:199], v[44:47]
	v_mfma_f32_16x16x32_bf16 v[40:43], v[160:163], v[196:199], v[40:43]
	v_mfma_f32_16x16x32_bf16 v[28:31], v[152:155], v[204:207], v[28:31]
	v_mfma_f32_16x16x32_bf16 v[24:27], v[160:163], v[204:207], v[24:27]
	v_mfma_f32_16x16x32_bf16 v[12:15], v[152:155], v[212:215], v[12:15]
	v_mfma_f32_16x16x32_bf16 v[8:11], v[160:163], v[212:215], v[8:11]
	v_mfma_f32_16x16x32_bf16 v[60:63], v[156:159], v[192:195], v[60:63]
	v_mfma_f32_16x16x32_bf16 v[56:59], v[164:167], v[192:195], v[56:59]
	v_mfma_f32_16x16x32_bf16 v[44:47], v[156:159], v[200:203], v[44:47]
	v_mfma_f32_16x16x32_bf16 v[40:43], v[164:167], v[200:203], v[40:43]
	v_mfma_f32_16x16x32_bf16 v[28:31], v[156:159], v[208:211], v[28:31]
	v_mfma_f32_16x16x32_bf16 v[24:27], v[164:167], v[208:211], v[24:27]
	v_mfma_f32_16x16x32_bf16 v[12:15], v[156:159], v[216:219], v[12:15]
	v_mfma_f32_16x16x32_bf16 v[8:11], v[164:167], v[216:219], v[8:11]
	v_mfma_f32_16x16x32_bf16 v[52:55], v[168:171], v[188:191], v[52:55]
	v_mfma_f32_16x16x32_bf16 v[48:51], v[180:183], v[188:191], v[48:51]
	v_mfma_f32_16x16x32_bf16 v[36:39], v[168:171], v[196:199], v[36:39]
	v_mfma_f32_16x16x32_bf16 v[32:35], v[180:183], v[196:199], v[32:35]
	v_mfma_f32_16x16x32_bf16 v[20:23], v[168:171], v[204:207], v[20:23]
	v_mfma_f32_16x16x32_bf16 v[16:19], v[180:183], v[204:207], v[16:19]
	v_mfma_f32_16x16x32_bf16 v[4:7], v[168:171], v[212:215], v[4:7]
	v_mfma_f32_16x16x32_bf16 v[0:3], v[180:183], v[212:215], v[0:3]
	v_mfma_f32_16x16x32_bf16 v[52:55], v[176:179], v[192:195], v[52:55]
	v_mfma_f32_16x16x32_bf16 v[48:51], v[184:187], v[192:195], v[48:51]
	v_mfma_f32_16x16x32_bf16 v[36:39], v[176:179], v[200:203], v[36:39]
	v_mfma_f32_16x16x32_bf16 v[32:35], v[184:187], v[200:203], v[32:35]
	v_mfma_f32_16x16x32_bf16 v[20:23], v[176:179], v[208:211], v[20:23]
	v_mfma_f32_16x16x32_bf16 v[16:19], v[184:187], v[208:211], v[16:19]
	v_mfma_f32_16x16x32_bf16 v[4:7], v[176:179], v[216:219], v[4:7]
	v_mfma_f32_16x16x32_bf16 v[0:3], v[184:187], v[216:219], v[0:3]
	s_barrier
	s_add_i32 s61, s61, 2
	s_add_u32 s36, s36, 0x100
	s_addc_u32 s37, s37, 0
	s_add_u32 s59, s59, 0x100
	s_addc_u32 s60, s60, 0
	s_cmp_gt_u32 s61, 29
	s_cbranch_scc0 .LBB0_1908
	s_and_b64 vcc, exec, s[12:13]
	s_cbranch_vccz .LBB0_1911
	s_barrier

;     __device__ __forceinline__ bool next(int i, pg8::Unit& u) const { const int L = i * G + c; if (L >= nM * nN * nS) return false; u.ks = L % nS; const int t = L / nS; u.pm = t % nM; u.pn = t / nM; return true; }
;     __host__ __device__ bool next(int i, Unit& u) const {
;         const long L = (long)i * G + c; if (L >= nwg) return false;
;         int wgid = (int)L; { const int q = nwg / NXCD, r = nwg % NXCD, xcd = wgid % NXCD, off = wgid / NXCD; wgid = (xcd < r ? xcd * (q + 1) : r * (q + 1) + (xcd - r) * q) + off; }
;     ...
;             pg8::Gemm g{(bf16*)(ws + WS_HM), (bf16*)(ws + WS_WDN), ML, D, DFF}; pg8::StaticOrder S; S.init(ML, D, (int)gridDim.x, (int)blockIdx.x, WGM_N2048);
;             EpiRes E{XL, XC, XL, XC, modl + 5 * D};
;             pg8::gemm_phase<EpiRes, pg8::StaticOrder, true, true>(lds, g, S, E); }
.LBB0_1969:
	s_setprio 0
	s_cmp_lt_i32 s72, 20
	s_cselect_b64 s[0:1], -1, 0
	s_cmp_gt_i32 s73, 19
	s_cselect_b64 s[4:5], -1, 0
	s_and_b64 s[0:1], s[0:1], s[4:5]
	s_andn2_b64 vcc, exec, s[0:1]
	s_cbranch_vccnz .LBB0_2052
	v_readfirstlane_b32 vcc_lo, v174
	s_bitcmp1_b32 vcc_lo, 8
	s_cbranch_scc0 .Lsp_8
	s_setprio 1
.Lsp_8:
	v_readlane_b32 s0, v246, 0
	s_cmpk_gt_i32 s0, 0x1ff
	v_readfirstlane_b32 s4, v174
	s_cbranch_scc1 .LBB0_1998
	v_readlane_b32 s1, v246, 0
	s_ashr_i32 s3, s1, 31
	s_lshr_b32 s0, s3, 29
	s_add_i32 s7, s1, s0
	s_and_b32 s0, s7, -8
	s_sub_i32 s6, s1, s0
	s_cmp_gt_i32 s6, -1
	s_cbranch_scc0 .LBB0_1973
	s_lshl_b32 s5, s6, 6
	s_ashr_i32 s0, s7, 3
	s_cbranch_execz .LBB0_1974
	s_branch .LBB0_1975

; #define PG8_STAGE(bufoff, gbase, voff) do { _Pragma("unroll") for (int _i = 0; _i < 2; ++_i) \
;         __builtin_amdgcn_global_load_lds((const unsigned*)((const char*)(gbase) + (voff)[_i]), (PG8_LAS unsigned*)(lds + (bufoff) + ldsw + _i * 8192), 16, 0, 0); } while (0)
; #define PG8_LDA(dst, b, h) do { _Pragma("unroll") for (int m = 0; m < 4; ++m) _Pragma("unroll") for (int k = 0; k < 2; ++k) dst[m][k] = *(const PG8_LAS bf16x8*)(lds + PG8_SA(b, h) + aoff + m * 2048 + k * 1024); } while (0)
; #define PG8_LDB(dst, b, h) do { _Pragma("unroll") for (int n = 0; n < 2; ++n) _Pragma("unroll") for (int k = 0; k < 2; ++k) dst[n][k] = *(const PG8_LAS bf16x8*)(lds + PG8_SB(b, h) + boff + n * 2048 + k * 1024); } while (0)
; #define PG8_MMA(ai, bj, At, Bt) do { __builtin_amdgcn_s_setprio(1); _Pragma("unroll") for (int m = 0; m < 4; ++m) _Pragma("unroll") for (int n = 0; n < 2; ++n) _Pragma("unroll") for (int k = 0; k < 2; ++k) \
;         acc[ai][bj][m][n] = __builtin_amdgcn_mfma_f32_16x16x32_bf16(Bt[n][k], At[m][k], acc[ai][bj][m][n], 0, 0, 0); __builtin_amdgcn_s_setprio(0); } while (0)
; #define PG8_WAIT_V(n) asm volatile("s_waitcnt vmcnt(" #n ")" ::: "memory")
; #define PG8_WAIT_L(n) asm volatile("s_waitcnt lgkmcnt(" #n ")" ::: "memory")
; #define PG8_BAR __builtin_amdgcn_s_barrier()
; #define PG8_SCHED __builtin_amdgcn_sched_barrier(0)
; template <class Epi, class Sched, bool ALIGN_EPI = false, bool SP2 = false>
; __device__ __forceinline__ void gemm_phase(PG8_LAS unsigned char* lds, const Gemm g, const Sched& S, const Epi& E) {
;     ...
;             PG8_LDB(B0, 0, 0); PG8_LDB(B1, 0, 1); PG8_SCHED; PG8_LDA(At, 0, 0); PG8_STAGE(PG8_SA(1, 1), a1 + hstep, voffA);
;             PG8_WAIT_V(8); PG8_WAIT_L(0); PG8_BAR; PG8_MMA(0, 0, At, B0); PG8_MMA(0, 1, At, B1); PG8_BAR; PG8_SCHED;
;             PG8_LDA(At, 0, 1); PG8_STAGE(PG8_SB(0, 0), b2, voffB); PG8_STAGE(PG8_SB(0, 1), b2 + hstep, voffB); PG8_STAGE(PG8_SA(0, 0), a2, voffA);
;             PG8_WAIT_V(8); PG8_WAIT_L(0); PG8_BAR; PG8_MMA(1, 0, At, B0); PG8_MMA(1, 1, At, B1); PG8_BAR; PG8_SCHED;
.LBB0_1987:
	ds_read_b128 v[128:131], v177
	ds_read_b128 v[132:135], v177 offset:1024
	ds_read_b128 v[136:139], v177 offset:2048
	ds_read_b128 v[140:143], v177 offset:3072
	ds_read_b128 v[180:183], v178
	ds_read_b128 v[184:187], v178 offset:1024
	ds_read_b128 v[188:191], v178 offset:2048
	ds_read_b128 v[192:195], v178 offset:3072
	s_add_u32 s2, s26, 0xffe00080
	s_addc_u32 s30, s27, -1
	s_cmpk_eq_i32 s53, 0x7c
	s_cselect_b32 s35, s4, s30
	s_cselect_b32 s34, s19, s2
	s_cselect_b32 s31, s17, s52
	s_cselect_b32 s30, s50, s51
	v_lshl_add_u64 v[172:173], s[26:27], 0, v[164:165]
	s_add_i32 m0, s25, 0xc000
	ds_read_b128 v[196:199], v179
	ds_read_b128 v[200:203], v179 offset:1024
	ds_read_b128 v[204:207], v179 offset:2048
	ds_read_b128 v[208:211], v179 offset:3072
	ds_read_b128 v[212:215], v179 offset:4096
	ds_read_b128 v[216:219], v179 offset:5120
	ds_read_b128 v[220:223], v179 offset:6144
	ds_read_b128 v[224:227], v179 offset:7168
	global_load_lds_dwordx4 v[172:173], off
	v_lshl_add_u64 v[172:173], s[26:27], 0, v[166:167]
	s_add_i32 m0, s25, 0xe000
	s_nop 0
	global_load_lds_dwordx4 v[172:173], off
	s_waitcnt vmcnt(8)
	s_waitcnt lgkmcnt(0)
	s_barrier
	s_waitcnt lgkmcnt(0)
	v_mfma_f32_16x16x32_bf16 v[124:127], v[128:131], v[196:199], v[124:127]
	v_mfma_f32_16x16x32_bf16 v[120:123], v[136:139], v[196:199], v[120:123]
	v_mfma_f32_16x16x32_bf16 v[108:111], v[128:131], v[204:207], v[108:111]
	v_mfma_f32_16x16x32_bf16 v[104:107], v[136:139], v[204:207], v[104:107]
	v_mfma_f32_16x16x32_bf16 v[92:95], v[128:131], v[212:215], v[92:95]
	v_mfma_f32_16x16x32_bf16 v[88:91], v[136:139], v[212:215], v[88:91]
	v_mfma_f32_16x16x32_bf16 v[76:79], v[128:131], v[220:223], v[76:79]
	v_mfma_f32_16x16x32_bf16 v[72:75], v[136:139], v[220:223], v[72:75]
	v_mfma_f32_16x16x32_bf16 v[124:127], v[132:135], v[200:203], v[124:127]
	v_mfma_f32_16x16x32_bf16 v[120:123], v[140:143], v[200:203], v[120:123]
	v_mfma_f32_16x16x32_bf16 v[108:111], v[132:135], v[208:211], v[108:111]
	v_mfma_f32_16x16x32_bf16 v[104:107], v[140:143], v[208:211], v[104:107]
	v_mfma_f32_16x16x32_bf16 v[92:95], v[132:135], v[216:219], v[92:95]
	v_mfma_f32_16x16x32_bf16 v[88:91], v[140:143], v[216:219], v[88:91]
	v_mfma_f32_16x16x32_bf16 v[76:79], v[132:135], v[224:227], v[76:79]
	v_mfma_f32_16x16x32_bf16 v[72:75], v[140:143], v[224:227], v[72:75]
	v_mfma_f32_16x16x32_bf16 v[116:119], v[180:183], v[196:199], v[116:119]
	v_mfma_f32_16x16x32_bf16 v[112:115], v[188:191], v[196:199], v[112:115]
	v_mfma_f32_16x16x32_bf16 v[100:103], v[180:183], v[204:207], v[100:103]
	v_mfma_f32_16x16x32_bf16 v[96:99], v[188:191], v[204:207], v[96:99]
	v_mfma_f32_16x16x32_bf16 v[84:87], v[180:183], v[212:215], v[84:87]
	v_mfma_f32_16x16x32_bf16 v[80:83], v[188:191], v[212:215], v[80:83]
	v_mfma_f32_16x16x32_bf16 v[68:71], v[180:183], v[220:223], v[68:71]
	v_mfma_f32_16x16x32_bf16 v[64:67], v[188:191], v[220:223], v[64:67]
	v_mfma_f32_16x16x32_bf16 v[116:119], v[184:187], v[200:203], v[116:119]
	v_mfma_f32_16x16x32_bf16 v[112:115], v[192:195], v[200:203], v[112:115]
	v_mfma_f32_16x16x32_bf16 v[100:103], v[184:187], v[208:211], v[100:103]
	v_mfma_f32_16x16x32_bf16 v[96:99], v[192:195], v[208:211], v[96:99]
	v_mfma_f32_16x16x32_bf16 v[84:87], v[184:187], v[216:219], v[84:87]
	v_mfma_f32_16x16x32_bf16 v[80:83], v[192:195], v[216:219], v[80:83]
	v_mfma_f32_16x16x32_bf16 v[68:71], v[184:187], v[224:227], v[68:71]
	v_mfma_f32_16x16x32_bf16 v[64:67], v[192:195], v[224:227], v[64:67]
	s_barrier
	s_add_i32 s2, s46, s29
	v_lshl_add_u64 v[172:173], s[30:31], 0, v[144:145]
	s_mov_b32 m0, s2
	ds_read_b128 v[196:199], v179 offset:16384
	ds_read_b128 v[200:203], v179 offset:17408
	ds_read_b128 v[204:207], v179 offset:18432
	ds_read_b128 v[208:211], v179 offset:19456
	ds_read_b128 v[212:215], v179 offset:20480
	ds_read_b128 v[216:219], v179 offset:21504
	ds_read_b128 v[220:223], v179 offset:22528
	ds_read_b128 v[224:227], v179 offset:23552
	global_load_lds_dwordx4 v[172:173], off
	s_add_i32 m0, s2, 0x2000
	s_add_u32 s54, s30, 0x200000
	v_lshl_add_u64 v[228:229], s[30:31], 0, v[146:147]
	s_addc_u32 s55, s31, 0
	s_add_i32 s2, s47, s29
	global_load_lds_dwordx4 v[228:229], off
	v_lshl_add_u64 v[230:231], s[54:55], 0, v[144:145]
	s_mov_b32 m0, s2
	v_lshl_add_u64 v[232:233], s[34:35], 0, v[146:147]
	global_load_lds_dwordx4 v[230:231], off
	v_lshl_add_u64 v[230:231], s[54:55], 0, v[146:147]
	s_add_i32 m0, s2, 0x2000
	s_nop 0
	global_load_lds_dwordx4 v[230:231], off
	v_lshl_add_u64 v[230:231], s[34:35], 0, v[144:145]
	s_mov_b32 m0, s25
	s_nop 0
	global_load_lds_dwordx4 v[230:231], off
	s_mov_b32 m0, s33
	s_nop 0
	global_load_lds_dwordx4 v[232:233], off
	s_waitcnt vmcnt(8)
	s_waitcnt lgkmcnt(0)
	s_barrier
; #define PG8_STAGE(bufoff, gbase, voff) do { _Pragma("unroll") for (int _i = 0; _i < 2; ++_i) \
;         __builtin_amdgcn_global_load_lds((const unsigned*)((const char*)(gbase) + (voff)[_i]), (PG8_LAS unsigned*)(lds + (bufoff) + ldsw + _i * 8192), 16, 0, 0); } while (0)
; #define PG8_LDA(dst, b, h) do { _Pragma("unroll") for (int m = 0; m < 4; ++m) _Pragma("unroll") for (int k = 0; k < 2; ++k) dst[m][k] = *(const PG8_LAS bf16x8*)(lds + PG8_SA(b, h) + aoff + m * 2048 + k * 1024); } while (0)
; #define PG8_LDB(dst, b, h) do { _Pragma("unroll") for (int n = 0; n < 2; ++n) _Pragma("unroll") for (int k = 0; k < 2; ++k) dst[n][k] = *(const PG8_LAS bf16x8*)(lds + PG8_SB(b, h) + boff + n * 2048 + k * 1024); } while (0)
; #define PG8_MMA(ai, bj, At, Bt) do { __builtin_amdgcn_s_setprio(1); _Pragma("unroll") for (int m = 0; m < 4; ++m) _Pragma("unroll") for (int n = 0; n < 2; ++n) _Pragma("unroll") for (int k = 0; k < 2; ++k) \
;         acc[ai][bj][m][n] = __builtin_amdgcn_mfma_f32_16x16x32_bf16(Bt[n][k], At[m][k], acc[ai][bj][m][n], 0, 0, 0); __builtin_amdgcn_s_setprio(0); } while (0)
; #define PG8_WAIT_V(n) asm volatile("s_waitcnt vmcnt(" #n ")" ::: "memory")
; #define PG8_WAIT_L(n) asm volatile("s_waitcnt lgkmcnt(" #n ")" ::: "memory")
; #define PG8_BAR __builtin_amdgcn_s_barrier()
; #define PG8_SCHED __builtin_amdgcn_sched_barrier(0)
; template <class Epi, class Sched, bool ALIGN_EPI = false, bool SP2 = false>
; __device__ __forceinline__ void gemm_phase(PG8_LAS unsigned char* lds, const Gemm g, const Sched& S, const Epi& E) {
;     ...
;             PG8_WAIT_V(8); PG8_WAIT_L(0); PG8_BAR; PG8_MMA(1, 0, At, B0); PG8_MMA(1, 1, At, B1); PG8_BAR; PG8_SCHED;
;             PG8_LDB(B0, 1, 0); PG8_LDB(B1, 1, 1); PG8_SCHED; PG8_LDA(At, 1, 0); PG8_STAGE(PG8_SA(0, 1), a2 + hstep, voffA);
;             PG8_WAIT_V(8); PG8_WAIT_L(0); PG8_BAR; PG8_MMA(0, 0, At, B0); PG8_MMA(0, 1, At, B1); PG8_BAR; PG8_SCHED;
	s_waitcnt lgkmcnt(0)
	v_mfma_f32_16x16x32_bf16 v[60:63], v[128:131], v[196:199], v[60:63]
	v_mfma_f32_16x16x32_bf16 v[56:59], v[136:139], v[196:199], v[56:59]
	v_mfma_f32_16x16x32_bf16 v[44:47], v[128:131], v[204:207], v[44:47]
	v_mfma_f32_16x16x32_bf16 v[40:43], v[136:139], v[204:207], v[40:43]
	v_mfma_f32_16x16x32_bf16 v[28:31], v[128:131], v[212:215], v[28:31]
	v_mfma_f32_16x16x32_bf16 v[24:27], v[136:139], v[212:215], v[24:27]
	v_mfma_f32_16x16x32_bf16 v[12:15], v[128:131], v[220:223], v[12:15]
	v_mfma_f32_16x16x32_bf16 v[8:11], v[136:139], v[220:223], v[8:11]
	v_mfma_f32_16x16x32_bf16 v[60:63], v[132:135], v[200:203], v[60:63]
	v_mfma_f32_16x16x32_bf16 v[56:59], v[140:143], v[200:203], v[56:59]
	v_mfma_f32_16x16x32_bf16 v[44:47], v[132:135], v[208:211], v[44:47]
	v_mfma_f32_16x16x32_bf16 v[40:43], v[140:143], v[208:211], v[40:43]
	v_mfma_f32_16x16x32_bf16 v[28:31], v[132:135], v[216:219], v[28:31]
	v_mfma_f32_16x16x32_bf16 v[24:27], v[140:143], v[216:219], v[24:27]
	v_mfma_f32_16x16x32_bf16 v[12:15], v[132:135], v[224:227], v[12:15]
	v_mfma_f32_16x16x32_bf16 v[8:11], v[140:143], v[224:227], v[8:11]
	v_mfma_f32_16x16x32_bf16 v[52:55], v[180:183], v[196:199], v[52:55]
	v_mfma_f32_16x16x32_bf16 v[48:51], v[188:191], v[196:199], v[48:51]
	v_mfma_f32_16x16x32_bf16 v[36:39], v[180:183], v[204:207], v[36:39]
	v_mfma_f32_16x16x32_bf16 v[32:35], v[188:191], v[204:207], v[32:35]
	v_mfma_f32_16x16x32_bf16 v[20:23], v[180:183], v[212:215], v[20:23]
	v_mfma_f32_16x16x32_bf16 v[16:19], v[188:191], v[212:215], v[16:19]
	v_mfma_f32_16x16x32_bf16 v[4:7], v[180:183], v[220:223], v[4:7]
	v_mfma_f32_16x16x32_bf16 v[0:3], v[188:191], v[220:223], v[0:3]
	v_mfma_f32_16x16x32_bf16 v[52:55], v[184:187], v[200:203], v[52:55]
	v_mfma_f32_16x16x32_bf16 v[48:51], v[192:195], v[200:203], v[48:51]
	v_mfma_f32_16x16x32_bf16 v[36:39], v[184:187], v[208:211], v[36:39]
	v_mfma_f32_16x16x32_bf16 v[32:35], v[192:195], v[208:211], v[32:35]
	v_mfma_f32_16x16x32_bf16 v[20:23], v[184:187], v[216:219], v[20:23]
	v_mfma_f32_16x16x32_bf16 v[16:19], v[192:195], v[216:219], v[16:19]
	v_mfma_f32_16x16x32_bf16 v[4:7], v[184:187], v[224:227], v[4:7]
	v_mfma_f32_16x16x32_bf16 v[0:3], v[192:195], v[224:227], v[0:3]
	s_barrier
	s_add_i32 s2, 0, 0x18000
	s_add_i32 s54, 0, 0x1c000
	v_add_u32_e32 v140, s2, v175
	v_add_u32_e32 v192, s54, v175
	ds_read_b128 v[128:131], v140
	ds_read_b128 v[132:135], v140 offset:1024
	ds_read_b128 v[136:139], v140 offset:2048
	ds_read_b128 v[140:143], v140 offset:3072
	ds_read_b128 v[180:183], v192
	ds_read_b128 v[184:187], v192 offset:1024
	ds_read_b128 v[188:191], v192 offset:2048
	ds_read_b128 v[192:195], v192 offset:3072
	s_add_u32 s34, s34, 0x200000
	s_addc_u32 s35, s35, 0
	s_mov_b32 m0, s36
	v_lshl_add_u64 v[234:235], s[34:35], 0, v[144:145]
	ds_read_b128 v[196:199], v179 offset:32768
	ds_read_b128 v[200:203], v179 offset:33792
	ds_read_b128 v[204:207], v179 offset:34816
	ds_read_b128 v[208:211], v179 offset:35840
	ds_read_b128 v[212:215], v179 offset:36864
	ds_read_b128 v[216:219], v179 offset:37888
	ds_read_b128 v[220:223], v179 offset:38912
	ds_read_b128 v[224:227], v179 offset:39936
	global_load_lds_dwordx4 v[234:235], off
	v_lshl_add_u64 v[234:235], s[34:35], 0, v[146:147]
	s_mov_b32 m0, s37
	s_nop 0
	global_load_lds_dwordx4 v[234:235], off
	s_waitcnt vmcnt(8)
	s_waitcnt lgkmcnt(0)
	s_barrier
	s_waitcnt lgkmcnt(0)
	v_mfma_f32_16x16x32_bf16 v[124:127], v[128:131], v[196:199], v[124:127]
	v_mfma_f32_16x16x32_bf16 v[120:123], v[136:139], v[196:199], v[120:123]
	v_mfma_f32_16x16x32_bf16 v[108:111], v[128:131], v[204:207], v[108:111]
	v_mfma_f32_16x16x32_bf16 v[104:107], v[136:139], v[204:207], v[104:107]
	v_mfma_f32_16x16x32_bf16 v[92:95], v[128:131], v[212:215], v[92:95]
	v_mfma_f32_16x16x32_bf16 v[88:91], v[136:139], v[212:215], v[88:91]
	v_mfma_f32_16x16x32_bf16 v[76:79], v[128:131], v[220:223], v[76:79]
	v_mfma_f32_16x16x32_bf16 v[72:75], v[136:139], v[220:223], v[72:75]
	v_mfma_f32_16x16x32_bf16 v[124:127], v[132:135], v[200:203], v[124:127]
	v_mfma_f32_16x16x32_bf16 v[120:123], v[140:143], v[200:203], v[120:123]
	v_mfma_f32_16x16x32_bf16 v[108:111], v[132:135], v[208:211], v[108:111]
	v_mfma_f32_16x16x32_bf16 v[104:107], v[140:143], v[208:211], v[104:107]
	v_mfma_f32_16x16x32_bf16 v[92:95], v[132:135], v[216:219], v[92:95]
	v_mfma_f32_16x16x32_bf16 v[88:91], v[140:143], v[216:219], v[88:91]
	v_mfma_f32_16x16x32_bf16 v[76:79], v[132:135], v[224:227], v[76:79]
	v_mfma_f32_16x16x32_bf16 v[72:75], v[140:143], v[224:227], v[72:75]
	v_mfma_f32_16x16x32_bf16 v[116:119], v[180:183], v[196:199], v[116:119]
	v_mfma_f32_16x16x32_bf16 v[112:115], v[188:191], v[196:199], v[112:115]
	v_mfma_f32_16x16x32_bf16 v[100:103], v[180:183], v[204:207], v[100:103]
	v_mfma_f32_16x16x32_bf16 v[96:99], v[188:191], v[204:207], v[96:99]
	v_mfma_f32_16x16x32_bf16 v[84:87], v[180:183], v[212:215], v[84:87]
	v_mfma_f32_16x16x32_bf16 v[80:83], v[188:191], v[212:215], v[80:83]
	v_mfma_f32_16x16x32_bf16 v[68:71], v[180:183], v[220:223], v[68:71]
	v_mfma_f32_16x16x32_bf16 v[64:67], v[188:191], v[220:223], v[64:67]
	v_mfma_f32_16x16x32_bf16 v[116:119], v[184:187], v[200:203], v[116:119]
	v_mfma_f32_16x16x32_bf16 v[112:115], v[192:195], v[200:203], v[112:115]
	v_mfma_f32_16x16x32_bf16 v[100:103], v[184:187], v[208:211], v[100:103]
	v_mfma_f32_16x16x32_bf16 v[96:99], v[192:195], v[208:211], v[96:99]
	v_mfma_f32_16x16x32_bf16 v[84:87], v[184:187], v[216:219], v[84:87]
	v_mfma_f32_16x16x32_bf16 v[80:83], v[192:195], v[216:219], v[80:83]
	v_mfma_f32_16x16x32_bf16 v[68:71], v[184:187], v[224:227], v[68:71]
	v_mfma_f32_16x16x32_bf16 v[64:67], v[192:195], v[224:227], v[64:67]
	s_barrier
; #define PG8_STAGE(bufoff, gbase, voff) do { _Pragma("unroll") for (int _i = 0; _i < 2; ++_i) \
;         __builtin_amdgcn_global_load_lds((const unsigned*)((const char*)(gbase) + (voff)[_i]), (PG8_LAS unsigned*)(lds + (bufoff) + ldsw + _i * 8192), 16, 0, 0); } while (0)
; #define PG8_LDA(dst, b, h) do { _Pragma("unroll") for (int m = 0; m < 4; ++m) _Pragma("unroll") for (int k = 0; k < 2; ++k) dst[m][k] = *(const PG8_LAS bf16x8*)(lds + PG8_SA(b, h) + aoff + m * 2048 + k * 1024); } while (0)
; #define PG8_MMA(ai, bj, At, Bt) do { __builtin_amdgcn_s_setprio(1); _Pragma("unroll") for (int m = 0; m < 4; ++m) _Pragma("unroll") for (int n = 0; n < 2; ++n) _Pragma("unroll") for (int k = 0; k < 2; ++k) \
;         acc[ai][bj][m][n] = __builtin_amdgcn_mfma_f32_16x16x32_bf16(Bt[n][k], At[m][k], acc[ai][bj][m][n], 0, 0, 0); __builtin_amdgcn_s_setprio(0); } while (0)
; #define PG8_WAIT_V(n) asm volatile("s_waitcnt vmcnt(" #n ")" ::: "memory")
; #define PG8_WAIT_L(n) asm volatile("s_waitcnt lgkmcnt(" #n ")" ::: "memory")
; #define PG8_BAR __builtin_amdgcn_s_barrier()
; #define PG8_SCHED __builtin_amdgcn_sched_barrier(0)
; template <class Epi, class Sched, bool ALIGN_EPI = false, bool SP2 = false>
; __device__ __forceinline__ void gemm_phase(PG8_LAS unsigned char* lds, const Gemm g, const Sched& S, const Epi& E) {
;     ...
;         for (int t = 0; t < nt; t += 2) {
;             const bool last = (t == nt - 2);
;             const char* a1 = cA + (size_t)(t + 1) * kstep;
;             const char* a2 = last ? nA : cA + (size_t)(t + 2) * kstep; const char* b2 = last ? nB : cB + (size_t)(t + 2) * kstep;
;             const char* a3 = a2 + kstep; const char* b3 = b2 + kstep;
;     ...
;             PG8_LDA(At, 1, 1); PG8_STAGE(PG8_SB(1, 0), b3, voffB); PG8_STAGE(PG8_SB(1, 1), b3 + hstep, voffB); PG8_STAGE(PG8_SA(1, 0), a3, voffA);
;             PG8_WAIT_V(8); PG8_WAIT_L(0); PG8_BAR; PG8_MMA(1, 0, At, B0); PG8_MMA(1, 1, At, B1); PG8_BAR; PG8_SCHED;
	s_add_i32 s2, s2, s29
	v_lshl_add_u64 v[172:173], v[172:173], 0, s[10:11]
	s_mov_b32 m0, s2
	ds_read_b128 v[196:199], v179 offset:49152
	ds_read_b128 v[200:203], v179 offset:50176
	ds_read_b128 v[204:207], v179 offset:51200
	ds_read_b128 v[208:211], v179 offset:52224
	ds_read_b128 v[212:215], v179 offset:53248
	ds_read_b128 v[216:219], v179 offset:54272
	ds_read_b128 v[220:223], v179 offset:55296
	ds_read_b128 v[224:227], v179 offset:56320
	global_load_lds_dwordx4 v[172:173], off
	s_add_i32 m0, s2, 0x2000
	s_add_u32 s30, s30, 0x200080
	v_lshl_add_u64 v[172:173], v[228:229], 0, s[10:11]
	s_addc_u32 s31, s31, 0
	s_add_i32 s2, s54, s29
	global_load_lds_dwordx4 v[172:173], off
	v_lshl_add_u64 v[172:173], s[30:31], 0, v[144:145]
	s_mov_b32 m0, s2
	s_nop 0
	global_load_lds_dwordx4 v[172:173], off
	v_lshl_add_u64 v[172:173], s[30:31], 0, v[146:147]
	s_add_i32 m0, s2, 0x2000
	s_nop 0
	global_load_lds_dwordx4 v[172:173], off
	v_lshl_add_u64 v[172:173], v[230:231], 0, s[10:11]
	s_mov_b32 m0, s42
	s_nop 0
	global_load_lds_dwordx4 v[172:173], off
	v_lshl_add_u64 v[172:173], v[232:233], 0, s[10:11]
	s_mov_b32 m0, s43
	s_nop 0
	global_load_lds_dwordx4 v[172:173], off
	s_waitcnt vmcnt(8)
	s_waitcnt lgkmcnt(0)
	s_barrier
	s_waitcnt lgkmcnt(0)
	v_mfma_f32_16x16x32_bf16 v[60:63], v[128:131], v[196:199], v[60:63]
	v_mfma_f32_16x16x32_bf16 v[56:59], v[136:139], v[196:199], v[56:59]
	v_mfma_f32_16x16x32_bf16 v[44:47], v[128:131], v[204:207], v[44:47]
	v_mfma_f32_16x16x32_bf16 v[40:43], v[136:139], v[204:207], v[40:43]
	v_mfma_f32_16x16x32_bf16 v[28:31], v[128:131], v[212:215], v[28:31]
	v_mfma_f32_16x16x32_bf16 v[24:27], v[136:139], v[212:215], v[24:27]
	v_mfma_f32_16x16x32_bf16 v[12:15], v[128:131], v[220:223], v[12:15]
	v_mfma_f32_16x16x32_bf16 v[8:11], v[136:139], v[220:223], v[8:11]
	v_mfma_f32_16x16x32_bf16 v[60:63], v[132:135], v[200:203], v[60:63]
	v_mfma_f32_16x16x32_bf16 v[56:59], v[140:143], v[200:203], v[56:59]
	v_mfma_f32_16x16x32_bf16 v[44:47], v[132:135], v[208:211], v[44:47]
	v_mfma_f32_16x16x32_bf16 v[40:43], v[140:143], v[208:211], v[40:43]
	v_mfma_f32_16x16x32_bf16 v[28:31], v[132:135], v[216:219], v[28:31]
	v_mfma_f32_16x16x32_bf16 v[24:27], v[140:143], v[216:219], v[24:27]
	v_mfma_f32_16x16x32_bf16 v[12:15], v[132:135], v[224:227], v[12:15]
	v_mfma_f32_16x16x32_bf16 v[8:11], v[140:143], v[224:227], v[8:11]
	v_mfma_f32_16x16x32_bf16 v[52:55], v[180:183], v[196:199], v[52:55]
	v_mfma_f32_16x16x32_bf16 v[48:51], v[188:191], v[196:199], v[48:51]
	v_mfma_f32_16x16x32_bf16 v[36:39], v[180:183], v[204:207], v[36:39]
	v_mfma_f32_16x16x32_bf16 v[32:35], v[188:191], v[204:207], v[32:35]
	v_mfma_f32_16x16x32_bf16 v[20:23], v[180:183], v[212:215], v[20:23]
	v_mfma_f32_16x16x32_bf16 v[16:19], v[188:191], v[212:215], v[16:19]
	v_mfma_f32_16x16x32_bf16 v[4:7], v[180:183], v[220:223], v[4:7]
	v_mfma_f32_16x16x32_bf16 v[0:3], v[188:191], v[220:223], v[0:3]
	v_mfma_f32_16x16x32_bf16 v[52:55], v[184:187], v[200:203], v[52:55]
	v_mfma_f32_16x16x32_bf16 v[48:51], v[192:195], v[200:203], v[48:51]
	v_mfma_f32_16x16x32_bf16 v[36:39], v[184:187], v[208:211], v[36:39]
	v_mfma_f32_16x16x32_bf16 v[32:35], v[192:195], v[208:211], v[32:35]
	v_mfma_f32_16x16x32_bf16 v[20:23], v[184:187], v[216:219], v[20:23]
	v_mfma_f32_16x16x32_bf16 v[16:19], v[192:195], v[216:219], v[16:19]
	v_mfma_f32_16x16x32_bf16 v[4:7], v[184:187], v[224:227], v[4:7]
	v_mfma_f32_16x16x32_bf16 v[0:3], v[192:195], v[224:227], v[0:3]
	s_barrier
	s_add_i32 s53, s53, 2
	s_add_u32 s26, s26, 0x100
	s_addc_u32 s27, s27, 0
	s_add_u32 s51, s51, 0x100
	s_addc_u32 s52, s52, 0
	s_cmpk_gt_u32 s53, 0x7d
	s_cbranch_scc0 .LBB0_1987
	s_and_b64 vcc, exec, s[12:13]
	s_cbranch_vccz .LBB0_1990
	s_barrier

; __device__ __forceinline__ float wave_sum(float v) {
; #pragma unroll
;     for (int o = 1; o < 64; o <<= 1) v += __shfl_xor(v, o);
;     return v;
;     f32x4 nv[8];
;     if (gw < nrows) { const float* s0_ = (gw < ML) ? srcL + (size_t)gw * D : srcC + (size_t)(gw - ML) * D;
; #pragma unroll
;         for (int j = 0; j < 8; ++j) nv[j] = *(const f32x4*)(s0_ + lane * 4 + 256 * j); }
;     for (int m = gw; m < nrows; m += NGW) {
;         float* dst; int mv;
;         if (m < ML) { dst = dstL + (size_t)m * D; mv = (m >= SEQ) ? 1 : 0; }
;         else { dst = dstC + (size_t)(m - ML) * D; mv = 2; }
;         f32x4 v[8];
; #pragma unroll
;         for (int j = 0; j < 8; ++j) v[j] = nv[j];
;         { const int mn = m + NGW;
;           if (mn < nrows) { const float* s1_ = (mn < ML) ? srcL + (size_t)mn * D : srcC + (size_t)(mn - ML) * D;
; #pragma unroll
;               for (int j = 0; j < 8; ++j) nv[j] = *(const f32x4*)(s1_ + lane * 4 + 256 * j); } }
.LBB0_2052:
	s_setprio 0
	s_cmp_lt_i32 s72, 21
	s_cselect_b64 s[0:1], -1, 0
	s_cmp_gt_i32 s73, 20
	s_cselect_b64 s[4:5], -1, 0
	s_and_b64 s[0:1], s[0:1], s[4:5]
	s_andn2_b64 vcc, exec, s[0:1]
	s_cbranch_vccnz .LBB0_2112
	v_readfirstlane_b32 s0, v174
	v_readlane_b32 s1, v246, 0
	s_lshr_b32 s0, s0, 6
	s_lshl_b32 s1, s1, 3
	s_add_i32 s0, s0, s1
	s_cmpk_gt_i32 s0, 0x3fff
	s_cbranch_scc1 .LBB0_2058
	s_ashr_i32 s1, s0, 31
	s_lshl_b32 s2, s74, 3
	s_lshl_b64 s[4:5], s[0:1], 13
	s_add_u32 s4, s68, s4
	v_lshlrev_b32_e32 v0, 4, v174
	s_addc_u32 s5, s69, s5
	v_and_b32_e32 v64, 0x3f0, v0
	v_mov_b32_e32 v65, 0
	v_lshl_add_u64 v[0:1], s[4:5], 0, v[64:65]
	s_movk_i32 s1, 0x1000
	s_waitcnt vmcnt(0)
	v_add_co_u32_e32 v24, vcc, s1, v0
	v_readlane_b32 s20, v246, 1
	s_nop 0
	v_addc_co_u32_e32 v25, vcc, 0, v1, vcc
	global_load_dwordx4 v[0:3], v[24:25], off offset:3072
	global_load_dwordx4 v[4:7], v[24:25], off offset:2048
	global_load_dwordx4 v[8:11], v[24:25], off offset:1024
	global_load_dwordx4 v[12:15], v[24:25], off
	global_load_dwordx4 v[16:19], v64, s[4:5] offset:3072
	global_load_dwordx4 v[20:23], v64, s[4:5] offset:2048
	global_load_dwordx4 v[56:59], v64, s[4:5] offset:1024
	global_load_dwordx4 v[60:63], v64, s[4:5]
	v_mbcnt_lo_u32_b32 v24, -1, 0
	v_readlane_b32 s21, v246, 2
	v_readlane_b32 s22, v246, 3
	v_readlane_b32 s23, v246, 4
	v_readlane_b32 s24, v246, 5
	v_readlane_b32 s25, v246, 6
	v_mbcnt_hi_u32_b32 v29, -1, v24
	v_readlane_b32 s26, v246, 7
	v_readlane_b32 s27, v246, 8
	s_mov_b64 s[20:21], s[24:25]
	s_mov_b64 s[8:9], 0x2000
	s_mov_b64 s[10:11], 0x3000
	s_mov_b64 s[12:13], 0x3400
	s_mov_b64 s[14:15], 0x3800
	s_mov_b64 s[16:17], 0x3c00
	v_lshl_add_u64 v[24:25], s[20:21], 0, v[64:65]
	v_and_b32_e32 v30, 64, v29
	v_xor_b32_e32 v31, 1, v29
	v_lshl_add_u64 v[66:67], v[24:25], 0, s[8:9]
	v_lshl_add_u64 v[70:71], v[24:25], 0, s[10:11]
	v_lshl_add_u64 v[74:75], v[24:25], 0, s[12:13]
	v_lshl_add_u64 v[78:79], v[24:25], 0, s[14:15]
	v_lshl_add_u64 v[82:83], v[24:25], 0, s[16:17]
	v_add_u32_e32 v24, 64, v30
	s_mov_b64 s[22:23], s[26:27]
	v_xor_b32_e32 v32, 2, v29
	v_cmp_lt_i32_e32 vcc, v31, v24
	v_lshl_add_u64 v[26:27], s[22:23], 0, v[64:65]
	v_xor_b32_e32 v33, 4, v29
	v_cndmask_b32_e32 v25, v29, v31, vcc
	v_cmp_lt_i32_e32 vcc, v32, v24
	v_xor_b32_e32 v34, 8, v29
	v_lshl_add_u64 v[68:69], v[26:27], 0, s[8:9]
	v_lshl_add_u64 v[72:73], v[26:27], 0, s[10:11]
	v_lshl_add_u64 v[76:77], v[26:27], 0, s[12:13]
	v_lshl_add_u64 v[80:81], v[26:27], 0, s[14:15]
	v_lshl_add_u64 v[84:85], v[26:27], 0, s[16:17]
	v_cndmask_b32_e32 v26, v29, v32, vcc
	v_cmp_lt_i32_e32 vcc, v33, v24
	v_xor_b32_e32 v35, 16, v29
	s_add_i32 s8, s0, s2
	v_cndmask_b32_e32 v27, v29, v33, vcc
	v_cmp_lt_i32_e32 vcc, v34, v24
	v_xor_b32_e32 v36, 32, v29
	s_ashr_i32 s9, s8, 31
	v_cndmask_b32_e32 v30, v29, v34, vcc
	v_cmp_lt_i32_e32 vcc, v35, v24
	s_lshl_b64 s[8:9], s[8:9], 13
	v_and_b32_e32 v28, 63, v174
	v_cndmask_b32_e32 v31, v29, v35, vcc
	v_cmp_lt_i32_e32 vcc, v36, v24
	s_add_u32 s8, s68, s8
	v_lshlrev_b32_e32 v64, 4, v28
	v_cndmask_b32_e32 v24, v29, v36, vcc
	v_lshlrev_b32_e32 v87, 2, v25
	v_lshlrev_b32_e32 v88, 2, v26
	v_lshlrev_b32_e32 v89, 2, v27
	v_lshlrev_b32_e32 v90, 2, v30
	v_lshlrev_b32_e32 v91, 2, v31
	v_lshlrev_b32_e32 v92, 2, v24
	s_addc_u32 s9, s69, s9
	s_ashr_i32 s3, s2, 31
	v_mov_b32_e32 v86, 0x3727c5ac
	s_mov_b32 s6, 0x800000
	s_lshl_b64 s[10:11], s[2:3], 13
	s_waitcnt vmcnt(7)
	v_mov_b64_e32 v[42:43], v[2:3]
	s_waitcnt vmcnt(6)
	v_mov_b64_e32 v[46:47], v[6:7]
	s_waitcnt vmcnt(5)
	v_mov_b64_e32 v[50:51], v[10:11]
	s_waitcnt vmcnt(4)
	v_mov_b64_e32 v[54:55], v[14:15]
	s_waitcnt vmcnt(3)
	v_mov_b64_e32 v[26:27], v[18:19]
	s_waitcnt vmcnt(2)
	v_mov_b64_e32 v[30:31], v[22:23]
	s_waitcnt vmcnt(1)
	v_mov_b64_e32 v[32:33], v[56:57]
	s_waitcnt vmcnt(0)
	v_mov_b64_e32 v[36:37], v[60:61]
	v_mov_b64_e32 v[40:41], v[0:1]
	v_mov_b64_e32 v[44:45], v[4:5]
	v_mov_b64_e32 v[48:49], v[8:9]
	v_mov_b64_e32 v[52:53], v[12:13]
	v_mov_b64_e32 v[24:25], v[16:17]
	v_mov_b64_e32 v[28:29], v[20:21]
	v_mov_b64_e32 v[34:35], v[58:59]
	v_mov_b64_e32 v[38:39], v[62:63]
	s_branch .LBB0_2056
